# non-temporal hints on more single-use streams: P4 epilogue gate loads, attention Q and gate loads, f32 weight / adaLN weight loads in the conversion and gemv code
# speedup vs baseline: 1.0034x; 1.0034x over previous
; __device__ __forceinline__ float silu_f(float v) { return v * __builtin_amdgcn_rcpf(1.f + __builtin_amdgcn_exp2f(-1.4426950408889634f * v)); }
; __device__ __forceinline__ void gemv_item(const float* c, const float* c_ctx, const float* ada_w, const float* ada_b, float* mod, int it, int lane) {
;     const int l = it / 768, rem = it % 768, kc = rem / 24, cgp = rem % 24, k0 = kc * 64;
;     float s[9];
; #pragma unroll
;     for (int r = 0; r < 8; ++r) s[r] = silu_f(c[r * DM + k0 + lane]);
;     s[8] = silu_f(c_ctx[k0 + lane]);
;     const float* W = ada_w + (size_t)l * DM * 6144 + (size_t)k0 * 6144 + cgp * 256 + lane * 4;
;     f32x4 acc[9];
; #pragma unroll
;     for (int r = 0; r < 9; ++r) acc[r] = (f32x4){0.f, 0.f, 0.f, 0.f};
; #pragma unroll 16
;     for (int kk = 0; kk < 64; ++kk) { const f32x4 w = *(const f32x4*)(W + (size_t)kk * 6144);
; #pragma unroll
;         for (int r = 0; r < 9; ++r) { const float sk = __uint_as_float(__builtin_amdgcn_readlane(__float_as_uint(s[r]), kk)); acc[r] += w * sk; } }
.LBB0_25:
	s_mov_b32 s0, 0xfffd0000
	v_add_co_u32_e32 v46, vcc, s0, v20
	global_load_dwordx4 v[0:3], v[20:21], off nt
	s_nop 0
	v_addc_co_u32_e32 v47, vcc, -1, v21, vcc
	global_load_dwordx4 v[88:91], v[46:47], off nt
	s_mov_b32 s0, 0xfffd6000
	v_add_co_u32_e64 v50, s[0:1], s0, v20
	v_readlane_b32 s30, v79, s45
	v_readlane_b32 s34, v81, s45
	v_readlane_b32 s36, v82, s45
	v_readlane_b32 s38, v83, s45
	v_readlane_b32 s40, v84, s45
	v_readlane_b32 s42, v85, s45
	v_readlane_b32 s44, v86, s45
	v_readlane_b32 s46, v87, s45
	v_readlane_b32 s48, v80, s45
	s_add_i32 s47, s45, 1
	s_add_i32 s49, s45, 2
	s_add_i32 s50, s45, 3
	s_add_i32 s51, s45, 4
	s_add_i32 s52, s45, 5
	s_add_i32 s53, s45, 6
	s_add_i32 s54, s45, 7
	s_add_i32 s55, s45, 8
	s_add_i32 s56, s45, 9
	s_add_i32 s60, s45, 10
	s_add_i32 s69, s45, 11
	s_add_i32 s70, s45, 12
	s_add_i32 s71, s45, 13
	s_add_i32 s72, s45, 14
	s_add_i32 s73, s45, 15
	s_add_i32 s45, s45, 16
	v_addc_co_u32_e64 v51, vcc, -1, v21, s[0:1]
	s_mov_b32 s4, 0xfffdc000
	v_add_co_u32_e64 v48, s[28:29], s4, v20
	s_mov_b32 s4, 0xfffe2000
	s_mov_b32 s6, 0xfffe8000
	s_mov_b32 s8, 0xfffee000
	s_mov_b32 s10, 0xffff4000
	s_movk_i32 s12, 0xa000
	s_mov_b32 s18, 0x12000
	v_add_co_u32_e64 v52, s[4:5], s4, v20
	v_add_co_u32_e64 v54, s[6:7], s6, v20
	v_add_co_u32_e64 v56, s[8:9], s8, v20
	v_add_co_u32_e64 v58, s[10:11], s10, v20
	v_add_co_u32_e64 v60, s[12:13], s12, v20
	v_add_co_u32_e64 v62, s[14:15], s35, v20
	v_add_co_u32_e64 v64, s[16:17], s37, v20
	v_add_co_u32_e64 v66, s[18:19], s18, v20
	v_addc_co_u32_e64 v49, vcc, -1, v21, s[28:29]
	v_addc_co_u32_e64 v53, vcc, -1, v21, s[4:5]
	v_addc_co_u32_e64 v55, vcc, -1, v21, s[6:7]
	v_addc_co_u32_e64 v57, vcc, -1, v21, s[8:9]
	v_addc_co_u32_e64 v59, vcc, -1, v21, s[10:11]
	v_addc_co_u32_e64 v61, vcc, -1, v21, s[12:13]
	v_addc_co_u32_e64 v63, vcc, 0, v21, s[14:15]
	v_addc_co_u32_e64 v65, vcc, 0, v21, s[16:17]
	v_addc_co_u32_e64 v67, vcc, 0, v21, s[18:19]
	v_readlane_b32 s0, v79, s47
	v_readlane_b32 s4, v81, s47
	v_readlane_b32 s6, v82, s47
	v_readlane_b32 s8, v83, s47
	v_readlane_b32 s10, v84, s47
	v_readlane_b32 s12, v85, s47
	s_waitcnt vmcnt(0)
	v_pk_fma_f32 v[44:45], v[88:89], s[30:31], v[44:45] op_sel_hi:[1,0,1]
	v_pk_fma_f32 v[40:41], v[88:89], s[34:35], v[40:41] op_sel_hi:[1,0,1]
	v_pk_fma_f32 v[36:37], v[88:89], s[36:37], v[36:37] op_sel_hi:[1,0,1]
	v_pk_fma_f32 v[32:33], v[88:89], s[38:39], v[32:33] op_sel_hi:[1,0,1]
	v_pk_fma_f32 v[28:29], v[88:89], s[40:41], v[28:29] op_sel_hi:[1,0,1]
	v_pk_fma_f32 v[24:25], v[88:89], s[42:43], v[24:25] op_sel_hi:[1,0,1]
	v_pk_fma_f32 v[14:15], v[88:89], s[44:45], v[14:15] op_sel_hi:[1,0,1]
	v_pk_fma_f32 v[10:11], v[88:89], s[46:47], v[10:11] op_sel_hi:[1,0,1]
	v_pk_fma_f32 v[46:47], v[90:91], s[48:49], v[4:5] op_sel_hi:[1,0,1]
	v_pk_fma_f32 v[88:89], v[88:89], s[48:49], v[6:7] op_sel_hi:[1,0,1]
	global_load_dwordx4 v[4:7], v[50:51], off nt
	v_readlane_b32 s14, v86, s47
	v_readlane_b32 s16, v87, s47
	v_readlane_b32 s18, v80, s47
	v_pk_fma_f32 v[42:43], v[90:91], s[30:31], v[42:43] op_sel_hi:[1,0,1]
	v_pk_fma_f32 v[38:39], v[90:91], s[34:35], v[38:39] op_sel_hi:[1,0,1]
	v_pk_fma_f32 v[34:35], v[90:91], s[36:37], v[34:35] op_sel_hi:[1,0,1]
	v_pk_fma_f32 v[30:31], v[90:91], s[38:39], v[30:31] op_sel_hi:[1,0,1]
	v_pk_fma_f32 v[26:27], v[90:91], s[40:41], v[26:27] op_sel_hi:[1,0,1]
	v_pk_fma_f32 v[22:23], v[90:91], s[42:43], v[22:23] op_sel_hi:[1,0,1]
	v_pk_fma_f32 v[12:13], v[90:91], s[44:45], v[12:13] op_sel_hi:[1,0,1]
	v_pk_fma_f32 v[8:9], v[90:91], s[46:47], v[8:9] op_sel_hi:[1,0,1]
	s_mov_b32 s20, 0x18000
	s_mov_b32 s22, 0x1e000
	s_mov_b32 s24, 0x24000
	s_mov_b32 s26, 0x2a000
	v_add_co_u32_e64 v68, s[20:21], s20, v20
	v_add_co_u32_e64 v70, s[22:23], s22, v20
	v_add_co_u32_e64 v72, s[24:25], s24, v20
	v_add_co_u32_e64 v74, s[26:27], s26, v20
	v_addc_co_u32_e64 v69, vcc, 0, v21, s[20:21]
	v_addc_co_u32_e64 v71, vcc, 0, v21, s[22:23]
	v_addc_co_u32_e64 v73, vcc, 0, v21, s[24:25]
	v_addc_co_u32_e64 v75, vcc, 0, v21, s[26:27]
	v_readlane_b32 s20, v79, s49
	v_readlane_b32 s22, v81, s49
	v_readlane_b32 s24, v82, s49
	v_readlane_b32 s26, v83, s49
	v_readlane_b32 s28, v84, s49
	v_readlane_b32 s58, v85, s49
	v_readlane_b32 s62, v86, s49
	v_readlane_b32 s64, v87, s49
	v_readlane_b32 s66, v80, s49
	v_readlane_b32 s68, v79, s50
	v_readlane_b32 s30, v81, s50
	v_readlane_b32 s34, v82, s50
	v_readlane_b32 s36, v83, s50
	v_readlane_b32 s38, v84, s50
	v_readlane_b32 s40, v85, s50
	v_readlane_b32 s42, v86, s50
	v_readlane_b32 s44, v87, s50
	v_readlane_b32 s50, v80, s50
	v_readlane_b32 s46, v79, s51
	v_readlane_b32 s48, v81, s51
	v_readlane_b32 s74, v79, s54
	v_readlane_b32 s80, v81, s54
	v_readlane_b32 s82, v85, s54
	v_readlane_b32 s84, v80, s54
	v_readlane_b32 s86, v82, s55
	v_readlane_b32 s88, v84, s55
	v_readlane_b32 s90, v85, s55
	v_readlane_b32 s92, v85, s56
	v_readlane_b32 s94, v86, s56
	v_readlane_b32 s76, v87, s56
	s_cmp_eq_u32 s45, 64
	s_waitcnt vmcnt(0)
; __device__ __forceinline__ void gemv_item(const float* c, const float* c_ctx, const float* ada_w, const float* ada_b, float* mod, int it, int lane) {
;     ...
;     for (int kk = 0; kk < 64; ++kk) { const f32x4 w = *(const f32x4*)(W + (size_t)kk * 6144);
; #pragma unroll
;         for (int r = 0; r < 9; ++r) { const float sk = __uint_as_float(__builtin_amdgcn_readlane(__float_as_uint(s[r]), kk)); acc[r] += w * sk; } }
	v_pk_fma_f32 v[42:43], v[6:7], s[0:1], v[42:43] op_sel_hi:[1,0,1]
	v_pk_fma_f32 v[44:45], v[4:5], s[0:1], v[44:45] op_sel_hi:[1,0,1]
	v_pk_fma_f32 v[38:39], v[6:7], s[4:5], v[38:39] op_sel_hi:[1,0,1]
	v_pk_fma_f32 v[40:41], v[4:5], s[4:5], v[40:41] op_sel_hi:[1,0,1]
	v_pk_fma_f32 v[34:35], v[6:7], s[6:7], v[34:35] op_sel_hi:[1,0,1]
	v_pk_fma_f32 v[36:37], v[4:5], s[6:7], v[36:37] op_sel_hi:[1,0,1]
	v_pk_fma_f32 v[30:31], v[6:7], s[8:9], v[30:31] op_sel_hi:[1,0,1]
	v_pk_fma_f32 v[32:33], v[4:5], s[8:9], v[32:33] op_sel_hi:[1,0,1]
	v_pk_fma_f32 v[26:27], v[6:7], s[10:11], v[26:27] op_sel_hi:[1,0,1]
	v_pk_fma_f32 v[28:29], v[4:5], s[10:11], v[28:29] op_sel_hi:[1,0,1]
	v_pk_fma_f32 v[22:23], v[6:7], s[12:13], v[22:23] op_sel_hi:[1,0,1]
	v_pk_fma_f32 v[24:25], v[4:5], s[12:13], v[24:25] op_sel_hi:[1,0,1]
	v_pk_fma_f32 v[12:13], v[6:7], s[14:15], v[12:13] op_sel_hi:[1,0,1]
	v_pk_fma_f32 v[14:15], v[4:5], s[14:15], v[14:15] op_sel_hi:[1,0,1]
	v_pk_fma_f32 v[8:9], v[6:7], s[16:17], v[8:9] op_sel_hi:[1,0,1]
	v_pk_fma_f32 v[10:11], v[4:5], s[16:17], v[10:11] op_sel_hi:[1,0,1]
	v_pk_fma_f32 v[46:47], v[6:7], s[18:19], v[46:47] op_sel_hi:[1,0,1]
	v_pk_fma_f32 v[50:51], v[4:5], s[18:19], v[88:89] op_sel_hi:[1,0,1]
	global_load_dwordx4 v[4:7], v[48:49], off nt
	v_readlane_b32 s0, v82, s51
	v_readlane_b32 s4, v83, s51
	v_readlane_b32 s6, v84, s51
	v_readlane_b32 s8, v85, s51
	v_readlane_b32 s10, v86, s51
	v_readlane_b32 s12, v87, s51
	v_readlane_b32 s14, v80, s51
	v_readlane_b32 s16, v79, s52
	v_readlane_b32 s18, v81, s52
	s_waitcnt vmcnt(0)
	v_pk_fma_f32 v[42:43], v[6:7], s[20:21], v[42:43] op_sel_hi:[1,0,1]
	v_pk_fma_f32 v[44:45], v[4:5], s[20:21], v[44:45] op_sel_hi:[1,0,1]
	v_pk_fma_f32 v[38:39], v[6:7], s[22:23], v[38:39] op_sel_hi:[1,0,1]
	v_pk_fma_f32 v[40:41], v[4:5], s[22:23], v[40:41] op_sel_hi:[1,0,1]
	v_pk_fma_f32 v[34:35], v[6:7], s[24:25], v[34:35] op_sel_hi:[1,0,1]
	v_pk_fma_f32 v[36:37], v[4:5], s[24:25], v[36:37] op_sel_hi:[1,0,1]
	v_pk_fma_f32 v[30:31], v[6:7], s[26:27], v[30:31] op_sel_hi:[1,0,1]
	v_pk_fma_f32 v[32:33], v[4:5], s[26:27], v[32:33] op_sel_hi:[1,0,1]
	v_pk_fma_f32 v[26:27], v[6:7], s[28:29], v[26:27] op_sel_hi:[1,0,1]
	v_pk_fma_f32 v[28:29], v[4:5], s[28:29], v[28:29] op_sel_hi:[1,0,1]
	v_pk_fma_f32 v[22:23], v[6:7], s[58:59], v[22:23] op_sel_hi:[1,0,1]
	v_pk_fma_f32 v[24:25], v[4:5], s[58:59], v[24:25] op_sel_hi:[1,0,1]
	v_pk_fma_f32 v[12:13], v[6:7], s[62:63], v[12:13] op_sel_hi:[1,0,1]
	v_pk_fma_f32 v[14:15], v[4:5], s[62:63], v[14:15] op_sel_hi:[1,0,1]
	v_pk_fma_f32 v[8:9], v[6:7], s[64:65], v[8:9] op_sel_hi:[1,0,1]
	v_pk_fma_f32 v[10:11], v[4:5], s[64:65], v[10:11] op_sel_hi:[1,0,1]
	v_pk_fma_f32 v[46:47], v[6:7], s[66:67], v[46:47] op_sel_hi:[1,0,1]
	v_pk_fma_f32 v[48:49], v[4:5], s[66:67], v[50:51] op_sel_hi:[1,0,1]
	global_load_dwordx4 v[4:7], v[52:53], off nt
	v_readlane_b32 s20, v82, s52
	v_readlane_b32 s22, v83, s52
	v_readlane_b32 s24, v84, s52
	v_readlane_b32 s26, v85, s52
	v_readlane_b32 s28, v86, s52
	v_readlane_b32 s58, v87, s52
	v_readlane_b32 s52, v80, s52
	v_readlane_b32 s62, v79, s53
	v_readlane_b32 s64, v81, s53
	v_readlane_b32 s66, v82, s53
	s_waitcnt vmcnt(0)
	v_pk_fma_f32 v[42:43], v[6:7], s[68:69], v[42:43] op_sel_hi:[1,0,1]
	v_pk_fma_f32 v[44:45], v[4:5], s[68:69], v[44:45] op_sel_hi:[1,0,1]
	v_pk_fma_f32 v[38:39], v[6:7], s[30:31], v[38:39] op_sel_hi:[1,0,1]
	v_pk_fma_f32 v[40:41], v[4:5], s[30:31], v[40:41] op_sel_hi:[1,0,1]
	v_pk_fma_f32 v[34:35], v[6:7], s[34:35], v[34:35] op_sel_hi:[1,0,1]
	v_pk_fma_f32 v[36:37], v[4:5], s[34:35], v[36:37] op_sel_hi:[1,0,1]
	v_pk_fma_f32 v[30:31], v[6:7], s[36:37], v[30:31] op_sel_hi:[1,0,1]
	v_pk_fma_f32 v[32:33], v[4:5], s[36:37], v[32:33] op_sel_hi:[1,0,1]
	v_pk_fma_f32 v[26:27], v[6:7], s[38:39], v[26:27] op_sel_hi:[1,0,1]
	v_pk_fma_f32 v[28:29], v[4:5], s[38:39], v[28:29] op_sel_hi:[1,0,1]
	v_pk_fma_f32 v[22:23], v[6:7], s[40:41], v[22:23] op_sel_hi:[1,0,1]
	v_pk_fma_f32 v[24:25], v[4:5], s[40:41], v[24:25] op_sel_hi:[1,0,1]
	v_pk_fma_f32 v[12:13], v[6:7], s[42:43], v[12:13] op_sel_hi:[1,0,1]
	v_pk_fma_f32 v[14:15], v[4:5], s[42:43], v[14:15] op_sel_hi:[1,0,1]
	v_pk_fma_f32 v[8:9], v[6:7], s[44:45], v[8:9] op_sel_hi:[1,0,1]
	v_pk_fma_f32 v[10:11], v[4:5], s[44:45], v[10:11] op_sel_hi:[1,0,1]
	v_pk_fma_f32 v[46:47], v[6:7], s[50:51], v[46:47] op_sel_hi:[1,0,1]
	v_pk_fma_f32 v[48:49], v[4:5], s[50:51], v[48:49] op_sel_hi:[1,0,1]
	global_load_dwordx4 v[4:7], v[54:55], off nt
	v_readlane_b32 s68, v83, s53
	v_readlane_b32 s30, v84, s53
	v_readlane_b32 s34, v85, s53
	v_readlane_b32 s36, v86, s53
	v_readlane_b32 s38, v87, s53
	v_readlane_b32 s40, v80, s53
	v_readlane_b32 s50, v82, s54
	v_readlane_b32 s42, v83, s60
	v_readlane_b32 s44, v84, s60
	global_load_dwordx4 v[52:55], v[66:67], off nt
	s_waitcnt vmcnt(1)
	v_pk_fma_f32 v[42:43], v[6:7], s[46:47], v[42:43] op_sel_hi:[1,0,1]
	v_pk_fma_f32 v[44:45], v[4:5], s[46:47], v[44:45] op_sel_hi:[1,0,1]
	v_pk_fma_f32 v[38:39], v[6:7], s[48:49], v[38:39] op_sel_hi:[1,0,1]
	v_pk_fma_f32 v[40:41], v[4:5], s[48:49], v[40:41] op_sel_hi:[1,0,1]
	v_pk_fma_f32 v[34:35], v[6:7], s[0:1], v[34:35] op_sel_hi:[1,0,1]
	v_pk_fma_f32 v[36:37], v[4:5], s[0:1], v[36:37] op_sel_hi:[1,0,1]
	v_pk_fma_f32 v[30:31], v[6:7], s[4:5], v[30:31] op_sel_hi:[1,0,1]
	v_pk_fma_f32 v[32:33], v[4:5], s[4:5], v[32:33] op_sel_hi:[1,0,1]
	v_pk_fma_f32 v[26:27], v[6:7], s[6:7], v[26:27] op_sel_hi:[1,0,1]
	v_pk_fma_f32 v[28:29], v[4:5], s[6:7], v[28:29] op_sel_hi:[1,0,1]
	v_pk_fma_f32 v[22:23], v[6:7], s[8:9], v[22:23] op_sel_hi:[1,0,1]
	v_pk_fma_f32 v[24:25], v[4:5], s[8:9], v[24:25] op_sel_hi:[1,0,1]
	v_pk_fma_f32 v[12:13], v[6:7], s[10:11], v[12:13] op_sel_hi:[1,0,1]
	v_pk_fma_f32 v[14:15], v[4:5], s[10:11], v[14:15] op_sel_hi:[1,0,1]
	v_pk_fma_f32 v[8:9], v[6:7], s[12:13], v[8:9] op_sel_hi:[1,0,1]
	v_pk_fma_f32 v[10:11], v[4:5], s[12:13], v[10:11] op_sel_hi:[1,0,1]
	v_pk_fma_f32 v[46:47], v[6:7], s[14:15], v[46:47] op_sel_hi:[1,0,1]
	v_pk_fma_f32 v[48:49], v[4:5], s[14:15], v[48:49] op_sel_hi:[1,0,1]
	global_load_dwordx4 v[4:7], v[56:57], off nt
	v_readlane_b32 s46, v83, s54
	v_readlane_b32 s48, v84, s54
	v_readlane_b32 s4, v86, s54
	v_readlane_b32 s6, v87, s54
	v_readlane_b32 s8, v79, s55
	v_readlane_b32 s10, v81, s55
	v_readlane_b32 s0, v83, s55
	v_readlane_b32 s12, v79, s56
	v_readlane_b32 s14, v81, s56
	v_readlane_b32 s54, v85, s60
	s_waitcnt vmcnt(0)
; __device__ __forceinline__ void gemv_item(const float* c, const float* c_ctx, const float* ada_w, const float* ada_b, float* mod, int it, int lane) {
;     ...
;     for (int kk = 0; kk < 64; ++kk) { const f32x4 w = *(const f32x4*)(W + (size_t)kk * 6144);
; #pragma unroll
;         for (int r = 0; r < 9; ++r) { const float sk = __uint_as_float(__builtin_amdgcn_readlane(__float_as_uint(s[r]), kk)); acc[r] += w * sk; } }
	v_pk_fma_f32 v[42:43], v[6:7], s[16:17], v[42:43] op_sel_hi:[1,0,1]
	v_pk_fma_f32 v[44:45], v[4:5], s[16:17], v[44:45] op_sel_hi:[1,0,1]
	v_pk_fma_f32 v[38:39], v[6:7], s[18:19], v[38:39] op_sel_hi:[1,0,1]
	v_pk_fma_f32 v[40:41], v[4:5], s[18:19], v[40:41] op_sel_hi:[1,0,1]
	v_pk_fma_f32 v[34:35], v[6:7], s[20:21], v[34:35] op_sel_hi:[1,0,1]
	v_pk_fma_f32 v[36:37], v[4:5], s[20:21], v[36:37] op_sel_hi:[1,0,1]
	v_pk_fma_f32 v[30:31], v[6:7], s[22:23], v[30:31] op_sel_hi:[1,0,1]
	v_pk_fma_f32 v[32:33], v[4:5], s[22:23], v[32:33] op_sel_hi:[1,0,1]
	v_pk_fma_f32 v[26:27], v[6:7], s[24:25], v[26:27] op_sel_hi:[1,0,1]
	v_pk_fma_f32 v[28:29], v[4:5], s[24:25], v[28:29] op_sel_hi:[1,0,1]
	v_pk_fma_f32 v[22:23], v[6:7], s[26:27], v[22:23] op_sel_hi:[1,0,1]
	v_pk_fma_f32 v[24:25], v[4:5], s[26:27], v[24:25] op_sel_hi:[1,0,1]
	v_pk_fma_f32 v[12:13], v[6:7], s[28:29], v[12:13] op_sel_hi:[1,0,1]
	v_pk_fma_f32 v[14:15], v[4:5], s[28:29], v[14:15] op_sel_hi:[1,0,1]
	v_pk_fma_f32 v[8:9], v[6:7], s[58:59], v[8:9] op_sel_hi:[1,0,1]
	v_pk_fma_f32 v[10:11], v[4:5], s[58:59], v[10:11] op_sel_hi:[1,0,1]
	v_pk_fma_f32 v[46:47], v[6:7], s[52:53], v[46:47] op_sel_hi:[1,0,1]
	v_pk_fma_f32 v[48:49], v[4:5], s[52:53], v[48:49] op_sel_hi:[1,0,1]
	global_load_dwordx4 v[4:7], v[58:59], off nt
	v_readlane_b32 s20, v86, s55
	v_readlane_b32 s22, v87, s55
	v_readlane_b32 s24, v80, s55
	v_readlane_b32 s16, v82, s56
	v_readlane_b32 s18, v83, s56
	v_readlane_b32 s26, v84, s56
	v_readlane_b32 s28, v80, s56
	v_readlane_b32 s56, v86, s60
	v_readlane_b32 s52, v81, s60
	v_readlane_b32 s58, v87, s60
	s_waitcnt vmcnt(0)
	v_pk_fma_f32 v[42:43], v[6:7], s[62:63], v[42:43] op_sel_hi:[1,0,1]
	v_pk_fma_f32 v[44:45], v[4:5], s[62:63], v[44:45] op_sel_hi:[1,0,1]
	v_pk_fma_f32 v[38:39], v[6:7], s[64:65], v[38:39] op_sel_hi:[1,0,1]
	v_pk_fma_f32 v[40:41], v[4:5], s[64:65], v[40:41] op_sel_hi:[1,0,1]
	v_pk_fma_f32 v[34:35], v[6:7], s[66:67], v[34:35] op_sel_hi:[1,0,1]
	v_pk_fma_f32 v[36:37], v[4:5], s[66:67], v[36:37] op_sel_hi:[1,0,1]
	v_pk_fma_f32 v[30:31], v[6:7], s[68:69], v[30:31] op_sel_hi:[1,0,1]
	v_pk_fma_f32 v[32:33], v[4:5], s[68:69], v[32:33] op_sel_hi:[1,0,1]
	v_pk_fma_f32 v[26:27], v[6:7], s[30:31], v[26:27] op_sel_hi:[1,0,1]
	v_pk_fma_f32 v[28:29], v[4:5], s[30:31], v[28:29] op_sel_hi:[1,0,1]
	v_pk_fma_f32 v[22:23], v[6:7], s[34:35], v[22:23] op_sel_hi:[1,0,1]
	v_pk_fma_f32 v[24:25], v[4:5], s[34:35], v[24:25] op_sel_hi:[1,0,1]
	v_pk_fma_f32 v[12:13], v[6:7], s[36:37], v[12:13] op_sel_hi:[1,0,1]
	v_pk_fma_f32 v[14:15], v[4:5], s[36:37], v[14:15] op_sel_hi:[1,0,1]
	v_pk_fma_f32 v[8:9], v[6:7], s[38:39], v[8:9] op_sel_hi:[1,0,1]
	v_pk_fma_f32 v[10:11], v[4:5], s[38:39], v[10:11] op_sel_hi:[1,0,1]
	v_pk_fma_f32 v[46:47], v[6:7], s[40:41], v[46:47] op_sel_hi:[1,0,1]
	v_pk_fma_f32 v[48:49], v[4:5], s[40:41], v[48:49] op_sel_hi:[1,0,1]
	global_load_dwordx4 v[4:7], v[60:61], off nt
	v_readlane_b32 s30, v79, s60
	v_readlane_b32 s34, v82, s60
	v_readlane_b32 s68, v80, s60
	v_readlane_b32 s66, v86, s69
	v_readlane_b32 s60, v83, s69
	v_readlane_b32 s62, v84, s69
	v_readlane_b32 s64, v85, s69
	v_readlane_b32 s40, v87, s69
	v_readlane_b32 s36, v80, s69
	v_readlane_b32 s38, v79, s70
	s_waitcnt vmcnt(0)
	v_pk_fma_f32 v[42:43], v[6:7], s[74:75], v[42:43] op_sel_hi:[1,0,1]
	v_pk_fma_f32 v[44:45], v[4:5], s[74:75], v[44:45] op_sel_hi:[1,0,1]
	v_pk_fma_f32 v[38:39], v[6:7], s[80:81], v[38:39] op_sel_hi:[1,0,1]
	v_pk_fma_f32 v[40:41], v[4:5], s[80:81], v[40:41] op_sel_hi:[1,0,1]
	v_pk_fma_f32 v[34:35], v[6:7], s[50:51], v[34:35] op_sel_hi:[1,0,1]
	v_pk_fma_f32 v[36:37], v[4:5], s[50:51], v[36:37] op_sel_hi:[1,0,1]
	v_pk_fma_f32 v[30:31], v[6:7], s[46:47], v[30:31] op_sel_hi:[1,0,1]
	v_pk_fma_f32 v[32:33], v[4:5], s[46:47], v[32:33] op_sel_hi:[1,0,1]
	v_pk_fma_f32 v[26:27], v[6:7], s[48:49], v[26:27] op_sel_hi:[1,0,1]
	v_pk_fma_f32 v[28:29], v[4:5], s[48:49], v[28:29] op_sel_hi:[1,0,1]
	v_pk_fma_f32 v[22:23], v[6:7], s[82:83], v[22:23] op_sel_hi:[1,0,1]
	v_pk_fma_f32 v[24:25], v[4:5], s[82:83], v[24:25] op_sel_hi:[1,0,1]
	v_pk_fma_f32 v[12:13], v[6:7], s[4:5], v[12:13] op_sel_hi:[1,0,1]
	v_pk_fma_f32 v[14:15], v[4:5], s[4:5], v[14:15] op_sel_hi:[1,0,1]
	v_pk_fma_f32 v[8:9], v[6:7], s[6:7], v[8:9] op_sel_hi:[1,0,1]
	v_pk_fma_f32 v[10:11], v[4:5], s[6:7], v[10:11] op_sel_hi:[1,0,1]
	v_pk_fma_f32 v[6:7], v[6:7], s[84:85], v[46:47] op_sel_hi:[1,0,1]
	v_pk_fma_f32 v[4:5], v[4:5], s[84:85], v[48:49] op_sel_hi:[1,0,1]
	v_pk_fma_f32 v[42:43], v[2:3], s[8:9], v[42:43] op_sel_hi:[1,0,1]
	v_pk_fma_f32 v[44:45], v[0:1], s[8:9], v[44:45] op_sel_hi:[1,0,1]
	v_pk_fma_f32 v[38:39], v[2:3], s[10:11], v[38:39] op_sel_hi:[1,0,1]
	v_pk_fma_f32 v[40:41], v[0:1], s[10:11], v[40:41] op_sel_hi:[1,0,1]
	v_pk_fma_f32 v[34:35], v[2:3], s[86:87], v[34:35] op_sel_hi:[1,0,1]
	v_pk_fma_f32 v[36:37], v[0:1], s[86:87], v[36:37] op_sel_hi:[1,0,1]
	v_pk_fma_f32 v[30:31], v[2:3], s[0:1], v[30:31] op_sel_hi:[1,0,1]
	v_pk_fma_f32 v[32:33], v[0:1], s[0:1], v[32:33] op_sel_hi:[1,0,1]
	v_pk_fma_f32 v[26:27], v[2:3], s[88:89], v[26:27] op_sel_hi:[1,0,1]
	v_pk_fma_f32 v[28:29], v[0:1], s[88:89], v[28:29] op_sel_hi:[1,0,1]
	v_pk_fma_f32 v[22:23], v[2:3], s[90:91], v[22:23] op_sel_hi:[1,0,1]
	v_pk_fma_f32 v[24:25], v[0:1], s[90:91], v[24:25] op_sel_hi:[1,0,1]
	v_pk_fma_f32 v[12:13], v[2:3], s[20:21], v[12:13] op_sel_hi:[1,0,1]
	v_pk_fma_f32 v[14:15], v[0:1], s[20:21], v[14:15] op_sel_hi:[1,0,1]
	v_pk_fma_f32 v[8:9], v[2:3], s[22:23], v[8:9] op_sel_hi:[1,0,1]
	v_pk_fma_f32 v[10:11], v[0:1], s[22:23], v[10:11] op_sel_hi:[1,0,1]
	v_pk_fma_f32 v[6:7], v[2:3], s[24:25], v[6:7] op_sel_hi:[1,0,1]
	v_pk_fma_f32 v[4:5], v[0:1], s[24:25], v[4:5] op_sel_hi:[1,0,1]
	global_load_dwordx4 v[0:3], v[62:63], off nt
	v_readlane_b32 s46, v79, s69
	v_readlane_b32 s48, v81, s69
	v_readlane_b32 s50, v82, s69
	v_readlane_b32 s0, v81, s70
	v_readlane_b32 s4, v82, s70
	v_readlane_b32 s6, v83, s70
	v_readlane_b32 s8, v84, s70
	v_readlane_b32 s10, v85, s70
	v_readlane_b32 s20, v81, s71
	v_readlane_b32 s22, v82, s71
	v_readlane_b32 s24, v83, s71
	v_readlane_b32 s84, v86, s71
	v_readlane_b32 s82, v79, s72
	v_readlane_b32 s80, v81, s72
	v_readlane_b32 s86, v82, s72
	v_readlane_b32 s90, v84, s72
	v_readlane_b32 s88, v85, s72
	s_waitcnt vmcnt(0)
; __device__ __forceinline__ void gemv_item(const float* c, const float* c_ctx, const float* ada_w, const float* ada_b, float* mod, int it, int lane) {
;     ...
;     for (int kk = 0; kk < 64; ++kk) { const f32x4 w = *(const f32x4*)(W + (size_t)kk * 6144);
; #pragma unroll
;         for (int r = 0; r < 9; ++r) { const float sk = __uint_as_float(__builtin_amdgcn_readlane(__float_as_uint(s[r]), kk)); acc[r] += w * sk; } }
	v_pk_fma_f32 v[42:43], v[2:3], s[12:13], v[42:43] op_sel_hi:[1,0,1]
	v_pk_fma_f32 v[44:45], v[0:1], s[12:13], v[44:45] op_sel_hi:[1,0,1]
	v_pk_fma_f32 v[38:39], v[2:3], s[14:15], v[38:39] op_sel_hi:[1,0,1]
	v_pk_fma_f32 v[40:41], v[0:1], s[14:15], v[40:41] op_sel_hi:[1,0,1]
	v_pk_fma_f32 v[34:35], v[2:3], s[16:17], v[34:35] op_sel_hi:[1,0,1]
	v_pk_fma_f32 v[36:37], v[0:1], s[16:17], v[36:37] op_sel_hi:[1,0,1]
	v_pk_fma_f32 v[30:31], v[2:3], s[18:19], v[30:31] op_sel_hi:[1,0,1]
	v_pk_fma_f32 v[32:33], v[0:1], s[18:19], v[32:33] op_sel_hi:[1,0,1]
	v_pk_fma_f32 v[26:27], v[2:3], s[26:27], v[26:27] op_sel_hi:[1,0,1]
	v_pk_fma_f32 v[28:29], v[0:1], s[26:27], v[28:29] op_sel_hi:[1,0,1]
	v_pk_fma_f32 v[22:23], v[2:3], s[92:93], v[22:23] op_sel_hi:[1,0,1]
	v_pk_fma_f32 v[24:25], v[0:1], s[92:93], v[24:25] op_sel_hi:[1,0,1]
	v_pk_fma_f32 v[12:13], v[2:3], s[94:95], v[12:13] op_sel_hi:[1,0,1]
	v_pk_fma_f32 v[14:15], v[0:1], s[94:95], v[14:15] op_sel_hi:[1,0,1]
	v_pk_fma_f32 v[8:9], v[2:3], s[76:77], v[8:9] op_sel_hi:[1,0,1]
	v_pk_fma_f32 v[10:11], v[0:1], s[76:77], v[10:11] op_sel_hi:[1,0,1]
	v_pk_fma_f32 v[6:7], v[2:3], s[28:29], v[6:7] op_sel_hi:[1,0,1]
	v_pk_fma_f32 v[4:5], v[0:1], s[28:29], v[4:5] op_sel_hi:[1,0,1]
	global_load_dwordx4 v[0:3], v[64:65], off nt
	v_readlane_b32 s12, v86, s70
	v_readlane_b32 s14, v87, s70
	v_readlane_b32 s16, v80, s70
	v_readlane_b32 s18, v79, s71
	v_readlane_b32 s26, v84, s71
	v_readlane_b32 s28, v85, s71
	v_readlane_b32 s94, v87, s71
	v_readlane_b32 s92, v85, s73
	v_readlane_b32 s70, v80, s73
	s_waitcnt vmcnt(0)
	v_pk_fma_f32 v[42:43], v[2:3], s[30:31], v[42:43] op_sel_hi:[1,0,1]
	v_pk_fma_f32 v[44:45], v[0:1], s[30:31], v[44:45] op_sel_hi:[1,0,1]
	v_pk_fma_f32 v[12:13], v[2:3], s[56:57], v[12:13] op_sel_hi:[1,0,1]
	v_pk_fma_f32 v[14:15], v[0:1], s[56:57], v[14:15] op_sel_hi:[1,0,1]
	v_pk_fma_f32 v[38:39], v[2:3], s[52:53], v[38:39] op_sel_hi:[1,0,1]
	v_pk_fma_f32 v[40:41], v[0:1], s[52:53], v[40:41] op_sel_hi:[1,0,1]
	v_pk_fma_f32 v[34:35], v[2:3], s[34:35], v[34:35] op_sel_hi:[1,0,1]
	v_pk_fma_f32 v[36:37], v[0:1], s[34:35], v[36:37] op_sel_hi:[1,0,1]
	v_pk_fma_f32 v[30:31], v[2:3], s[42:43], v[30:31] op_sel_hi:[1,0,1]
	v_pk_fma_f32 v[32:33], v[0:1], s[42:43], v[32:33] op_sel_hi:[1,0,1]
	v_pk_fma_f32 v[46:47], v[2:3], s[44:45], v[26:27] op_sel_hi:[1,0,1]
	v_pk_fma_f32 v[48:49], v[0:1], s[44:45], v[28:29] op_sel_hi:[1,0,1]
	v_pk_fma_f32 v[50:51], v[2:3], s[54:55], v[22:23] op_sel_hi:[1,0,1]
	v_pk_fma_f32 v[56:57], v[0:1], s[54:55], v[24:25] op_sel_hi:[1,0,1]
	v_pk_fma_f32 v[58:59], v[2:3], s[58:59], v[8:9] op_sel_hi:[1,0,1]
	v_pk_fma_f32 v[60:61], v[0:1], s[58:59], v[10:11] op_sel_hi:[1,0,1]
	v_pk_fma_f32 v[62:63], v[2:3], s[68:69], v[6:7] op_sel_hi:[1,0,1]
	v_pk_fma_f32 v[64:65], v[0:1], s[68:69], v[4:5] op_sel_hi:[1,0,1]
	v_pk_fma_f32 v[66:67], v[54:55], s[46:47], v[42:43] op_sel_hi:[1,0,1]
	v_pk_fma_f32 v[88:89], v[52:53], s[46:47], v[44:45] op_sel_hi:[1,0,1]
	v_pk_fma_f32 v[42:43], v[54:55], s[66:67], v[12:13] op_sel_hi:[1,0,1]
	v_pk_fma_f32 v[44:45], v[52:53], s[66:67], v[14:15] op_sel_hi:[1,0,1]
	global_load_dwordx4 v[12:15], v[68:69], off nt
	global_load_dwordx4 v[8:11], v[70:71], off nt
	global_load_dwordx4 v[4:7], v[72:73], off nt
	global_load_dwordx4 v[0:3], v[74:75], off nt
	v_pk_fma_f32 v[22:23], v[54:55], s[48:49], v[38:39] op_sel_hi:[1,0,1]
	v_pk_fma_f32 v[24:25], v[52:53], s[48:49], v[40:41] op_sel_hi:[1,0,1]
	v_pk_fma_f32 v[26:27], v[54:55], s[50:51], v[34:35] op_sel_hi:[1,0,1]
	v_pk_fma_f32 v[28:29], v[52:53], s[50:51], v[36:37] op_sel_hi:[1,0,1]
	v_pk_fma_f32 v[30:31], v[54:55], s[60:61], v[30:31] op_sel_hi:[1,0,1]
	v_pk_fma_f32 v[32:33], v[52:53], s[60:61], v[32:33] op_sel_hi:[1,0,1]
	v_pk_fma_f32 v[34:35], v[54:55], s[62:63], v[46:47] op_sel_hi:[1,0,1]
	v_pk_fma_f32 v[36:37], v[52:53], s[62:63], v[48:49] op_sel_hi:[1,0,1]
	v_pk_fma_f32 v[38:39], v[54:55], s[64:65], v[50:51] op_sel_hi:[1,0,1]
	v_pk_fma_f32 v[40:41], v[52:53], s[64:65], v[56:57] op_sel_hi:[1,0,1]
	v_pk_fma_f32 v[46:47], v[54:55], s[40:41], v[58:59] op_sel_hi:[1,0,1]
	v_pk_fma_f32 v[48:49], v[52:53], s[40:41], v[60:61] op_sel_hi:[1,0,1]
	v_pk_fma_f32 v[50:51], v[54:55], s[36:37], v[62:63] op_sel_hi:[1,0,1]
	v_pk_fma_f32 v[52:53], v[52:53], s[36:37], v[64:65] op_sel_hi:[1,0,1]
	v_readlane_b32 s30, v80, s71
	v_readlane_b32 s34, v83, s72
	v_readlane_b32 s52, v86, s72
	v_readlane_b32 s54, v87, s72
	v_readlane_b32 s56, v80, s72
	v_readlane_b32 s58, v79, s73
	v_readlane_b32 s60, v81, s73
	v_readlane_b32 s62, v82, s73
	v_readlane_b32 s64, v83, s73
	v_readlane_b32 s66, v84, s73
	v_readlane_b32 s68, v86, s73
	v_readlane_b32 s72, v87, s73
	s_mov_b64 s[46:47], 0x60000
	v_lshl_add_u64 v[20:21], v[20:21], 0, s[46:47]
	s_waitcnt vmcnt(3)
	v_pk_fma_f32 v[54:55], v[14:15], s[38:39], v[66:67] op_sel_hi:[1,0,1]
	v_pk_fma_f32 v[56:57], v[12:13], s[38:39], v[88:89] op_sel_hi:[1,0,1]
	v_pk_fma_f32 v[22:23], v[14:15], s[0:1], v[22:23] op_sel_hi:[1,0,1]
	v_pk_fma_f32 v[24:25], v[12:13], s[0:1], v[24:25] op_sel_hi:[1,0,1]
	v_pk_fma_f32 v[26:27], v[14:15], s[4:5], v[26:27] op_sel_hi:[1,0,1]
	v_pk_fma_f32 v[28:29], v[12:13], s[4:5], v[28:29] op_sel_hi:[1,0,1]
	v_pk_fma_f32 v[30:31], v[14:15], s[6:7], v[30:31] op_sel_hi:[1,0,1]
	v_pk_fma_f32 v[32:33], v[12:13], s[6:7], v[32:33] op_sel_hi:[1,0,1]
	v_pk_fma_f32 v[34:35], v[14:15], s[8:9], v[34:35] op_sel_hi:[1,0,1]
	v_pk_fma_f32 v[36:37], v[12:13], s[8:9], v[36:37] op_sel_hi:[1,0,1]
	v_pk_fma_f32 v[38:39], v[14:15], s[10:11], v[38:39] op_sel_hi:[1,0,1]
	v_pk_fma_f32 v[40:41], v[12:13], s[10:11], v[40:41] op_sel_hi:[1,0,1]
	v_pk_fma_f32 v[42:43], v[14:15], s[12:13], v[42:43] op_sel_hi:[1,0,1]
	v_pk_fma_f32 v[44:45], v[12:13], s[12:13], v[44:45] op_sel_hi:[1,0,1]
	v_pk_fma_f32 v[46:47], v[14:15], s[14:15], v[46:47] op_sel_hi:[1,0,1]
	v_pk_fma_f32 v[48:49], v[12:13], s[14:15], v[48:49] op_sel_hi:[1,0,1]
	v_pk_fma_f32 v[14:15], v[14:15], s[16:17], v[50:51] op_sel_hi:[1,0,1]
	v_pk_fma_f32 v[12:13], v[12:13], s[16:17], v[52:53] op_sel_hi:[1,0,1]
	s_waitcnt vmcnt(2)
; __device__ __forceinline__ void gemv_item(const float* c, const float* c_ctx, const float* ada_w, const float* ada_b, float* mod, int it, int lane) {
;     ...
;     for (int kk = 0; kk < 64; ++kk) { const f32x4 w = *(const f32x4*)(W + (size_t)kk * 6144);
; #pragma unroll
;         for (int r = 0; r < 9; ++r) { const float sk = __uint_as_float(__builtin_amdgcn_readlane(__float_as_uint(s[r]), kk)); acc[r] += w * sk; } }
;     const int col = cgp * 256 + lane * 4;
;     f32x4 bv = (f32x4){0.f, 0.f, 0.f, 0.f};
;     if (kc == 0) bv = *(const f32x4*)(ada_b + l * 6144 + col);
	v_pk_fma_f32 v[50:51], v[10:11], s[18:19], v[54:55] op_sel_hi:[1,0,1]
	v_pk_fma_f32 v[52:53], v[8:9], s[18:19], v[56:57] op_sel_hi:[1,0,1]
	v_pk_fma_f32 v[22:23], v[10:11], s[20:21], v[22:23] op_sel_hi:[1,0,1]
	v_pk_fma_f32 v[24:25], v[8:9], s[20:21], v[24:25] op_sel_hi:[1,0,1]
	v_pk_fma_f32 v[26:27], v[10:11], s[22:23], v[26:27] op_sel_hi:[1,0,1]
	v_pk_fma_f32 v[28:29], v[8:9], s[22:23], v[28:29] op_sel_hi:[1,0,1]
	v_pk_fma_f32 v[30:31], v[10:11], s[24:25], v[30:31] op_sel_hi:[1,0,1]
	v_pk_fma_f32 v[32:33], v[8:9], s[24:25], v[32:33] op_sel_hi:[1,0,1]
	v_pk_fma_f32 v[34:35], v[10:11], s[26:27], v[34:35] op_sel_hi:[1,0,1]
	v_pk_fma_f32 v[36:37], v[8:9], s[26:27], v[36:37] op_sel_hi:[1,0,1]
	v_pk_fma_f32 v[38:39], v[10:11], s[28:29], v[38:39] op_sel_hi:[1,0,1]
	v_pk_fma_f32 v[40:41], v[8:9], s[28:29], v[40:41] op_sel_hi:[1,0,1]
	v_pk_fma_f32 v[42:43], v[10:11], s[84:85], v[42:43] op_sel_hi:[1,0,1]
	v_pk_fma_f32 v[44:45], v[8:9], s[84:85], v[44:45] op_sel_hi:[1,0,1]
	v_pk_fma_f32 v[46:47], v[10:11], s[94:95], v[46:47] op_sel_hi:[1,0,1]
	v_pk_fma_f32 v[48:49], v[8:9], s[94:95], v[48:49] op_sel_hi:[1,0,1]
	v_pk_fma_f32 v[10:11], v[10:11], s[30:31], v[14:15] op_sel_hi:[1,0,1]
	v_pk_fma_f32 v[8:9], v[8:9], s[30:31], v[12:13] op_sel_hi:[1,0,1]
	s_waitcnt vmcnt(1)
	v_pk_fma_f32 v[12:13], v[6:7], s[82:83], v[50:51] op_sel_hi:[1,0,1]
	v_pk_fma_f32 v[14:15], v[4:5], s[82:83], v[52:53] op_sel_hi:[1,0,1]
	v_pk_fma_f32 v[22:23], v[6:7], s[80:81], v[22:23] op_sel_hi:[1,0,1]
	v_pk_fma_f32 v[24:25], v[4:5], s[80:81], v[24:25] op_sel_hi:[1,0,1]
	v_pk_fma_f32 v[26:27], v[6:7], s[86:87], v[26:27] op_sel_hi:[1,0,1]
	v_pk_fma_f32 v[28:29], v[4:5], s[86:87], v[28:29] op_sel_hi:[1,0,1]
	v_pk_fma_f32 v[30:31], v[6:7], s[34:35], v[30:31] op_sel_hi:[1,0,1]
	v_pk_fma_f32 v[32:33], v[4:5], s[34:35], v[32:33] op_sel_hi:[1,0,1]
	v_pk_fma_f32 v[50:51], v[6:7], s[90:91], v[34:35] op_sel_hi:[1,0,1]
	v_pk_fma_f32 v[52:53], v[4:5], s[90:91], v[36:37] op_sel_hi:[1,0,1]
	v_pk_fma_f32 v[54:55], v[6:7], s[88:89], v[38:39] op_sel_hi:[1,0,1]
	v_pk_fma_f32 v[56:57], v[4:5], s[88:89], v[40:41] op_sel_hi:[1,0,1]
	v_pk_fma_f32 v[58:59], v[6:7], s[52:53], v[42:43] op_sel_hi:[1,0,1]
	v_pk_fma_f32 v[60:61], v[4:5], s[52:53], v[44:45] op_sel_hi:[1,0,1]
	v_pk_fma_f32 v[46:47], v[6:7], s[54:55], v[46:47] op_sel_hi:[1,0,1]
	v_pk_fma_f32 v[48:49], v[4:5], s[54:55], v[48:49] op_sel_hi:[1,0,1]
	v_pk_fma_f32 v[6:7], v[6:7], s[56:57], v[10:11] op_sel_hi:[1,0,1]
	v_pk_fma_f32 v[62:63], v[4:5], s[56:57], v[8:9] op_sel_hi:[1,0,1]
	s_waitcnt vmcnt(0)
	v_pk_fma_f32 v[42:43], v[2:3], s[58:59], v[12:13] op_sel_hi:[1,0,1]
	v_pk_fma_f32 v[44:45], v[0:1], s[58:59], v[14:15] op_sel_hi:[1,0,1]
	v_pk_fma_f32 v[38:39], v[2:3], s[60:61], v[22:23] op_sel_hi:[1,0,1]
	v_pk_fma_f32 v[40:41], v[0:1], s[60:61], v[24:25] op_sel_hi:[1,0,1]
	v_pk_fma_f32 v[34:35], v[2:3], s[62:63], v[26:27] op_sel_hi:[1,0,1]
	v_pk_fma_f32 v[36:37], v[0:1], s[62:63], v[28:29] op_sel_hi:[1,0,1]
	v_pk_fma_f32 v[30:31], v[2:3], s[64:65], v[30:31] op_sel_hi:[1,0,1]
	v_pk_fma_f32 v[32:33], v[0:1], s[64:65], v[32:33] op_sel_hi:[1,0,1]
	v_pk_fma_f32 v[26:27], v[2:3], s[66:67], v[50:51] op_sel_hi:[1,0,1]
	v_pk_fma_f32 v[28:29], v[0:1], s[66:67], v[52:53] op_sel_hi:[1,0,1]
	v_pk_fma_f32 v[22:23], v[2:3], s[92:93], v[54:55] op_sel_hi:[1,0,1]
	v_pk_fma_f32 v[24:25], v[0:1], s[92:93], v[56:57] op_sel_hi:[1,0,1]
	v_pk_fma_f32 v[12:13], v[2:3], s[68:69], v[58:59] op_sel_hi:[1,0,1]
	v_pk_fma_f32 v[14:15], v[0:1], s[68:69], v[60:61] op_sel_hi:[1,0,1]
	v_pk_fma_f32 v[8:9], v[2:3], s[72:73], v[46:47] op_sel_hi:[1,0,1]
	v_pk_fma_f32 v[10:11], v[0:1], s[72:73], v[48:49] op_sel_hi:[1,0,1]
	v_pk_fma_f32 v[4:5], v[2:3], s[70:71], v[6:7] op_sel_hi:[1,0,1]
	v_pk_fma_f32 v[6:7], v[0:1], s[70:71], v[62:63] op_sel_hi:[1,0,1]
	s_cbranch_scc0 .LBB0_25
	v_or_b32_e32 v20, s96, v78
	s_add_i32 s43, s43, 23
	s_mov_b64 s[0:1], -1
	s_cmp_lt_u32 s43, 47
	v_ashrrev_i32_e32 v21, 31, v20
	s_cbranch_scc1 .LBB0_28
	s_mov_b64 s[0:1], 0
.LBB0_28:
	v_readlane_b32 s84, v247, 52
	v_readlane_b32 s88, v247, 56
	v_readlane_b32 s68, v247, 34
	v_mov_b32_e32 v0, 0
	s_andn2_b64 vcc, exec, s[0:1]
	v_mov_b32_e32 v1, 0
	v_mov_b32_e32 v2, 0
	v_mov_b32_e32 v3, 0
	v_readlane_b32 s85, v247, 53
	v_readlane_b32 s86, v247, 54
	v_readlane_b32 s87, v247, 55
	v_readlane_b32 s89, v247, 57
	v_readlane_b32 s90, v247, 58
	v_readlane_b32 s91, v247, 59
	v_readlane_b32 s92, v247, 60
	v_readlane_b32 s93, v247, 61
	v_readlane_b32 s94, v247, 62
	v_readlane_b32 s95, v247, 63
	v_readlane_b32 s69, v247, 35
	v_readlane_b32 s70, v247, 36
	v_readlane_b32 s71, v247, 37
	v_readlane_b32 s72, v247, 38
	v_readlane_b32 s73, v247, 39
	v_readlane_b32 s74, v247, 40
	v_readlane_b32 s75, v247, 41
	v_readlane_b32 s76, v247, 42
	v_readlane_b32 s77, v247, 43
	v_readlane_b32 s78, v247, 44
	v_readlane_b32 s79, v247, 45
	v_readlane_b32 s80, v247, 46
	v_readlane_b32 s81, v247, 47
	v_readlane_b32 s82, v247, 48
	v_readlane_b32 s83, v247, 49
	s_cbranch_vccnz .LBB0_23
	s_mul_i32 s0, s41, 0x1800
	s_ashr_i32 s1, s0, 31
	s_lshl_b64 s[0:1], s[0:1], 2
	s_add_u32 s0, s78, s0
	s_addc_u32 s1, s79, s1
	v_lshl_add_u64 v[0:1], v[20:21], 2, s[0:1]
	global_load_dwordx4 v[0:3], v[0:1], off nt
	s_branch .LBB0_23

; #define LAS __attribute__((address_space(3)))
; __device__ __forceinline__ void tr_load(const TrDesc& d, int lane, f32x4 (&wv)[8]) {
;     const int nblk = d.N / 32, kb = d.item / nblk, nb = d.item % nblk, k0 = 64 * kb, n0 = 32 * nb;
; #pragma unroll
;     for (int i = 0; i < 8; ++i) wv[i] = *(const f32x4*)(d.W + (size_t)(k0 + 8 * i + (lane >> 3)) * d.N + n0 + (lane & 7) * 4);
; }
; __device__ __forceinline__ void tr_run(const Args& a, int list, int first, int stride, int lane, LAS float* scr, int n_end = -1) {
;     const int n = n_end >= 0 ? n_end : (list == 0 ? I_LIST0 : (list == 1 ? I_LIST1 : I_LIST2));
;     int it = first; if (it >= n) return;
;     TrDesc d = tr_desc(a, list, it); f32x4 wv[8]; tr_load(d, lane, wv);
.LBB0_39:
	s_lshr_b32 s6, s18, 5
	v_cvt_f32_ubyte0_e32 v0, s6
	v_rcp_iflag_f32_e32 v0, v0
	s_sub_i32 s9, 0, s6
	s_abs_i32 s8, s15
	s_ashr_i32 s7, s15, 31
	v_mul_f32_e32 v0, 0x4f7ffffe, v0
	v_cvt_u32_f32_e32 v0, v0
	v_lshrrev_b32_e32 v68, 3, v77
	v_mov_b32_e32 v65, 0
	v_lshlrev_b32_e32 v33, 2, v68
	v_readfirstlane_b32 s10, v0
	s_mul_i32 s9, s9, s10
	s_mul_hi_u32 s9, s10, s9
	s_add_i32 s10, s10, s9
	s_mul_hi_u32 s9, s8, s10
	s_mul_i32 s10, s9, s6
	s_sub_i32 s8, s8, s10
	s_add_i32 s11, s9, 1
	s_sub_i32 s10, s8, s6
	s_cmp_ge_u32 s8, s6
	s_cselect_b32 s9, s11, s9
	s_cselect_b32 s8, s10, s8
	s_add_i32 s10, s9, 1
	s_cmp_ge_u32 s8, s6
	s_cselect_b32 s8, s10, s9
	s_xor_b32 s8, s8, s7
	s_sub_i32 s7, s8, s7
	s_mul_i32 s6, s7, s6
	s_sub_i32 s6, s15, s6
	v_lshl_or_b32 v6, s7, 6, v68
	s_lshl_b32 s6, s6, 5
	v_lshlrev_b32_e32 v0, 2, v77
	v_or_b32_e32 v2, 8, v6
	s_ashr_i32 s7, s6, 31
	v_and_b32_e32 v28, 28, v0
	v_mad_i64_i32 v[0:1], s[8:9], v6, s18, 0
	v_mad_i64_i32 v[2:3], s[8:9], v2, s18, 0
	v_lshl_add_u64 v[0:1], v[0:1], 2, s[4:5]
	s_lshl_b64 s[6:7], s[6:7], 2
	v_lshl_add_u64 v[2:3], v[2:3], 2, s[4:5]
	v_lshl_add_u64 v[0:1], v[0:1], 0, s[6:7]
	v_lshlrev_b32_e32 v64, 2, v28
	v_lshl_add_u64 v[2:3], v[2:3], 0, s[6:7]
	v_lshl_add_u64 v[0:1], v[0:1], 0, v[64:65]
	v_lshl_add_u64 v[2:3], v[2:3], 0, v[64:65]
	global_load_dwordx4 v[24:27], v[0:1], off nt
	global_load_dwordx4 v[20:23], v[2:3], off nt
	v_or_b32_e32 v0, 16, v6
	v_or_b32_e32 v2, 24, v6
	v_mad_i64_i32 v[0:1], s[8:9], v0, s18, 0
	v_mad_i64_i32 v[2:3], s[8:9], v2, s18, 0
	v_lshl_add_u64 v[0:1], v[0:1], 2, s[4:5]
	v_lshl_add_u64 v[2:3], v[2:3], 2, s[4:5]
	v_lshl_add_u64 v[0:1], v[0:1], 0, s[6:7]
	v_lshl_add_u64 v[2:3], v[2:3], 0, s[6:7]
	v_lshl_add_u64 v[0:1], v[0:1], 0, v[64:65]
	v_lshl_add_u64 v[2:3], v[2:3], 0, v[64:65]
	global_load_dwordx4 v[16:19], v[0:1], off nt
	global_load_dwordx4 v[8:11], v[2:3], off nt
	v_or_b32_e32 v0, 32, v6
	v_or_b32_e32 v2, 40, v6
	v_or_b32_e32 v4, 48, v6
	v_mad_i64_i32 v[0:1], s[8:9], v0, s18, 0
	v_mad_i64_i32 v[2:3], s[8:9], v2, s18, 0
	v_mad_i64_i32 v[4:5], s[8:9], v4, s18, 0
	v_or_b32_e32 v6, 56, v6
	v_lshl_add_u64 v[0:1], v[0:1], 2, s[4:5]
	v_lshl_add_u64 v[2:3], v[2:3], 2, s[4:5]
	v_lshl_add_u64 v[4:5], v[4:5], 2, s[4:5]
	v_mad_i64_i32 v[6:7], s[8:9], v6, s18, 0
	v_lshl_add_u64 v[0:1], v[0:1], 0, s[6:7]
	v_lshl_add_u64 v[2:3], v[2:3], 0, s[6:7]
	v_lshl_add_u64 v[4:5], v[4:5], 0, s[6:7]
	v_lshl_add_u64 v[6:7], v[6:7], 2, s[4:5]
	v_lshl_add_u64 v[0:1], v[0:1], 0, v[64:65]
	v_lshl_add_u64 v[2:3], v[2:3], 0, v[64:65]
	v_lshl_add_u64 v[4:5], v[4:5], 0, v[64:65]
	v_lshl_add_u64 v[6:7], v[6:7], 0, s[6:7]
	global_load_dwordx4 v[12:15], v[0:1], off nt
	s_nop 0
	global_load_dwordx4 v[0:3], v[2:3], off nt
	v_lshl_add_u64 v[30:31], v[6:7], 0, v[64:65]
	global_load_dwordx4 v[4:7], v[4:5], off nt
	s_nop 0
	global_load_dwordx4 v[60:63], v[30:31], off nt
	v_lshlrev_b32_e32 v30, 3, v77
	v_and_b32_e32 v30, 56, v30
	v_add_u32_e32 v29, s31, v64
	v_mul_u32_u24_e32 v31, 0x84, v68
	v_mul_u32_u24_e32 v32, 0x84, v30
	s_mov_b32 s5, 0
	v_or_b32_e32 v69, 8, v68
	v_or_b32_e32 v70, 16, v68
	v_or_b32_e32 v71, 24, v68
	v_add3_u32 v72, s31, v32, v33
	s_add_i32 s13, s33, s61
	v_lshlrev_b32_e32 v64, 2, v28
	v_add_u32_e32 v73, v29, v31
	v_lshlrev_b32_e32 v66, 1, v30
	s_mov_b32 s14, s33
	s_mov_b64 s[6:7], s[0:1]
	s_mov_b32 s16, s12
	s_mov_b32 s17, s18
	s_mov_b32 s4, s15
	s_branch .LBB0_41

; __device__ __forceinline__ void tr_load(const TrDesc& d, int lane, f32x4 (&wv)[8]) {
;     const int nblk = d.N / 32, kb = d.item / nblk, nb = d.item % nblk, k0 = 64 * kb, n0 = 32 * nb;
; #pragma unroll
;     for (int i = 0; i < 8; ++i) wv[i] = *(const f32x4*)(d.W + (size_t)(k0 + 8 * i + (lane >> 3)) * d.N + n0 + (lane & 7) * 4);
; }
; __device__ __forceinline__ void tr_run(const Args& a, int list, int first, int stride, int lane, LAS float* scr, int n_end = -1) {
;     ...
;     for (;;) {
;         const int nit = it + stride; const bool more = nit < n;
;         TrDesc dn = d; f32x4 wn[8];
;         if (more) { dn = tr_desc(a, list, nit); tr_load(dn, lane, wn); }
.LBB0_49:
	s_lshr_b32 s19, s17, 5
	v_cvt_f32_ubyte0_e32 v28, s19
	v_rcp_iflag_f32_e32 v28, v28
	s_sub_i32 s22, 0, s19
	s_abs_i32 s21, s4
	s_ashr_i32 s20, s4, 31
	v_mul_f32_e32 v28, 0x4f7ffffe, v28
	v_cvt_u32_f32_e32 v28, v28
	s_nop 0
	v_readfirstlane_b32 s23, v28
	s_mul_i32 s22, s22, s23
	s_mul_hi_u32 s22, s23, s22
	s_add_i32 s23, s23, s22
	s_mul_hi_u32 s22, s21, s23
	s_mul_i32 s23, s22, s19
	s_sub_i32 s21, s21, s23
	s_add_i32 s24, s22, 1
	s_sub_i32 s23, s21, s19
	s_cmp_ge_u32 s21, s19
	s_cselect_b32 s22, s24, s22
	s_cselect_b32 s21, s23, s21
	s_add_i32 s23, s22, 1
	s_cmp_ge_u32 s21, s19
	s_cselect_b32 s21, s23, s22
	s_xor_b32 s21, s21, s20
	s_sub_i32 s20, s21, s20
	s_mul_i32 s19, s20, s19
	v_lshl_or_b32 v54, s20, 6, v68
	s_sub_i32 s19, s4, s19
	s_lshl_b32 s20, s19, 5
	v_mad_i64_i32 v[28:29], s[22:23], v54, s17, 0
	v_or_b32_e32 v30, 8, v54
	v_or_b32_e32 v36, 16, v54
	v_or_b32_e32 v38, 24, v54
	v_or_b32_e32 v44, 32, v54
	v_or_b32_e32 v46, 40, v54
	v_or_b32_e32 v52, 48, v54
	v_or_b32_e32 v54, 56, v54
	s_ashr_i32 s21, s20, 31
	v_mad_i64_i32 v[30:31], s[22:23], v30, s17, 0
	v_mad_i64_i32 v[36:37], s[22:23], v36, s17, 0
	v_mad_i64_i32 v[38:39], s[22:23], v38, s17, 0
	v_mad_i64_i32 v[44:45], s[22:23], v44, s17, 0
	v_mad_i64_i32 v[46:47], s[22:23], v46, s17, 0
	v_mad_i64_i32 v[52:53], s[22:23], v52, s17, 0
	v_mad_i64_i32 v[54:55], s[22:23], v54, s17, 0
	v_lshl_add_u64 v[28:29], v[28:29], 2, s[10:11]
	s_lshl_b64 s[20:21], s[20:21], 2
	v_lshl_add_u64 v[30:31], v[30:31], 2, s[10:11]
	v_lshl_add_u64 v[36:37], v[36:37], 2, s[10:11]
	v_lshl_add_u64 v[38:39], v[38:39], 2, s[10:11]
	v_lshl_add_u64 v[44:45], v[44:45], 2, s[10:11]
	v_lshl_add_u64 v[46:47], v[46:47], 2, s[10:11]
	v_lshl_add_u64 v[52:53], v[52:53], 2, s[10:11]
	v_lshl_add_u64 v[54:55], v[54:55], 2, s[10:11]
	v_lshl_add_u64 v[28:29], v[28:29], 0, s[20:21]
	v_lshl_add_u64 v[30:31], v[30:31], 0, s[20:21]
	v_lshl_add_u64 v[36:37], v[36:37], 0, s[20:21]
	v_lshl_add_u64 v[38:39], v[38:39], 0, s[20:21]
	v_lshl_add_u64 v[44:45], v[44:45], 0, s[20:21]
	v_lshl_add_u64 v[46:47], v[46:47], 0, s[20:21]
	v_lshl_add_u64 v[52:53], v[52:53], 0, s[20:21]
	v_lshl_add_u64 v[54:55], v[54:55], 0, s[20:21]
	v_lshl_add_u64 v[28:29], v[28:29], 0, v[64:65]
	v_lshl_add_u64 v[30:31], v[30:31], 0, v[64:65]
	v_lshl_add_u64 v[36:37], v[36:37], 0, v[64:65]
	v_lshl_add_u64 v[38:39], v[38:39], 0, v[64:65]
	v_lshl_add_u64 v[44:45], v[44:45], 0, v[64:65]
	v_lshl_add_u64 v[46:47], v[46:47], 0, v[64:65]
	v_lshl_add_u64 v[52:53], v[52:53], 0, v[64:65]
	v_lshl_add_u64 v[54:55], v[54:55], 0, v[64:65]
	global_load_dwordx4 v[32:35], v[28:29], off nt
	s_nop 0
	global_load_dwordx4 v[28:31], v[30:31], off nt
	s_nop 0
	global_load_dwordx4 v[40:43], v[36:37], off nt
	s_nop 0
	global_load_dwordx4 v[36:39], v[38:39], off nt
	s_nop 0
	global_load_dwordx4 v[48:51], v[44:45], off nt
	s_nop 0
	global_load_dwordx4 v[44:47], v[46:47], off nt
	s_nop 0
	global_load_dwordx4 v[56:59], v[52:53], off nt
	s_nop 0
	global_load_dwordx4 v[52:55], v[54:55], off nt

; #define LAS __attribute__((address_space(3)))
; __device__ __forceinline__ void tr_load(const TrDesc& d, int lane, f32x4 (&wv)[8]) {
;     const int nblk = d.N / 32, kb = d.item / nblk, nb = d.item % nblk, k0 = 64 * kb, n0 = 32 * nb;
; #pragma unroll
;     for (int i = 0; i < 8; ++i) wv[i] = *(const f32x4*)(d.W + (size_t)(k0 + 8 * i + (lane >> 3)) * d.N + n0 + (lane & 7) * 4);
; }
; __device__ __forceinline__ void tr_run(const Args& a, int list, int first, int stride, int lane, LAS float* scr, int n_end = -1) {
;     const int n = n_end >= 0 ? n_end : (list == 0 ? I_LIST0 : (list == 1 ? I_LIST1 : I_LIST2));
;     int it = first; if (it >= n) return;
;     TrDesc d = tr_desc(a, list, it); f32x4 wv[8]; tr_load(d, lane, wv);
.LBB0_60:
	s_lshr_b32 s8, s18, 5
	v_cvt_f32_ubyte0_e32 v0, s8
	v_rcp_iflag_f32_e32 v0, v0
	s_sub_i32 s11, 0, s8
	s_abs_i32 s10, s27
	s_ashr_i32 s9, s27, 31
	v_mul_f32_e32 v0, 0x4f7ffffe, v0
	v_cvt_u32_f32_e32 v0, v0
	v_lshrrev_b32_e32 v64, 3, v77
	v_mov_b32_e32 v67, 0
	v_lshlrev_b32_e32 v21, 2, v64
	v_readfirstlane_b32 s12, v0
	s_mul_i32 s11, s11, s12
	s_mul_hi_u32 s11, s12, s11
	s_add_i32 s12, s12, s11
	s_mul_hi_u32 s11, s10, s12
	s_mul_i32 s12, s11, s8
	s_sub_i32 s10, s10, s12
	s_add_i32 s13, s11, 1
	s_sub_i32 s12, s10, s8
	s_cmp_ge_u32 s10, s8
	s_cselect_b32 s11, s13, s11
	s_cselect_b32 s10, s12, s10
	s_add_i32 s12, s11, 1
	s_cmp_ge_u32 s10, s8
	s_cselect_b32 s10, s12, s11
	s_xor_b32 s10, s10, s9
	s_sub_i32 s9, s10, s9
	s_mul_i32 s8, s9, s8
	s_sub_i32 s8, s27, s8
	v_lshl_or_b32 v10, s9, 6, v64
	s_lshl_b32 s8, s8, 5
	v_lshlrev_b32_e32 v0, 2, v77
	v_or_b32_e32 v2, 8, v10
	s_ashr_i32 s9, s8, 31
	v_and_b32_e32 v16, 28, v0
	v_mad_i64_i32 v[0:1], s[10:11], v10, s18, 0
	v_mad_i64_i32 v[2:3], s[10:11], v2, s18, 0
	v_lshl_add_u64 v[0:1], v[0:1], 2, s[0:1]
	s_lshl_b64 s[8:9], s[8:9], 2
	v_lshl_add_u64 v[2:3], v[2:3], 2, s[0:1]
	v_lshl_add_u64 v[0:1], v[0:1], 0, s[8:9]
	v_lshlrev_b32_e32 v66, 2, v16
	v_lshl_add_u64 v[2:3], v[2:3], 0, s[8:9]
	v_lshl_add_u64 v[0:1], v[0:1], 0, v[66:67]
	v_lshl_add_u64 v[2:3], v[2:3], 0, v[66:67]
	global_load_dwordx4 v[60:63], v[0:1], off nt
	global_load_dwordx4 v[56:59], v[2:3], off nt
	v_or_b32_e32 v0, 16, v10
	v_or_b32_e32 v2, 24, v10
	v_mad_i64_i32 v[0:1], s[10:11], v0, s18, 0
	v_mad_i64_i32 v[2:3], s[10:11], v2, s18, 0
	v_lshl_add_u64 v[0:1], v[0:1], 2, s[0:1]
	v_lshl_add_u64 v[2:3], v[2:3], 2, s[0:1]
	v_lshl_add_u64 v[0:1], v[0:1], 0, s[8:9]
	v_lshl_add_u64 v[2:3], v[2:3], 0, s[8:9]
	v_lshl_add_u64 v[0:1], v[0:1], 0, v[66:67]
	v_lshl_add_u64 v[2:3], v[2:3], 0, v[66:67]
	global_load_dwordx4 v[52:55], v[0:1], off nt
	global_load_dwordx4 v[4:7], v[2:3], off nt
	v_or_b32_e32 v0, 32, v10
	v_or_b32_e32 v2, 40, v10
	v_or_b32_e32 v8, 48, v10
	v_mad_i64_i32 v[0:1], s[10:11], v0, s18, 0
	v_mad_i64_i32 v[2:3], s[10:11], v2, s18, 0
	v_mad_i64_i32 v[8:9], s[10:11], v8, s18, 0
	v_or_b32_e32 v10, 56, v10
	v_lshl_add_u64 v[0:1], v[0:1], 2, s[0:1]
	v_lshl_add_u64 v[2:3], v[2:3], 2, s[0:1]
	v_lshl_add_u64 v[8:9], v[8:9], 2, s[0:1]
	v_mad_i64_i32 v[10:11], s[10:11], v10, s18, 0
	v_lshl_add_u64 v[0:1], v[0:1], 0, s[8:9]
	v_lshl_add_u64 v[2:3], v[2:3], 0, s[8:9]
	v_lshl_add_u64 v[8:9], v[8:9], 0, s[8:9]
	v_lshl_add_u64 v[10:11], v[10:11], 2, s[0:1]
	v_lshl_add_u64 v[0:1], v[0:1], 0, v[66:67]
	v_lshl_add_u64 v[2:3], v[2:3], 0, v[66:67]
	v_lshl_add_u64 v[8:9], v[8:9], 0, v[66:67]
	v_lshl_add_u64 v[10:11], v[10:11], 0, s[8:9]
	global_load_dwordx4 v[12:15], v[0:1], off nt
	s_nop 0
	global_load_dwordx4 v[0:3], v[2:3], off nt
	v_lshl_add_u64 v[18:19], v[10:11], 0, v[66:67]
	global_load_dwordx4 v[8:11], v[8:9], off nt
	s_nop 0
	global_load_dwordx4 v[48:51], v[18:19], off nt
	v_lshlrev_b32_e32 v18, 3, v77
	v_and_b32_e32 v18, 56, v18
	v_add_u32_e32 v17, s31, v66
	v_mul_u32_u24_e32 v19, 0x84, v64
	v_mul_u32_u24_e32 v20, 0x84, v18
	v_or_b32_e32 v70, 8, v64
	v_or_b32_e32 v71, 16, v64
	v_or_b32_e32 v72, 24, v64
	v_add3_u32 v73, s31, v20, v21
	v_mov_b32_e32 v65, v67
	s_add_i32 s23, s33, s61
	v_lshlrev_b32_e32 v68, 2, v16
	v_lshlrev_b32_e32 v66, 1, v18
	v_add_u32_e32 v74, v17, v19
	s_mov_b32 s24, s33
	s_mov_b64 s[12:13], s[4:5]
	s_mov_b64 s[10:11], s[14:15]
	s_mov_b32 s28, s22
	s_mov_b32 s25, s18
	s_mov_b32 s26, s27
	s_mov_b64 s[8:9], s[6:7]
	s_branch .LBB0_62

; __device__ __forceinline__ void tr_load(const TrDesc& d, int lane, f32x4 (&wv)[8]) {
;     const int nblk = d.N / 32, kb = d.item / nblk, nb = d.item % nblk, k0 = 64 * kb, n0 = 32 * nb;
; #pragma unroll
;     for (int i = 0; i < 8; ++i) wv[i] = *(const f32x4*)(d.W + (size_t)(k0 + 8 * i + (lane >> 3)) * d.N + n0 + (lane & 7) * 4);
; }
; __device__ __forceinline__ void tr_run(const Args& a, int list, int first, int stride, int lane, LAS float* scr, int n_end = -1) {
;     ...
;     for (;;) {
;         const int nit = it + stride; const bool more = nit < n;
;         TrDesc dn = d; f32x4 wn[8];
;         if (more) { dn = tr_desc(a, list, nit); tr_load(dn, lane, wn); }
.LBB0_71:
	s_lshr_b32 s19, s25, 5
	v_cvt_f32_ubyte0_e32 v16, s19
	v_rcp_iflag_f32_e32 v16, v16
	s_sub_i32 s29, 0, s19
	s_abs_i32 s21, s26
	s_ashr_i32 s20, s26, 31
	v_mul_f32_e32 v16, 0x4f7ffffe, v16
	v_cvt_u32_f32_e32 v16, v16
	v_mov_b32_e32 v69, v67
	v_readfirstlane_b32 s30, v16
	s_mul_i32 s29, s29, s30
	s_mul_hi_u32 s29, s30, s29
	s_add_i32 s30, s30, s29
	s_mul_hi_u32 s29, s21, s30
	s_mul_i32 s30, s29, s19
	s_sub_i32 s21, s21, s30
	s_add_i32 s34, s29, 1
	s_sub_i32 s30, s21, s19
	s_cmp_ge_u32 s21, s19
	s_cselect_b32 s29, s34, s29
	s_cselect_b32 s21, s30, s21
	s_add_i32 s30, s29, 1
	s_cmp_ge_u32 s21, s19
	s_cselect_b32 s21, s30, s29
	s_xor_b32 s21, s21, s20
	s_sub_i32 s20, s21, s20
	s_mul_i32 s19, s20, s19
	v_lshl_or_b32 v42, s20, 6, v64
	s_sub_i32 s19, s26, s19
	s_lshl_b32 s20, s19, 5
	v_mad_i64_i32 v[16:17], s[34:35], v42, s25, 0
	v_or_b32_e32 v18, 8, v42
	v_or_b32_e32 v24, 16, v42
	v_or_b32_e32 v26, 24, v42
	v_or_b32_e32 v32, 32, v42
	v_or_b32_e32 v34, 40, v42
	v_or_b32_e32 v40, 48, v42
	v_or_b32_e32 v42, 56, v42
	s_ashr_i32 s21, s20, 31
	v_mad_i64_i32 v[18:19], s[34:35], v18, s25, 0
	v_mad_i64_i32 v[24:25], s[34:35], v24, s25, 0
	v_mad_i64_i32 v[26:27], s[34:35], v26, s25, 0
	v_mad_i64_i32 v[32:33], s[34:35], v32, s25, 0
	v_mad_i64_i32 v[34:35], s[34:35], v34, s25, 0
	v_mad_i64_i32 v[40:41], s[34:35], v40, s25, 0
	v_mad_i64_i32 v[42:43], s[34:35], v42, s25, 0
	v_lshl_add_u64 v[16:17], v[16:17], 2, s[0:1]
	s_lshl_b64 s[20:21], s[20:21], 2
	v_lshl_add_u64 v[18:19], v[18:19], 2, s[0:1]
	v_lshl_add_u64 v[24:25], v[24:25], 2, s[0:1]
	v_lshl_add_u64 v[26:27], v[26:27], 2, s[0:1]
	v_lshl_add_u64 v[32:33], v[32:33], 2, s[0:1]
	v_lshl_add_u64 v[34:35], v[34:35], 2, s[0:1]
	v_lshl_add_u64 v[40:41], v[40:41], 2, s[0:1]
	v_lshl_add_u64 v[42:43], v[42:43], 2, s[0:1]
	v_lshl_add_u64 v[16:17], v[16:17], 0, s[20:21]
	v_lshl_add_u64 v[18:19], v[18:19], 0, s[20:21]
	v_lshl_add_u64 v[24:25], v[24:25], 0, s[20:21]
	v_lshl_add_u64 v[26:27], v[26:27], 0, s[20:21]
	v_lshl_add_u64 v[32:33], v[32:33], 0, s[20:21]
	v_lshl_add_u64 v[34:35], v[34:35], 0, s[20:21]
	v_lshl_add_u64 v[40:41], v[40:41], 0, s[20:21]
	v_lshl_add_u64 v[42:43], v[42:43], 0, s[20:21]
	v_lshl_add_u64 v[16:17], v[16:17], 0, v[68:69]
	v_lshl_add_u64 v[18:19], v[18:19], 0, v[68:69]
	v_lshl_add_u64 v[24:25], v[24:25], 0, v[68:69]
	v_lshl_add_u64 v[26:27], v[26:27], 0, v[68:69]
	v_lshl_add_u64 v[32:33], v[32:33], 0, v[68:69]
	v_lshl_add_u64 v[34:35], v[34:35], 0, v[68:69]
	v_lshl_add_u64 v[40:41], v[40:41], 0, v[68:69]
	v_lshl_add_u64 v[42:43], v[42:43], 0, v[68:69]
	global_load_dwordx4 v[20:23], v[16:17], off nt
	s_nop 0
	global_load_dwordx4 v[16:19], v[18:19], off nt
	s_nop 0
	global_load_dwordx4 v[28:31], v[24:25], off nt
	s_nop 0
	global_load_dwordx4 v[24:27], v[26:27], off nt
	s_nop 0
	global_load_dwordx4 v[36:39], v[32:33], off nt
	s_nop 0
	global_load_dwordx4 v[32:35], v[34:35], off nt
	s_nop 0
	global_load_dwordx4 v[44:47], v[40:41], off nt
	s_nop 0
	global_load_dwordx4 v[40:43], v[42:43], off nt

; #define LAS __attribute__((address_space(3)))
; __device__ __forceinline__ void tr_load(const TrDesc& d, int lane, f32x4 (&wv)[8]) {
;     const int nblk = d.N / 32, kb = d.item / nblk, nb = d.item % nblk, k0 = 64 * kb, n0 = 32 * nb;
; #pragma unroll
;     for (int i = 0; i < 8; ++i) wv[i] = *(const f32x4*)(d.W + (size_t)(k0 + 8 * i + (lane >> 3)) * d.N + n0 + (lane & 7) * 4);
; }
; __device__ __forceinline__ void tr_run(const Args& a, int list, int first, int stride, int lane, LAS float* scr, int n_end = -1) {
;     const int n = n_end >= 0 ? n_end : (list == 0 ? I_LIST0 : (list == 1 ? I_LIST1 : I_LIST2));
;     int it = first; if (it >= n) return;
;     TrDesc d = tr_desc(a, list, it); f32x4 wv[8]; tr_load(d, lane, wv);
.LBB0_84:
	s_cmpk_gt_i32 s33, 0x7ff
	s_cbranch_scc1 .LBB0_91
	s_ashr_i32 s0, s33, 31
	s_lshr_b32 s0, s0, 26
	s_add_i32 s0, s33, s0
	s_and_b32 s1, s0, 0xffffffc0
	v_lshrrev_b32_e32 v68, 3, v77
	s_sub_i32 s0, s33, s1
	v_or_b32_e32 v0, s1, v68
	v_lshlrev_b32_e32 v1, 2, v77
	s_lshl_b32 s0, s0, 5
	v_and_b32_e32 v2, 28, v1
	v_ashrrev_i32_e32 v1, 31, v0
	v_or_b32_e32 v6, 8, v0
	s_ashr_i32 s1, s0, 31
	v_lshlrev_b64 v[4:5], 13, v[0:1]
	v_ashrrev_i32_e32 v7, 31, v6
	v_lshl_add_u64 v[4:5], s[92:93], 0, v[4:5]
	s_lshl_b64 s[0:1], s[0:1], 2
	v_lshlrev_b64 v[6:7], 13, v[6:7]
	v_mov_b32_e32 v65, 0
	v_lshl_add_u64 v[4:5], v[4:5], 0, s[0:1]
	v_lshlrev_b32_e32 v64, 2, v2
	v_lshl_add_u64 v[6:7], s[92:93], 0, v[6:7]
	v_lshl_add_u64 v[4:5], v[4:5], 0, v[64:65]
	v_lshl_add_u64 v[6:7], v[6:7], 0, s[0:1]
	v_lshl_add_u64 v[6:7], v[6:7], 0, v[64:65]
	global_load_dwordx4 v[56:59], v[4:5], off nt
	global_load_dwordx4 v[44:47], v[6:7], off nt
	v_or_b32_e32 v4, 16, v0
	v_ashrrev_i32_e32 v5, 31, v4
	v_or_b32_e32 v6, 24, v0
	v_lshlrev_b64 v[4:5], 13, v[4:5]
	v_ashrrev_i32_e32 v7, 31, v6
	v_lshl_add_u64 v[4:5], s[92:93], 0, v[4:5]
	v_lshlrev_b64 v[6:7], 13, v[6:7]
	v_lshl_add_u64 v[4:5], v[4:5], 0, s[0:1]
	v_lshl_add_u64 v[6:7], s[92:93], 0, v[6:7]
	v_lshl_add_u64 v[4:5], v[4:5], 0, v[64:65]
	v_lshl_add_u64 v[6:7], v[6:7], 0, s[0:1]
	v_lshl_add_u64 v[6:7], v[6:7], 0, v[64:65]
	global_load_dwordx4 v[52:55], v[4:5], off nt
	global_load_dwordx4 v[36:39], v[6:7], off nt
	v_or_b32_e32 v4, 32, v0
	v_ashrrev_i32_e32 v5, 31, v4
	v_or_b32_e32 v6, 40, v0
	v_lshlrev_b64 v[4:5], 13, v[4:5]
	v_ashrrev_i32_e32 v7, 31, v6
	v_lshl_add_u64 v[4:5], s[92:93], 0, v[4:5]
	v_lshlrev_b64 v[6:7], 13, v[6:7]
	v_lshl_add_u64 v[4:5], v[4:5], 0, s[0:1]
	v_lshl_add_u64 v[6:7], s[92:93], 0, v[6:7]
	v_lshl_add_u64 v[4:5], v[4:5], 0, v[64:65]
	v_lshl_add_u64 v[6:7], v[6:7], 0, s[0:1]
	v_lshl_add_u64 v[6:7], v[6:7], 0, v[64:65]
	global_load_dwordx4 v[48:51], v[4:5], off nt
	global_load_dwordx4 v[32:35], v[6:7], off nt
	v_or_b32_e32 v4, 48, v0
	v_ashrrev_i32_e32 v5, 31, v4
	v_or_b32_e32 v0, 56, v0
	v_lshlrev_b64 v[4:5], 13, v[4:5]
	v_ashrrev_i32_e32 v1, 31, v0
	v_lshl_add_u64 v[4:5], s[92:93], 0, v[4:5]
	v_lshlrev_b64 v[0:1], 13, v[0:1]
	v_lshl_add_u64 v[4:5], v[4:5], 0, s[0:1]
	v_lshl_add_u64 v[0:1], s[92:93], 0, v[0:1]
	v_lshl_add_u64 v[4:5], v[4:5], 0, v[64:65]
	v_lshl_add_u64 v[0:1], v[0:1], 0, s[0:1]
	v_lshl_add_u64 v[0:1], v[0:1], 0, v[64:65]
	global_load_dwordx4 v[40:43], v[4:5], off nt
	global_load_dwordx4 v[60:63], v[0:1], off nt
	v_lshlrev_b32_e32 v0, 3, v77
	v_and_b32_e32 v0, 56, v0
	v_add_u32_e32 v1, s31, v64
	v_mul_u32_u24_e32 v3, 0x84, v68
	v_mul_u32_u24_e32 v4, 0x84, v0
	v_lshlrev_b32_e32 v5, 2, v68
	s_add_i32 s4, s61, s33
	v_or_b32_e32 v69, 8, v68
	v_or_b32_e32 v70, 16, v68
	v_or_b32_e32 v71, 24, v68
	v_add3_u32 v72, s31, v4, v5
	s_lshl_b32 s5, s4, 5
	s_lshl_b32 s6, s61, 5
	v_lshlrev_b32_e32 v66, 2, v2
	v_add_u32_e32 v73, v1, v3
	v_lshlrev_b32_e32 v64, 1, v0
	s_mov_b32 s8, s33
	s_mov_b32 s7, s33
	s_branch .LBB0_87

; __device__ __forceinline__ void tr_load(const TrDesc& d, int lane, f32x4 (&wv)[8]) {
;     const int nblk = d.N / 32, kb = d.item / nblk, nb = d.item % nblk, k0 = 64 * kb, n0 = 32 * nb;
; #pragma unroll
;     for (int i = 0; i < 8; ++i) wv[i] = *(const f32x4*)(d.W + (size_t)(k0 + 8 * i + (lane >> 3)) * d.N + n0 + (lane & 7) * 4);
; }
; __device__ __forceinline__ void tr_run(const Args& a, int list, int first, int stride, int lane, LAS float* scr, int n_end = -1) {
;     ...
;     for (;;) {
;         const int nit = it + stride; const bool more = nit < n;
;         TrDesc dn = d; f32x4 wn[8];
;         if (more) { dn = tr_desc(a, list, nit); tr_load(dn, lane, wn); }
.LBB0_87:
	s_cmpk_lt_i32 s4, 0x800
	s_cselect_b64 s[0:1], -1, 0
	s_cmpk_gt_i32 s4, 0x7ff
	s_cbranch_scc1 .LBB0_89
	s_ashr_i32 s7, s4, 31
	s_lshr_b32 s7, s7, 26
	s_add_i32 s7, s4, s7
	s_and_b32 s9, s7, 0xffffffc0
	v_or_b32_e32 v24, s9, v68
	s_lshl_b32 s7, s7, 5
	v_ashrrev_i32_e32 v25, 31, v24
	s_and_b32 s7, s7, 0xfffff800
	v_lshlrev_b64 v[0:1], 13, v[24:25]
	v_or_b32_e32 v2, 8, v24
	v_or_b32_e32 v8, 16, v24
	v_or_b32_e32 v10, 24, v24
	v_or_b32_e32 v16, 32, v24
	v_or_b32_e32 v18, 40, v24
	v_or_b32_e32 v26, 48, v24
	v_or_b32_e32 v24, 56, v24
	s_sub_i32 s10, s5, s7
	v_ashrrev_i32_e32 v3, 31, v2
	v_ashrrev_i32_e32 v9, 31, v8
	v_ashrrev_i32_e32 v11, 31, v10
	v_ashrrev_i32_e32 v17, 31, v16
	v_ashrrev_i32_e32 v19, 31, v18
	v_ashrrev_i32_e32 v27, 31, v26
	v_ashrrev_i32_e32 v25, 31, v24
	s_ashr_i32 s11, s10, 31
	v_lshlrev_b64 v[2:3], 13, v[2:3]
	v_lshlrev_b64 v[8:9], 13, v[8:9]
	v_lshlrev_b64 v[10:11], 13, v[10:11]
	v_lshlrev_b64 v[16:17], 13, v[16:17]
	v_lshlrev_b64 v[18:19], 13, v[18:19]
	v_lshlrev_b64 v[26:27], 13, v[26:27]
	v_lshlrev_b64 v[24:25], 13, v[24:25]
	v_lshl_add_u64 v[0:1], s[92:93], 0, v[0:1]
	s_lshl_b64 s[10:11], s[10:11], 2
	v_lshl_add_u64 v[2:3], s[92:93], 0, v[2:3]
	v_lshl_add_u64 v[8:9], s[92:93], 0, v[8:9]
	v_lshl_add_u64 v[10:11], s[92:93], 0, v[10:11]
	v_lshl_add_u64 v[16:17], s[92:93], 0, v[16:17]
	v_lshl_add_u64 v[18:19], s[92:93], 0, v[18:19]
	v_lshl_add_u64 v[26:27], s[92:93], 0, v[26:27]
	v_lshl_add_u64 v[24:25], s[92:93], 0, v[24:25]
	v_lshl_add_u64 v[0:1], v[0:1], 0, s[10:11]
	v_mov_b32_e32 v67, v65
	v_lshl_add_u64 v[2:3], v[2:3], 0, s[10:11]
	v_lshl_add_u64 v[8:9], v[8:9], 0, s[10:11]
	v_lshl_add_u64 v[10:11], v[10:11], 0, s[10:11]
	v_lshl_add_u64 v[16:17], v[16:17], 0, s[10:11]
	v_lshl_add_u64 v[18:19], v[18:19], 0, s[10:11]
	v_lshl_add_u64 v[26:27], v[26:27], 0, s[10:11]
	v_lshl_add_u64 v[24:25], v[24:25], 0, s[10:11]
	v_lshl_add_u64 v[0:1], v[0:1], 0, v[66:67]
	v_lshl_add_u64 v[2:3], v[2:3], 0, v[66:67]
	v_lshl_add_u64 v[8:9], v[8:9], 0, v[66:67]
	v_lshl_add_u64 v[10:11], v[10:11], 0, v[66:67]
	v_lshl_add_u64 v[16:17], v[16:17], 0, v[66:67]
	v_lshl_add_u64 v[18:19], v[18:19], 0, v[66:67]
	v_lshl_add_u64 v[26:27], v[26:27], 0, v[66:67]
	v_lshl_add_u64 v[24:25], v[24:25], 0, v[66:67]
	global_load_dwordx4 v[4:7], v[0:1], off nt
	s_nop 0
	global_load_dwordx4 v[0:3], v[2:3], off nt
	s_nop 0
	global_load_dwordx4 v[12:15], v[8:9], off nt
	s_nop 0
	global_load_dwordx4 v[8:11], v[10:11], off nt
	s_nop 0
	global_load_dwordx4 v[20:23], v[16:17], off nt
	s_nop 0
	global_load_dwordx4 v[16:19], v[18:19], off nt
	s_nop 0
	global_load_dwordx4 v[28:31], v[26:27], off nt
	s_nop 0
	global_load_dwordx4 v[24:27], v[24:25], off nt
	s_mov_b32 s7, s4

; __device__ __forceinline__ float silu_f(float v) { return v * __builtin_amdgcn_rcpf(1.f + __builtin_amdgcn_exp2f(-1.4426950408889634f * v)); }
; __device__ __forceinline__ void gemv_item(const float* c, const float* c_ctx, const float* ada_w, const float* ada_b, float* mod, int it, int lane) {
;     const int l = it / 768, rem = it % 768, kc = rem / 24, cgp = rem % 24, k0 = kc * 64;
;     float s[9];
; #pragma unroll
;     for (int r = 0; r < 8; ++r) s[r] = silu_f(c[r * DM + k0 + lane]);
;     s[8] = silu_f(c_ctx[k0 + lane]);
;     const float* W = ada_w + (size_t)l * DM * 6144 + (size_t)k0 * 6144 + cgp * 256 + lane * 4;
;     f32x4 acc[9];
; #pragma unroll
;     for (int r = 0; r < 9; ++r) acc[r] = (f32x4){0.f, 0.f, 0.f, 0.f};
; #pragma unroll 16
;     for (int kk = 0; kk < 64; ++kk) { const f32x4 w = *(const f32x4*)(W + (size_t)kk * 6144);
; #pragma unroll
;         for (int r = 0; r < 9; ++r) { const float sk = __uint_as_float(__builtin_amdgcn_readlane(__float_as_uint(s[r]), kk)); acc[r] += w * sk; } }
;     const int col = cgp * 256 + lane * 4;
;     f32x4 bv = (f32x4){0.f, 0.f, 0.f, 0.f};
;     if (kc == 0) bv = *(const f32x4*)(ada_b + l * 6144 + col);
.LBB0_92:
	s_and_b64 vcc, exec, s[0:1]
	s_cbranch_vccz .LBB0_124
	s_cmpk_lt_u32 s57, 0xc0
	s_cselect_b64 s[8:9], -1, 0
	s_cmpk_gt_u32 s57, 0xbf
	s_mov_b32 s0, 4
	s_cbranch_scc1 .LBB0_102
	s_mul_i32 s0, s2, 3
	s_add_i32 s0, s0, s3
	s_mul_i32 s1, s0, 2731
	s_lshr_b32 s1, s1, 16
	s_mul_i32 s4, s1, 24
	s_sub_i32 s4, s0, s4
	v_lshlrev_b32_e32 v45, 2, v77
	v_lshlrev_b32_e32 v46, 4, v77
	s_lshl_b32 s5, s1, 8
	s_add_u32 s20, s70, s5
	s_addc_u32 s21, s71, 0
	global_load_dword v36, v45, s[20:21]
	s_add_u32 s20, s20, 0x2000
	s_addc_u32 s21, s21, 0
	global_load_dword v37, v45, s[20:21]
	s_add_u32 s20, s20, 0x2000
	s_addc_u32 s21, s21, 0
	global_load_dword v38, v45, s[20:21]
	s_add_u32 s20, s20, 0x2000
	s_addc_u32 s21, s21, 0
	global_load_dword v39, v45, s[20:21]
	s_add_u32 s20, s20, 0x2000
	s_addc_u32 s21, s21, 0
	global_load_dword v40, v45, s[20:21]
	s_add_u32 s20, s20, 0x2000
	s_addc_u32 s21, s21, 0
	global_load_dword v41, v45, s[20:21]
	s_add_u32 s20, s20, 0x2000
	s_addc_u32 s21, s21, 0
	global_load_dword v42, v45, s[20:21]
	s_add_u32 s20, s20, 0x2000
	s_addc_u32 s21, s21, 0
	global_load_dword v43, v45, s[20:21]
	s_add_u32 s20, s74, s5
	s_addc_u32 s21, s75, 0
	global_load_dword v44, v45, s[20:21]
	s_mul_i32 s5, s1, 0x180000
	s_lshl_b32 s6, s4, 10
	s_add_i32 s5, s5, s6
	s_add_u32 s22, s76, s5
	s_addc_u32 s23, s77, 0
	global_load_dwordx4 v[80:83], v46, s[22:23] nt
	s_add_u32 s22, s22, 0x6000
	s_addc_u32 s23, s23, 0
	global_load_dwordx4 v[84:87], v46, s[22:23] nt
	s_add_u32 s22, s22, 0x6000
	s_addc_u32 s23, s23, 0
	global_load_dwordx4 v[88:91], v46, s[22:23] nt
	s_add_u32 s22, s22, 0x6000
	s_addc_u32 s23, s23, 0
	global_load_dwordx4 v[92:95], v46, s[22:23] nt
	s_add_u32 s22, s22, 0x6000
	s_addc_u32 s23, s23, 0
	global_load_dwordx4 v[96:99], v46, s[22:23] nt
	s_add_u32 s22, s22, 0x6000
	s_addc_u32 s23, s23, 0
	global_load_dwordx4 v[100:103], v46, s[22:23] nt
	s_add_u32 s22, s22, 0x6000
	s_addc_u32 s23, s23, 0
	global_load_dwordx4 v[104:107], v46, s[22:23] nt
	s_add_u32 s22, s22, 0x6000
	s_addc_u32 s23, s23, 0
	global_load_dwordx4 v[108:111], v46, s[22:23] nt
	s_add_u32 s22, s22, 0x6000
	s_addc_u32 s23, s23, 0
	global_load_dwordx4 v[112:115], v46, s[22:23] nt
	s_add_u32 s22, s22, 0x6000
	s_addc_u32 s23, s23, 0
	global_load_dwordx4 v[116:119], v46, s[22:23] nt
	s_add_u32 s22, s22, 0x6000
	s_addc_u32 s23, s23, 0
	global_load_dwordx4 v[120:123], v46, s[22:23] nt
	s_add_u32 s22, s22, 0x6000
	s_addc_u32 s23, s23, 0
	global_load_dwordx4 v[124:127], v46, s[22:23] nt
	s_add_u32 s22, s22, 0x6000
	s_addc_u32 s23, s23, 0
	global_load_dwordx4 v[128:131], v46, s[22:23] nt
	s_add_u32 s22, s22, 0x6000
	s_addc_u32 s23, s23, 0
	global_load_dwordx4 v[132:135], v46, s[22:23] nt
	s_add_u32 s22, s22, 0x6000
	s_addc_u32 s23, s23, 0
	global_load_dwordx4 v[136:139], v46, s[22:23] nt
	s_add_u32 s22, s22, 0x6000
	s_addc_u32 s23, s23, 0
	global_load_dwordx4 v[140:143], v46, s[22:23] nt
	s_add_u32 s22, s22, 0x6000
	s_addc_u32 s23, s23, 0
	global_load_dwordx4 v[144:147], v46, s[22:23] nt
	s_add_u32 s22, s22, 0x6000
	s_addc_u32 s23, s23, 0
	global_load_dwordx4 v[148:151], v46, s[22:23] nt
	s_add_u32 s22, s22, 0x6000
	s_addc_u32 s23, s23, 0
	global_load_dwordx4 v[152:155], v46, s[22:23] nt
	s_add_u32 s22, s22, 0x6000
	s_addc_u32 s23, s23, 0
	global_load_dwordx4 v[156:159], v46, s[22:23] nt
	s_add_u32 s22, s22, 0x6000
	s_addc_u32 s23, s23, 0
	global_load_dwordx4 v[160:163], v46, s[22:23] nt
	s_add_u32 s22, s22, 0x6000
	s_addc_u32 s23, s23, 0
	global_load_dwordx4 v[164:167], v46, s[22:23] nt
	s_add_u32 s22, s22, 0x6000
	s_addc_u32 s23, s23, 0
	global_load_dwordx4 v[168:171], v46, s[22:23] nt
	s_add_u32 s22, s22, 0x6000
	s_addc_u32 s23, s23, 0
	global_load_dwordx4 v[172:175], v46, s[22:23] nt
	s_add_u32 s22, s22, 0x6000
	s_addc_u32 s23, s23, 0
	global_load_dwordx4 v[176:179], v46, s[22:23] nt
	s_add_u32 s22, s22, 0x6000
	s_addc_u32 s23, s23, 0
	global_load_dwordx4 v[180:183], v46, s[22:23] nt
	s_add_u32 s22, s22, 0x6000
	s_addc_u32 s23, s23, 0
	global_load_dwordx4 v[184:187], v46, s[22:23] nt
	s_add_u32 s22, s22, 0x6000
	s_addc_u32 s23, s23, 0
	global_load_dwordx4 v[188:191], v46, s[22:23] nt
	s_add_u32 s22, s22, 0x6000
	s_addc_u32 s23, s23, 0
	global_load_dwordx4 v[192:195], v46, s[22:23] nt
	s_add_u32 s22, s22, 0x6000
	s_addc_u32 s23, s23, 0
	global_load_dwordx4 v[200:203], v46, s[22:23] nt
	s_add_u32 s22, s22, 0x6000
	s_addc_u32 s23, s23, 0
	global_load_dwordx4 v[204:207], v46, s[22:23] nt
	s_add_u32 s22, s22, 0x6000
	s_addc_u32 s23, s23, 0
	global_load_dwordx4 v[208:211], v46, s[22:23] nt
	s_add_u32 s22, s22, 0x6000
	s_addc_u32 s23, s23, 0
	v_mov_b32_e32 v52, 0
	v_mov_b32_e32 v53, 0
	v_mov_b32_e32 v54, 0
	v_mov_b32_e32 v55, 0
	s_cmp_lg_u32 s1, 0
	s_cbranch_scc1 .Lgv0_nobias
	s_lshl_b32 s5, s4, 10
	s_add_u32 s20, s78, s5
	s_addc_u32 s21, s79, 0
	global_load_dwordx4 v[52:55], v46, s[20:21] nt
	s_waitcnt vmcnt(0)
; __device__ __forceinline__ float silu_f(float v) { return v * __builtin_amdgcn_rcpf(1.f + __builtin_amdgcn_exp2f(-1.4426950408889634f * v)); }
; __device__ __forceinline__ void gemv_item(const float* c, const float* c_ctx, const float* ada_w, const float* ada_b, float* mod, int it, int lane) {
;     ...
;     for (int r = 0; r < 8; ++r) s[r] = silu_f(c[r * DM + k0 + lane]);
;     s[8] = silu_f(c_ctx[k0 + lane]);
;     const float* W = ada_w + (size_t)l * DM * 6144 + (size_t)k0 * 6144 + cgp * 256 + lane * 4;
;     f32x4 acc[9];
; #pragma unroll
;     for (int r = 0; r < 9; ++r) acc[r] = (f32x4){0.f, 0.f, 0.f, 0.f};
; #pragma unroll 16
;     for (int kk = 0; kk < 64; ++kk) { const f32x4 w = *(const f32x4*)(W + (size_t)kk * 6144);
; #pragma unroll
;         for (int r = 0; r < 9; ++r) { const float sk = __uint_as_float(__builtin_amdgcn_readlane(__float_as_uint(s[r]), kk)); acc[r] += w * sk; } }
.Lgv0_nobias:
	s_waitcnt vmcnt(32)
	v_mul_f32_e32 v47, 0xbfb8aa3b, v36
	v_exp_f32_e32 v47, v47
	s_nop 0
	v_add_f32_e32 v47, 1.0, v47
	v_rcp_f32_e32 v47, v47
	s_nop 0
	v_mul_f32_e32 v36, v36, v47
	v_mul_f32_e32 v47, 0xbfb8aa3b, v37
	v_exp_f32_e32 v47, v47
	s_nop 0
	v_add_f32_e32 v47, 1.0, v47
	v_rcp_f32_e32 v47, v47
	s_nop 0
	v_mul_f32_e32 v37, v37, v47
	v_mul_f32_e32 v47, 0xbfb8aa3b, v38
	v_exp_f32_e32 v47, v47
	s_nop 0
	v_add_f32_e32 v47, 1.0, v47
	v_rcp_f32_e32 v47, v47
	s_nop 0
	v_mul_f32_e32 v38, v38, v47
	v_mul_f32_e32 v47, 0xbfb8aa3b, v39
	v_exp_f32_e32 v47, v47
	s_nop 0
	v_add_f32_e32 v47, 1.0, v47
	v_rcp_f32_e32 v47, v47
	s_nop 0
	v_mul_f32_e32 v39, v39, v47
	v_mul_f32_e32 v47, 0xbfb8aa3b, v40
	v_exp_f32_e32 v47, v47
	s_nop 0
	v_add_f32_e32 v47, 1.0, v47
	v_rcp_f32_e32 v47, v47
	s_nop 0
	v_mul_f32_e32 v40, v40, v47
	v_mul_f32_e32 v47, 0xbfb8aa3b, v41
	v_exp_f32_e32 v47, v47
	s_nop 0
	v_add_f32_e32 v47, 1.0, v47
	v_rcp_f32_e32 v47, v47
	s_nop 0
	v_mul_f32_e32 v41, v41, v47
	v_mul_f32_e32 v47, 0xbfb8aa3b, v42
	v_exp_f32_e32 v47, v47
	s_nop 0
	v_add_f32_e32 v47, 1.0, v47
	v_rcp_f32_e32 v47, v47
	s_nop 0
	v_mul_f32_e32 v42, v42, v47
	v_mul_f32_e32 v47, 0xbfb8aa3b, v43
	v_exp_f32_e32 v47, v47
	s_nop 0
	v_add_f32_e32 v47, 1.0, v47
	v_rcp_f32_e32 v47, v47
	s_nop 0
	v_mul_f32_e32 v43, v43, v47
	v_mul_f32_e32 v47, 0xbfb8aa3b, v44
	v_exp_f32_e32 v47, v47
	s_nop 0
	v_add_f32_e32 v47, 1.0, v47
	v_rcp_f32_e32 v47, v47
	s_nop 0
	v_mul_f32_e32 v44, v44, v47
	v_mov_b32_e32 v0, 0
	v_mov_b32_e32 v1, 0
	v_mov_b32_e32 v2, 0
	v_mov_b32_e32 v3, 0
	v_mov_b32_e32 v4, 0
	v_mov_b32_e32 v5, 0
	v_mov_b32_e32 v6, 0
	v_mov_b32_e32 v7, 0
	v_mov_b32_e32 v8, 0
	v_mov_b32_e32 v9, 0
	v_mov_b32_e32 v10, 0
	v_mov_b32_e32 v11, 0
	v_mov_b32_e32 v12, 0
	v_mov_b32_e32 v13, 0
	v_mov_b32_e32 v14, 0
	v_mov_b32_e32 v15, 0
	v_mov_b32_e32 v16, 0
	v_mov_b32_e32 v17, 0
	v_mov_b32_e32 v18, 0
	v_mov_b32_e32 v19, 0
	v_mov_b32_e32 v20, 0
	v_mov_b32_e32 v21, 0
	v_mov_b32_e32 v22, 0
	v_mov_b32_e32 v23, 0
	v_mov_b32_e32 v24, 0
	v_mov_b32_e32 v25, 0
	v_mov_b32_e32 v26, 0
	v_mov_b32_e32 v27, 0
	v_mov_b32_e32 v28, 0
	v_mov_b32_e32 v29, 0
	v_mov_b32_e32 v30, 0
	v_mov_b32_e32 v31, 0
	v_mov_b32_e32 v32, 0
	v_mov_b32_e32 v33, 0
	v_mov_b32_e32 v34, 0
	v_mov_b32_e32 v35, 0
	s_waitcnt vmcnt(16)
	v_readlane_b32 s10, v36, 0
	v_readlane_b32 s11, v37, 0
	v_readlane_b32 s12, v38, 0
	v_readlane_b32 s13, v39, 0
	v_readlane_b32 s14, v40, 0
	v_readlane_b32 s15, v41, 0
	v_readlane_b32 s16, v42, 0
	v_readlane_b32 s17, v43, 0
	v_readlane_b32 s18, v44, 0
	v_fmac_f32_e32 v0, s10, v80
	v_fmac_f32_e32 v1, s10, v81
	v_fmac_f32_e32 v2, s10, v82
	v_fmac_f32_e32 v3, s10, v83
	v_fmac_f32_e32 v4, s11, v80
	v_fmac_f32_e32 v5, s11, v81
	v_fmac_f32_e32 v6, s11, v82
	v_fmac_f32_e32 v7, s11, v83
	v_fmac_f32_e32 v8, s12, v80
	v_fmac_f32_e32 v9, s12, v81
	v_fmac_f32_e32 v10, s12, v82
	v_fmac_f32_e32 v11, s12, v83
	v_fmac_f32_e32 v12, s13, v80
	v_fmac_f32_e32 v13, s13, v81
	v_fmac_f32_e32 v14, s13, v82
	v_fmac_f32_e32 v15, s13, v83
	v_fmac_f32_e32 v16, s14, v80
	v_fmac_f32_e32 v17, s14, v81
	v_fmac_f32_e32 v18, s14, v82
	v_fmac_f32_e32 v19, s14, v83
	v_fmac_f32_e32 v20, s15, v80
	v_fmac_f32_e32 v21, s15, v81
	v_fmac_f32_e32 v22, s15, v82
	v_fmac_f32_e32 v23, s15, v83
	v_fmac_f32_e32 v24, s16, v80
	v_fmac_f32_e32 v25, s16, v81
	v_fmac_f32_e32 v26, s16, v82
	v_fmac_f32_e32 v27, s16, v83
	v_fmac_f32_e32 v28, s17, v80
	v_fmac_f32_e32 v29, s17, v81
	v_fmac_f32_e32 v30, s17, v82
	v_fmac_f32_e32 v31, s17, v83
	v_fmac_f32_e32 v32, s18, v80
	v_fmac_f32_e32 v33, s18, v81
	v_fmac_f32_e32 v34, s18, v82
	v_fmac_f32_e32 v35, s18, v83
	v_readlane_b32 s10, v36, 1
	v_readlane_b32 s11, v37, 1
	v_readlane_b32 s12, v38, 1
	v_readlane_b32 s13, v39, 1
	v_readlane_b32 s14, v40, 1
	v_readlane_b32 s15, v41, 1
	v_readlane_b32 s16, v42, 1
	v_readlane_b32 s17, v43, 1
	v_readlane_b32 s18, v44, 1
	v_fmac_f32_e32 v0, s10, v84
	v_fmac_f32_e32 v1, s10, v85
	v_fmac_f32_e32 v2, s10, v86
	v_fmac_f32_e32 v3, s10, v87
	v_fmac_f32_e32 v4, s11, v84
	v_fmac_f32_e32 v5, s11, v85
	v_fmac_f32_e32 v6, s11, v86
	v_fmac_f32_e32 v7, s11, v87
	v_fmac_f32_e32 v8, s12, v84
	v_fmac_f32_e32 v9, s12, v85
	v_fmac_f32_e32 v10, s12, v86
	v_fmac_f32_e32 v11, s12, v87
	v_fmac_f32_e32 v12, s13, v84
	v_fmac_f32_e32 v13, s13, v85
	v_fmac_f32_e32 v14, s13, v86
	v_fmac_f32_e32 v15, s13, v87
	v_fmac_f32_e32 v16, s14, v84
	v_fmac_f32_e32 v17, s14, v85
	v_fmac_f32_e32 v18, s14, v86
	v_fmac_f32_e32 v19, s14, v87
	v_fmac_f32_e32 v20, s15, v84
	v_fmac_f32_e32 v21, s15, v85
	v_fmac_f32_e32 v22, s15, v86
	v_fmac_f32_e32 v23, s15, v87
	v_fmac_f32_e32 v24, s16, v84
	v_fmac_f32_e32 v25, s16, v85
	v_fmac_f32_e32 v26, s16, v86
	v_fmac_f32_e32 v27, s16, v87
	v_fmac_f32_e32 v28, s17, v84
	v_fmac_f32_e32 v29, s17, v85
	v_fmac_f32_e32 v30, s17, v86
	v_fmac_f32_e32 v31, s17, v87
	v_fmac_f32_e32 v32, s18, v84
	v_fmac_f32_e32 v33, s18, v85
	v_fmac_f32_e32 v34, s18, v86
	v_fmac_f32_e32 v35, s18, v87
	v_readlane_b32 s10, v36, 2
	v_readlane_b32 s11, v37, 2
	v_readlane_b32 s12, v38, 2
	v_readlane_b32 s13, v39, 2
	v_readlane_b32 s14, v40, 2
	v_readlane_b32 s15, v41, 2
	v_readlane_b32 s16, v42, 2
	v_readlane_b32 s17, v43, 2
	v_readlane_b32 s18, v44, 2
	v_fmac_f32_e32 v0, s10, v88
	v_fmac_f32_e32 v1, s10, v89
	v_fmac_f32_e32 v2, s10, v90
	v_fmac_f32_e32 v3, s10, v91
	v_fmac_f32_e32 v4, s11, v88
	v_fmac_f32_e32 v5, s11, v89
	v_fmac_f32_e32 v6, s11, v90
	v_fmac_f32_e32 v7, s11, v91
	v_fmac_f32_e32 v8, s12, v88
	v_fmac_f32_e32 v9, s12, v89
	v_fmac_f32_e32 v10, s12, v90
	v_fmac_f32_e32 v11, s12, v91
	v_fmac_f32_e32 v12, s13, v88
	v_fmac_f32_e32 v13, s13, v89
	v_fmac_f32_e32 v14, s13, v90
	v_fmac_f32_e32 v15, s13, v91
; __device__ __forceinline__ void gemv_item(const float* c, const float* c_ctx, const float* ada_w, const float* ada_b, float* mod, int it, int lane) {
;     ...
;     for (int kk = 0; kk < 64; ++kk) { const f32x4 w = *(const f32x4*)(W + (size_t)kk * 6144);
; #pragma unroll
;         for (int r = 0; r < 9; ++r) { const float sk = __uint_as_float(__builtin_amdgcn_readlane(__float_as_uint(s[r]), kk)); acc[r] += w * sk; } }
	v_fmac_f32_e32 v16, s14, v88
	v_fmac_f32_e32 v17, s14, v89
	v_fmac_f32_e32 v18, s14, v90
	v_fmac_f32_e32 v19, s14, v91
	v_fmac_f32_e32 v20, s15, v88
	v_fmac_f32_e32 v21, s15, v89
	v_fmac_f32_e32 v22, s15, v90
	v_fmac_f32_e32 v23, s15, v91
	v_fmac_f32_e32 v24, s16, v88
	v_fmac_f32_e32 v25, s16, v89
	v_fmac_f32_e32 v26, s16, v90
	v_fmac_f32_e32 v27, s16, v91
	v_fmac_f32_e32 v28, s17, v88
	v_fmac_f32_e32 v29, s17, v89
	v_fmac_f32_e32 v30, s17, v90
	v_fmac_f32_e32 v31, s17, v91
	v_fmac_f32_e32 v32, s18, v88
	v_fmac_f32_e32 v33, s18, v89
	v_fmac_f32_e32 v34, s18, v90
	v_fmac_f32_e32 v35, s18, v91
	v_readlane_b32 s10, v36, 3
	v_readlane_b32 s11, v37, 3
	v_readlane_b32 s12, v38, 3
	v_readlane_b32 s13, v39, 3
	v_readlane_b32 s14, v40, 3
	v_readlane_b32 s15, v41, 3
	v_readlane_b32 s16, v42, 3
	v_readlane_b32 s17, v43, 3
	v_readlane_b32 s18, v44, 3
	v_fmac_f32_e32 v0, s10, v92
	v_fmac_f32_e32 v1, s10, v93
	v_fmac_f32_e32 v2, s10, v94
	v_fmac_f32_e32 v3, s10, v95
	v_fmac_f32_e32 v4, s11, v92
	v_fmac_f32_e32 v5, s11, v93
	v_fmac_f32_e32 v6, s11, v94
	v_fmac_f32_e32 v7, s11, v95
	v_fmac_f32_e32 v8, s12, v92
	v_fmac_f32_e32 v9, s12, v93
	v_fmac_f32_e32 v10, s12, v94
	v_fmac_f32_e32 v11, s12, v95
	v_fmac_f32_e32 v12, s13, v92
	v_fmac_f32_e32 v13, s13, v93
	v_fmac_f32_e32 v14, s13, v94
	v_fmac_f32_e32 v15, s13, v95
	v_fmac_f32_e32 v16, s14, v92
	v_fmac_f32_e32 v17, s14, v93
	v_fmac_f32_e32 v18, s14, v94
	v_fmac_f32_e32 v19, s14, v95
	v_fmac_f32_e32 v20, s15, v92
	v_fmac_f32_e32 v21, s15, v93
	v_fmac_f32_e32 v22, s15, v94
	v_fmac_f32_e32 v23, s15, v95
	v_fmac_f32_e32 v24, s16, v92
	v_fmac_f32_e32 v25, s16, v93
	v_fmac_f32_e32 v26, s16, v94
	v_fmac_f32_e32 v27, s16, v95
	v_fmac_f32_e32 v28, s17, v92
	v_fmac_f32_e32 v29, s17, v93
	v_fmac_f32_e32 v30, s17, v94
	v_fmac_f32_e32 v31, s17, v95
	v_fmac_f32_e32 v32, s18, v92
	v_fmac_f32_e32 v33, s18, v93
	v_fmac_f32_e32 v34, s18, v94
	v_fmac_f32_e32 v35, s18, v95
	v_readlane_b32 s10, v36, 4
	v_readlane_b32 s11, v37, 4
	v_readlane_b32 s12, v38, 4
	v_readlane_b32 s13, v39, 4
	v_readlane_b32 s14, v40, 4
	v_readlane_b32 s15, v41, 4
	v_readlane_b32 s16, v42, 4
	v_readlane_b32 s17, v43, 4
	v_readlane_b32 s18, v44, 4
	v_fmac_f32_e32 v0, s10, v96
	v_fmac_f32_e32 v1, s10, v97
	v_fmac_f32_e32 v2, s10, v98
	v_fmac_f32_e32 v3, s10, v99
	v_fmac_f32_e32 v4, s11, v96
	v_fmac_f32_e32 v5, s11, v97
	v_fmac_f32_e32 v6, s11, v98
	v_fmac_f32_e32 v7, s11, v99
	v_fmac_f32_e32 v8, s12, v96
	v_fmac_f32_e32 v9, s12, v97
	v_fmac_f32_e32 v10, s12, v98
	v_fmac_f32_e32 v11, s12, v99
	v_fmac_f32_e32 v12, s13, v96
	v_fmac_f32_e32 v13, s13, v97
	v_fmac_f32_e32 v14, s13, v98
	v_fmac_f32_e32 v15, s13, v99
	v_fmac_f32_e32 v16, s14, v96
	v_fmac_f32_e32 v17, s14, v97
	v_fmac_f32_e32 v18, s14, v98
	v_fmac_f32_e32 v19, s14, v99
	v_fmac_f32_e32 v20, s15, v96
	v_fmac_f32_e32 v21, s15, v97
	v_fmac_f32_e32 v22, s15, v98
	v_fmac_f32_e32 v23, s15, v99
	v_fmac_f32_e32 v24, s16, v96
	v_fmac_f32_e32 v25, s16, v97
	v_fmac_f32_e32 v26, s16, v98
	v_fmac_f32_e32 v27, s16, v99
	v_fmac_f32_e32 v28, s17, v96
	v_fmac_f32_e32 v29, s17, v97
	v_fmac_f32_e32 v30, s17, v98
	v_fmac_f32_e32 v31, s17, v99
	v_fmac_f32_e32 v32, s18, v96
	v_fmac_f32_e32 v33, s18, v97
	v_fmac_f32_e32 v34, s18, v98
	v_fmac_f32_e32 v35, s18, v99
	v_readlane_b32 s10, v36, 5
	v_readlane_b32 s11, v37, 5
	v_readlane_b32 s12, v38, 5
	v_readlane_b32 s13, v39, 5
	v_readlane_b32 s14, v40, 5
	v_readlane_b32 s15, v41, 5
	v_readlane_b32 s16, v42, 5
	v_readlane_b32 s17, v43, 5
	v_readlane_b32 s18, v44, 5
	v_fmac_f32_e32 v0, s10, v100
	v_fmac_f32_e32 v1, s10, v101
	v_fmac_f32_e32 v2, s10, v102
	v_fmac_f32_e32 v3, s10, v103
	v_fmac_f32_e32 v4, s11, v100
	v_fmac_f32_e32 v5, s11, v101
	v_fmac_f32_e32 v6, s11, v102
	v_fmac_f32_e32 v7, s11, v103
	v_fmac_f32_e32 v8, s12, v100
	v_fmac_f32_e32 v9, s12, v101
	v_fmac_f32_e32 v10, s12, v102
	v_fmac_f32_e32 v11, s12, v103
	v_fmac_f32_e32 v12, s13, v100
	v_fmac_f32_e32 v13, s13, v101
	v_fmac_f32_e32 v14, s13, v102
	v_fmac_f32_e32 v15, s13, v103
	v_fmac_f32_e32 v16, s14, v100
	v_fmac_f32_e32 v17, s14, v101
	v_fmac_f32_e32 v18, s14, v102
	v_fmac_f32_e32 v19, s14, v103
	v_fmac_f32_e32 v20, s15, v100
	v_fmac_f32_e32 v21, s15, v101
	v_fmac_f32_e32 v22, s15, v102
	v_fmac_f32_e32 v23, s15, v103
	v_fmac_f32_e32 v24, s16, v100
	v_fmac_f32_e32 v25, s16, v101
	v_fmac_f32_e32 v26, s16, v102
	v_fmac_f32_e32 v27, s16, v103
	v_fmac_f32_e32 v28, s17, v100
	v_fmac_f32_e32 v29, s17, v101
	v_fmac_f32_e32 v30, s17, v102
	v_fmac_f32_e32 v31, s17, v103
	v_fmac_f32_e32 v32, s18, v100
	v_fmac_f32_e32 v33, s18, v101
	v_fmac_f32_e32 v34, s18, v102
	v_fmac_f32_e32 v35, s18, v103
	v_readlane_b32 s10, v36, 6
	v_readlane_b32 s11, v37, 6
	v_readlane_b32 s12, v38, 6
	v_readlane_b32 s13, v39, 6
	v_readlane_b32 s14, v40, 6
	v_readlane_b32 s15, v41, 6
	v_readlane_b32 s16, v42, 6
	v_readlane_b32 s17, v43, 6
	v_readlane_b32 s18, v44, 6
	v_fmac_f32_e32 v0, s10, v104
	v_fmac_f32_e32 v1, s10, v105
	v_fmac_f32_e32 v2, s10, v106
	v_fmac_f32_e32 v3, s10, v107
	v_fmac_f32_e32 v4, s11, v104
	v_fmac_f32_e32 v5, s11, v105
	v_fmac_f32_e32 v6, s11, v106
	v_fmac_f32_e32 v7, s11, v107
	v_fmac_f32_e32 v8, s12, v104
	v_fmac_f32_e32 v9, s12, v105
	v_fmac_f32_e32 v10, s12, v106
	v_fmac_f32_e32 v11, s12, v107
	v_fmac_f32_e32 v12, s13, v104
	v_fmac_f32_e32 v13, s13, v105
	v_fmac_f32_e32 v14, s13, v106
	v_fmac_f32_e32 v15, s13, v107
	v_fmac_f32_e32 v16, s14, v104
	v_fmac_f32_e32 v17, s14, v105
	v_fmac_f32_e32 v18, s14, v106
	v_fmac_f32_e32 v19, s14, v107
	v_fmac_f32_e32 v20, s15, v104
	v_fmac_f32_e32 v21, s15, v105
	v_fmac_f32_e32 v22, s15, v106
	v_fmac_f32_e32 v23, s15, v107
	v_fmac_f32_e32 v24, s16, v104
	v_fmac_f32_e32 v25, s16, v105
; __device__ __forceinline__ void gemv_item(const float* c, const float* c_ctx, const float* ada_w, const float* ada_b, float* mod, int it, int lane) {
;     ...
;     for (int kk = 0; kk < 64; ++kk) { const f32x4 w = *(const f32x4*)(W + (size_t)kk * 6144);
; #pragma unroll
;         for (int r = 0; r < 9; ++r) { const float sk = __uint_as_float(__builtin_amdgcn_readlane(__float_as_uint(s[r]), kk)); acc[r] += w * sk; } }
	v_fmac_f32_e32 v26, s16, v106
	v_fmac_f32_e32 v27, s16, v107
	v_fmac_f32_e32 v28, s17, v104
	v_fmac_f32_e32 v29, s17, v105
	v_fmac_f32_e32 v30, s17, v106
	v_fmac_f32_e32 v31, s17, v107
	v_fmac_f32_e32 v32, s18, v104
	v_fmac_f32_e32 v33, s18, v105
	v_fmac_f32_e32 v34, s18, v106
	v_fmac_f32_e32 v35, s18, v107
	v_readlane_b32 s10, v36, 7
	v_readlane_b32 s11, v37, 7
	v_readlane_b32 s12, v38, 7
	v_readlane_b32 s13, v39, 7
	v_readlane_b32 s14, v40, 7
	v_readlane_b32 s15, v41, 7
	v_readlane_b32 s16, v42, 7
	v_readlane_b32 s17, v43, 7
	v_readlane_b32 s18, v44, 7
	v_fmac_f32_e32 v0, s10, v108
	v_fmac_f32_e32 v1, s10, v109
	v_fmac_f32_e32 v2, s10, v110
	v_fmac_f32_e32 v3, s10, v111
	v_fmac_f32_e32 v4, s11, v108
	v_fmac_f32_e32 v5, s11, v109
	v_fmac_f32_e32 v6, s11, v110
	v_fmac_f32_e32 v7, s11, v111
	v_fmac_f32_e32 v8, s12, v108
	v_fmac_f32_e32 v9, s12, v109
	v_fmac_f32_e32 v10, s12, v110
	v_fmac_f32_e32 v11, s12, v111
	v_fmac_f32_e32 v12, s13, v108
	v_fmac_f32_e32 v13, s13, v109
	v_fmac_f32_e32 v14, s13, v110
	v_fmac_f32_e32 v15, s13, v111
	v_fmac_f32_e32 v16, s14, v108
	v_fmac_f32_e32 v17, s14, v109
	v_fmac_f32_e32 v18, s14, v110
	v_fmac_f32_e32 v19, s14, v111
	v_fmac_f32_e32 v20, s15, v108
	v_fmac_f32_e32 v21, s15, v109
	v_fmac_f32_e32 v22, s15, v110
	v_fmac_f32_e32 v23, s15, v111
	v_fmac_f32_e32 v24, s16, v108
	v_fmac_f32_e32 v25, s16, v109
	v_fmac_f32_e32 v26, s16, v110
	v_fmac_f32_e32 v27, s16, v111
	v_fmac_f32_e32 v28, s17, v108
	v_fmac_f32_e32 v29, s17, v109
	v_fmac_f32_e32 v30, s17, v110
	v_fmac_f32_e32 v31, s17, v111
	v_fmac_f32_e32 v32, s18, v108
	v_fmac_f32_e32 v33, s18, v109
	v_fmac_f32_e32 v34, s18, v110
	v_fmac_f32_e32 v35, s18, v111
	v_readlane_b32 s10, v36, 8
	v_readlane_b32 s11, v37, 8
	v_readlane_b32 s12, v38, 8
	v_readlane_b32 s13, v39, 8
	v_readlane_b32 s14, v40, 8
	v_readlane_b32 s15, v41, 8
	v_readlane_b32 s16, v42, 8
	v_readlane_b32 s17, v43, 8
	v_readlane_b32 s18, v44, 8
	v_fmac_f32_e32 v0, s10, v112
	v_fmac_f32_e32 v1, s10, v113
	v_fmac_f32_e32 v2, s10, v114
	v_fmac_f32_e32 v3, s10, v115
	v_fmac_f32_e32 v4, s11, v112
	v_fmac_f32_e32 v5, s11, v113
	v_fmac_f32_e32 v6, s11, v114
	v_fmac_f32_e32 v7, s11, v115
	v_fmac_f32_e32 v8, s12, v112
	v_fmac_f32_e32 v9, s12, v113
	v_fmac_f32_e32 v10, s12, v114
	v_fmac_f32_e32 v11, s12, v115
	v_fmac_f32_e32 v12, s13, v112
	v_fmac_f32_e32 v13, s13, v113
	v_fmac_f32_e32 v14, s13, v114
	v_fmac_f32_e32 v15, s13, v115
	v_fmac_f32_e32 v16, s14, v112
	v_fmac_f32_e32 v17, s14, v113
	v_fmac_f32_e32 v18, s14, v114
	v_fmac_f32_e32 v19, s14, v115
	v_fmac_f32_e32 v20, s15, v112
	v_fmac_f32_e32 v21, s15, v113
	v_fmac_f32_e32 v22, s15, v114
	v_fmac_f32_e32 v23, s15, v115
	v_fmac_f32_e32 v24, s16, v112
	v_fmac_f32_e32 v25, s16, v113
	v_fmac_f32_e32 v26, s16, v114
	v_fmac_f32_e32 v27, s16, v115
	v_fmac_f32_e32 v28, s17, v112
	v_fmac_f32_e32 v29, s17, v113
	v_fmac_f32_e32 v30, s17, v114
	v_fmac_f32_e32 v31, s17, v115
	v_fmac_f32_e32 v32, s18, v112
	v_fmac_f32_e32 v33, s18, v113
	v_fmac_f32_e32 v34, s18, v114
	v_fmac_f32_e32 v35, s18, v115
	v_readlane_b32 s10, v36, 9
	v_readlane_b32 s11, v37, 9
	v_readlane_b32 s12, v38, 9
	v_readlane_b32 s13, v39, 9
	v_readlane_b32 s14, v40, 9
	v_readlane_b32 s15, v41, 9
	v_readlane_b32 s16, v42, 9
	v_readlane_b32 s17, v43, 9
	v_readlane_b32 s18, v44, 9
	v_fmac_f32_e32 v0, s10, v116
	v_fmac_f32_e32 v1, s10, v117
	v_fmac_f32_e32 v2, s10, v118
	v_fmac_f32_e32 v3, s10, v119
	v_fmac_f32_e32 v4, s11, v116
	v_fmac_f32_e32 v5, s11, v117
	v_fmac_f32_e32 v6, s11, v118
	v_fmac_f32_e32 v7, s11, v119
	v_fmac_f32_e32 v8, s12, v116
	v_fmac_f32_e32 v9, s12, v117
	v_fmac_f32_e32 v10, s12, v118
	v_fmac_f32_e32 v11, s12, v119
	v_fmac_f32_e32 v12, s13, v116
	v_fmac_f32_e32 v13, s13, v117
	v_fmac_f32_e32 v14, s13, v118
	v_fmac_f32_e32 v15, s13, v119
	v_fmac_f32_e32 v16, s14, v116
	v_fmac_f32_e32 v17, s14, v117
	v_fmac_f32_e32 v18, s14, v118
	v_fmac_f32_e32 v19, s14, v119
	v_fmac_f32_e32 v20, s15, v116
	v_fmac_f32_e32 v21, s15, v117
	v_fmac_f32_e32 v22, s15, v118
	v_fmac_f32_e32 v23, s15, v119
	v_fmac_f32_e32 v24, s16, v116
	v_fmac_f32_e32 v25, s16, v117
	v_fmac_f32_e32 v26, s16, v118
	v_fmac_f32_e32 v27, s16, v119
	v_fmac_f32_e32 v28, s17, v116
	v_fmac_f32_e32 v29, s17, v117
	v_fmac_f32_e32 v30, s17, v118
	v_fmac_f32_e32 v31, s17, v119
	v_fmac_f32_e32 v32, s18, v116
	v_fmac_f32_e32 v33, s18, v117
	v_fmac_f32_e32 v34, s18, v118
	v_fmac_f32_e32 v35, s18, v119
	v_readlane_b32 s10, v36, 10
	v_readlane_b32 s11, v37, 10
	v_readlane_b32 s12, v38, 10
	v_readlane_b32 s13, v39, 10
	v_readlane_b32 s14, v40, 10
	v_readlane_b32 s15, v41, 10
	v_readlane_b32 s16, v42, 10
	v_readlane_b32 s17, v43, 10
	v_readlane_b32 s18, v44, 10
	v_fmac_f32_e32 v0, s10, v120
	v_fmac_f32_e32 v1, s10, v121
	v_fmac_f32_e32 v2, s10, v122
	v_fmac_f32_e32 v3, s10, v123
	v_fmac_f32_e32 v4, s11, v120
	v_fmac_f32_e32 v5, s11, v121
	v_fmac_f32_e32 v6, s11, v122
	v_fmac_f32_e32 v7, s11, v123
	v_fmac_f32_e32 v8, s12, v120
	v_fmac_f32_e32 v9, s12, v121
	v_fmac_f32_e32 v10, s12, v122
	v_fmac_f32_e32 v11, s12, v123
	v_fmac_f32_e32 v12, s13, v120
	v_fmac_f32_e32 v13, s13, v121
	v_fmac_f32_e32 v14, s13, v122
	v_fmac_f32_e32 v15, s13, v123
	v_fmac_f32_e32 v16, s14, v120
	v_fmac_f32_e32 v17, s14, v121
	v_fmac_f32_e32 v18, s14, v122
	v_fmac_f32_e32 v19, s14, v123
	v_fmac_f32_e32 v20, s15, v120
	v_fmac_f32_e32 v21, s15, v121
	v_fmac_f32_e32 v22, s15, v122
	v_fmac_f32_e32 v23, s15, v123
	v_fmac_f32_e32 v24, s16, v120
	v_fmac_f32_e32 v25, s16, v121
	v_fmac_f32_e32 v26, s16, v122
	v_fmac_f32_e32 v27, s16, v123
	v_fmac_f32_e32 v28, s17, v120
	v_fmac_f32_e32 v29, s17, v121
	v_fmac_f32_e32 v30, s17, v122
	v_fmac_f32_e32 v31, s17, v123
; __device__ __forceinline__ void gemv_item(const float* c, const float* c_ctx, const float* ada_w, const float* ada_b, float* mod, int it, int lane) {
;     ...
;     for (int kk = 0; kk < 64; ++kk) { const f32x4 w = *(const f32x4*)(W + (size_t)kk * 6144);
; #pragma unroll
;         for (int r = 0; r < 9; ++r) { const float sk = __uint_as_float(__builtin_amdgcn_readlane(__float_as_uint(s[r]), kk)); acc[r] += w * sk; } }
	v_fmac_f32_e32 v32, s18, v120
	v_fmac_f32_e32 v33, s18, v121
	v_fmac_f32_e32 v34, s18, v122
	v_fmac_f32_e32 v35, s18, v123
	v_readlane_b32 s10, v36, 11
	v_readlane_b32 s11, v37, 11
	v_readlane_b32 s12, v38, 11
	v_readlane_b32 s13, v39, 11
	v_readlane_b32 s14, v40, 11
	v_readlane_b32 s15, v41, 11
	v_readlane_b32 s16, v42, 11
	v_readlane_b32 s17, v43, 11
	v_readlane_b32 s18, v44, 11
	v_fmac_f32_e32 v0, s10, v124
	v_fmac_f32_e32 v1, s10, v125
	v_fmac_f32_e32 v2, s10, v126
	v_fmac_f32_e32 v3, s10, v127
	v_fmac_f32_e32 v4, s11, v124
	v_fmac_f32_e32 v5, s11, v125
	v_fmac_f32_e32 v6, s11, v126
	v_fmac_f32_e32 v7, s11, v127
	v_fmac_f32_e32 v8, s12, v124
	v_fmac_f32_e32 v9, s12, v125
	v_fmac_f32_e32 v10, s12, v126
	v_fmac_f32_e32 v11, s12, v127
	v_fmac_f32_e32 v12, s13, v124
	v_fmac_f32_e32 v13, s13, v125
	v_fmac_f32_e32 v14, s13, v126
	v_fmac_f32_e32 v15, s13, v127
	v_fmac_f32_e32 v16, s14, v124
	v_fmac_f32_e32 v17, s14, v125
	v_fmac_f32_e32 v18, s14, v126
	v_fmac_f32_e32 v19, s14, v127
	v_fmac_f32_e32 v20, s15, v124
	v_fmac_f32_e32 v21, s15, v125
	v_fmac_f32_e32 v22, s15, v126
	v_fmac_f32_e32 v23, s15, v127
	v_fmac_f32_e32 v24, s16, v124
	v_fmac_f32_e32 v25, s16, v125
	v_fmac_f32_e32 v26, s16, v126
	v_fmac_f32_e32 v27, s16, v127
	v_fmac_f32_e32 v28, s17, v124
	v_fmac_f32_e32 v29, s17, v125
	v_fmac_f32_e32 v30, s17, v126
	v_fmac_f32_e32 v31, s17, v127
	v_fmac_f32_e32 v32, s18, v124
	v_fmac_f32_e32 v33, s18, v125
	v_fmac_f32_e32 v34, s18, v126
	v_fmac_f32_e32 v35, s18, v127
	v_readlane_b32 s10, v36, 12
	v_readlane_b32 s11, v37, 12
	v_readlane_b32 s12, v38, 12
	v_readlane_b32 s13, v39, 12
	v_readlane_b32 s14, v40, 12
	v_readlane_b32 s15, v41, 12
	v_readlane_b32 s16, v42, 12
	v_readlane_b32 s17, v43, 12
	v_readlane_b32 s18, v44, 12
	v_fmac_f32_e32 v0, s10, v128
	v_fmac_f32_e32 v1, s10, v129
	v_fmac_f32_e32 v2, s10, v130
	v_fmac_f32_e32 v3, s10, v131
	v_fmac_f32_e32 v4, s11, v128
	v_fmac_f32_e32 v5, s11, v129
	v_fmac_f32_e32 v6, s11, v130
	v_fmac_f32_e32 v7, s11, v131
	v_fmac_f32_e32 v8, s12, v128
	v_fmac_f32_e32 v9, s12, v129
	v_fmac_f32_e32 v10, s12, v130
	v_fmac_f32_e32 v11, s12, v131
	v_fmac_f32_e32 v12, s13, v128
	v_fmac_f32_e32 v13, s13, v129
	v_fmac_f32_e32 v14, s13, v130
	v_fmac_f32_e32 v15, s13, v131
	v_fmac_f32_e32 v16, s14, v128
	v_fmac_f32_e32 v17, s14, v129
	v_fmac_f32_e32 v18, s14, v130
	v_fmac_f32_e32 v19, s14, v131
	v_fmac_f32_e32 v20, s15, v128
	v_fmac_f32_e32 v21, s15, v129
	v_fmac_f32_e32 v22, s15, v130
	v_fmac_f32_e32 v23, s15, v131
	v_fmac_f32_e32 v24, s16, v128
	v_fmac_f32_e32 v25, s16, v129
	v_fmac_f32_e32 v26, s16, v130
	v_fmac_f32_e32 v27, s16, v131
	v_fmac_f32_e32 v28, s17, v128
	v_fmac_f32_e32 v29, s17, v129
	v_fmac_f32_e32 v30, s17, v130
	v_fmac_f32_e32 v31, s17, v131
	v_fmac_f32_e32 v32, s18, v128
	v_fmac_f32_e32 v33, s18, v129
	v_fmac_f32_e32 v34, s18, v130
	v_fmac_f32_e32 v35, s18, v131
	v_readlane_b32 s10, v36, 13
	v_readlane_b32 s11, v37, 13
	v_readlane_b32 s12, v38, 13
	v_readlane_b32 s13, v39, 13
	v_readlane_b32 s14, v40, 13
	v_readlane_b32 s15, v41, 13
	v_readlane_b32 s16, v42, 13
	v_readlane_b32 s17, v43, 13
	v_readlane_b32 s18, v44, 13
	v_fmac_f32_e32 v0, s10, v132
	v_fmac_f32_e32 v1, s10, v133
	v_fmac_f32_e32 v2, s10, v134
	v_fmac_f32_e32 v3, s10, v135
	v_fmac_f32_e32 v4, s11, v132
	v_fmac_f32_e32 v5, s11, v133
	v_fmac_f32_e32 v6, s11, v134
	v_fmac_f32_e32 v7, s11, v135
	v_fmac_f32_e32 v8, s12, v132
	v_fmac_f32_e32 v9, s12, v133
	v_fmac_f32_e32 v10, s12, v134
	v_fmac_f32_e32 v11, s12, v135
	v_fmac_f32_e32 v12, s13, v132
	v_fmac_f32_e32 v13, s13, v133
	v_fmac_f32_e32 v14, s13, v134
	v_fmac_f32_e32 v15, s13, v135
	v_fmac_f32_e32 v16, s14, v132
	v_fmac_f32_e32 v17, s14, v133
	v_fmac_f32_e32 v18, s14, v134
	v_fmac_f32_e32 v19, s14, v135
	v_fmac_f32_e32 v20, s15, v132
	v_fmac_f32_e32 v21, s15, v133
	v_fmac_f32_e32 v22, s15, v134
	v_fmac_f32_e32 v23, s15, v135
	v_fmac_f32_e32 v24, s16, v132
	v_fmac_f32_e32 v25, s16, v133
	v_fmac_f32_e32 v26, s16, v134
	v_fmac_f32_e32 v27, s16, v135
	v_fmac_f32_e32 v28, s17, v132
	v_fmac_f32_e32 v29, s17, v133
	v_fmac_f32_e32 v30, s17, v134
	v_fmac_f32_e32 v31, s17, v135
	v_fmac_f32_e32 v32, s18, v132
	v_fmac_f32_e32 v33, s18, v133
	v_fmac_f32_e32 v34, s18, v134
	v_fmac_f32_e32 v35, s18, v135
	v_readlane_b32 s10, v36, 14
	v_readlane_b32 s11, v37, 14
	v_readlane_b32 s12, v38, 14
	v_readlane_b32 s13, v39, 14
	v_readlane_b32 s14, v40, 14
	v_readlane_b32 s15, v41, 14
	v_readlane_b32 s16, v42, 14
	v_readlane_b32 s17, v43, 14
	v_readlane_b32 s18, v44, 14
	v_fmac_f32_e32 v0, s10, v136
	v_fmac_f32_e32 v1, s10, v137
	v_fmac_f32_e32 v2, s10, v138
	v_fmac_f32_e32 v3, s10, v139
	v_fmac_f32_e32 v4, s11, v136
	v_fmac_f32_e32 v5, s11, v137
	v_fmac_f32_e32 v6, s11, v138
	v_fmac_f32_e32 v7, s11, v139
	v_fmac_f32_e32 v8, s12, v136
	v_fmac_f32_e32 v9, s12, v137
	v_fmac_f32_e32 v10, s12, v138
	v_fmac_f32_e32 v11, s12, v139
	v_fmac_f32_e32 v12, s13, v136
	v_fmac_f32_e32 v13, s13, v137
	v_fmac_f32_e32 v14, s13, v138
	v_fmac_f32_e32 v15, s13, v139
	v_fmac_f32_e32 v16, s14, v136
	v_fmac_f32_e32 v17, s14, v137
	v_fmac_f32_e32 v18, s14, v138
	v_fmac_f32_e32 v19, s14, v139
	v_fmac_f32_e32 v20, s15, v136
	v_fmac_f32_e32 v21, s15, v137
	v_fmac_f32_e32 v22, s15, v138
	v_fmac_f32_e32 v23, s15, v139
	v_fmac_f32_e32 v24, s16, v136
	v_fmac_f32_e32 v25, s16, v137
	v_fmac_f32_e32 v26, s16, v138
	v_fmac_f32_e32 v27, s16, v139
	v_fmac_f32_e32 v28, s17, v136
	v_fmac_f32_e32 v29, s17, v137
	v_fmac_f32_e32 v30, s17, v138
	v_fmac_f32_e32 v31, s17, v139
	v_fmac_f32_e32 v32, s18, v136
	v_fmac_f32_e32 v33, s18, v137
	v_fmac_f32_e32 v34, s18, v138
	v_fmac_f32_e32 v35, s18, v139
	v_readlane_b32 s10, v36, 15
	v_readlane_b32 s11, v37, 15
; __device__ __forceinline__ void gemv_item(const float* c, const float* c_ctx, const float* ada_w, const float* ada_b, float* mod, int it, int lane) {
;     ...
;     for (int kk = 0; kk < 64; ++kk) { const f32x4 w = *(const f32x4*)(W + (size_t)kk * 6144);
; #pragma unroll
;         for (int r = 0; r < 9; ++r) { const float sk = __uint_as_float(__builtin_amdgcn_readlane(__float_as_uint(s[r]), kk)); acc[r] += w * sk; } }
	v_readlane_b32 s12, v38, 15
	v_readlane_b32 s13, v39, 15
	v_readlane_b32 s14, v40, 15
	v_readlane_b32 s15, v41, 15
	v_readlane_b32 s16, v42, 15
	v_readlane_b32 s17, v43, 15
	v_readlane_b32 s18, v44, 15
	v_fmac_f32_e32 v0, s10, v140
	v_fmac_f32_e32 v1, s10, v141
	v_fmac_f32_e32 v2, s10, v142
	v_fmac_f32_e32 v3, s10, v143
	v_fmac_f32_e32 v4, s11, v140
	v_fmac_f32_e32 v5, s11, v141
	v_fmac_f32_e32 v6, s11, v142
	v_fmac_f32_e32 v7, s11, v143
	v_fmac_f32_e32 v8, s12, v140
	v_fmac_f32_e32 v9, s12, v141
	v_fmac_f32_e32 v10, s12, v142
	v_fmac_f32_e32 v11, s12, v143
	v_fmac_f32_e32 v12, s13, v140
	v_fmac_f32_e32 v13, s13, v141
	v_fmac_f32_e32 v14, s13, v142
	v_fmac_f32_e32 v15, s13, v143
	v_fmac_f32_e32 v16, s14, v140
	v_fmac_f32_e32 v17, s14, v141
	v_fmac_f32_e32 v18, s14, v142
	v_fmac_f32_e32 v19, s14, v143
	v_fmac_f32_e32 v20, s15, v140
	v_fmac_f32_e32 v21, s15, v141
	v_fmac_f32_e32 v22, s15, v142
	v_fmac_f32_e32 v23, s15, v143
	v_fmac_f32_e32 v24, s16, v140
	v_fmac_f32_e32 v25, s16, v141
	v_fmac_f32_e32 v26, s16, v142
	v_fmac_f32_e32 v27, s16, v143
	v_fmac_f32_e32 v28, s17, v140
	v_fmac_f32_e32 v29, s17, v141
	v_fmac_f32_e32 v30, s17, v142
	v_fmac_f32_e32 v31, s17, v143
	v_fmac_f32_e32 v32, s18, v140
	v_fmac_f32_e32 v33, s18, v141
	v_fmac_f32_e32 v34, s18, v142
	v_fmac_f32_e32 v35, s18, v143
	global_load_dwordx4 v[80:83], v46, s[22:23] nt
	s_add_u32 s22, s22, 0x6000
	s_addc_u32 s23, s23, 0
	global_load_dwordx4 v[84:87], v46, s[22:23] nt
	s_add_u32 s22, s22, 0x6000
	s_addc_u32 s23, s23, 0
	global_load_dwordx4 v[88:91], v46, s[22:23] nt
	s_add_u32 s22, s22, 0x6000
	s_addc_u32 s23, s23, 0
	global_load_dwordx4 v[92:95], v46, s[22:23] nt
	s_add_u32 s22, s22, 0x6000
	s_addc_u32 s23, s23, 0
	global_load_dwordx4 v[96:99], v46, s[22:23] nt
	s_add_u32 s22, s22, 0x6000
	s_addc_u32 s23, s23, 0
	global_load_dwordx4 v[100:103], v46, s[22:23] nt
	s_add_u32 s22, s22, 0x6000
	s_addc_u32 s23, s23, 0
	global_load_dwordx4 v[104:107], v46, s[22:23] nt
	s_add_u32 s22, s22, 0x6000
	s_addc_u32 s23, s23, 0
	global_load_dwordx4 v[108:111], v46, s[22:23] nt
	s_add_u32 s22, s22, 0x6000
	s_addc_u32 s23, s23, 0
	global_load_dwordx4 v[112:115], v46, s[22:23] nt
	s_add_u32 s22, s22, 0x6000
	s_addc_u32 s23, s23, 0
	global_load_dwordx4 v[116:119], v46, s[22:23] nt
	s_add_u32 s22, s22, 0x6000
	s_addc_u32 s23, s23, 0
	global_load_dwordx4 v[120:123], v46, s[22:23] nt
	s_add_u32 s22, s22, 0x6000
	s_addc_u32 s23, s23, 0
	global_load_dwordx4 v[124:127], v46, s[22:23] nt
	s_add_u32 s22, s22, 0x6000
	s_addc_u32 s23, s23, 0
	global_load_dwordx4 v[128:131], v46, s[22:23] nt
	s_add_u32 s22, s22, 0x6000
	s_addc_u32 s23, s23, 0
	global_load_dwordx4 v[132:135], v46, s[22:23] nt
	s_add_u32 s22, s22, 0x6000
	s_addc_u32 s23, s23, 0
	global_load_dwordx4 v[136:139], v46, s[22:23] nt
	s_add_u32 s22, s22, 0x6000
	s_addc_u32 s23, s23, 0
	global_load_dwordx4 v[140:143], v46, s[22:23] nt
	s_add_u32 s22, s22, 0x6000
	s_addc_u32 s23, s23, 0
	s_waitcnt vmcnt(16)
	v_readlane_b32 s10, v36, 16
	v_readlane_b32 s11, v37, 16
	v_readlane_b32 s12, v38, 16
	v_readlane_b32 s13, v39, 16
	v_readlane_b32 s14, v40, 16
	v_readlane_b32 s15, v41, 16
	v_readlane_b32 s16, v42, 16
	v_readlane_b32 s17, v43, 16
	v_readlane_b32 s18, v44, 16
	v_fmac_f32_e32 v0, s10, v144
	v_fmac_f32_e32 v1, s10, v145
	v_fmac_f32_e32 v2, s10, v146
	v_fmac_f32_e32 v3, s10, v147
	v_fmac_f32_e32 v4, s11, v144
	v_fmac_f32_e32 v5, s11, v145
	v_fmac_f32_e32 v6, s11, v146
	v_fmac_f32_e32 v7, s11, v147
	v_fmac_f32_e32 v8, s12, v144
	v_fmac_f32_e32 v9, s12, v145
	v_fmac_f32_e32 v10, s12, v146
	v_fmac_f32_e32 v11, s12, v147
	v_fmac_f32_e32 v12, s13, v144
	v_fmac_f32_e32 v13, s13, v145
	v_fmac_f32_e32 v14, s13, v146
	v_fmac_f32_e32 v15, s13, v147
	v_fmac_f32_e32 v16, s14, v144
	v_fmac_f32_e32 v17, s14, v145
	v_fmac_f32_e32 v18, s14, v146
	v_fmac_f32_e32 v19, s14, v147
	v_fmac_f32_e32 v20, s15, v144
	v_fmac_f32_e32 v21, s15, v145
	v_fmac_f32_e32 v22, s15, v146
	v_fmac_f32_e32 v23, s15, v147
	v_fmac_f32_e32 v24, s16, v144
	v_fmac_f32_e32 v25, s16, v145
	v_fmac_f32_e32 v26, s16, v146
	v_fmac_f32_e32 v27, s16, v147
	v_fmac_f32_e32 v28, s17, v144
	v_fmac_f32_e32 v29, s17, v145
	v_fmac_f32_e32 v30, s17, v146
	v_fmac_f32_e32 v31, s17, v147
	v_fmac_f32_e32 v32, s18, v144
	v_fmac_f32_e32 v33, s18, v145
	v_fmac_f32_e32 v34, s18, v146
	v_fmac_f32_e32 v35, s18, v147
	v_readlane_b32 s10, v36, 17
	v_readlane_b32 s11, v37, 17
	v_readlane_b32 s12, v38, 17
	v_readlane_b32 s13, v39, 17
	v_readlane_b32 s14, v40, 17
	v_readlane_b32 s15, v41, 17
	v_readlane_b32 s16, v42, 17
	v_readlane_b32 s17, v43, 17
	v_readlane_b32 s18, v44, 17
	v_fmac_f32_e32 v0, s10, v148
	v_fmac_f32_e32 v1, s10, v149
	v_fmac_f32_e32 v2, s10, v150
	v_fmac_f32_e32 v3, s10, v151
	v_fmac_f32_e32 v4, s11, v148
	v_fmac_f32_e32 v5, s11, v149
	v_fmac_f32_e32 v6, s11, v150
	v_fmac_f32_e32 v7, s11, v151
	v_fmac_f32_e32 v8, s12, v148
	v_fmac_f32_e32 v9, s12, v149
	v_fmac_f32_e32 v10, s12, v150
	v_fmac_f32_e32 v11, s12, v151
	v_fmac_f32_e32 v12, s13, v148
	v_fmac_f32_e32 v13, s13, v149
	v_fmac_f32_e32 v14, s13, v150
	v_fmac_f32_e32 v15, s13, v151
	v_fmac_f32_e32 v16, s14, v148
	v_fmac_f32_e32 v17, s14, v149
	v_fmac_f32_e32 v18, s14, v150
	v_fmac_f32_e32 v19, s14, v151
	v_fmac_f32_e32 v20, s15, v148
	v_fmac_f32_e32 v21, s15, v149
	v_fmac_f32_e32 v22, s15, v150
	v_fmac_f32_e32 v23, s15, v151
	v_fmac_f32_e32 v24, s16, v148
	v_fmac_f32_e32 v25, s16, v149
	v_fmac_f32_e32 v26, s16, v150
	v_fmac_f32_e32 v27, s16, v151
	v_fmac_f32_e32 v28, s17, v148
	v_fmac_f32_e32 v29, s17, v149
	v_fmac_f32_e32 v30, s17, v150
	v_fmac_f32_e32 v31, s17, v151
	v_fmac_f32_e32 v32, s18, v148
	v_fmac_f32_e32 v33, s18, v149
	v_fmac_f32_e32 v34, s18, v150
; __device__ __forceinline__ void gemv_item(const float* c, const float* c_ctx, const float* ada_w, const float* ada_b, float* mod, int it, int lane) {
;     ...
;     for (int kk = 0; kk < 64; ++kk) { const f32x4 w = *(const f32x4*)(W + (size_t)kk * 6144);
; #pragma unroll
;         for (int r = 0; r < 9; ++r) { const float sk = __uint_as_float(__builtin_amdgcn_readlane(__float_as_uint(s[r]), kk)); acc[r] += w * sk; } }
	v_fmac_f32_e32 v35, s18, v151
	v_readlane_b32 s10, v36, 18
	v_readlane_b32 s11, v37, 18
	v_readlane_b32 s12, v38, 18
	v_readlane_b32 s13, v39, 18
	v_readlane_b32 s14, v40, 18
	v_readlane_b32 s15, v41, 18
	v_readlane_b32 s16, v42, 18
	v_readlane_b32 s17, v43, 18
	v_readlane_b32 s18, v44, 18
	v_fmac_f32_e32 v0, s10, v152
	v_fmac_f32_e32 v1, s10, v153
	v_fmac_f32_e32 v2, s10, v154
	v_fmac_f32_e32 v3, s10, v155
	v_fmac_f32_e32 v4, s11, v152
	v_fmac_f32_e32 v5, s11, v153
	v_fmac_f32_e32 v6, s11, v154
	v_fmac_f32_e32 v7, s11, v155
	v_fmac_f32_e32 v8, s12, v152
	v_fmac_f32_e32 v9, s12, v153
	v_fmac_f32_e32 v10, s12, v154
	v_fmac_f32_e32 v11, s12, v155
	v_fmac_f32_e32 v12, s13, v152
	v_fmac_f32_e32 v13, s13, v153
	v_fmac_f32_e32 v14, s13, v154
	v_fmac_f32_e32 v15, s13, v155
	v_fmac_f32_e32 v16, s14, v152
	v_fmac_f32_e32 v17, s14, v153
	v_fmac_f32_e32 v18, s14, v154
	v_fmac_f32_e32 v19, s14, v155
	v_fmac_f32_e32 v20, s15, v152
	v_fmac_f32_e32 v21, s15, v153
	v_fmac_f32_e32 v22, s15, v154
	v_fmac_f32_e32 v23, s15, v155
	v_fmac_f32_e32 v24, s16, v152
	v_fmac_f32_e32 v25, s16, v153
	v_fmac_f32_e32 v26, s16, v154
	v_fmac_f32_e32 v27, s16, v155
	v_fmac_f32_e32 v28, s17, v152
	v_fmac_f32_e32 v29, s17, v153
	v_fmac_f32_e32 v30, s17, v154
	v_fmac_f32_e32 v31, s17, v155
	v_fmac_f32_e32 v32, s18, v152
	v_fmac_f32_e32 v33, s18, v153
	v_fmac_f32_e32 v34, s18, v154
	v_fmac_f32_e32 v35, s18, v155
	v_readlane_b32 s10, v36, 19
	v_readlane_b32 s11, v37, 19
	v_readlane_b32 s12, v38, 19
	v_readlane_b32 s13, v39, 19
	v_readlane_b32 s14, v40, 19
	v_readlane_b32 s15, v41, 19
	v_readlane_b32 s16, v42, 19
	v_readlane_b32 s17, v43, 19
	v_readlane_b32 s18, v44, 19
	v_fmac_f32_e32 v0, s10, v156
	v_fmac_f32_e32 v1, s10, v157
	v_fmac_f32_e32 v2, s10, v158
	v_fmac_f32_e32 v3, s10, v159
	v_fmac_f32_e32 v4, s11, v156
	v_fmac_f32_e32 v5, s11, v157
	v_fmac_f32_e32 v6, s11, v158
	v_fmac_f32_e32 v7, s11, v159
	v_fmac_f32_e32 v8, s12, v156
	v_fmac_f32_e32 v9, s12, v157
	v_fmac_f32_e32 v10, s12, v158
	v_fmac_f32_e32 v11, s12, v159
	v_fmac_f32_e32 v12, s13, v156
	v_fmac_f32_e32 v13, s13, v157
	v_fmac_f32_e32 v14, s13, v158
	v_fmac_f32_e32 v15, s13, v159
	v_fmac_f32_e32 v16, s14, v156
	v_fmac_f32_e32 v17, s14, v157
	v_fmac_f32_e32 v18, s14, v158
	v_fmac_f32_e32 v19, s14, v159
	v_fmac_f32_e32 v20, s15, v156
	v_fmac_f32_e32 v21, s15, v157
	v_fmac_f32_e32 v22, s15, v158
	v_fmac_f32_e32 v23, s15, v159
	v_fmac_f32_e32 v24, s16, v156
	v_fmac_f32_e32 v25, s16, v157
	v_fmac_f32_e32 v26, s16, v158
	v_fmac_f32_e32 v27, s16, v159
	v_fmac_f32_e32 v28, s17, v156
	v_fmac_f32_e32 v29, s17, v157
	v_fmac_f32_e32 v30, s17, v158
	v_fmac_f32_e32 v31, s17, v159
	v_fmac_f32_e32 v32, s18, v156
	v_fmac_f32_e32 v33, s18, v157
	v_fmac_f32_e32 v34, s18, v158
	v_fmac_f32_e32 v35, s18, v159
	v_readlane_b32 s10, v36, 20
	v_readlane_b32 s11, v37, 20
	v_readlane_b32 s12, v38, 20
	v_readlane_b32 s13, v39, 20
	v_readlane_b32 s14, v40, 20
	v_readlane_b32 s15, v41, 20
	v_readlane_b32 s16, v42, 20
	v_readlane_b32 s17, v43, 20
	v_readlane_b32 s18, v44, 20
	v_fmac_f32_e32 v0, s10, v160
	v_fmac_f32_e32 v1, s10, v161
	v_fmac_f32_e32 v2, s10, v162
	v_fmac_f32_e32 v3, s10, v163
	v_fmac_f32_e32 v4, s11, v160
	v_fmac_f32_e32 v5, s11, v161
	v_fmac_f32_e32 v6, s11, v162
	v_fmac_f32_e32 v7, s11, v163
	v_fmac_f32_e32 v8, s12, v160
	v_fmac_f32_e32 v9, s12, v161
	v_fmac_f32_e32 v10, s12, v162
	v_fmac_f32_e32 v11, s12, v163
	v_fmac_f32_e32 v12, s13, v160
	v_fmac_f32_e32 v13, s13, v161
	v_fmac_f32_e32 v14, s13, v162
	v_fmac_f32_e32 v15, s13, v163
	v_fmac_f32_e32 v16, s14, v160
	v_fmac_f32_e32 v17, s14, v161
	v_fmac_f32_e32 v18, s14, v162
	v_fmac_f32_e32 v19, s14, v163
	v_fmac_f32_e32 v20, s15, v160
	v_fmac_f32_e32 v21, s15, v161
	v_fmac_f32_e32 v22, s15, v162
	v_fmac_f32_e32 v23, s15, v163
	v_fmac_f32_e32 v24, s16, v160
	v_fmac_f32_e32 v25, s16, v161
	v_fmac_f32_e32 v26, s16, v162
	v_fmac_f32_e32 v27, s16, v163
	v_fmac_f32_e32 v28, s17, v160
	v_fmac_f32_e32 v29, s17, v161
	v_fmac_f32_e32 v30, s17, v162
	v_fmac_f32_e32 v31, s17, v163
	v_fmac_f32_e32 v32, s18, v160
	v_fmac_f32_e32 v33, s18, v161
	v_fmac_f32_e32 v34, s18, v162
	v_fmac_f32_e32 v35, s18, v163
	v_readlane_b32 s10, v36, 21
	v_readlane_b32 s11, v37, 21
	v_readlane_b32 s12, v38, 21
	v_readlane_b32 s13, v39, 21
	v_readlane_b32 s14, v40, 21
	v_readlane_b32 s15, v41, 21
	v_readlane_b32 s16, v42, 21
	v_readlane_b32 s17, v43, 21
	v_readlane_b32 s18, v44, 21
	v_fmac_f32_e32 v0, s10, v164
	v_fmac_f32_e32 v1, s10, v165
	v_fmac_f32_e32 v2, s10, v166
	v_fmac_f32_e32 v3, s10, v167
	v_fmac_f32_e32 v4, s11, v164
	v_fmac_f32_e32 v5, s11, v165
	v_fmac_f32_e32 v6, s11, v166
	v_fmac_f32_e32 v7, s11, v167
	v_fmac_f32_e32 v8, s12, v164
	v_fmac_f32_e32 v9, s12, v165
	v_fmac_f32_e32 v10, s12, v166
	v_fmac_f32_e32 v11, s12, v167
	v_fmac_f32_e32 v12, s13, v164
	v_fmac_f32_e32 v13, s13, v165
	v_fmac_f32_e32 v14, s13, v166
	v_fmac_f32_e32 v15, s13, v167
	v_fmac_f32_e32 v16, s14, v164
	v_fmac_f32_e32 v17, s14, v165
	v_fmac_f32_e32 v18, s14, v166
	v_fmac_f32_e32 v19, s14, v167
	v_fmac_f32_e32 v20, s15, v164
	v_fmac_f32_e32 v21, s15, v165
	v_fmac_f32_e32 v22, s15, v166
	v_fmac_f32_e32 v23, s15, v167
	v_fmac_f32_e32 v24, s16, v164
	v_fmac_f32_e32 v25, s16, v165
	v_fmac_f32_e32 v26, s16, v166
	v_fmac_f32_e32 v27, s16, v167
	v_fmac_f32_e32 v28, s17, v164
	v_fmac_f32_e32 v29, s17, v165
	v_fmac_f32_e32 v30, s17, v166
	v_fmac_f32_e32 v31, s17, v167
	v_fmac_f32_e32 v32, s18, v164
	v_fmac_f32_e32 v33, s18, v165
	v_fmac_f32_e32 v34, s18, v166
	v_fmac_f32_e32 v35, s18, v167
	v_readlane_b32 s10, v36, 22
	v_readlane_b32 s11, v37, 22
	v_readlane_b32 s12, v38, 22
	v_readlane_b32 s13, v39, 22
	v_readlane_b32 s14, v40, 22
; __device__ __forceinline__ void gemv_item(const float* c, const float* c_ctx, const float* ada_w, const float* ada_b, float* mod, int it, int lane) {
;     ...
;     for (int kk = 0; kk < 64; ++kk) { const f32x4 w = *(const f32x4*)(W + (size_t)kk * 6144);
; #pragma unroll
;         for (int r = 0; r < 9; ++r) { const float sk = __uint_as_float(__builtin_amdgcn_readlane(__float_as_uint(s[r]), kk)); acc[r] += w * sk; } }
	v_readlane_b32 s15, v41, 22
	v_readlane_b32 s16, v42, 22
	v_readlane_b32 s17, v43, 22
	v_readlane_b32 s18, v44, 22
	v_fmac_f32_e32 v0, s10, v168
	v_fmac_f32_e32 v1, s10, v169
	v_fmac_f32_e32 v2, s10, v170
	v_fmac_f32_e32 v3, s10, v171
	v_fmac_f32_e32 v4, s11, v168
	v_fmac_f32_e32 v5, s11, v169
	v_fmac_f32_e32 v6, s11, v170
	v_fmac_f32_e32 v7, s11, v171
	v_fmac_f32_e32 v8, s12, v168
	v_fmac_f32_e32 v9, s12, v169
	v_fmac_f32_e32 v10, s12, v170
	v_fmac_f32_e32 v11, s12, v171
	v_fmac_f32_e32 v12, s13, v168
	v_fmac_f32_e32 v13, s13, v169
	v_fmac_f32_e32 v14, s13, v170
	v_fmac_f32_e32 v15, s13, v171
	v_fmac_f32_e32 v16, s14, v168
	v_fmac_f32_e32 v17, s14, v169
	v_fmac_f32_e32 v18, s14, v170
	v_fmac_f32_e32 v19, s14, v171
	v_fmac_f32_e32 v20, s15, v168
	v_fmac_f32_e32 v21, s15, v169
	v_fmac_f32_e32 v22, s15, v170
	v_fmac_f32_e32 v23, s15, v171
	v_fmac_f32_e32 v24, s16, v168
	v_fmac_f32_e32 v25, s16, v169
	v_fmac_f32_e32 v26, s16, v170
	v_fmac_f32_e32 v27, s16, v171
	v_fmac_f32_e32 v28, s17, v168
	v_fmac_f32_e32 v29, s17, v169
	v_fmac_f32_e32 v30, s17, v170
	v_fmac_f32_e32 v31, s17, v171
	v_fmac_f32_e32 v32, s18, v168
	v_fmac_f32_e32 v33, s18, v169
	v_fmac_f32_e32 v34, s18, v170
	v_fmac_f32_e32 v35, s18, v171
	v_readlane_b32 s10, v36, 23
	v_readlane_b32 s11, v37, 23
	v_readlane_b32 s12, v38, 23
	v_readlane_b32 s13, v39, 23
	v_readlane_b32 s14, v40, 23
	v_readlane_b32 s15, v41, 23
	v_readlane_b32 s16, v42, 23
	v_readlane_b32 s17, v43, 23
	v_readlane_b32 s18, v44, 23
	v_fmac_f32_e32 v0, s10, v172
	v_fmac_f32_e32 v1, s10, v173
	v_fmac_f32_e32 v2, s10, v174
	v_fmac_f32_e32 v3, s10, v175
	v_fmac_f32_e32 v4, s11, v172
	v_fmac_f32_e32 v5, s11, v173
	v_fmac_f32_e32 v6, s11, v174
	v_fmac_f32_e32 v7, s11, v175
	v_fmac_f32_e32 v8, s12, v172
	v_fmac_f32_e32 v9, s12, v173
	v_fmac_f32_e32 v10, s12, v174
	v_fmac_f32_e32 v11, s12, v175
	v_fmac_f32_e32 v12, s13, v172
	v_fmac_f32_e32 v13, s13, v173
	v_fmac_f32_e32 v14, s13, v174
	v_fmac_f32_e32 v15, s13, v175
	v_fmac_f32_e32 v16, s14, v172
	v_fmac_f32_e32 v17, s14, v173
	v_fmac_f32_e32 v18, s14, v174
	v_fmac_f32_e32 v19, s14, v175
	v_fmac_f32_e32 v20, s15, v172
	v_fmac_f32_e32 v21, s15, v173
	v_fmac_f32_e32 v22, s15, v174
	v_fmac_f32_e32 v23, s15, v175
	v_fmac_f32_e32 v24, s16, v172
	v_fmac_f32_e32 v25, s16, v173
	v_fmac_f32_e32 v26, s16, v174
	v_fmac_f32_e32 v27, s16, v175
	v_fmac_f32_e32 v28, s17, v172
	v_fmac_f32_e32 v29, s17, v173
	v_fmac_f32_e32 v30, s17, v174
	v_fmac_f32_e32 v31, s17, v175
	v_fmac_f32_e32 v32, s18, v172
	v_fmac_f32_e32 v33, s18, v173
	v_fmac_f32_e32 v34, s18, v174
	v_fmac_f32_e32 v35, s18, v175
	v_readlane_b32 s10, v36, 24
	v_readlane_b32 s11, v37, 24
	v_readlane_b32 s12, v38, 24
	v_readlane_b32 s13, v39, 24
	v_readlane_b32 s14, v40, 24
	v_readlane_b32 s15, v41, 24
	v_readlane_b32 s16, v42, 24
	v_readlane_b32 s17, v43, 24
	v_readlane_b32 s18, v44, 24
	v_fmac_f32_e32 v0, s10, v176
	v_fmac_f32_e32 v1, s10, v177
	v_fmac_f32_e32 v2, s10, v178
	v_fmac_f32_e32 v3, s10, v179
	v_fmac_f32_e32 v4, s11, v176
	v_fmac_f32_e32 v5, s11, v177
	v_fmac_f32_e32 v6, s11, v178
	v_fmac_f32_e32 v7, s11, v179
	v_fmac_f32_e32 v8, s12, v176
	v_fmac_f32_e32 v9, s12, v177
	v_fmac_f32_e32 v10, s12, v178
	v_fmac_f32_e32 v11, s12, v179
	v_fmac_f32_e32 v12, s13, v176
	v_fmac_f32_e32 v13, s13, v177
	v_fmac_f32_e32 v14, s13, v178
	v_fmac_f32_e32 v15, s13, v179
	v_fmac_f32_e32 v16, s14, v176
	v_fmac_f32_e32 v17, s14, v177
	v_fmac_f32_e32 v18, s14, v178
	v_fmac_f32_e32 v19, s14, v179
	v_fmac_f32_e32 v20, s15, v176
	v_fmac_f32_e32 v21, s15, v177
	v_fmac_f32_e32 v22, s15, v178
	v_fmac_f32_e32 v23, s15, v179
	v_fmac_f32_e32 v24, s16, v176
	v_fmac_f32_e32 v25, s16, v177
	v_fmac_f32_e32 v26, s16, v178
	v_fmac_f32_e32 v27, s16, v179
	v_fmac_f32_e32 v28, s17, v176
	v_fmac_f32_e32 v29, s17, v177
	v_fmac_f32_e32 v30, s17, v178
	v_fmac_f32_e32 v31, s17, v179
	v_fmac_f32_e32 v32, s18, v176
	v_fmac_f32_e32 v33, s18, v177
	v_fmac_f32_e32 v34, s18, v178
	v_fmac_f32_e32 v35, s18, v179
	v_readlane_b32 s10, v36, 25
	v_readlane_b32 s11, v37, 25
	v_readlane_b32 s12, v38, 25
	v_readlane_b32 s13, v39, 25
	v_readlane_b32 s14, v40, 25
	v_readlane_b32 s15, v41, 25
	v_readlane_b32 s16, v42, 25
	v_readlane_b32 s17, v43, 25
	v_readlane_b32 s18, v44, 25
	v_fmac_f32_e32 v0, s10, v180
	v_fmac_f32_e32 v1, s10, v181
	v_fmac_f32_e32 v2, s10, v182
	v_fmac_f32_e32 v3, s10, v183
	v_fmac_f32_e32 v4, s11, v180
	v_fmac_f32_e32 v5, s11, v181
	v_fmac_f32_e32 v6, s11, v182
	v_fmac_f32_e32 v7, s11, v183
	v_fmac_f32_e32 v8, s12, v180
	v_fmac_f32_e32 v9, s12, v181
	v_fmac_f32_e32 v10, s12, v182
	v_fmac_f32_e32 v11, s12, v183
	v_fmac_f32_e32 v12, s13, v180
	v_fmac_f32_e32 v13, s13, v181
	v_fmac_f32_e32 v14, s13, v182
	v_fmac_f32_e32 v15, s13, v183
	v_fmac_f32_e32 v16, s14, v180
	v_fmac_f32_e32 v17, s14, v181
	v_fmac_f32_e32 v18, s14, v182
	v_fmac_f32_e32 v19, s14, v183
	v_fmac_f32_e32 v20, s15, v180
	v_fmac_f32_e32 v21, s15, v181
	v_fmac_f32_e32 v22, s15, v182
	v_fmac_f32_e32 v23, s15, v183
	v_fmac_f32_e32 v24, s16, v180
	v_fmac_f32_e32 v25, s16, v181
	v_fmac_f32_e32 v26, s16, v182
	v_fmac_f32_e32 v27, s16, v183
	v_fmac_f32_e32 v28, s17, v180
	v_fmac_f32_e32 v29, s17, v181
	v_fmac_f32_e32 v30, s17, v182
	v_fmac_f32_e32 v31, s17, v183
	v_fmac_f32_e32 v32, s18, v180
	v_fmac_f32_e32 v33, s18, v181
	v_fmac_f32_e32 v34, s18, v182
	v_fmac_f32_e32 v35, s18, v183
	v_readlane_b32 s10, v36, 26
	v_readlane_b32 s11, v37, 26
	v_readlane_b32 s12, v38, 26
	v_readlane_b32 s13, v39, 26
	v_readlane_b32 s14, v40, 26
	v_readlane_b32 s15, v41, 26
	v_readlane_b32 s16, v42, 26
	v_readlane_b32 s17, v43, 26
	v_readlane_b32 s18, v44, 26
	v_fmac_f32_e32 v0, s10, v184
	v_fmac_f32_e32 v1, s10, v185
; __device__ __forceinline__ void gemv_item(const float* c, const float* c_ctx, const float* ada_w, const float* ada_b, float* mod, int it, int lane) {
;     ...
;     for (int kk = 0; kk < 64; ++kk) { const f32x4 w = *(const f32x4*)(W + (size_t)kk * 6144);
; #pragma unroll
;         for (int r = 0; r < 9; ++r) { const float sk = __uint_as_float(__builtin_amdgcn_readlane(__float_as_uint(s[r]), kk)); acc[r] += w * sk; } }
	v_fmac_f32_e32 v2, s10, v186
	v_fmac_f32_e32 v3, s10, v187
	v_fmac_f32_e32 v4, s11, v184
	v_fmac_f32_e32 v5, s11, v185
	v_fmac_f32_e32 v6, s11, v186
	v_fmac_f32_e32 v7, s11, v187
	v_fmac_f32_e32 v8, s12, v184
	v_fmac_f32_e32 v9, s12, v185
	v_fmac_f32_e32 v10, s12, v186
	v_fmac_f32_e32 v11, s12, v187
	v_fmac_f32_e32 v12, s13, v184
	v_fmac_f32_e32 v13, s13, v185
	v_fmac_f32_e32 v14, s13, v186
	v_fmac_f32_e32 v15, s13, v187
	v_fmac_f32_e32 v16, s14, v184
	v_fmac_f32_e32 v17, s14, v185
	v_fmac_f32_e32 v18, s14, v186
	v_fmac_f32_e32 v19, s14, v187
	v_fmac_f32_e32 v20, s15, v184
	v_fmac_f32_e32 v21, s15, v185
	v_fmac_f32_e32 v22, s15, v186
	v_fmac_f32_e32 v23, s15, v187
	v_fmac_f32_e32 v24, s16, v184
	v_fmac_f32_e32 v25, s16, v185
	v_fmac_f32_e32 v26, s16, v186
	v_fmac_f32_e32 v27, s16, v187
	v_fmac_f32_e32 v28, s17, v184
	v_fmac_f32_e32 v29, s17, v185
	v_fmac_f32_e32 v30, s17, v186
	v_fmac_f32_e32 v31, s17, v187
	v_fmac_f32_e32 v32, s18, v184
	v_fmac_f32_e32 v33, s18, v185
	v_fmac_f32_e32 v34, s18, v186
	v_fmac_f32_e32 v35, s18, v187
	v_readlane_b32 s10, v36, 27
	v_readlane_b32 s11, v37, 27
	v_readlane_b32 s12, v38, 27
	v_readlane_b32 s13, v39, 27
	v_readlane_b32 s14, v40, 27
	v_readlane_b32 s15, v41, 27
	v_readlane_b32 s16, v42, 27
	v_readlane_b32 s17, v43, 27
	v_readlane_b32 s18, v44, 27
	v_fmac_f32_e32 v0, s10, v188
	v_fmac_f32_e32 v1, s10, v189
	v_fmac_f32_e32 v2, s10, v190
	v_fmac_f32_e32 v3, s10, v191
	v_fmac_f32_e32 v4, s11, v188
	v_fmac_f32_e32 v5, s11, v189
	v_fmac_f32_e32 v6, s11, v190
	v_fmac_f32_e32 v7, s11, v191
	v_fmac_f32_e32 v8, s12, v188
	v_fmac_f32_e32 v9, s12, v189
	v_fmac_f32_e32 v10, s12, v190
	v_fmac_f32_e32 v11, s12, v191
	v_fmac_f32_e32 v12, s13, v188
	v_fmac_f32_e32 v13, s13, v189
	v_fmac_f32_e32 v14, s13, v190
	v_fmac_f32_e32 v15, s13, v191
	v_fmac_f32_e32 v16, s14, v188
	v_fmac_f32_e32 v17, s14, v189
	v_fmac_f32_e32 v18, s14, v190
	v_fmac_f32_e32 v19, s14, v191
	v_fmac_f32_e32 v20, s15, v188
	v_fmac_f32_e32 v21, s15, v189
	v_fmac_f32_e32 v22, s15, v190
	v_fmac_f32_e32 v23, s15, v191
	v_fmac_f32_e32 v24, s16, v188
	v_fmac_f32_e32 v25, s16, v189
	v_fmac_f32_e32 v26, s16, v190
	v_fmac_f32_e32 v27, s16, v191
	v_fmac_f32_e32 v28, s17, v188
	v_fmac_f32_e32 v29, s17, v189
	v_fmac_f32_e32 v30, s17, v190
	v_fmac_f32_e32 v31, s17, v191
	v_fmac_f32_e32 v32, s18, v188
	v_fmac_f32_e32 v33, s18, v189
	v_fmac_f32_e32 v34, s18, v190
	v_fmac_f32_e32 v35, s18, v191
	v_readlane_b32 s10, v36, 28
	v_readlane_b32 s11, v37, 28
	v_readlane_b32 s12, v38, 28
	v_readlane_b32 s13, v39, 28
	v_readlane_b32 s14, v40, 28
	v_readlane_b32 s15, v41, 28
	v_readlane_b32 s16, v42, 28
	v_readlane_b32 s17, v43, 28
	v_readlane_b32 s18, v44, 28
	v_fmac_f32_e32 v0, s10, v192
	v_fmac_f32_e32 v1, s10, v193
	v_fmac_f32_e32 v2, s10, v194
	v_fmac_f32_e32 v3, s10, v195
	v_fmac_f32_e32 v4, s11, v192
	v_fmac_f32_e32 v5, s11, v193
	v_fmac_f32_e32 v6, s11, v194
	v_fmac_f32_e32 v7, s11, v195
	v_fmac_f32_e32 v8, s12, v192
	v_fmac_f32_e32 v9, s12, v193
	v_fmac_f32_e32 v10, s12, v194
	v_fmac_f32_e32 v11, s12, v195
	v_fmac_f32_e32 v12, s13, v192
	v_fmac_f32_e32 v13, s13, v193
	v_fmac_f32_e32 v14, s13, v194
	v_fmac_f32_e32 v15, s13, v195
	v_fmac_f32_e32 v16, s14, v192
	v_fmac_f32_e32 v17, s14, v193
	v_fmac_f32_e32 v18, s14, v194
	v_fmac_f32_e32 v19, s14, v195
	v_fmac_f32_e32 v20, s15, v192
	v_fmac_f32_e32 v21, s15, v193
	v_fmac_f32_e32 v22, s15, v194
	v_fmac_f32_e32 v23, s15, v195
	v_fmac_f32_e32 v24, s16, v192
	v_fmac_f32_e32 v25, s16, v193
	v_fmac_f32_e32 v26, s16, v194
	v_fmac_f32_e32 v27, s16, v195
	v_fmac_f32_e32 v28, s17, v192
	v_fmac_f32_e32 v29, s17, v193
	v_fmac_f32_e32 v30, s17, v194
	v_fmac_f32_e32 v31, s17, v195
	v_fmac_f32_e32 v32, s18, v192
	v_fmac_f32_e32 v33, s18, v193
	v_fmac_f32_e32 v34, s18, v194
	v_fmac_f32_e32 v35, s18, v195
	v_readlane_b32 s10, v36, 29
	v_readlane_b32 s11, v37, 29
	v_readlane_b32 s12, v38, 29
	v_readlane_b32 s13, v39, 29
	v_readlane_b32 s14, v40, 29
	v_readlane_b32 s15, v41, 29
	v_readlane_b32 s16, v42, 29
	v_readlane_b32 s17, v43, 29
	v_readlane_b32 s18, v44, 29
	v_fmac_f32_e32 v0, s10, v200
	v_fmac_f32_e32 v1, s10, v201
	v_fmac_f32_e32 v2, s10, v202
	v_fmac_f32_e32 v3, s10, v203
	v_fmac_f32_e32 v4, s11, v200
	v_fmac_f32_e32 v5, s11, v201
	v_fmac_f32_e32 v6, s11, v202
	v_fmac_f32_e32 v7, s11, v203
	v_fmac_f32_e32 v8, s12, v200
	v_fmac_f32_e32 v9, s12, v201
	v_fmac_f32_e32 v10, s12, v202
	v_fmac_f32_e32 v11, s12, v203
	v_fmac_f32_e32 v12, s13, v200
	v_fmac_f32_e32 v13, s13, v201
	v_fmac_f32_e32 v14, s13, v202
	v_fmac_f32_e32 v15, s13, v203
	v_fmac_f32_e32 v16, s14, v200
	v_fmac_f32_e32 v17, s14, v201
	v_fmac_f32_e32 v18, s14, v202
	v_fmac_f32_e32 v19, s14, v203
	v_fmac_f32_e32 v20, s15, v200
	v_fmac_f32_e32 v21, s15, v201
	v_fmac_f32_e32 v22, s15, v202
	v_fmac_f32_e32 v23, s15, v203
	v_fmac_f32_e32 v24, s16, v200
	v_fmac_f32_e32 v25, s16, v201
	v_fmac_f32_e32 v26, s16, v202
	v_fmac_f32_e32 v27, s16, v203
	v_fmac_f32_e32 v28, s17, v200
	v_fmac_f32_e32 v29, s17, v201
	v_fmac_f32_e32 v30, s17, v202
	v_fmac_f32_e32 v31, s17, v203
	v_fmac_f32_e32 v32, s18, v200
	v_fmac_f32_e32 v33, s18, v201
	v_fmac_f32_e32 v34, s18, v202
	v_fmac_f32_e32 v35, s18, v203
	v_readlane_b32 s10, v36, 30
	v_readlane_b32 s11, v37, 30
	v_readlane_b32 s12, v38, 30
	v_readlane_b32 s13, v39, 30
	v_readlane_b32 s14, v40, 30
	v_readlane_b32 s15, v41, 30
	v_readlane_b32 s16, v42, 30
	v_readlane_b32 s17, v43, 30
	v_readlane_b32 s18, v44, 30
	v_fmac_f32_e32 v0, s10, v204
	v_fmac_f32_e32 v1, s10, v205
	v_fmac_f32_e32 v2, s10, v206
	v_fmac_f32_e32 v3, s10, v207
	v_fmac_f32_e32 v4, s11, v204
	v_fmac_f32_e32 v5, s11, v205
	v_fmac_f32_e32 v6, s11, v206
	v_fmac_f32_e32 v7, s11, v207
; __device__ __forceinline__ void gemv_item(const float* c, const float* c_ctx, const float* ada_w, const float* ada_b, float* mod, int it, int lane) {
;     ...
;     const float* W = ada_w + (size_t)l * DM * 6144 + (size_t)k0 * 6144 + cgp * 256 + lane * 4;
;     f32x4 acc[9];
; #pragma unroll
;     for (int r = 0; r < 9; ++r) acc[r] = (f32x4){0.f, 0.f, 0.f, 0.f};
; #pragma unroll 16
;     for (int kk = 0; kk < 64; ++kk) { const f32x4 w = *(const f32x4*)(W + (size_t)kk * 6144);
; #pragma unroll
;         for (int r = 0; r < 9; ++r) { const float sk = __uint_as_float(__builtin_amdgcn_readlane(__float_as_uint(s[r]), kk)); acc[r] += w * sk; } }
	v_fmac_f32_e32 v8, s12, v204
	v_fmac_f32_e32 v9, s12, v205
	v_fmac_f32_e32 v10, s12, v206
	v_fmac_f32_e32 v11, s12, v207
	v_fmac_f32_e32 v12, s13, v204
	v_fmac_f32_e32 v13, s13, v205
	v_fmac_f32_e32 v14, s13, v206
	v_fmac_f32_e32 v15, s13, v207
	v_fmac_f32_e32 v16, s14, v204
	v_fmac_f32_e32 v17, s14, v205
	v_fmac_f32_e32 v18, s14, v206
	v_fmac_f32_e32 v19, s14, v207
	v_fmac_f32_e32 v20, s15, v204
	v_fmac_f32_e32 v21, s15, v205
	v_fmac_f32_e32 v22, s15, v206
	v_fmac_f32_e32 v23, s15, v207
	v_fmac_f32_e32 v24, s16, v204
	v_fmac_f32_e32 v25, s16, v205
	v_fmac_f32_e32 v26, s16, v206
	v_fmac_f32_e32 v27, s16, v207
	v_fmac_f32_e32 v28, s17, v204
	v_fmac_f32_e32 v29, s17, v205
	v_fmac_f32_e32 v30, s17, v206
	v_fmac_f32_e32 v31, s17, v207
	v_fmac_f32_e32 v32, s18, v204
	v_fmac_f32_e32 v33, s18, v205
	v_fmac_f32_e32 v34, s18, v206
	v_fmac_f32_e32 v35, s18, v207
	v_readlane_b32 s10, v36, 31
	v_readlane_b32 s11, v37, 31
	v_readlane_b32 s12, v38, 31
	v_readlane_b32 s13, v39, 31
	v_readlane_b32 s14, v40, 31
	v_readlane_b32 s15, v41, 31
	v_readlane_b32 s16, v42, 31
	v_readlane_b32 s17, v43, 31
	v_readlane_b32 s18, v44, 31
	v_fmac_f32_e32 v0, s10, v208
	v_fmac_f32_e32 v1, s10, v209
	v_fmac_f32_e32 v2, s10, v210
	v_fmac_f32_e32 v3, s10, v211
	v_fmac_f32_e32 v4, s11, v208
	v_fmac_f32_e32 v5, s11, v209
	v_fmac_f32_e32 v6, s11, v210
	v_fmac_f32_e32 v7, s11, v211
	v_fmac_f32_e32 v8, s12, v208
	v_fmac_f32_e32 v9, s12, v209
	v_fmac_f32_e32 v10, s12, v210
	v_fmac_f32_e32 v11, s12, v211
	v_fmac_f32_e32 v12, s13, v208
	v_fmac_f32_e32 v13, s13, v209
	v_fmac_f32_e32 v14, s13, v210
	v_fmac_f32_e32 v15, s13, v211
	v_fmac_f32_e32 v16, s14, v208
	v_fmac_f32_e32 v17, s14, v209
	v_fmac_f32_e32 v18, s14, v210
	v_fmac_f32_e32 v19, s14, v211
	v_fmac_f32_e32 v20, s15, v208
	v_fmac_f32_e32 v21, s15, v209
	v_fmac_f32_e32 v22, s15, v210
	v_fmac_f32_e32 v23, s15, v211
	v_fmac_f32_e32 v24, s16, v208
	v_fmac_f32_e32 v25, s16, v209
	v_fmac_f32_e32 v26, s16, v210
	v_fmac_f32_e32 v27, s16, v211
	v_fmac_f32_e32 v28, s17, v208
	v_fmac_f32_e32 v29, s17, v209
	v_fmac_f32_e32 v30, s17, v210
	v_fmac_f32_e32 v31, s17, v211
	v_fmac_f32_e32 v32, s18, v208
	v_fmac_f32_e32 v33, s18, v209
	v_fmac_f32_e32 v34, s18, v210
	v_fmac_f32_e32 v35, s18, v211
	global_load_dwordx4 v[144:147], v46, s[22:23] nt
	s_add_u32 s22, s22, 0x6000
	s_addc_u32 s23, s23, 0
	global_load_dwordx4 v[148:151], v46, s[22:23] nt
	s_add_u32 s22, s22, 0x6000
	s_addc_u32 s23, s23, 0
	global_load_dwordx4 v[152:155], v46, s[22:23] nt
	s_add_u32 s22, s22, 0x6000
	s_addc_u32 s23, s23, 0
	global_load_dwordx4 v[156:159], v46, s[22:23] nt
	s_add_u32 s22, s22, 0x6000
	s_addc_u32 s23, s23, 0
	global_load_dwordx4 v[160:163], v46, s[22:23] nt
	s_add_u32 s22, s22, 0x6000
	s_addc_u32 s23, s23, 0
	global_load_dwordx4 v[164:167], v46, s[22:23] nt
	s_add_u32 s22, s22, 0x6000
	s_addc_u32 s23, s23, 0
	global_load_dwordx4 v[168:171], v46, s[22:23] nt
	s_add_u32 s22, s22, 0x6000
	s_addc_u32 s23, s23, 0
	global_load_dwordx4 v[172:175], v46, s[22:23] nt
	s_add_u32 s22, s22, 0x6000
	s_addc_u32 s23, s23, 0
	global_load_dwordx4 v[176:179], v46, s[22:23] nt
	s_add_u32 s22, s22, 0x6000
	s_addc_u32 s23, s23, 0
	global_load_dwordx4 v[180:183], v46, s[22:23] nt
	s_add_u32 s22, s22, 0x6000
	s_addc_u32 s23, s23, 0
	global_load_dwordx4 v[184:187], v46, s[22:23] nt
	s_add_u32 s22, s22, 0x6000
	s_addc_u32 s23, s23, 0
	global_load_dwordx4 v[188:191], v46, s[22:23] nt
	s_add_u32 s22, s22, 0x6000
	s_addc_u32 s23, s23, 0
	global_load_dwordx4 v[192:195], v46, s[22:23] nt
	s_add_u32 s22, s22, 0x6000
	s_addc_u32 s23, s23, 0
	global_load_dwordx4 v[200:203], v46, s[22:23] nt
	s_add_u32 s22, s22, 0x6000
	s_addc_u32 s23, s23, 0
	global_load_dwordx4 v[204:207], v46, s[22:23] nt
	s_add_u32 s22, s22, 0x6000
	s_addc_u32 s23, s23, 0
	global_load_dwordx4 v[208:211], v46, s[22:23] nt
	s_add_u32 s22, s22, 0x6000
	s_addc_u32 s23, s23, 0
	s_waitcnt vmcnt(16)
	v_readlane_b32 s10, v36, 32
	v_readlane_b32 s11, v37, 32
	v_readlane_b32 s12, v38, 32
	v_readlane_b32 s13, v39, 32
	v_readlane_b32 s14, v40, 32
	v_readlane_b32 s15, v41, 32
	v_readlane_b32 s16, v42, 32
	v_readlane_b32 s17, v43, 32
	v_readlane_b32 s18, v44, 32
	v_fmac_f32_e32 v0, s10, v80
	v_fmac_f32_e32 v1, s10, v81
	v_fmac_f32_e32 v2, s10, v82
	v_fmac_f32_e32 v3, s10, v83
	v_fmac_f32_e32 v4, s11, v80
	v_fmac_f32_e32 v5, s11, v81
	v_fmac_f32_e32 v6, s11, v82
	v_fmac_f32_e32 v7, s11, v83
	v_fmac_f32_e32 v8, s12, v80
	v_fmac_f32_e32 v9, s12, v81
	v_fmac_f32_e32 v10, s12, v82
	v_fmac_f32_e32 v11, s12, v83
	v_fmac_f32_e32 v12, s13, v80
	v_fmac_f32_e32 v13, s13, v81
	v_fmac_f32_e32 v14, s13, v82
	v_fmac_f32_e32 v15, s13, v83
	v_fmac_f32_e32 v16, s14, v80
	v_fmac_f32_e32 v17, s14, v81
	v_fmac_f32_e32 v18, s14, v82
	v_fmac_f32_e32 v19, s14, v83
	v_fmac_f32_e32 v20, s15, v80
	v_fmac_f32_e32 v21, s15, v81
	v_fmac_f32_e32 v22, s15, v82
	v_fmac_f32_e32 v23, s15, v83
	v_fmac_f32_e32 v24, s16, v80
	v_fmac_f32_e32 v25, s16, v81
	v_fmac_f32_e32 v26, s16, v82
	v_fmac_f32_e32 v27, s16, v83
	v_fmac_f32_e32 v28, s17, v80
	v_fmac_f32_e32 v29, s17, v81
	v_fmac_f32_e32 v30, s17, v82
	v_fmac_f32_e32 v31, s17, v83
	v_fmac_f32_e32 v32, s18, v80
	v_fmac_f32_e32 v33, s18, v81
	v_fmac_f32_e32 v34, s18, v82
	v_fmac_f32_e32 v35, s18, v83
	v_readlane_b32 s10, v36, 33
	v_readlane_b32 s11, v37, 33
	v_readlane_b32 s12, v38, 33
	v_readlane_b32 s13, v39, 33
	v_readlane_b32 s14, v40, 33
	v_readlane_b32 s15, v41, 33
	v_readlane_b32 s16, v42, 33
	v_readlane_b32 s17, v43, 33
	v_readlane_b32 s18, v44, 33
	v_fmac_f32_e32 v0, s10, v84
	v_fmac_f32_e32 v1, s10, v85
	v_fmac_f32_e32 v2, s10, v86
	v_fmac_f32_e32 v3, s10, v87
	v_fmac_f32_e32 v4, s11, v84
	v_fmac_f32_e32 v5, s11, v85
; __device__ __forceinline__ void gemv_item(const float* c, const float* c_ctx, const float* ada_w, const float* ada_b, float* mod, int it, int lane) {
;     ...
;     for (int kk = 0; kk < 64; ++kk) { const f32x4 w = *(const f32x4*)(W + (size_t)kk * 6144);
; #pragma unroll
;         for (int r = 0; r < 9; ++r) { const float sk = __uint_as_float(__builtin_amdgcn_readlane(__float_as_uint(s[r]), kk)); acc[r] += w * sk; } }
	v_fmac_f32_e32 v6, s11, v86
	v_fmac_f32_e32 v7, s11, v87
	v_fmac_f32_e32 v8, s12, v84
	v_fmac_f32_e32 v9, s12, v85
	v_fmac_f32_e32 v10, s12, v86
	v_fmac_f32_e32 v11, s12, v87
	v_fmac_f32_e32 v12, s13, v84
	v_fmac_f32_e32 v13, s13, v85
	v_fmac_f32_e32 v14, s13, v86
	v_fmac_f32_e32 v15, s13, v87
	v_fmac_f32_e32 v16, s14, v84
	v_fmac_f32_e32 v17, s14, v85
	v_fmac_f32_e32 v18, s14, v86
	v_fmac_f32_e32 v19, s14, v87
	v_fmac_f32_e32 v20, s15, v84
	v_fmac_f32_e32 v21, s15, v85
	v_fmac_f32_e32 v22, s15, v86
	v_fmac_f32_e32 v23, s15, v87
	v_fmac_f32_e32 v24, s16, v84
	v_fmac_f32_e32 v25, s16, v85
	v_fmac_f32_e32 v26, s16, v86
	v_fmac_f32_e32 v27, s16, v87
	v_fmac_f32_e32 v28, s17, v84
	v_fmac_f32_e32 v29, s17, v85
	v_fmac_f32_e32 v30, s17, v86
	v_fmac_f32_e32 v31, s17, v87
	v_fmac_f32_e32 v32, s18, v84
	v_fmac_f32_e32 v33, s18, v85
	v_fmac_f32_e32 v34, s18, v86
	v_fmac_f32_e32 v35, s18, v87
	v_readlane_b32 s10, v36, 34
	v_readlane_b32 s11, v37, 34
	v_readlane_b32 s12, v38, 34
	v_readlane_b32 s13, v39, 34
	v_readlane_b32 s14, v40, 34
	v_readlane_b32 s15, v41, 34
	v_readlane_b32 s16, v42, 34
	v_readlane_b32 s17, v43, 34
	v_readlane_b32 s18, v44, 34
	v_fmac_f32_e32 v0, s10, v88
	v_fmac_f32_e32 v1, s10, v89
	v_fmac_f32_e32 v2, s10, v90
	v_fmac_f32_e32 v3, s10, v91
	v_fmac_f32_e32 v4, s11, v88
	v_fmac_f32_e32 v5, s11, v89
	v_fmac_f32_e32 v6, s11, v90
	v_fmac_f32_e32 v7, s11, v91
	v_fmac_f32_e32 v8, s12, v88
	v_fmac_f32_e32 v9, s12, v89
	v_fmac_f32_e32 v10, s12, v90
	v_fmac_f32_e32 v11, s12, v91
	v_fmac_f32_e32 v12, s13, v88
	v_fmac_f32_e32 v13, s13, v89
	v_fmac_f32_e32 v14, s13, v90
	v_fmac_f32_e32 v15, s13, v91
	v_fmac_f32_e32 v16, s14, v88
	v_fmac_f32_e32 v17, s14, v89
	v_fmac_f32_e32 v18, s14, v90
	v_fmac_f32_e32 v19, s14, v91
	v_fmac_f32_e32 v20, s15, v88
	v_fmac_f32_e32 v21, s15, v89
	v_fmac_f32_e32 v22, s15, v90
	v_fmac_f32_e32 v23, s15, v91
	v_fmac_f32_e32 v24, s16, v88
	v_fmac_f32_e32 v25, s16, v89
	v_fmac_f32_e32 v26, s16, v90
	v_fmac_f32_e32 v27, s16, v91
	v_fmac_f32_e32 v28, s17, v88
	v_fmac_f32_e32 v29, s17, v89
	v_fmac_f32_e32 v30, s17, v90
	v_fmac_f32_e32 v31, s17, v91
	v_fmac_f32_e32 v32, s18, v88
	v_fmac_f32_e32 v33, s18, v89
	v_fmac_f32_e32 v34, s18, v90
	v_fmac_f32_e32 v35, s18, v91
	v_readlane_b32 s10, v36, 35
	v_readlane_b32 s11, v37, 35
	v_readlane_b32 s12, v38, 35
	v_readlane_b32 s13, v39, 35
	v_readlane_b32 s14, v40, 35
	v_readlane_b32 s15, v41, 35
	v_readlane_b32 s16, v42, 35
	v_readlane_b32 s17, v43, 35
	v_readlane_b32 s18, v44, 35
	v_fmac_f32_e32 v0, s10, v92
	v_fmac_f32_e32 v1, s10, v93
	v_fmac_f32_e32 v2, s10, v94
	v_fmac_f32_e32 v3, s10, v95
	v_fmac_f32_e32 v4, s11, v92
	v_fmac_f32_e32 v5, s11, v93
	v_fmac_f32_e32 v6, s11, v94
	v_fmac_f32_e32 v7, s11, v95
	v_fmac_f32_e32 v8, s12, v92
	v_fmac_f32_e32 v9, s12, v93
	v_fmac_f32_e32 v10, s12, v94
	v_fmac_f32_e32 v11, s12, v95
	v_fmac_f32_e32 v12, s13, v92
	v_fmac_f32_e32 v13, s13, v93
	v_fmac_f32_e32 v14, s13, v94
	v_fmac_f32_e32 v15, s13, v95
	v_fmac_f32_e32 v16, s14, v92
	v_fmac_f32_e32 v17, s14, v93
	v_fmac_f32_e32 v18, s14, v94
	v_fmac_f32_e32 v19, s14, v95
	v_fmac_f32_e32 v20, s15, v92
	v_fmac_f32_e32 v21, s15, v93
	v_fmac_f32_e32 v22, s15, v94
	v_fmac_f32_e32 v23, s15, v95
	v_fmac_f32_e32 v24, s16, v92
	v_fmac_f32_e32 v25, s16, v93
	v_fmac_f32_e32 v26, s16, v94
	v_fmac_f32_e32 v27, s16, v95
	v_fmac_f32_e32 v28, s17, v92
	v_fmac_f32_e32 v29, s17, v93
	v_fmac_f32_e32 v30, s17, v94
	v_fmac_f32_e32 v31, s17, v95
	v_fmac_f32_e32 v32, s18, v92
	v_fmac_f32_e32 v33, s18, v93
	v_fmac_f32_e32 v34, s18, v94
	v_fmac_f32_e32 v35, s18, v95
	v_readlane_b32 s10, v36, 36
	v_readlane_b32 s11, v37, 36
	v_readlane_b32 s12, v38, 36
	v_readlane_b32 s13, v39, 36
	v_readlane_b32 s14, v40, 36
	v_readlane_b32 s15, v41, 36
	v_readlane_b32 s16, v42, 36
	v_readlane_b32 s17, v43, 36
	v_readlane_b32 s18, v44, 36
	v_fmac_f32_e32 v0, s10, v96
	v_fmac_f32_e32 v1, s10, v97
	v_fmac_f32_e32 v2, s10, v98
	v_fmac_f32_e32 v3, s10, v99
	v_fmac_f32_e32 v4, s11, v96
	v_fmac_f32_e32 v5, s11, v97
	v_fmac_f32_e32 v6, s11, v98
	v_fmac_f32_e32 v7, s11, v99
	v_fmac_f32_e32 v8, s12, v96
	v_fmac_f32_e32 v9, s12, v97
	v_fmac_f32_e32 v10, s12, v98
	v_fmac_f32_e32 v11, s12, v99
	v_fmac_f32_e32 v12, s13, v96
	v_fmac_f32_e32 v13, s13, v97
	v_fmac_f32_e32 v14, s13, v98
	v_fmac_f32_e32 v15, s13, v99
	v_fmac_f32_e32 v16, s14, v96
	v_fmac_f32_e32 v17, s14, v97
	v_fmac_f32_e32 v18, s14, v98
	v_fmac_f32_e32 v19, s14, v99
	v_fmac_f32_e32 v20, s15, v96
	v_fmac_f32_e32 v21, s15, v97
	v_fmac_f32_e32 v22, s15, v98
	v_fmac_f32_e32 v23, s15, v99
	v_fmac_f32_e32 v24, s16, v96
	v_fmac_f32_e32 v25, s16, v97
	v_fmac_f32_e32 v26, s16, v98
	v_fmac_f32_e32 v27, s16, v99
	v_fmac_f32_e32 v28, s17, v96
	v_fmac_f32_e32 v29, s17, v97
	v_fmac_f32_e32 v30, s17, v98
	v_fmac_f32_e32 v31, s17, v99
	v_fmac_f32_e32 v32, s18, v96
	v_fmac_f32_e32 v33, s18, v97
	v_fmac_f32_e32 v34, s18, v98
	v_fmac_f32_e32 v35, s18, v99
	v_readlane_b32 s10, v36, 37
	v_readlane_b32 s11, v37, 37
	v_readlane_b32 s12, v38, 37
	v_readlane_b32 s13, v39, 37
	v_readlane_b32 s14, v40, 37
	v_readlane_b32 s15, v41, 37
	v_readlane_b32 s16, v42, 37
	v_readlane_b32 s17, v43, 37
	v_readlane_b32 s18, v44, 37
	v_fmac_f32_e32 v0, s10, v100
	v_fmac_f32_e32 v1, s10, v101
	v_fmac_f32_e32 v2, s10, v102
	v_fmac_f32_e32 v3, s10, v103
	v_fmac_f32_e32 v4, s11, v100
	v_fmac_f32_e32 v5, s11, v101
	v_fmac_f32_e32 v6, s11, v102
	v_fmac_f32_e32 v7, s11, v103
	v_fmac_f32_e32 v8, s12, v100
	v_fmac_f32_e32 v9, s12, v101
	v_fmac_f32_e32 v10, s12, v102
	v_fmac_f32_e32 v11, s12, v103
	v_fmac_f32_e32 v12, s13, v100
	v_fmac_f32_e32 v13, s13, v101
	v_fmac_f32_e32 v14, s13, v102
	v_fmac_f32_e32 v15, s13, v103
; __device__ __forceinline__ void gemv_item(const float* c, const float* c_ctx, const float* ada_w, const float* ada_b, float* mod, int it, int lane) {
;     ...
;     for (int kk = 0; kk < 64; ++kk) { const f32x4 w = *(const f32x4*)(W + (size_t)kk * 6144);
; #pragma unroll
;         for (int r = 0; r < 9; ++r) { const float sk = __uint_as_float(__builtin_amdgcn_readlane(__float_as_uint(s[r]), kk)); acc[r] += w * sk; } }
	v_fmac_f32_e32 v16, s14, v100
	v_fmac_f32_e32 v17, s14, v101
	v_fmac_f32_e32 v18, s14, v102
	v_fmac_f32_e32 v19, s14, v103
	v_fmac_f32_e32 v20, s15, v100
	v_fmac_f32_e32 v21, s15, v101
	v_fmac_f32_e32 v22, s15, v102
	v_fmac_f32_e32 v23, s15, v103
	v_fmac_f32_e32 v24, s16, v100
	v_fmac_f32_e32 v25, s16, v101
	v_fmac_f32_e32 v26, s16, v102
	v_fmac_f32_e32 v27, s16, v103
	v_fmac_f32_e32 v28, s17, v100
	v_fmac_f32_e32 v29, s17, v101
	v_fmac_f32_e32 v30, s17, v102
	v_fmac_f32_e32 v31, s17, v103
	v_fmac_f32_e32 v32, s18, v100
	v_fmac_f32_e32 v33, s18, v101
	v_fmac_f32_e32 v34, s18, v102
	v_fmac_f32_e32 v35, s18, v103
	v_readlane_b32 s10, v36, 38
	v_readlane_b32 s11, v37, 38
	v_readlane_b32 s12, v38, 38
	v_readlane_b32 s13, v39, 38
	v_readlane_b32 s14, v40, 38
	v_readlane_b32 s15, v41, 38
	v_readlane_b32 s16, v42, 38
	v_readlane_b32 s17, v43, 38
	v_readlane_b32 s18, v44, 38
	v_fmac_f32_e32 v0, s10, v104
	v_fmac_f32_e32 v1, s10, v105
	v_fmac_f32_e32 v2, s10, v106
	v_fmac_f32_e32 v3, s10, v107
	v_fmac_f32_e32 v4, s11, v104
	v_fmac_f32_e32 v5, s11, v105
	v_fmac_f32_e32 v6, s11, v106
	v_fmac_f32_e32 v7, s11, v107
	v_fmac_f32_e32 v8, s12, v104
	v_fmac_f32_e32 v9, s12, v105
	v_fmac_f32_e32 v10, s12, v106
	v_fmac_f32_e32 v11, s12, v107
	v_fmac_f32_e32 v12, s13, v104
	v_fmac_f32_e32 v13, s13, v105
	v_fmac_f32_e32 v14, s13, v106
	v_fmac_f32_e32 v15, s13, v107
	v_fmac_f32_e32 v16, s14, v104
	v_fmac_f32_e32 v17, s14, v105
	v_fmac_f32_e32 v18, s14, v106
	v_fmac_f32_e32 v19, s14, v107
	v_fmac_f32_e32 v20, s15, v104
	v_fmac_f32_e32 v21, s15, v105
	v_fmac_f32_e32 v22, s15, v106
	v_fmac_f32_e32 v23, s15, v107
	v_fmac_f32_e32 v24, s16, v104
	v_fmac_f32_e32 v25, s16, v105
	v_fmac_f32_e32 v26, s16, v106
	v_fmac_f32_e32 v27, s16, v107
	v_fmac_f32_e32 v28, s17, v104
	v_fmac_f32_e32 v29, s17, v105
	v_fmac_f32_e32 v30, s17, v106
	v_fmac_f32_e32 v31, s17, v107
	v_fmac_f32_e32 v32, s18, v104
	v_fmac_f32_e32 v33, s18, v105
	v_fmac_f32_e32 v34, s18, v106
	v_fmac_f32_e32 v35, s18, v107
	v_readlane_b32 s10, v36, 39
	v_readlane_b32 s11, v37, 39
	v_readlane_b32 s12, v38, 39
	v_readlane_b32 s13, v39, 39
	v_readlane_b32 s14, v40, 39
	v_readlane_b32 s15, v41, 39
	v_readlane_b32 s16, v42, 39
	v_readlane_b32 s17, v43, 39
	v_readlane_b32 s18, v44, 39
	v_fmac_f32_e32 v0, s10, v108
	v_fmac_f32_e32 v1, s10, v109
	v_fmac_f32_e32 v2, s10, v110
	v_fmac_f32_e32 v3, s10, v111
	v_fmac_f32_e32 v4, s11, v108
	v_fmac_f32_e32 v5, s11, v109
	v_fmac_f32_e32 v6, s11, v110
	v_fmac_f32_e32 v7, s11, v111
	v_fmac_f32_e32 v8, s12, v108
	v_fmac_f32_e32 v9, s12, v109
	v_fmac_f32_e32 v10, s12, v110
	v_fmac_f32_e32 v11, s12, v111
	v_fmac_f32_e32 v12, s13, v108
	v_fmac_f32_e32 v13, s13, v109
	v_fmac_f32_e32 v14, s13, v110
	v_fmac_f32_e32 v15, s13, v111
	v_fmac_f32_e32 v16, s14, v108
	v_fmac_f32_e32 v17, s14, v109
	v_fmac_f32_e32 v18, s14, v110
	v_fmac_f32_e32 v19, s14, v111
	v_fmac_f32_e32 v20, s15, v108
	v_fmac_f32_e32 v21, s15, v109
	v_fmac_f32_e32 v22, s15, v110
	v_fmac_f32_e32 v23, s15, v111
	v_fmac_f32_e32 v24, s16, v108
	v_fmac_f32_e32 v25, s16, v109
	v_fmac_f32_e32 v26, s16, v110
	v_fmac_f32_e32 v27, s16, v111
	v_fmac_f32_e32 v28, s17, v108
	v_fmac_f32_e32 v29, s17, v109
	v_fmac_f32_e32 v30, s17, v110
	v_fmac_f32_e32 v31, s17, v111
	v_fmac_f32_e32 v32, s18, v108
	v_fmac_f32_e32 v33, s18, v109
	v_fmac_f32_e32 v34, s18, v110
	v_fmac_f32_e32 v35, s18, v111
	v_readlane_b32 s10, v36, 40
	v_readlane_b32 s11, v37, 40
	v_readlane_b32 s12, v38, 40
	v_readlane_b32 s13, v39, 40
	v_readlane_b32 s14, v40, 40
	v_readlane_b32 s15, v41, 40
	v_readlane_b32 s16, v42, 40
	v_readlane_b32 s17, v43, 40
	v_readlane_b32 s18, v44, 40
	v_fmac_f32_e32 v0, s10, v112
	v_fmac_f32_e32 v1, s10, v113
	v_fmac_f32_e32 v2, s10, v114
	v_fmac_f32_e32 v3, s10, v115
	v_fmac_f32_e32 v4, s11, v112
	v_fmac_f32_e32 v5, s11, v113
	v_fmac_f32_e32 v6, s11, v114
	v_fmac_f32_e32 v7, s11, v115
	v_fmac_f32_e32 v8, s12, v112
	v_fmac_f32_e32 v9, s12, v113
	v_fmac_f32_e32 v10, s12, v114
	v_fmac_f32_e32 v11, s12, v115
	v_fmac_f32_e32 v12, s13, v112
	v_fmac_f32_e32 v13, s13, v113
	v_fmac_f32_e32 v14, s13, v114
	v_fmac_f32_e32 v15, s13, v115
	v_fmac_f32_e32 v16, s14, v112
	v_fmac_f32_e32 v17, s14, v113
	v_fmac_f32_e32 v18, s14, v114
	v_fmac_f32_e32 v19, s14, v115
	v_fmac_f32_e32 v20, s15, v112
	v_fmac_f32_e32 v21, s15, v113
	v_fmac_f32_e32 v22, s15, v114
	v_fmac_f32_e32 v23, s15, v115
	v_fmac_f32_e32 v24, s16, v112
	v_fmac_f32_e32 v25, s16, v113
	v_fmac_f32_e32 v26, s16, v114
	v_fmac_f32_e32 v27, s16, v115
	v_fmac_f32_e32 v28, s17, v112
	v_fmac_f32_e32 v29, s17, v113
	v_fmac_f32_e32 v30, s17, v114
	v_fmac_f32_e32 v31, s17, v115
	v_fmac_f32_e32 v32, s18, v112
	v_fmac_f32_e32 v33, s18, v113
	v_fmac_f32_e32 v34, s18, v114
	v_fmac_f32_e32 v35, s18, v115
	v_readlane_b32 s10, v36, 41
	v_readlane_b32 s11, v37, 41
	v_readlane_b32 s12, v38, 41
	v_readlane_b32 s13, v39, 41
	v_readlane_b32 s14, v40, 41
	v_readlane_b32 s15, v41, 41
	v_readlane_b32 s16, v42, 41
	v_readlane_b32 s17, v43, 41
	v_readlane_b32 s18, v44, 41
	v_fmac_f32_e32 v0, s10, v116
	v_fmac_f32_e32 v1, s10, v117
	v_fmac_f32_e32 v2, s10, v118
	v_fmac_f32_e32 v3, s10, v119
	v_fmac_f32_e32 v4, s11, v116
	v_fmac_f32_e32 v5, s11, v117
	v_fmac_f32_e32 v6, s11, v118
	v_fmac_f32_e32 v7, s11, v119
	v_fmac_f32_e32 v8, s12, v116
	v_fmac_f32_e32 v9, s12, v117
	v_fmac_f32_e32 v10, s12, v118
	v_fmac_f32_e32 v11, s12, v119
	v_fmac_f32_e32 v12, s13, v116
	v_fmac_f32_e32 v13, s13, v117
	v_fmac_f32_e32 v14, s13, v118
	v_fmac_f32_e32 v15, s13, v119
	v_fmac_f32_e32 v16, s14, v116
	v_fmac_f32_e32 v17, s14, v117
	v_fmac_f32_e32 v18, s14, v118
	v_fmac_f32_e32 v19, s14, v119
	v_fmac_f32_e32 v20, s15, v116
	v_fmac_f32_e32 v21, s15, v117
; __device__ __forceinline__ void gemv_item(const float* c, const float* c_ctx, const float* ada_w, const float* ada_b, float* mod, int it, int lane) {
;     ...
;     for (int kk = 0; kk < 64; ++kk) { const f32x4 w = *(const f32x4*)(W + (size_t)kk * 6144);
; #pragma unroll
;         for (int r = 0; r < 9; ++r) { const float sk = __uint_as_float(__builtin_amdgcn_readlane(__float_as_uint(s[r]), kk)); acc[r] += w * sk; } }
	v_fmac_f32_e32 v22, s15, v118
	v_fmac_f32_e32 v23, s15, v119
	v_fmac_f32_e32 v24, s16, v116
	v_fmac_f32_e32 v25, s16, v117
	v_fmac_f32_e32 v26, s16, v118
	v_fmac_f32_e32 v27, s16, v119
	v_fmac_f32_e32 v28, s17, v116
	v_fmac_f32_e32 v29, s17, v117
	v_fmac_f32_e32 v30, s17, v118
	v_fmac_f32_e32 v31, s17, v119
	v_fmac_f32_e32 v32, s18, v116
	v_fmac_f32_e32 v33, s18, v117
	v_fmac_f32_e32 v34, s18, v118
	v_fmac_f32_e32 v35, s18, v119
	v_readlane_b32 s10, v36, 42
	v_readlane_b32 s11, v37, 42
	v_readlane_b32 s12, v38, 42
	v_readlane_b32 s13, v39, 42
	v_readlane_b32 s14, v40, 42
	v_readlane_b32 s15, v41, 42
	v_readlane_b32 s16, v42, 42
	v_readlane_b32 s17, v43, 42
	v_readlane_b32 s18, v44, 42
	v_fmac_f32_e32 v0, s10, v120
	v_fmac_f32_e32 v1, s10, v121
	v_fmac_f32_e32 v2, s10, v122
	v_fmac_f32_e32 v3, s10, v123
	v_fmac_f32_e32 v4, s11, v120
	v_fmac_f32_e32 v5, s11, v121
	v_fmac_f32_e32 v6, s11, v122
	v_fmac_f32_e32 v7, s11, v123
	v_fmac_f32_e32 v8, s12, v120
	v_fmac_f32_e32 v9, s12, v121
	v_fmac_f32_e32 v10, s12, v122
	v_fmac_f32_e32 v11, s12, v123
	v_fmac_f32_e32 v12, s13, v120
	v_fmac_f32_e32 v13, s13, v121
	v_fmac_f32_e32 v14, s13, v122
	v_fmac_f32_e32 v15, s13, v123
	v_fmac_f32_e32 v16, s14, v120
	v_fmac_f32_e32 v17, s14, v121
	v_fmac_f32_e32 v18, s14, v122
	v_fmac_f32_e32 v19, s14, v123
	v_fmac_f32_e32 v20, s15, v120
	v_fmac_f32_e32 v21, s15, v121
	v_fmac_f32_e32 v22, s15, v122
	v_fmac_f32_e32 v23, s15, v123
	v_fmac_f32_e32 v24, s16, v120
	v_fmac_f32_e32 v25, s16, v121
	v_fmac_f32_e32 v26, s16, v122
	v_fmac_f32_e32 v27, s16, v123
	v_fmac_f32_e32 v28, s17, v120
	v_fmac_f32_e32 v29, s17, v121
	v_fmac_f32_e32 v30, s17, v122
	v_fmac_f32_e32 v31, s17, v123
	v_fmac_f32_e32 v32, s18, v120
	v_fmac_f32_e32 v33, s18, v121
	v_fmac_f32_e32 v34, s18, v122
	v_fmac_f32_e32 v35, s18, v123
	v_readlane_b32 s10, v36, 43
	v_readlane_b32 s11, v37, 43
	v_readlane_b32 s12, v38, 43
	v_readlane_b32 s13, v39, 43
	v_readlane_b32 s14, v40, 43
	v_readlane_b32 s15, v41, 43
	v_readlane_b32 s16, v42, 43
	v_readlane_b32 s17, v43, 43
	v_readlane_b32 s18, v44, 43
	v_fmac_f32_e32 v0, s10, v124
	v_fmac_f32_e32 v1, s10, v125
	v_fmac_f32_e32 v2, s10, v126
	v_fmac_f32_e32 v3, s10, v127
	v_fmac_f32_e32 v4, s11, v124
	v_fmac_f32_e32 v5, s11, v125
	v_fmac_f32_e32 v6, s11, v126
	v_fmac_f32_e32 v7, s11, v127
	v_fmac_f32_e32 v8, s12, v124
	v_fmac_f32_e32 v9, s12, v125
	v_fmac_f32_e32 v10, s12, v126
	v_fmac_f32_e32 v11, s12, v127
	v_fmac_f32_e32 v12, s13, v124
	v_fmac_f32_e32 v13, s13, v125
	v_fmac_f32_e32 v14, s13, v126
	v_fmac_f32_e32 v15, s13, v127
	v_fmac_f32_e32 v16, s14, v124
	v_fmac_f32_e32 v17, s14, v125
	v_fmac_f32_e32 v18, s14, v126
	v_fmac_f32_e32 v19, s14, v127
	v_fmac_f32_e32 v20, s15, v124
	v_fmac_f32_e32 v21, s15, v125
	v_fmac_f32_e32 v22, s15, v126
	v_fmac_f32_e32 v23, s15, v127
	v_fmac_f32_e32 v24, s16, v124
	v_fmac_f32_e32 v25, s16, v125
	v_fmac_f32_e32 v26, s16, v126
	v_fmac_f32_e32 v27, s16, v127
	v_fmac_f32_e32 v28, s17, v124
	v_fmac_f32_e32 v29, s17, v125
	v_fmac_f32_e32 v30, s17, v126
	v_fmac_f32_e32 v31, s17, v127
	v_fmac_f32_e32 v32, s18, v124
	v_fmac_f32_e32 v33, s18, v125
	v_fmac_f32_e32 v34, s18, v126
	v_fmac_f32_e32 v35, s18, v127
	v_readlane_b32 s10, v36, 44
	v_readlane_b32 s11, v37, 44
	v_readlane_b32 s12, v38, 44
	v_readlane_b32 s13, v39, 44
	v_readlane_b32 s14, v40, 44
	v_readlane_b32 s15, v41, 44
	v_readlane_b32 s16, v42, 44
	v_readlane_b32 s17, v43, 44
	v_readlane_b32 s18, v44, 44
	v_fmac_f32_e32 v0, s10, v128
	v_fmac_f32_e32 v1, s10, v129
	v_fmac_f32_e32 v2, s10, v130
	v_fmac_f32_e32 v3, s10, v131
	v_fmac_f32_e32 v4, s11, v128
	v_fmac_f32_e32 v5, s11, v129
	v_fmac_f32_e32 v6, s11, v130
	v_fmac_f32_e32 v7, s11, v131
	v_fmac_f32_e32 v8, s12, v128
	v_fmac_f32_e32 v9, s12, v129
	v_fmac_f32_e32 v10, s12, v130
	v_fmac_f32_e32 v11, s12, v131
	v_fmac_f32_e32 v12, s13, v128
	v_fmac_f32_e32 v13, s13, v129
	v_fmac_f32_e32 v14, s13, v130
	v_fmac_f32_e32 v15, s13, v131
	v_fmac_f32_e32 v16, s14, v128
	v_fmac_f32_e32 v17, s14, v129
	v_fmac_f32_e32 v18, s14, v130
	v_fmac_f32_e32 v19, s14, v131
	v_fmac_f32_e32 v20, s15, v128
	v_fmac_f32_e32 v21, s15, v129
	v_fmac_f32_e32 v22, s15, v130
	v_fmac_f32_e32 v23, s15, v131
	v_fmac_f32_e32 v24, s16, v128
	v_fmac_f32_e32 v25, s16, v129
	v_fmac_f32_e32 v26, s16, v130
	v_fmac_f32_e32 v27, s16, v131
	v_fmac_f32_e32 v28, s17, v128
	v_fmac_f32_e32 v29, s17, v129
	v_fmac_f32_e32 v30, s17, v130
	v_fmac_f32_e32 v31, s17, v131
	v_fmac_f32_e32 v32, s18, v128
	v_fmac_f32_e32 v33, s18, v129
	v_fmac_f32_e32 v34, s18, v130
	v_fmac_f32_e32 v35, s18, v131
	v_readlane_b32 s10, v36, 45
	v_readlane_b32 s11, v37, 45
	v_readlane_b32 s12, v38, 45
	v_readlane_b32 s13, v39, 45
	v_readlane_b32 s14, v40, 45
	v_readlane_b32 s15, v41, 45
	v_readlane_b32 s16, v42, 45
	v_readlane_b32 s17, v43, 45
	v_readlane_b32 s18, v44, 45
	v_fmac_f32_e32 v0, s10, v132
	v_fmac_f32_e32 v1, s10, v133
	v_fmac_f32_e32 v2, s10, v134
	v_fmac_f32_e32 v3, s10, v135
	v_fmac_f32_e32 v4, s11, v132
	v_fmac_f32_e32 v5, s11, v133
	v_fmac_f32_e32 v6, s11, v134
	v_fmac_f32_e32 v7, s11, v135
	v_fmac_f32_e32 v8, s12, v132
	v_fmac_f32_e32 v9, s12, v133
	v_fmac_f32_e32 v10, s12, v134
	v_fmac_f32_e32 v11, s12, v135
	v_fmac_f32_e32 v12, s13, v132
	v_fmac_f32_e32 v13, s13, v133
	v_fmac_f32_e32 v14, s13, v134
	v_fmac_f32_e32 v15, s13, v135
	v_fmac_f32_e32 v16, s14, v132
	v_fmac_f32_e32 v17, s14, v133
	v_fmac_f32_e32 v18, s14, v134
	v_fmac_f32_e32 v19, s14, v135
	v_fmac_f32_e32 v20, s15, v132
	v_fmac_f32_e32 v21, s15, v133
	v_fmac_f32_e32 v22, s15, v134
	v_fmac_f32_e32 v23, s15, v135
	v_fmac_f32_e32 v24, s16, v132
	v_fmac_f32_e32 v25, s16, v133
	v_fmac_f32_e32 v26, s16, v134
	v_fmac_f32_e32 v27, s16, v135
; __device__ __forceinline__ void gemv_item(const float* c, const float* c_ctx, const float* ada_w, const float* ada_b, float* mod, int it, int lane) {
;     ...
;     for (int kk = 0; kk < 64; ++kk) { const f32x4 w = *(const f32x4*)(W + (size_t)kk * 6144);
; #pragma unroll
;         for (int r = 0; r < 9; ++r) { const float sk = __uint_as_float(__builtin_amdgcn_readlane(__float_as_uint(s[r]), kk)); acc[r] += w * sk; } }
	v_fmac_f32_e32 v28, s17, v132
	v_fmac_f32_e32 v29, s17, v133
	v_fmac_f32_e32 v30, s17, v134
	v_fmac_f32_e32 v31, s17, v135
	v_fmac_f32_e32 v32, s18, v132
	v_fmac_f32_e32 v33, s18, v133
	v_fmac_f32_e32 v34, s18, v134
	v_fmac_f32_e32 v35, s18, v135
	v_readlane_b32 s10, v36, 46
	v_readlane_b32 s11, v37, 46
	v_readlane_b32 s12, v38, 46
	v_readlane_b32 s13, v39, 46
	v_readlane_b32 s14, v40, 46
	v_readlane_b32 s15, v41, 46
	v_readlane_b32 s16, v42, 46
	v_readlane_b32 s17, v43, 46
	v_readlane_b32 s18, v44, 46
	v_fmac_f32_e32 v0, s10, v136
	v_fmac_f32_e32 v1, s10, v137
	v_fmac_f32_e32 v2, s10, v138
	v_fmac_f32_e32 v3, s10, v139
	v_fmac_f32_e32 v4, s11, v136
	v_fmac_f32_e32 v5, s11, v137
	v_fmac_f32_e32 v6, s11, v138
	v_fmac_f32_e32 v7, s11, v139
	v_fmac_f32_e32 v8, s12, v136
	v_fmac_f32_e32 v9, s12, v137
	v_fmac_f32_e32 v10, s12, v138
	v_fmac_f32_e32 v11, s12, v139
	v_fmac_f32_e32 v12, s13, v136
	v_fmac_f32_e32 v13, s13, v137
	v_fmac_f32_e32 v14, s13, v138
	v_fmac_f32_e32 v15, s13, v139
	v_fmac_f32_e32 v16, s14, v136
	v_fmac_f32_e32 v17, s14, v137
	v_fmac_f32_e32 v18, s14, v138
	v_fmac_f32_e32 v19, s14, v139
	v_fmac_f32_e32 v20, s15, v136
	v_fmac_f32_e32 v21, s15, v137
	v_fmac_f32_e32 v22, s15, v138
	v_fmac_f32_e32 v23, s15, v139
	v_fmac_f32_e32 v24, s16, v136
	v_fmac_f32_e32 v25, s16, v137
	v_fmac_f32_e32 v26, s16, v138
	v_fmac_f32_e32 v27, s16, v139
	v_fmac_f32_e32 v28, s17, v136
	v_fmac_f32_e32 v29, s17, v137
	v_fmac_f32_e32 v30, s17, v138
	v_fmac_f32_e32 v31, s17, v139
	v_fmac_f32_e32 v32, s18, v136
	v_fmac_f32_e32 v33, s18, v137
	v_fmac_f32_e32 v34, s18, v138
	v_fmac_f32_e32 v35, s18, v139
	v_readlane_b32 s10, v36, 47
	v_readlane_b32 s11, v37, 47
	v_readlane_b32 s12, v38, 47
	v_readlane_b32 s13, v39, 47
	v_readlane_b32 s14, v40, 47
	v_readlane_b32 s15, v41, 47
	v_readlane_b32 s16, v42, 47
	v_readlane_b32 s17, v43, 47
	v_readlane_b32 s18, v44, 47
	v_fmac_f32_e32 v0, s10, v140
	v_fmac_f32_e32 v1, s10, v141
	v_fmac_f32_e32 v2, s10, v142
	v_fmac_f32_e32 v3, s10, v143
	v_fmac_f32_e32 v4, s11, v140
	v_fmac_f32_e32 v5, s11, v141
	v_fmac_f32_e32 v6, s11, v142
	v_fmac_f32_e32 v7, s11, v143
	v_fmac_f32_e32 v8, s12, v140
	v_fmac_f32_e32 v9, s12, v141
	v_fmac_f32_e32 v10, s12, v142
	v_fmac_f32_e32 v11, s12, v143
	v_fmac_f32_e32 v12, s13, v140
	v_fmac_f32_e32 v13, s13, v141
	v_fmac_f32_e32 v14, s13, v142
	v_fmac_f32_e32 v15, s13, v143
	v_fmac_f32_e32 v16, s14, v140
	v_fmac_f32_e32 v17, s14, v141
	v_fmac_f32_e32 v18, s14, v142
	v_fmac_f32_e32 v19, s14, v143
	v_fmac_f32_e32 v20, s15, v140
	v_fmac_f32_e32 v21, s15, v141
	v_fmac_f32_e32 v22, s15, v142
	v_fmac_f32_e32 v23, s15, v143
	v_fmac_f32_e32 v24, s16, v140
	v_fmac_f32_e32 v25, s16, v141
	v_fmac_f32_e32 v26, s16, v142
	v_fmac_f32_e32 v27, s16, v143
	v_fmac_f32_e32 v28, s17, v140
	v_fmac_f32_e32 v29, s17, v141
	v_fmac_f32_e32 v30, s17, v142
	v_fmac_f32_e32 v31, s17, v143
	v_fmac_f32_e32 v32, s18, v140
	v_fmac_f32_e32 v33, s18, v141
	v_fmac_f32_e32 v34, s18, v142
	v_fmac_f32_e32 v35, s18, v143
	s_waitcnt vmcnt(0)
	v_readlane_b32 s10, v36, 48
	v_readlane_b32 s11, v37, 48
	v_readlane_b32 s12, v38, 48
	v_readlane_b32 s13, v39, 48
	v_readlane_b32 s14, v40, 48
	v_readlane_b32 s15, v41, 48
	v_readlane_b32 s16, v42, 48
	v_readlane_b32 s17, v43, 48
	v_readlane_b32 s18, v44, 48
	v_fmac_f32_e32 v0, s10, v144
	v_fmac_f32_e32 v1, s10, v145
	v_fmac_f32_e32 v2, s10, v146
	v_fmac_f32_e32 v3, s10, v147
	v_fmac_f32_e32 v4, s11, v144
	v_fmac_f32_e32 v5, s11, v145
	v_fmac_f32_e32 v6, s11, v146
	v_fmac_f32_e32 v7, s11, v147
	v_fmac_f32_e32 v8, s12, v144
	v_fmac_f32_e32 v9, s12, v145
	v_fmac_f32_e32 v10, s12, v146
	v_fmac_f32_e32 v11, s12, v147
	v_fmac_f32_e32 v12, s13, v144
	v_fmac_f32_e32 v13, s13, v145
	v_fmac_f32_e32 v14, s13, v146
	v_fmac_f32_e32 v15, s13, v147
	v_fmac_f32_e32 v16, s14, v144
	v_fmac_f32_e32 v17, s14, v145
	v_fmac_f32_e32 v18, s14, v146
	v_fmac_f32_e32 v19, s14, v147
	v_fmac_f32_e32 v20, s15, v144
	v_fmac_f32_e32 v21, s15, v145
	v_fmac_f32_e32 v22, s15, v146
	v_fmac_f32_e32 v23, s15, v147
	v_fmac_f32_e32 v24, s16, v144
	v_fmac_f32_e32 v25, s16, v145
	v_fmac_f32_e32 v26, s16, v146
	v_fmac_f32_e32 v27, s16, v147
	v_fmac_f32_e32 v28, s17, v144
	v_fmac_f32_e32 v29, s17, v145
	v_fmac_f32_e32 v30, s17, v146
	v_fmac_f32_e32 v31, s17, v147
	v_fmac_f32_e32 v32, s18, v144
	v_fmac_f32_e32 v33, s18, v145
	v_fmac_f32_e32 v34, s18, v146
	v_fmac_f32_e32 v35, s18, v147
	v_readlane_b32 s10, v36, 49
	v_readlane_b32 s11, v37, 49
	v_readlane_b32 s12, v38, 49
	v_readlane_b32 s13, v39, 49
	v_readlane_b32 s14, v40, 49
	v_readlane_b32 s15, v41, 49
	v_readlane_b32 s16, v42, 49
	v_readlane_b32 s17, v43, 49
	v_readlane_b32 s18, v44, 49
	v_fmac_f32_e32 v0, s10, v148
	v_fmac_f32_e32 v1, s10, v149
	v_fmac_f32_e32 v2, s10, v150
	v_fmac_f32_e32 v3, s10, v151
	v_fmac_f32_e32 v4, s11, v148
	v_fmac_f32_e32 v5, s11, v149
	v_fmac_f32_e32 v6, s11, v150
	v_fmac_f32_e32 v7, s11, v151
	v_fmac_f32_e32 v8, s12, v148
	v_fmac_f32_e32 v9, s12, v149
	v_fmac_f32_e32 v10, s12, v150
	v_fmac_f32_e32 v11, s12, v151
	v_fmac_f32_e32 v12, s13, v148
	v_fmac_f32_e32 v13, s13, v149
	v_fmac_f32_e32 v14, s13, v150
	v_fmac_f32_e32 v15, s13, v151
	v_fmac_f32_e32 v16, s14, v148
	v_fmac_f32_e32 v17, s14, v149
	v_fmac_f32_e32 v18, s14, v150
	v_fmac_f32_e32 v19, s14, v151
	v_fmac_f32_e32 v20, s15, v148
	v_fmac_f32_e32 v21, s15, v149
	v_fmac_f32_e32 v22, s15, v150
	v_fmac_f32_e32 v23, s15, v151
	v_fmac_f32_e32 v24, s16, v148
	v_fmac_f32_e32 v25, s16, v149
	v_fmac_f32_e32 v26, s16, v150
	v_fmac_f32_e32 v27, s16, v151
	v_fmac_f32_e32 v28, s17, v148
	v_fmac_f32_e32 v29, s17, v149
	v_fmac_f32_e32 v30, s17, v150
	v_fmac_f32_e32 v31, s17, v151
	v_fmac_f32_e32 v32, s18, v148
; __device__ __forceinline__ void gemv_item(const float* c, const float* c_ctx, const float* ada_w, const float* ada_b, float* mod, int it, int lane) {
;     ...
;     for (int kk = 0; kk < 64; ++kk) { const f32x4 w = *(const f32x4*)(W + (size_t)kk * 6144);
; #pragma unroll
;         for (int r = 0; r < 9; ++r) { const float sk = __uint_as_float(__builtin_amdgcn_readlane(__float_as_uint(s[r]), kk)); acc[r] += w * sk; } }
	v_fmac_f32_e32 v33, s18, v149
	v_fmac_f32_e32 v34, s18, v150
	v_fmac_f32_e32 v35, s18, v151
	v_readlane_b32 s10, v36, 50
	v_readlane_b32 s11, v37, 50
	v_readlane_b32 s12, v38, 50
	v_readlane_b32 s13, v39, 50
	v_readlane_b32 s14, v40, 50
	v_readlane_b32 s15, v41, 50
	v_readlane_b32 s16, v42, 50
	v_readlane_b32 s17, v43, 50
	v_readlane_b32 s18, v44, 50
	v_fmac_f32_e32 v0, s10, v152
	v_fmac_f32_e32 v1, s10, v153
	v_fmac_f32_e32 v2, s10, v154
	v_fmac_f32_e32 v3, s10, v155
	v_fmac_f32_e32 v4, s11, v152
	v_fmac_f32_e32 v5, s11, v153
	v_fmac_f32_e32 v6, s11, v154
	v_fmac_f32_e32 v7, s11, v155
	v_fmac_f32_e32 v8, s12, v152
	v_fmac_f32_e32 v9, s12, v153
	v_fmac_f32_e32 v10, s12, v154
	v_fmac_f32_e32 v11, s12, v155
	v_fmac_f32_e32 v12, s13, v152
	v_fmac_f32_e32 v13, s13, v153
	v_fmac_f32_e32 v14, s13, v154
	v_fmac_f32_e32 v15, s13, v155
	v_fmac_f32_e32 v16, s14, v152
	v_fmac_f32_e32 v17, s14, v153
	v_fmac_f32_e32 v18, s14, v154
	v_fmac_f32_e32 v19, s14, v155
	v_fmac_f32_e32 v20, s15, v152
	v_fmac_f32_e32 v21, s15, v153
	v_fmac_f32_e32 v22, s15, v154
	v_fmac_f32_e32 v23, s15, v155
	v_fmac_f32_e32 v24, s16, v152
	v_fmac_f32_e32 v25, s16, v153
	v_fmac_f32_e32 v26, s16, v154
	v_fmac_f32_e32 v27, s16, v155
	v_fmac_f32_e32 v28, s17, v152
	v_fmac_f32_e32 v29, s17, v153
	v_fmac_f32_e32 v30, s17, v154
	v_fmac_f32_e32 v31, s17, v155
	v_fmac_f32_e32 v32, s18, v152
	v_fmac_f32_e32 v33, s18, v153
	v_fmac_f32_e32 v34, s18, v154
	v_fmac_f32_e32 v35, s18, v155
	v_readlane_b32 s10, v36, 51
	v_readlane_b32 s11, v37, 51
	v_readlane_b32 s12, v38, 51
	v_readlane_b32 s13, v39, 51
	v_readlane_b32 s14, v40, 51
	v_readlane_b32 s15, v41, 51
	v_readlane_b32 s16, v42, 51
	v_readlane_b32 s17, v43, 51
	v_readlane_b32 s18, v44, 51
	v_fmac_f32_e32 v0, s10, v156
	v_fmac_f32_e32 v1, s10, v157
	v_fmac_f32_e32 v2, s10, v158
	v_fmac_f32_e32 v3, s10, v159
	v_fmac_f32_e32 v4, s11, v156
	v_fmac_f32_e32 v5, s11, v157
	v_fmac_f32_e32 v6, s11, v158
	v_fmac_f32_e32 v7, s11, v159
	v_fmac_f32_e32 v8, s12, v156
	v_fmac_f32_e32 v9, s12, v157
	v_fmac_f32_e32 v10, s12, v158
	v_fmac_f32_e32 v11, s12, v159
	v_fmac_f32_e32 v12, s13, v156
	v_fmac_f32_e32 v13, s13, v157
	v_fmac_f32_e32 v14, s13, v158
	v_fmac_f32_e32 v15, s13, v159
	v_fmac_f32_e32 v16, s14, v156
	v_fmac_f32_e32 v17, s14, v157
	v_fmac_f32_e32 v18, s14, v158
	v_fmac_f32_e32 v19, s14, v159
	v_fmac_f32_e32 v20, s15, v156
	v_fmac_f32_e32 v21, s15, v157
	v_fmac_f32_e32 v22, s15, v158
	v_fmac_f32_e32 v23, s15, v159
	v_fmac_f32_e32 v24, s16, v156
	v_fmac_f32_e32 v25, s16, v157
	v_fmac_f32_e32 v26, s16, v158
	v_fmac_f32_e32 v27, s16, v159
	v_fmac_f32_e32 v28, s17, v156
	v_fmac_f32_e32 v29, s17, v157
	v_fmac_f32_e32 v30, s17, v158
	v_fmac_f32_e32 v31, s17, v159
	v_fmac_f32_e32 v32, s18, v156
	v_fmac_f32_e32 v33, s18, v157
	v_fmac_f32_e32 v34, s18, v158
	v_fmac_f32_e32 v35, s18, v159
	v_readlane_b32 s10, v36, 52
	v_readlane_b32 s11, v37, 52
	v_readlane_b32 s12, v38, 52
	v_readlane_b32 s13, v39, 52
	v_readlane_b32 s14, v40, 52
	v_readlane_b32 s15, v41, 52
	v_readlane_b32 s16, v42, 52
	v_readlane_b32 s17, v43, 52
	v_readlane_b32 s18, v44, 52
	v_fmac_f32_e32 v0, s10, v160
	v_fmac_f32_e32 v1, s10, v161
	v_fmac_f32_e32 v2, s10, v162
	v_fmac_f32_e32 v3, s10, v163
	v_fmac_f32_e32 v4, s11, v160
	v_fmac_f32_e32 v5, s11, v161
	v_fmac_f32_e32 v6, s11, v162
	v_fmac_f32_e32 v7, s11, v163
	v_fmac_f32_e32 v8, s12, v160
	v_fmac_f32_e32 v9, s12, v161
	v_fmac_f32_e32 v10, s12, v162
	v_fmac_f32_e32 v11, s12, v163
	v_fmac_f32_e32 v12, s13, v160
	v_fmac_f32_e32 v13, s13, v161
	v_fmac_f32_e32 v14, s13, v162
	v_fmac_f32_e32 v15, s13, v163
	v_fmac_f32_e32 v16, s14, v160
	v_fmac_f32_e32 v17, s14, v161
	v_fmac_f32_e32 v18, s14, v162
	v_fmac_f32_e32 v19, s14, v163
	v_fmac_f32_e32 v20, s15, v160
	v_fmac_f32_e32 v21, s15, v161
	v_fmac_f32_e32 v22, s15, v162
	v_fmac_f32_e32 v23, s15, v163
	v_fmac_f32_e32 v24, s16, v160
	v_fmac_f32_e32 v25, s16, v161
	v_fmac_f32_e32 v26, s16, v162
	v_fmac_f32_e32 v27, s16, v163
	v_fmac_f32_e32 v28, s17, v160
	v_fmac_f32_e32 v29, s17, v161
	v_fmac_f32_e32 v30, s17, v162
	v_fmac_f32_e32 v31, s17, v163
	v_fmac_f32_e32 v32, s18, v160
	v_fmac_f32_e32 v33, s18, v161
	v_fmac_f32_e32 v34, s18, v162
	v_fmac_f32_e32 v35, s18, v163
	v_readlane_b32 s10, v36, 53
	v_readlane_b32 s11, v37, 53
	v_readlane_b32 s12, v38, 53
	v_readlane_b32 s13, v39, 53
	v_readlane_b32 s14, v40, 53
	v_readlane_b32 s15, v41, 53
	v_readlane_b32 s16, v42, 53
	v_readlane_b32 s17, v43, 53
	v_readlane_b32 s18, v44, 53
	v_fmac_f32_e32 v0, s10, v164
	v_fmac_f32_e32 v1, s10, v165
	v_fmac_f32_e32 v2, s10, v166
	v_fmac_f32_e32 v3, s10, v167
	v_fmac_f32_e32 v4, s11, v164
	v_fmac_f32_e32 v5, s11, v165
	v_fmac_f32_e32 v6, s11, v166
	v_fmac_f32_e32 v7, s11, v167
	v_fmac_f32_e32 v8, s12, v164
	v_fmac_f32_e32 v9, s12, v165
	v_fmac_f32_e32 v10, s12, v166
	v_fmac_f32_e32 v11, s12, v167
	v_fmac_f32_e32 v12, s13, v164
	v_fmac_f32_e32 v13, s13, v165
	v_fmac_f32_e32 v14, s13, v166
	v_fmac_f32_e32 v15, s13, v167
	v_fmac_f32_e32 v16, s14, v164
	v_fmac_f32_e32 v17, s14, v165
	v_fmac_f32_e32 v18, s14, v166
	v_fmac_f32_e32 v19, s14, v167
	v_fmac_f32_e32 v20, s15, v164
	v_fmac_f32_e32 v21, s15, v165
	v_fmac_f32_e32 v22, s15, v166
	v_fmac_f32_e32 v23, s15, v167
	v_fmac_f32_e32 v24, s16, v164
	v_fmac_f32_e32 v25, s16, v165
	v_fmac_f32_e32 v26, s16, v166
	v_fmac_f32_e32 v27, s16, v167
	v_fmac_f32_e32 v28, s17, v164
	v_fmac_f32_e32 v29, s17, v165
	v_fmac_f32_e32 v30, s17, v166
	v_fmac_f32_e32 v31, s17, v167
	v_fmac_f32_e32 v32, s18, v164
	v_fmac_f32_e32 v33, s18, v165
	v_fmac_f32_e32 v34, s18, v166
	v_fmac_f32_e32 v35, s18, v167
	v_readlane_b32 s10, v36, 54
	v_readlane_b32 s11, v37, 54
	v_readlane_b32 s12, v38, 54
; __device__ __forceinline__ void gemv_item(const float* c, const float* c_ctx, const float* ada_w, const float* ada_b, float* mod, int it, int lane) {
;     ...
;     for (int kk = 0; kk < 64; ++kk) { const f32x4 w = *(const f32x4*)(W + (size_t)kk * 6144);
; #pragma unroll
;         for (int r = 0; r < 9; ++r) { const float sk = __uint_as_float(__builtin_amdgcn_readlane(__float_as_uint(s[r]), kk)); acc[r] += w * sk; } }
	v_readlane_b32 s13, v39, 54
	v_readlane_b32 s14, v40, 54
	v_readlane_b32 s15, v41, 54
	v_readlane_b32 s16, v42, 54
	v_readlane_b32 s17, v43, 54
	v_readlane_b32 s18, v44, 54
	v_fmac_f32_e32 v0, s10, v168
	v_fmac_f32_e32 v1, s10, v169
	v_fmac_f32_e32 v2, s10, v170
	v_fmac_f32_e32 v3, s10, v171
	v_fmac_f32_e32 v4, s11, v168
	v_fmac_f32_e32 v5, s11, v169
	v_fmac_f32_e32 v6, s11, v170
	v_fmac_f32_e32 v7, s11, v171
	v_fmac_f32_e32 v8, s12, v168
	v_fmac_f32_e32 v9, s12, v169
	v_fmac_f32_e32 v10, s12, v170
	v_fmac_f32_e32 v11, s12, v171
	v_fmac_f32_e32 v12, s13, v168
	v_fmac_f32_e32 v13, s13, v169
	v_fmac_f32_e32 v14, s13, v170
	v_fmac_f32_e32 v15, s13, v171
	v_fmac_f32_e32 v16, s14, v168
	v_fmac_f32_e32 v17, s14, v169
	v_fmac_f32_e32 v18, s14, v170
	v_fmac_f32_e32 v19, s14, v171
	v_fmac_f32_e32 v20, s15, v168
	v_fmac_f32_e32 v21, s15, v169
	v_fmac_f32_e32 v22, s15, v170
	v_fmac_f32_e32 v23, s15, v171
	v_fmac_f32_e32 v24, s16, v168
	v_fmac_f32_e32 v25, s16, v169
	v_fmac_f32_e32 v26, s16, v170
	v_fmac_f32_e32 v27, s16, v171
	v_fmac_f32_e32 v28, s17, v168
	v_fmac_f32_e32 v29, s17, v169
	v_fmac_f32_e32 v30, s17, v170
	v_fmac_f32_e32 v31, s17, v171
	v_fmac_f32_e32 v32, s18, v168
	v_fmac_f32_e32 v33, s18, v169
	v_fmac_f32_e32 v34, s18, v170
	v_fmac_f32_e32 v35, s18, v171
	v_readlane_b32 s10, v36, 55
	v_readlane_b32 s11, v37, 55
	v_readlane_b32 s12, v38, 55
	v_readlane_b32 s13, v39, 55
	v_readlane_b32 s14, v40, 55
	v_readlane_b32 s15, v41, 55
	v_readlane_b32 s16, v42, 55
	v_readlane_b32 s17, v43, 55
	v_readlane_b32 s18, v44, 55
	v_fmac_f32_e32 v0, s10, v172
	v_fmac_f32_e32 v1, s10, v173
	v_fmac_f32_e32 v2, s10, v174
	v_fmac_f32_e32 v3, s10, v175
	v_fmac_f32_e32 v4, s11, v172
	v_fmac_f32_e32 v5, s11, v173
	v_fmac_f32_e32 v6, s11, v174
	v_fmac_f32_e32 v7, s11, v175
	v_fmac_f32_e32 v8, s12, v172
	v_fmac_f32_e32 v9, s12, v173
	v_fmac_f32_e32 v10, s12, v174
	v_fmac_f32_e32 v11, s12, v175
	v_fmac_f32_e32 v12, s13, v172
	v_fmac_f32_e32 v13, s13, v173
	v_fmac_f32_e32 v14, s13, v174
	v_fmac_f32_e32 v15, s13, v175
	v_fmac_f32_e32 v16, s14, v172
	v_fmac_f32_e32 v17, s14, v173
	v_fmac_f32_e32 v18, s14, v174
	v_fmac_f32_e32 v19, s14, v175
	v_fmac_f32_e32 v20, s15, v172
	v_fmac_f32_e32 v21, s15, v173
	v_fmac_f32_e32 v22, s15, v174
	v_fmac_f32_e32 v23, s15, v175
	v_fmac_f32_e32 v24, s16, v172
	v_fmac_f32_e32 v25, s16, v173
	v_fmac_f32_e32 v26, s16, v174
	v_fmac_f32_e32 v27, s16, v175
	v_fmac_f32_e32 v28, s17, v172
	v_fmac_f32_e32 v29, s17, v173
	v_fmac_f32_e32 v30, s17, v174
	v_fmac_f32_e32 v31, s17, v175
	v_fmac_f32_e32 v32, s18, v172
	v_fmac_f32_e32 v33, s18, v173
	v_fmac_f32_e32 v34, s18, v174
	v_fmac_f32_e32 v35, s18, v175
	v_readlane_b32 s10, v36, 56
	v_readlane_b32 s11, v37, 56
	v_readlane_b32 s12, v38, 56
	v_readlane_b32 s13, v39, 56
	v_readlane_b32 s14, v40, 56
	v_readlane_b32 s15, v41, 56
	v_readlane_b32 s16, v42, 56
	v_readlane_b32 s17, v43, 56
	v_readlane_b32 s18, v44, 56
	v_fmac_f32_e32 v0, s10, v176
	v_fmac_f32_e32 v1, s10, v177
	v_fmac_f32_e32 v2, s10, v178
	v_fmac_f32_e32 v3, s10, v179
	v_fmac_f32_e32 v4, s11, v176
	v_fmac_f32_e32 v5, s11, v177
	v_fmac_f32_e32 v6, s11, v178
	v_fmac_f32_e32 v7, s11, v179
	v_fmac_f32_e32 v8, s12, v176
	v_fmac_f32_e32 v9, s12, v177
	v_fmac_f32_e32 v10, s12, v178
	v_fmac_f32_e32 v11, s12, v179
	v_fmac_f32_e32 v12, s13, v176
	v_fmac_f32_e32 v13, s13, v177
	v_fmac_f32_e32 v14, s13, v178
	v_fmac_f32_e32 v15, s13, v179
	v_fmac_f32_e32 v16, s14, v176
	v_fmac_f32_e32 v17, s14, v177
	v_fmac_f32_e32 v18, s14, v178
	v_fmac_f32_e32 v19, s14, v179
	v_fmac_f32_e32 v20, s15, v176
	v_fmac_f32_e32 v21, s15, v177
	v_fmac_f32_e32 v22, s15, v178
	v_fmac_f32_e32 v23, s15, v179
	v_fmac_f32_e32 v24, s16, v176
	v_fmac_f32_e32 v25, s16, v177
	v_fmac_f32_e32 v26, s16, v178
	v_fmac_f32_e32 v27, s16, v179
	v_fmac_f32_e32 v28, s17, v176
	v_fmac_f32_e32 v29, s17, v177
	v_fmac_f32_e32 v30, s17, v178
	v_fmac_f32_e32 v31, s17, v179
	v_fmac_f32_e32 v32, s18, v176
	v_fmac_f32_e32 v33, s18, v177
	v_fmac_f32_e32 v34, s18, v178
	v_fmac_f32_e32 v35, s18, v179
	v_readlane_b32 s10, v36, 57
	v_readlane_b32 s11, v37, 57
	v_readlane_b32 s12, v38, 57
	v_readlane_b32 s13, v39, 57
	v_readlane_b32 s14, v40, 57
	v_readlane_b32 s15, v41, 57
	v_readlane_b32 s16, v42, 57
	v_readlane_b32 s17, v43, 57
	v_readlane_b32 s18, v44, 57
	v_fmac_f32_e32 v0, s10, v180
	v_fmac_f32_e32 v1, s10, v181
	v_fmac_f32_e32 v2, s10, v182
	v_fmac_f32_e32 v3, s10, v183
	v_fmac_f32_e32 v4, s11, v180
	v_fmac_f32_e32 v5, s11, v181
	v_fmac_f32_e32 v6, s11, v182
	v_fmac_f32_e32 v7, s11, v183
	v_fmac_f32_e32 v8, s12, v180
	v_fmac_f32_e32 v9, s12, v181
	v_fmac_f32_e32 v10, s12, v182
	v_fmac_f32_e32 v11, s12, v183
	v_fmac_f32_e32 v12, s13, v180
	v_fmac_f32_e32 v13, s13, v181
	v_fmac_f32_e32 v14, s13, v182
	v_fmac_f32_e32 v15, s13, v183
	v_fmac_f32_e32 v16, s14, v180
	v_fmac_f32_e32 v17, s14, v181
	v_fmac_f32_e32 v18, s14, v182
	v_fmac_f32_e32 v19, s14, v183
	v_fmac_f32_e32 v20, s15, v180
	v_fmac_f32_e32 v21, s15, v181
	v_fmac_f32_e32 v22, s15, v182
	v_fmac_f32_e32 v23, s15, v183
	v_fmac_f32_e32 v24, s16, v180
	v_fmac_f32_e32 v25, s16, v181
	v_fmac_f32_e32 v26, s16, v182
	v_fmac_f32_e32 v27, s16, v183
	v_fmac_f32_e32 v28, s17, v180
	v_fmac_f32_e32 v29, s17, v181
	v_fmac_f32_e32 v30, s17, v182
	v_fmac_f32_e32 v31, s17, v183
	v_fmac_f32_e32 v32, s18, v180
	v_fmac_f32_e32 v33, s18, v181
	v_fmac_f32_e32 v34, s18, v182
	v_fmac_f32_e32 v35, s18, v183
	v_readlane_b32 s10, v36, 58
	v_readlane_b32 s11, v37, 58
	v_readlane_b32 s12, v38, 58
	v_readlane_b32 s13, v39, 58
	v_readlane_b32 s14, v40, 58
	v_readlane_b32 s15, v41, 58
	v_readlane_b32 s16, v42, 58
	v_readlane_b32 s17, v43, 58
	v_readlane_b32 s18, v44, 58
; __device__ __forceinline__ void gemv_item(const float* c, const float* c_ctx, const float* ada_w, const float* ada_b, float* mod, int it, int lane) {
;     ...
;     for (int kk = 0; kk < 64; ++kk) { const f32x4 w = *(const f32x4*)(W + (size_t)kk * 6144);
; #pragma unroll
;         for (int r = 0; r < 9; ++r) { const float sk = __uint_as_float(__builtin_amdgcn_readlane(__float_as_uint(s[r]), kk)); acc[r] += w * sk; } }
	v_fmac_f32_e32 v0, s10, v184
	v_fmac_f32_e32 v1, s10, v185
	v_fmac_f32_e32 v2, s10, v186
	v_fmac_f32_e32 v3, s10, v187
	v_fmac_f32_e32 v4, s11, v184
	v_fmac_f32_e32 v5, s11, v185
	v_fmac_f32_e32 v6, s11, v186
	v_fmac_f32_e32 v7, s11, v187
	v_fmac_f32_e32 v8, s12, v184
	v_fmac_f32_e32 v9, s12, v185
	v_fmac_f32_e32 v10, s12, v186
	v_fmac_f32_e32 v11, s12, v187
	v_fmac_f32_e32 v12, s13, v184
	v_fmac_f32_e32 v13, s13, v185
	v_fmac_f32_e32 v14, s13, v186
	v_fmac_f32_e32 v15, s13, v187
	v_fmac_f32_e32 v16, s14, v184
	v_fmac_f32_e32 v17, s14, v185
	v_fmac_f32_e32 v18, s14, v186
	v_fmac_f32_e32 v19, s14, v187
	v_fmac_f32_e32 v20, s15, v184
	v_fmac_f32_e32 v21, s15, v185
	v_fmac_f32_e32 v22, s15, v186
	v_fmac_f32_e32 v23, s15, v187
	v_fmac_f32_e32 v24, s16, v184
	v_fmac_f32_e32 v25, s16, v185
	v_fmac_f32_e32 v26, s16, v186
	v_fmac_f32_e32 v27, s16, v187
	v_fmac_f32_e32 v28, s17, v184
	v_fmac_f32_e32 v29, s17, v185
	v_fmac_f32_e32 v30, s17, v186
	v_fmac_f32_e32 v31, s17, v187
	v_fmac_f32_e32 v32, s18, v184
	v_fmac_f32_e32 v33, s18, v185
	v_fmac_f32_e32 v34, s18, v186
	v_fmac_f32_e32 v35, s18, v187
	v_readlane_b32 s10, v36, 59
	v_readlane_b32 s11, v37, 59
	v_readlane_b32 s12, v38, 59
	v_readlane_b32 s13, v39, 59
	v_readlane_b32 s14, v40, 59
	v_readlane_b32 s15, v41, 59
	v_readlane_b32 s16, v42, 59
	v_readlane_b32 s17, v43, 59
	v_readlane_b32 s18, v44, 59
	v_fmac_f32_e32 v0, s10, v188
	v_fmac_f32_e32 v1, s10, v189
	v_fmac_f32_e32 v2, s10, v190
	v_fmac_f32_e32 v3, s10, v191
	v_fmac_f32_e32 v4, s11, v188
	v_fmac_f32_e32 v5, s11, v189
	v_fmac_f32_e32 v6, s11, v190
	v_fmac_f32_e32 v7, s11, v191
	v_fmac_f32_e32 v8, s12, v188
	v_fmac_f32_e32 v9, s12, v189
	v_fmac_f32_e32 v10, s12, v190
	v_fmac_f32_e32 v11, s12, v191
	v_fmac_f32_e32 v12, s13, v188
	v_fmac_f32_e32 v13, s13, v189
	v_fmac_f32_e32 v14, s13, v190
	v_fmac_f32_e32 v15, s13, v191
	v_fmac_f32_e32 v16, s14, v188
	v_fmac_f32_e32 v17, s14, v189
	v_fmac_f32_e32 v18, s14, v190
	v_fmac_f32_e32 v19, s14, v191
	v_fmac_f32_e32 v20, s15, v188
	v_fmac_f32_e32 v21, s15, v189
	v_fmac_f32_e32 v22, s15, v190
	v_fmac_f32_e32 v23, s15, v191
	v_fmac_f32_e32 v24, s16, v188
	v_fmac_f32_e32 v25, s16, v189
	v_fmac_f32_e32 v26, s16, v190
	v_fmac_f32_e32 v27, s16, v191
	v_fmac_f32_e32 v28, s17, v188
	v_fmac_f32_e32 v29, s17, v189
	v_fmac_f32_e32 v30, s17, v190
	v_fmac_f32_e32 v31, s17, v191
	v_fmac_f32_e32 v32, s18, v188
	v_fmac_f32_e32 v33, s18, v189
	v_fmac_f32_e32 v34, s18, v190
	v_fmac_f32_e32 v35, s18, v191
	v_readlane_b32 s10, v36, 60
	v_readlane_b32 s11, v37, 60
	v_readlane_b32 s12, v38, 60
	v_readlane_b32 s13, v39, 60
	v_readlane_b32 s14, v40, 60
	v_readlane_b32 s15, v41, 60
	v_readlane_b32 s16, v42, 60
	v_readlane_b32 s17, v43, 60
	v_readlane_b32 s18, v44, 60
	v_fmac_f32_e32 v0, s10, v192
	v_fmac_f32_e32 v1, s10, v193
	v_fmac_f32_e32 v2, s10, v194
	v_fmac_f32_e32 v3, s10, v195
	v_fmac_f32_e32 v4, s11, v192
	v_fmac_f32_e32 v5, s11, v193
	v_fmac_f32_e32 v6, s11, v194
	v_fmac_f32_e32 v7, s11, v195
	v_fmac_f32_e32 v8, s12, v192
	v_fmac_f32_e32 v9, s12, v193
	v_fmac_f32_e32 v10, s12, v194
	v_fmac_f32_e32 v11, s12, v195
	v_fmac_f32_e32 v12, s13, v192
	v_fmac_f32_e32 v13, s13, v193
	v_fmac_f32_e32 v14, s13, v194
	v_fmac_f32_e32 v15, s13, v195
	v_fmac_f32_e32 v16, s14, v192
	v_fmac_f32_e32 v17, s14, v193
	v_fmac_f32_e32 v18, s14, v194
	v_fmac_f32_e32 v19, s14, v195
	v_fmac_f32_e32 v20, s15, v192
	v_fmac_f32_e32 v21, s15, v193
	v_fmac_f32_e32 v22, s15, v194
	v_fmac_f32_e32 v23, s15, v195
	v_fmac_f32_e32 v24, s16, v192
	v_fmac_f32_e32 v25, s16, v193
	v_fmac_f32_e32 v26, s16, v194
	v_fmac_f32_e32 v27, s16, v195
	v_fmac_f32_e32 v28, s17, v192
	v_fmac_f32_e32 v29, s17, v193
	v_fmac_f32_e32 v30, s17, v194
	v_fmac_f32_e32 v31, s17, v195
	v_fmac_f32_e32 v32, s18, v192
	v_fmac_f32_e32 v33, s18, v193
	v_fmac_f32_e32 v34, s18, v194
	v_fmac_f32_e32 v35, s18, v195
	v_readlane_b32 s10, v36, 61
	v_readlane_b32 s11, v37, 61
	v_readlane_b32 s12, v38, 61
	v_readlane_b32 s13, v39, 61
	v_readlane_b32 s14, v40, 61
	v_readlane_b32 s15, v41, 61
	v_readlane_b32 s16, v42, 61
	v_readlane_b32 s17, v43, 61
	v_readlane_b32 s18, v44, 61
	v_fmac_f32_e32 v0, s10, v200
	v_fmac_f32_e32 v1, s10, v201
	v_fmac_f32_e32 v2, s10, v202
	v_fmac_f32_e32 v3, s10, v203
	v_fmac_f32_e32 v4, s11, v200
	v_fmac_f32_e32 v5, s11, v201
	v_fmac_f32_e32 v6, s11, v202
	v_fmac_f32_e32 v7, s11, v203
	v_fmac_f32_e32 v8, s12, v200
	v_fmac_f32_e32 v9, s12, v201
	v_fmac_f32_e32 v10, s12, v202
	v_fmac_f32_e32 v11, s12, v203
	v_fmac_f32_e32 v12, s13, v200
	v_fmac_f32_e32 v13, s13, v201
	v_fmac_f32_e32 v14, s13, v202
	v_fmac_f32_e32 v15, s13, v203
	v_fmac_f32_e32 v16, s14, v200
	v_fmac_f32_e32 v17, s14, v201
	v_fmac_f32_e32 v18, s14, v202
	v_fmac_f32_e32 v19, s14, v203
	v_fmac_f32_e32 v20, s15, v200
	v_fmac_f32_e32 v21, s15, v201
	v_fmac_f32_e32 v22, s15, v202
	v_fmac_f32_e32 v23, s15, v203
	v_fmac_f32_e32 v24, s16, v200
	v_fmac_f32_e32 v25, s16, v201
	v_fmac_f32_e32 v26, s16, v202
	v_fmac_f32_e32 v27, s16, v203
	v_fmac_f32_e32 v28, s17, v200
	v_fmac_f32_e32 v29, s17, v201
	v_fmac_f32_e32 v30, s17, v202
	v_fmac_f32_e32 v31, s17, v203
	v_fmac_f32_e32 v32, s18, v200
	v_fmac_f32_e32 v33, s18, v201
	v_fmac_f32_e32 v34, s18, v202
	v_fmac_f32_e32 v35, s18, v203
	v_readlane_b32 s10, v36, 62
	v_readlane_b32 s11, v37, 62
	v_readlane_b32 s12, v38, 62
	v_readlane_b32 s13, v39, 62
	v_readlane_b32 s14, v40, 62
	v_readlane_b32 s15, v41, 62
	v_readlane_b32 s16, v42, 62
	v_readlane_b32 s17, v43, 62
	v_readlane_b32 s18, v44, 62
	v_fmac_f32_e32 v0, s10, v204
	v_fmac_f32_e32 v1, s10, v205
	v_fmac_f32_e32 v2, s10, v206
	v_fmac_f32_e32 v3, s10, v207
	v_fmac_f32_e32 v4, s11, v204
	v_fmac_f32_e32 v5, s11, v205
; __device__ __forceinline__ void gemv_item(const float* c, const float* c_ctx, const float* ada_w, const float* ada_b, float* mod, int it, int lane) {
;     ...
;     const int col = cgp * 256 + lane * 4;
;     f32x4 bv = (f32x4){0.f, 0.f, 0.f, 0.f};
;     if (kc == 0) bv = *(const f32x4*)(ada_b + l * 6144 + col);
; #pragma unroll
;     for (int r = 0; r < 9; ++r) { float* m = mod + (size_t)(l * 9 + r) * 6144 + col;
	v_fmac_f32_e32 v6, s11, v206
	v_fmac_f32_e32 v7, s11, v207
	v_fmac_f32_e32 v8, s12, v204
	v_fmac_f32_e32 v9, s12, v205
	v_fmac_f32_e32 v10, s12, v206
	v_fmac_f32_e32 v11, s12, v207
	v_fmac_f32_e32 v12, s13, v204
	v_fmac_f32_e32 v13, s13, v205
	v_fmac_f32_e32 v14, s13, v206
	v_fmac_f32_e32 v15, s13, v207
	v_fmac_f32_e32 v16, s14, v204
	v_fmac_f32_e32 v17, s14, v205
	v_fmac_f32_e32 v18, s14, v206
	v_fmac_f32_e32 v19, s14, v207
	v_fmac_f32_e32 v20, s15, v204
	v_fmac_f32_e32 v21, s15, v205
	v_fmac_f32_e32 v22, s15, v206
	v_fmac_f32_e32 v23, s15, v207
	v_fmac_f32_e32 v24, s16, v204
	v_fmac_f32_e32 v25, s16, v205
	v_fmac_f32_e32 v26, s16, v206
	v_fmac_f32_e32 v27, s16, v207
	v_fmac_f32_e32 v28, s17, v204
	v_fmac_f32_e32 v29, s17, v205
	v_fmac_f32_e32 v30, s17, v206
	v_fmac_f32_e32 v31, s17, v207
	v_fmac_f32_e32 v32, s18, v204
	v_fmac_f32_e32 v33, s18, v205
	v_fmac_f32_e32 v34, s18, v206
	v_fmac_f32_e32 v35, s18, v207
	v_readlane_b32 s10, v36, 63
	v_readlane_b32 s11, v37, 63
	v_readlane_b32 s12, v38, 63
	v_readlane_b32 s13, v39, 63
	v_readlane_b32 s14, v40, 63
	v_readlane_b32 s15, v41, 63
	v_readlane_b32 s16, v42, 63
	v_readlane_b32 s17, v43, 63
	v_readlane_b32 s18, v44, 63
	v_fmac_f32_e32 v0, s10, v208
	v_fmac_f32_e32 v1, s10, v209
	v_fmac_f32_e32 v2, s10, v210
	v_fmac_f32_e32 v3, s10, v211
	v_fmac_f32_e32 v4, s11, v208
	v_fmac_f32_e32 v5, s11, v209
	v_fmac_f32_e32 v6, s11, v210
	v_fmac_f32_e32 v7, s11, v211
	v_fmac_f32_e32 v8, s12, v208
	v_fmac_f32_e32 v9, s12, v209
	v_fmac_f32_e32 v10, s12, v210
	v_fmac_f32_e32 v11, s12, v211
	v_fmac_f32_e32 v12, s13, v208
	v_fmac_f32_e32 v13, s13, v209
	v_fmac_f32_e32 v14, s13, v210
	v_fmac_f32_e32 v15, s13, v211
	v_fmac_f32_e32 v16, s14, v208
	v_fmac_f32_e32 v17, s14, v209
	v_fmac_f32_e32 v18, s14, v210
	v_fmac_f32_e32 v19, s14, v211
	v_fmac_f32_e32 v20, s15, v208
	v_fmac_f32_e32 v21, s15, v209
	v_fmac_f32_e32 v22, s15, v210
	v_fmac_f32_e32 v23, s15, v211
	v_fmac_f32_e32 v24, s16, v208
	v_fmac_f32_e32 v25, s16, v209
	v_fmac_f32_e32 v26, s16, v210
	v_fmac_f32_e32 v27, s16, v211
	v_fmac_f32_e32 v28, s17, v208
	v_fmac_f32_e32 v29, s17, v209
	v_fmac_f32_e32 v30, s17, v210
	v_fmac_f32_e32 v31, s17, v211
	v_fmac_f32_e32 v32, s18, v208
	v_fmac_f32_e32 v33, s18, v209
	v_fmac_f32_e32 v34, s18, v210
	v_fmac_f32_e32 v35, s18, v211
	v_add_f32_e32 v0, v0, v52
	v_add_f32_e32 v1, v1, v53
	v_add_f32_e32 v2, v2, v54
	v_add_f32_e32 v3, v3, v55
	v_add_f32_e32 v4, v4, v52
	v_add_f32_e32 v5, v5, v53
	v_add_f32_e32 v6, v6, v54
	v_add_f32_e32 v7, v7, v55
	v_add_f32_e32 v8, v8, v52
	v_add_f32_e32 v9, v9, v53
	v_add_f32_e32 v10, v10, v54
	v_add_f32_e32 v11, v11, v55
	v_add_f32_e32 v12, v12, v52
	v_add_f32_e32 v13, v13, v53
	v_add_f32_e32 v14, v14, v54
	v_add_f32_e32 v15, v15, v55
	v_add_f32_e32 v16, v16, v52
	v_add_f32_e32 v17, v17, v53
	v_add_f32_e32 v18, v18, v54
	v_add_f32_e32 v19, v19, v55
	v_add_f32_e32 v20, v20, v52
	v_add_f32_e32 v21, v21, v53
	v_add_f32_e32 v22, v22, v54
	v_add_f32_e32 v23, v23, v55
	v_add_f32_e32 v24, v24, v52
	v_add_f32_e32 v25, v25, v53
	v_add_f32_e32 v26, v26, v54
	v_add_f32_e32 v27, v27, v55
	v_add_f32_e32 v28, v28, v52
	v_add_f32_e32 v29, v29, v53
	v_add_f32_e32 v30, v30, v54
	v_add_f32_e32 v31, v31, v55
	v_add_f32_e32 v32, v32, v52
	v_add_f32_e32 v33, v33, v53
	v_add_f32_e32 v34, v34, v54
	v_add_f32_e32 v35, v35, v55
	v_add_u32_e32 v47, s31, v46
	v_add_u32_e32 v48, s31, v45
	ds_write_b128 v47, v[0:3] offset:0
	ds_write_b128 v47, v[4:7] offset:1024
	ds_write_b128 v47, v[8:11] offset:2048
	ds_write_b128 v47, v[12:15] offset:3072
	ds_write_b128 v47, v[16:19] offset:4096
	ds_write_b128 v47, v[20:23] offset:5120
	ds_write_b128 v47, v[24:27] offset:6144
	ds_write_b128 v47, v[28:31] offset:7168
	ds_write_b128 v47, v[32:35] offset:8192
	s_waitcnt lgkmcnt(0)
; __device__ __forceinline__ void gemv_item(const float* c, const float* c_ctx, const float* ada_w, const float* ada_b, float* mod, int it, int lane) {
;     ...
;     for (int r = 0; r < 9; ++r) { float* m = mod + (size_t)(l * 9 + r) * 6144 + col;
; #pragma unroll
;         for (int j = 0; j < 4; ++j) atomicAdd(m + j, acc[r][j] + bv[j]); }
	ds_read_b32 v80, v48 offset:0
	ds_read_b32 v81, v48 offset:256
	ds_read_b32 v82, v48 offset:512
	ds_read_b32 v83, v48 offset:768
	ds_read_b32 v84, v48 offset:1024
	ds_read_b32 v85, v48 offset:1280
	ds_read_b32 v86, v48 offset:1536
	ds_read_b32 v87, v48 offset:1792
	ds_read_b32 v88, v48 offset:2048
	ds_read_b32 v89, v48 offset:2304
	ds_read_b32 v90, v48 offset:2560
	ds_read_b32 v91, v48 offset:2816
	ds_read_b32 v92, v48 offset:3072
	ds_read_b32 v93, v48 offset:3328
	ds_read_b32 v94, v48 offset:3584
	ds_read_b32 v95, v48 offset:3840
	ds_read_b32 v96, v48 offset:4096
	ds_read_b32 v97, v48 offset:4352
	ds_read_b32 v98, v48 offset:4608
	ds_read_b32 v99, v48 offset:4864
	ds_read_b32 v100, v48 offset:5120
	ds_read_b32 v101, v48 offset:5376
	ds_read_b32 v102, v48 offset:5632
	ds_read_b32 v103, v48 offset:5888
	ds_read_b32 v104, v48 offset:6144
	ds_read_b32 v105, v48 offset:6400
	ds_read_b32 v106, v48 offset:6656
	ds_read_b32 v107, v48 offset:6912
	ds_read_b32 v108, v48 offset:7168
	ds_read_b32 v109, v48 offset:7424
	ds_read_b32 v110, v48 offset:7680
	ds_read_b32 v111, v48 offset:7936
	ds_read_b32 v112, v48 offset:8192
	ds_read_b32 v113, v48 offset:8448
	ds_read_b32 v114, v48 offset:8704
	ds_read_b32 v115, v48 offset:8960
	s_lshl_b32 s5, s4, 10
	s_add_u32 s20, s84, s5
	s_addc_u32 s21, s85, 0
	s_waitcnt lgkmcnt(0)
	global_atomic_add_f32 v45, v80, s[20:21] offset:0
	global_atomic_add_f32 v45, v81, s[20:21] offset:256
	global_atomic_add_f32 v45, v82, s[20:21] offset:512
	global_atomic_add_f32 v45, v83, s[20:21] offset:768
	s_add_u32 s20, s20, 0x6000
	s_addc_u32 s21, s21, 0
	global_atomic_add_f32 v45, v84, s[20:21] offset:0
	global_atomic_add_f32 v45, v85, s[20:21] offset:256
	global_atomic_add_f32 v45, v86, s[20:21] offset:512
	global_atomic_add_f32 v45, v87, s[20:21] offset:768
	s_add_u32 s20, s20, 0x6000
	s_addc_u32 s21, s21, 0
	global_atomic_add_f32 v45, v88, s[20:21] offset:0
	global_atomic_add_f32 v45, v89, s[20:21] offset:256
	global_atomic_add_f32 v45, v90, s[20:21] offset:512
	global_atomic_add_f32 v45, v91, s[20:21] offset:768
	s_add_u32 s20, s20, 0x6000
	s_addc_u32 s21, s21, 0
	global_atomic_add_f32 v45, v92, s[20:21] offset:0
	global_atomic_add_f32 v45, v93, s[20:21] offset:256
	global_atomic_add_f32 v45, v94, s[20:21] offset:512
	global_atomic_add_f32 v45, v95, s[20:21] offset:768
	s_add_u32 s20, s20, 0x6000
	s_addc_u32 s21, s21, 0
	global_atomic_add_f32 v45, v96, s[20:21] offset:0
	global_atomic_add_f32 v45, v97, s[20:21] offset:256
	global_atomic_add_f32 v45, v98, s[20:21] offset:512
	global_atomic_add_f32 v45, v99, s[20:21] offset:768
	s_add_u32 s20, s20, 0x6000
	s_addc_u32 s21, s21, 0
	global_atomic_add_f32 v45, v100, s[20:21] offset:0
	global_atomic_add_f32 v45, v101, s[20:21] offset:256
	global_atomic_add_f32 v45, v102, s[20:21] offset:512
	global_atomic_add_f32 v45, v103, s[20:21] offset:768
	s_add_u32 s20, s20, 0x6000
	s_addc_u32 s21, s21, 0
	global_atomic_add_f32 v45, v104, s[20:21] offset:0
	global_atomic_add_f32 v45, v105, s[20:21] offset:256
	global_atomic_add_f32 v45, v106, s[20:21] offset:512
	global_atomic_add_f32 v45, v107, s[20:21] offset:768
	s_add_u32 s20, s20, 0x6000
	s_addc_u32 s21, s21, 0
	global_atomic_add_f32 v45, v108, s[20:21] offset:0
	global_atomic_add_f32 v45, v109, s[20:21] offset:256
	global_atomic_add_f32 v45, v110, s[20:21] offset:512
	global_atomic_add_f32 v45, v111, s[20:21] offset:768
	s_add_u32 s20, s20, 0x6000
	s_addc_u32 s21, s21, 0
	global_atomic_add_f32 v45, v112, s[20:21] offset:0
	global_atomic_add_f32 v45, v113, s[20:21] offset:256
	global_atomic_add_f32 v45, v114, s[20:21] offset:512
	global_atomic_add_f32 v45, v115, s[20:21] offset:768
	s_mov_b32 s0, 2

; #define LAS __attribute__((address_space(3)))
; __device__ __forceinline__ void tr_load(const TrDesc& d, int lane, f32x4 (&wv)[8]) {
;     const int nblk = d.N / 32, kb = d.item / nblk, nb = d.item % nblk, k0 = 64 * kb, n0 = 32 * nb;
; #pragma unroll
;     for (int i = 0; i < 8; ++i) wv[i] = *(const f32x4*)(d.W + (size_t)(k0 + 8 * i + (lane >> 3)) * d.N + n0 + (lane & 7) * 4);
; }
; __device__ __forceinline__ void tr_finish(const TrDesc& d, int lane, const f32x4 (&wv)[8], LAS float* scr) {
;     const int nblk = d.N / 32, kb = d.item / nblk, nb = d.item % nblk, k0 = 64 * kb, n0 = 32 * nb;
;     const int d0 = d.reorder ? (nb < 32 ? n0 : (nb < 34 ? n0 + 2048 : n0 - 64)) : n0;
; #pragma unroll
;     for (int i = 0; i < 8; ++i) { const int kk = 8 * i + (lane >> 3); f32x4 v = wv[i]; if (d.gk) v = v * d.gk[k0 + kk];
;         LAS float* p = scr + kk * 33 + (lane & 7) * 4; p[0] = v[0]; p[1] = v[1]; p[2] = v[2]; p[3] = v[3]; }
;     asm volatile("s_waitcnt lgkmcnt(0)" ::: "memory");
;     const int c = lane & 7;
; #pragma unroll
;     for (int j = 0; j < 4; ++j) { const int n = (lane >> 3) + 8 * j; const LAS float* sp = scr + (8 * c) * 33 + n;
; __device__ __forceinline__ void tr_run(const Args& a, int list, int first, int stride, int lane, LAS float* scr, int n_end = -1) {
;     const int n = n_end >= 0 ? n_end : (list == 0 ? I_LIST0 : (list == 1 ? I_LIST1 : I_LIST2));
;     int it = first; if (it >= n) return;
;     TrDesc d = tr_desc(a, list, it); f32x4 wv[8]; tr_load(d, lane, wv);
.LBB0_111:
	s_lshr_b32 s6, s18, 5
	v_cvt_f32_ubyte0_e32 v0, s6
	v_rcp_iflag_f32_e32 v0, v0
	s_sub_i32 s9, 0, s6
	s_abs_i32 s8, s14
	s_ashr_i32 s7, s14, 31
	v_mul_f32_e32 v0, 0x4f7ffffe, v0
	v_cvt_u32_f32_e32 v0, v0
	v_lshrrev_b32_e32 v68, 3, v77
	v_mov_b32_e32 v65, 0
	v_lshlrev_b32_e32 v33, 2, v68
	v_readfirstlane_b32 s10, v0
	s_mul_i32 s9, s9, s10
	s_mul_hi_u32 s9, s10, s9
	s_add_i32 s10, s10, s9
	s_mul_hi_u32 s9, s8, s10
	s_mul_i32 s10, s9, s6
	s_sub_i32 s8, s8, s10
	s_add_i32 s11, s9, 1
	s_sub_i32 s10, s8, s6
	s_cmp_ge_u32 s8, s6
	s_cselect_b32 s9, s11, s9
	s_cselect_b32 s8, s10, s8
	s_add_i32 s10, s9, 1
	s_cmp_ge_u32 s8, s6
	s_cselect_b32 s8, s10, s9
	s_xor_b32 s8, s8, s7
	s_sub_i32 s7, s8, s7
	s_mul_i32 s6, s7, s6
	s_sub_i32 s6, s14, s6
	v_lshl_or_b32 v6, s7, 6, v68
	s_lshl_b32 s6, s6, 5
	v_lshlrev_b32_e32 v0, 2, v77
	v_or_b32_e32 v2, 8, v6
	s_ashr_i32 s7, s6, 31
	v_and_b32_e32 v28, 28, v0
	v_mad_i64_i32 v[0:1], s[8:9], v6, s18, 0
	v_mad_i64_i32 v[2:3], s[8:9], v2, s18, 0
	v_lshl_add_u64 v[0:1], v[0:1], 2, s[4:5]
	s_lshl_b64 s[6:7], s[6:7], 2
	v_lshl_add_u64 v[2:3], v[2:3], 2, s[4:5]
	v_lshl_add_u64 v[0:1], v[0:1], 0, s[6:7]
	v_lshlrev_b32_e32 v64, 2, v28
	v_lshl_add_u64 v[2:3], v[2:3], 0, s[6:7]
	v_lshl_add_u64 v[0:1], v[0:1], 0, v[64:65]
	v_lshl_add_u64 v[2:3], v[2:3], 0, v[64:65]
	global_load_dwordx4 v[24:27], v[0:1], off nt
	global_load_dwordx4 v[20:23], v[2:3], off nt
	v_or_b32_e32 v0, 16, v6
	v_or_b32_e32 v2, 24, v6
	v_mad_i64_i32 v[0:1], s[8:9], v0, s18, 0
	v_mad_i64_i32 v[2:3], s[8:9], v2, s18, 0
	v_lshl_add_u64 v[0:1], v[0:1], 2, s[4:5]
	v_lshl_add_u64 v[2:3], v[2:3], 2, s[4:5]
	v_lshl_add_u64 v[0:1], v[0:1], 0, s[6:7]
	v_lshl_add_u64 v[2:3], v[2:3], 0, s[6:7]
	v_lshl_add_u64 v[0:1], v[0:1], 0, v[64:65]
	v_lshl_add_u64 v[2:3], v[2:3], 0, v[64:65]
	global_load_dwordx4 v[16:19], v[0:1], off nt
	global_load_dwordx4 v[8:11], v[2:3], off nt
	v_or_b32_e32 v0, 32, v6
	v_or_b32_e32 v2, 40, v6
	v_or_b32_e32 v4, 48, v6
	v_mad_i64_i32 v[0:1], s[8:9], v0, s18, 0
	v_mad_i64_i32 v[2:3], s[8:9], v2, s18, 0
	v_mad_i64_i32 v[4:5], s[8:9], v4, s18, 0
	v_or_b32_e32 v6, 56, v6
	v_lshl_add_u64 v[0:1], v[0:1], 2, s[4:5]
	v_lshl_add_u64 v[2:3], v[2:3], 2, s[4:5]
	v_lshl_add_u64 v[4:5], v[4:5], 2, s[4:5]
	v_mad_i64_i32 v[6:7], s[8:9], v6, s18, 0
	v_lshl_add_u64 v[0:1], v[0:1], 0, s[6:7]
	v_lshl_add_u64 v[2:3], v[2:3], 0, s[6:7]
	v_lshl_add_u64 v[4:5], v[4:5], 0, s[6:7]
	v_lshl_add_u64 v[6:7], v[6:7], 2, s[4:5]
	v_lshl_add_u64 v[0:1], v[0:1], 0, v[64:65]
	v_lshl_add_u64 v[2:3], v[2:3], 0, v[64:65]
	v_lshl_add_u64 v[4:5], v[4:5], 0, v[64:65]
	v_lshl_add_u64 v[6:7], v[6:7], 0, s[6:7]
	global_load_dwordx4 v[12:15], v[0:1], off nt
	s_nop 0
	global_load_dwordx4 v[0:3], v[2:3], off nt
	v_lshl_add_u64 v[30:31], v[6:7], 0, v[64:65]
	global_load_dwordx4 v[4:7], v[4:5], off nt
	s_nop 0
	global_load_dwordx4 v[60:63], v[30:31], off nt
	v_lshlrev_b32_e32 v30, 3, v77
	v_and_b32_e32 v30, 56, v30
	v_add_u32_e32 v29, s31, v64
	v_mul_u32_u24_e32 v31, 0x84, v68
	v_mul_u32_u24_e32 v32, 0x84, v30
	s_mov_b32 s5, 0
	v_or_b32_e32 v69, 8, v68
	v_or_b32_e32 v70, 16, v68
	v_or_b32_e32 v71, 24, v68
	v_add3_u32 v72, s31, v32, v33
	v_lshlrev_b32_e32 v64, 2, v28
	v_add_u32_e32 v73, v29, v31
	v_lshlrev_b32_e32 v66, 1, v30
	s_mov_b64 s[6:7], s[0:1]
	s_mov_b32 s15, s13
	s_mov_b32 s16, s18
	s_mov_b32 s4, s14
	s_branch .LBB0_113

; __device__ __forceinline__ void tr_load(const TrDesc& d, int lane, f32x4 (&wv)[8]) {
;     const int nblk = d.N / 32, kb = d.item / nblk, nb = d.item % nblk, k0 = 64 * kb, n0 = 32 * nb;
; #pragma unroll
;     for (int i = 0; i < 8; ++i) wv[i] = *(const f32x4*)(d.W + (size_t)(k0 + 8 * i + (lane >> 3)) * d.N + n0 + (lane & 7) * 4);
; }
; __device__ __forceinline__ void tr_run(const Args& a, int list, int first, int stride, int lane, LAS float* scr, int n_end = -1) {
;     ...
;         const int nit = it + stride; const bool more = nit < n;
;         TrDesc dn = d; f32x4 wn[8];
;         if (more) { dn = tr_desc(a, list, nit); tr_load(dn, lane, wn); }
.LBB0_121:
	s_lshr_b32 s19, s16, 5
	v_cvt_f32_ubyte0_e32 v28, s19
	v_rcp_iflag_f32_e32 v28, v28
	s_sub_i32 s22, 0, s19
	s_abs_i32 s21, s4
	s_ashr_i32 s20, s4, 31
	v_mul_f32_e32 v28, 0x4f7ffffe, v28
	v_cvt_u32_f32_e32 v28, v28
	s_nop 0
	v_readfirstlane_b32 s23, v28
	s_mul_i32 s22, s22, s23
	s_mul_hi_u32 s22, s23, s22
	s_add_i32 s23, s23, s22
	s_mul_hi_u32 s22, s21, s23
	s_mul_i32 s23, s22, s19
	s_sub_i32 s21, s21, s23
	s_add_i32 s24, s22, 1
	s_sub_i32 s23, s21, s19
	s_cmp_ge_u32 s21, s19
	s_cselect_b32 s22, s24, s22
	s_cselect_b32 s21, s23, s21
	s_add_i32 s23, s22, 1
	s_cmp_ge_u32 s21, s19
	s_cselect_b32 s21, s23, s22
	s_xor_b32 s21, s21, s20
	s_sub_i32 s20, s21, s20
	s_mul_i32 s19, s20, s19
	v_lshl_or_b32 v54, s20, 6, v68
	s_sub_i32 s19, s4, s19
	s_lshl_b32 s20, s19, 5
	v_mad_i64_i32 v[28:29], s[22:23], v54, s16, 0
	v_or_b32_e32 v30, 8, v54
	v_or_b32_e32 v36, 16, v54
	v_or_b32_e32 v38, 24, v54
	v_or_b32_e32 v44, 32, v54
	v_or_b32_e32 v46, 40, v54
	v_or_b32_e32 v52, 48, v54
	v_or_b32_e32 v54, 56, v54
	s_ashr_i32 s21, s20, 31
	v_mad_i64_i32 v[30:31], s[22:23], v30, s16, 0
	v_mad_i64_i32 v[36:37], s[22:23], v36, s16, 0
	v_mad_i64_i32 v[38:39], s[22:23], v38, s16, 0
	v_mad_i64_i32 v[44:45], s[22:23], v44, s16, 0
	v_mad_i64_i32 v[46:47], s[22:23], v46, s16, 0
	v_mad_i64_i32 v[52:53], s[22:23], v52, s16, 0
	v_mad_i64_i32 v[54:55], s[22:23], v54, s16, 0
	v_lshl_add_u64 v[28:29], v[28:29], 2, s[10:11]
	s_lshl_b64 s[20:21], s[20:21], 2
	v_lshl_add_u64 v[30:31], v[30:31], 2, s[10:11]
	v_lshl_add_u64 v[36:37], v[36:37], 2, s[10:11]
	v_lshl_add_u64 v[38:39], v[38:39], 2, s[10:11]
	v_lshl_add_u64 v[44:45], v[44:45], 2, s[10:11]
	v_lshl_add_u64 v[46:47], v[46:47], 2, s[10:11]
	v_lshl_add_u64 v[52:53], v[52:53], 2, s[10:11]
	v_lshl_add_u64 v[54:55], v[54:55], 2, s[10:11]
	v_lshl_add_u64 v[28:29], v[28:29], 0, s[20:21]
	v_lshl_add_u64 v[30:31], v[30:31], 0, s[20:21]
	v_lshl_add_u64 v[36:37], v[36:37], 0, s[20:21]
	v_lshl_add_u64 v[38:39], v[38:39], 0, s[20:21]
	v_lshl_add_u64 v[44:45], v[44:45], 0, s[20:21]
	v_lshl_add_u64 v[46:47], v[46:47], 0, s[20:21]
	v_lshl_add_u64 v[52:53], v[52:53], 0, s[20:21]
	v_lshl_add_u64 v[54:55], v[54:55], 0, s[20:21]
	v_lshl_add_u64 v[28:29], v[28:29], 0, v[64:65]
	v_lshl_add_u64 v[30:31], v[30:31], 0, v[64:65]
	v_lshl_add_u64 v[36:37], v[36:37], 0, v[64:65]
	v_lshl_add_u64 v[38:39], v[38:39], 0, v[64:65]
	v_lshl_add_u64 v[44:45], v[44:45], 0, v[64:65]
	v_lshl_add_u64 v[46:47], v[46:47], 0, v[64:65]
	v_lshl_add_u64 v[52:53], v[52:53], 0, v[64:65]
	v_lshl_add_u64 v[54:55], v[54:55], 0, v[64:65]
	global_load_dwordx4 v[32:35], v[28:29], off nt
	s_nop 0
	global_load_dwordx4 v[28:31], v[30:31], off nt
	s_nop 0
	global_load_dwordx4 v[40:43], v[36:37], off nt
	s_nop 0
	global_load_dwordx4 v[36:39], v[38:39], off nt
	s_nop 0
	global_load_dwordx4 v[48:51], v[44:45], off nt
	s_nop 0
	global_load_dwordx4 v[44:47], v[46:47], off nt
	s_nop 0
	global_load_dwordx4 v[56:59], v[52:53], off nt
	s_nop 0
	global_load_dwordx4 v[52:55], v[54:55], off nt

; #define LAS __attribute__((address_space(3)))
; __device__ __forceinline__ void tr_load(const TrDesc& d, int lane, f32x4 (&wv)[8]) {
;     const int nblk = d.N / 32, kb = d.item / nblk, nb = d.item % nblk, k0 = 64 * kb, n0 = 32 * nb;
; #pragma unroll
;     for (int i = 0; i < 8; ++i) wv[i] = *(const f32x4*)(d.W + (size_t)(k0 + 8 * i + (lane >> 3)) * d.N + n0 + (lane & 7) * 4);
; }
; __device__ __forceinline__ void tr_finish(const TrDesc& d, int lane, const f32x4 (&wv)[8], LAS float* scr) {
;     const int nblk = d.N / 32, kb = d.item / nblk, nb = d.item % nblk, k0 = 64 * kb, n0 = 32 * nb;
;     const int d0 = d.reorder ? (nb < 32 ? n0 : (nb < 34 ? n0 + 2048 : n0 - 64)) : n0;
; #pragma unroll
;     for (int i = 0; i < 8; ++i) { const int kk = 8 * i + (lane >> 3); f32x4 v = wv[i]; if (d.gk) v = v * d.gk[k0 + kk];
;         LAS float* p = scr + kk * 33 + (lane & 7) * 4; p[0] = v[0]; p[1] = v[1]; p[2] = v[2]; p[3] = v[3]; }
;     asm volatile("s_waitcnt lgkmcnt(0)" ::: "memory");
;     const int c = lane & 7;
; #pragma unroll
;     for (int j = 0; j < 4; ++j) { const int n = (lane >> 3) + 8 * j; const LAS float* sp = scr + (8 * c) * 33 + n;
; __device__ __forceinline__ void tr_run(const Args& a, int list, int first, int stride, int lane, LAS float* scr, int n_end = -1) {
;     const int n = n_end >= 0 ? n_end : (list == 0 ? I_LIST0 : (list == 1 ? I_LIST1 : I_LIST2));
;     int it = first; if (it >= n) return;
;     TrDesc d = tr_desc(a, list, it); f32x4 wv[8]; tr_load(d, lane, wv);
.LBB0_304:
	s_lshr_b32 s8, s26, 5
	v_cvt_f32_ubyte0_e32 v0, s8
	v_rcp_iflag_f32_e32 v0, v0
	s_lshl_b32 s9, s3, 14
	s_add_i32 s20, s9, 0
	s_sub_i32 s9, 0, s8
	v_mul_f32_e32 v0, 0x4f7ffffe, v0
	v_cvt_u32_f32_e32 v0, v0
	s_abs_i32 s11, s38
	s_ashr_i32 s10, s38, 31
	v_bfe_u32 v64, v198, 3, 3
	v_readfirstlane_b32 s21, v0
	s_mul_i32 s9, s9, s21
	s_mul_hi_u32 s9, s21, s9
	s_add_i32 s21, s21, s9
	s_mul_hi_u32 s9, s11, s21
	s_mul_i32 s21, s9, s8
	s_sub_i32 s11, s11, s21
	s_add_i32 s24, s9, 1
	s_sub_i32 s21, s11, s8
	s_cmp_ge_u32 s11, s8
	s_cselect_b32 s9, s24, s9
	s_cselect_b32 s11, s21, s11
	s_add_i32 s21, s9, 1
	s_cmp_ge_u32 s11, s8
	s_cselect_b32 s9, s21, s9
	s_xor_b32 s9, s9, s10
	s_sub_i32 s9, s9, s10
	s_mul_i32 s8, s9, s8
	s_sub_i32 s8, s38, s8
	v_lshl_or_b32 v10, s9, 6, v64
	s_lshl_b32 s8, s8, 5
	v_or_b32_e32 v2, 8, v10
	s_ashr_i32 s9, s8, 31
	v_mad_i64_i32 v[0:1], s[10:11], v10, s26, 0
	v_mad_i64_i32 v[2:3], s[10:11], v2, s26, 0
	v_and_b32_e32 v16, 28, v152
	v_lshl_add_u64 v[0:1], v[0:1], 2, s[0:1]
	s_lshl_b64 s[8:9], s[8:9], 2
	v_lshl_add_u64 v[2:3], v[2:3], 2, s[0:1]
	v_mov_b32_e32 v67, 0
	v_lshl_add_u64 v[0:1], v[0:1], 0, s[8:9]
	v_lshlrev_b32_e32 v66, 2, v16
	v_lshl_add_u64 v[2:3], v[2:3], 0, s[8:9]
	v_lshl_add_u64 v[0:1], v[0:1], 0, v[66:67]
	v_lshl_add_u64 v[2:3], v[2:3], 0, v[66:67]
	global_load_dwordx4 v[60:63], v[0:1], off nt
	global_load_dwordx4 v[56:59], v[2:3], off nt
	v_or_b32_e32 v0, 16, v10
	v_or_b32_e32 v2, 24, v10
	v_mad_i64_i32 v[0:1], s[10:11], v0, s26, 0
	v_mad_i64_i32 v[2:3], s[10:11], v2, s26, 0
	v_lshl_add_u64 v[0:1], v[0:1], 2, s[0:1]
	v_lshl_add_u64 v[2:3], v[2:3], 2, s[0:1]
	v_lshl_add_u64 v[0:1], v[0:1], 0, s[8:9]
	v_lshl_add_u64 v[2:3], v[2:3], 0, s[8:9]
	v_lshl_add_u64 v[0:1], v[0:1], 0, v[66:67]
	v_lshl_add_u64 v[2:3], v[2:3], 0, v[66:67]
	global_load_dwordx4 v[52:55], v[0:1], off nt
	global_load_dwordx4 v[4:7], v[2:3], off nt
	v_or_b32_e32 v0, 32, v10
	v_or_b32_e32 v2, 40, v10
	v_or_b32_e32 v8, 48, v10
	v_mad_i64_i32 v[0:1], s[10:11], v0, s26, 0
	v_mad_i64_i32 v[2:3], s[10:11], v2, s26, 0
	v_mad_i64_i32 v[8:9], s[10:11], v8, s26, 0
	v_or_b32_e32 v10, 56, v10
	v_lshl_add_u64 v[0:1], v[0:1], 2, s[0:1]
	v_lshl_add_u64 v[2:3], v[2:3], 2, s[0:1]
	v_lshl_add_u64 v[8:9], v[8:9], 2, s[0:1]
	v_mad_i64_i32 v[10:11], s[10:11], v10, s26, 0
	v_lshl_add_u64 v[0:1], v[0:1], 0, s[8:9]
	v_lshl_add_u64 v[2:3], v[2:3], 0, s[8:9]
	v_lshl_add_u64 v[8:9], v[8:9], 0, s[8:9]
	v_lshl_add_u64 v[10:11], v[10:11], 2, s[0:1]
	v_lshl_add_u64 v[0:1], v[0:1], 0, v[66:67]
	v_lshl_add_u64 v[2:3], v[2:3], 0, v[66:67]
	v_lshl_add_u64 v[8:9], v[8:9], 0, v[66:67]
	v_lshl_add_u64 v[10:11], v[10:11], 0, s[8:9]
	global_load_dwordx4 v[12:15], v[0:1], off nt
	s_nop 0
	global_load_dwordx4 v[0:3], v[2:3], off nt
	v_lshl_add_u64 v[18:19], v[10:11], 0, v[66:67]
	global_load_dwordx4 v[8:11], v[8:9], off nt
	s_nop 0
	global_load_dwordx4 v[48:51], v[18:19], off nt
	v_lshlrev_b32_e32 v18, 3, v198
	v_and_b32_e32 v18, 56, v18
	v_add_u32_e32 v17, s20, v66
	v_mul_u32_u24_e32 v19, 0x84, v64
	v_mul_u32_u24_e32 v20, 0x84, v18
	v_lshlrev_b32_e32 v21, 2, v64
	v_or_b32_e32 v70, 8, v64
	v_or_b32_e32 v71, 16, v64
	v_or_b32_e32 v72, 24, v64
	v_add3_u32 v73, s20, v20, v21
	v_mov_b32_e32 v65, v67
	v_lshlrev_b32_e32 v68, 2, v16
	s_movk_i32 s31, 0xffc0
	v_lshlrev_b32_e32 v66, 1, v18
	v_add_u32_e32 v74, v17, v19
	s_mov_b32 s34, s33
	s_mov_b64 s[20:21], s[4:5]
	s_mov_b64 s[10:11], s[22:23]
	s_mov_b32 s37, s30
	s_mov_b32 s36, s26
	s_mov_b32 s35, s38
	s_mov_b64 s[8:9], s[18:19]
	s_branch .LBB0_306

; __device__ __forceinline__ void tr_load(const TrDesc& d, int lane, f32x4 (&wv)[8]) {
;     const int nblk = d.N / 32, kb = d.item / nblk, nb = d.item % nblk, k0 = 64 * kb, n0 = 32 * nb;
; #pragma unroll
;     for (int i = 0; i < 8; ++i) wv[i] = *(const f32x4*)(d.W + (size_t)(k0 + 8 * i + (lane >> 3)) * d.N + n0 + (lane & 7) * 4);
; }
; __device__ __forceinline__ void tr_run(const Args& a, int list, int first, int stride, int lane, LAS float* scr, int n_end = -1) {
;     ...
;         const int nit = it + stride; const bool more = nit < n;
;         TrDesc dn = d; f32x4 wn[8];
;         if (more) { dn = tr_desc(a, list, nit); tr_load(dn, lane, wn); }
.LBB0_315:
	s_lshr_b32 s27, s36, 5
	v_cvt_f32_ubyte0_e32 v16, s27
	v_rcp_iflag_f32_e32 v16, v16
	s_sub_i32 s40, 0, s27
	s_abs_i32 s29, s35
	s_ashr_i32 s28, s35, 31
	v_mul_f32_e32 v16, 0x4f7ffffe, v16
	v_cvt_u32_f32_e32 v16, v16
	v_mov_b32_e32 v69, v67
	v_readfirstlane_b32 s41, v16
	s_mul_i32 s40, s40, s41
	s_mul_hi_u32 s40, s41, s40
	s_add_i32 s41, s41, s40
	s_mul_hi_u32 s40, s29, s41
	s_mul_i32 s41, s40, s27
	s_sub_i32 s29, s29, s41
	s_add_i32 s42, s40, 1
	s_sub_i32 s41, s29, s27
	s_cmp_ge_u32 s29, s27
	s_cselect_b32 s40, s42, s40
	s_cselect_b32 s29, s41, s29
	s_add_i32 s41, s40, 1
	s_cmp_ge_u32 s29, s27
	s_cselect_b32 s29, s41, s40
	s_xor_b32 s29, s29, s28
	s_sub_i32 s28, s29, s28
	s_mul_i32 s27, s28, s27
	v_lshl_or_b32 v42, s28, 6, v64
	s_sub_i32 s27, s35, s27
	s_lshl_b32 s28, s27, 5
	v_mad_i64_i32 v[16:17], s[40:41], v42, s36, 0
	v_or_b32_e32 v18, 8, v42
	v_or_b32_e32 v24, 16, v42
	v_or_b32_e32 v26, 24, v42
	v_or_b32_e32 v32, 32, v42
	v_or_b32_e32 v34, 40, v42
	v_or_b32_e32 v40, 48, v42
	v_or_b32_e32 v42, 56, v42
	s_ashr_i32 s29, s28, 31
	v_mad_i64_i32 v[18:19], s[40:41], v18, s36, 0
	v_mad_i64_i32 v[24:25], s[40:41], v24, s36, 0
	v_mad_i64_i32 v[26:27], s[40:41], v26, s36, 0
	v_mad_i64_i32 v[32:33], s[40:41], v32, s36, 0
	v_mad_i64_i32 v[34:35], s[40:41], v34, s36, 0
	v_mad_i64_i32 v[40:41], s[40:41], v40, s36, 0
	v_mad_i64_i32 v[42:43], s[40:41], v42, s36, 0
	v_lshl_add_u64 v[16:17], v[16:17], 2, s[0:1]
	s_lshl_b64 s[28:29], s[28:29], 2
	v_lshl_add_u64 v[18:19], v[18:19], 2, s[0:1]
	v_lshl_add_u64 v[24:25], v[24:25], 2, s[0:1]
	v_lshl_add_u64 v[26:27], v[26:27], 2, s[0:1]
	v_lshl_add_u64 v[32:33], v[32:33], 2, s[0:1]
	v_lshl_add_u64 v[34:35], v[34:35], 2, s[0:1]
	v_lshl_add_u64 v[40:41], v[40:41], 2, s[0:1]
	v_lshl_add_u64 v[42:43], v[42:43], 2, s[0:1]
	v_lshl_add_u64 v[16:17], v[16:17], 0, s[28:29]
	v_lshl_add_u64 v[18:19], v[18:19], 0, s[28:29]
	v_lshl_add_u64 v[24:25], v[24:25], 0, s[28:29]
	v_lshl_add_u64 v[26:27], v[26:27], 0, s[28:29]
	v_lshl_add_u64 v[32:33], v[32:33], 0, s[28:29]
	v_lshl_add_u64 v[34:35], v[34:35], 0, s[28:29]
	v_lshl_add_u64 v[40:41], v[40:41], 0, s[28:29]
	v_lshl_add_u64 v[42:43], v[42:43], 0, s[28:29]
	v_lshl_add_u64 v[16:17], v[16:17], 0, v[68:69]
	v_lshl_add_u64 v[18:19], v[18:19], 0, v[68:69]
	v_lshl_add_u64 v[24:25], v[24:25], 0, v[68:69]
	v_lshl_add_u64 v[26:27], v[26:27], 0, v[68:69]
	v_lshl_add_u64 v[32:33], v[32:33], 0, v[68:69]
	v_lshl_add_u64 v[34:35], v[34:35], 0, v[68:69]
	v_lshl_add_u64 v[40:41], v[40:41], 0, v[68:69]
	v_lshl_add_u64 v[42:43], v[42:43], 0, v[68:69]
	global_load_dwordx4 v[20:23], v[16:17], off nt
	s_nop 0
	global_load_dwordx4 v[16:19], v[18:19], off nt
	s_nop 0
	global_load_dwordx4 v[28:31], v[24:25], off nt
	s_nop 0
	global_load_dwordx4 v[24:27], v[26:27], off nt
	s_nop 0
	global_load_dwordx4 v[36:39], v[32:33], off nt
	s_nop 0
	global_load_dwordx4 v[32:35], v[34:35], off nt
	s_nop 0
	global_load_dwordx4 v[44:47], v[40:41], off nt
	s_nop 0
	global_load_dwordx4 v[40:43], v[42:43], off nt

; template <class Epi>
; __device__ __forceinline__ void gemm_phase(LAS unsigned char* lds, const Gemm g, const StaticOrder& S, const Epi& E) {
;     ...
;     Unit cur, nxt; int ui = 0;
;     if (!S.next(0, cur)) return;
;     f32x4 acc[2][2][4][2];
; #pragma unroll
;     for (int a = 0; a < 2; ++a)
; #pragma unroll
;         for (int b = 0; b < 2; ++b)
; #pragma unroll
;             for (int m = 0; m < 4; ++m)
; #pragma unroll
;                 for (int n = 0; n < 2; ++n) acc[a][b][m][n] = (f32x4){0.f, 0.f, 0.f, 0.f};
;     __device__ __forceinline__ void operator()(const f32x4 (&acc)[2][2][4][2], const Unit& u, int wr, int wc, int fr, int fq) const {
;     ...
;                 for (int bj = 0; bj < 2; ++bj) { const u32x4 gw = *(const u32x4*)(SG + off + bj * HALF);
.LBB0_573:
	s_ashr_i32 s25, s24, 31
	s_lshl_b64 s[52:53], s[24:25], 18
	s_add_u32 s52, s59, s52
	s_addc_u32 s53, s67, s53
	s_and_b64 s[4:5], s[4:5], exec
	s_cselect_b32 s25, s53, s35
	s_cselect_b32 s27, s52, s34
	s_add_u32 s4, s36, 0x80080
	s_addc_u32 s5, s37, 0
	s_add_u32 s51, s34, 0x100
	v_mov_b32_e32 v0, 0
	s_addc_u32 s54, s35, 0
	s_mov_b32 s55, -2
	v_mov_b32_e32 v1, v0
	v_mov_b32_e32 v2, v0
	v_mov_b32_e32 v3, v0
	v_mov_b32_e32 v4, v0
	v_mov_b32_e32 v5, v0
	v_mov_b32_e32 v6, v0
	v_mov_b32_e32 v7, v0
	v_mov_b32_e32 v12, v0
	v_mov_b32_e32 v13, v0
	v_mov_b32_e32 v14, v0
	v_mov_b32_e32 v15, v0
	v_mov_b32_e32 v20, v0
	v_mov_b32_e32 v21, v0
	v_mov_b32_e32 v22, v0
	v_mov_b32_e32 v23, v0
	v_mov_b32_e32 v28, v0
	v_mov_b32_e32 v29, v0
	v_mov_b32_e32 v30, v0
	v_mov_b32_e32 v31, v0
	v_mov_b32_e32 v36, v0
	v_mov_b32_e32 v37, v0
	v_mov_b32_e32 v38, v0
	v_mov_b32_e32 v39, v0
	v_mov_b32_e32 v44, v0
	v_mov_b32_e32 v45, v0
	v_mov_b32_e32 v46, v0
	v_mov_b32_e32 v47, v0
	v_mov_b32_e32 v52, v0
	v_mov_b32_e32 v53, v0
	v_mov_b32_e32 v54, v0
	v_mov_b32_e32 v55, v0
	v_mov_b32_e32 v8, v0
	v_mov_b32_e32 v9, v0
	v_mov_b32_e32 v10, v0
	v_mov_b32_e32 v11, v0
	v_mov_b32_e32 v16, v0
	v_mov_b32_e32 v17, v0
	v_mov_b32_e32 v18, v0
	v_mov_b32_e32 v19, v0
	v_mov_b32_e32 v24, v0
	v_mov_b32_e32 v25, v0
	v_mov_b32_e32 v26, v0
	v_mov_b32_e32 v27, v0
	v_mov_b32_e32 v32, v0
	v_mov_b32_e32 v33, v0
	v_mov_b32_e32 v34, v0
	v_mov_b32_e32 v35, v0
	v_mov_b32_e32 v40, v0
	v_mov_b32_e32 v41, v0
	v_mov_b32_e32 v42, v0
	v_mov_b32_e32 v43, v0
	v_mov_b32_e32 v48, v0
	v_mov_b32_e32 v49, v0
	v_mov_b32_e32 v50, v0
	v_mov_b32_e32 v51, v0
	v_mov_b32_e32 v56, v0
	v_mov_b32_e32 v57, v0
	v_mov_b32_e32 v58, v0
	v_mov_b32_e32 v59, v0
	v_mov_b32_e32 v60, v0
	v_mov_b32_e32 v61, v0
	v_mov_b32_e32 v62, v0
	v_mov_b32_e32 v63, v0
	v_mov_b32_e32 v64, v0
	v_mov_b32_e32 v65, v0
	v_mov_b32_e32 v66, v0
	v_mov_b32_e32 v67, v0
	v_mov_b32_e32 v68, v0
	v_mov_b32_e32 v69, v0
	v_mov_b32_e32 v70, v0
	v_mov_b32_e32 v71, v0
	v_mov_b32_e32 v76, v0
	v_mov_b32_e32 v77, v0
	v_mov_b32_e32 v78, v0
	v_mov_b32_e32 v79, v0
	v_mov_b32_e32 v84, v0
	v_mov_b32_e32 v85, v0
	v_mov_b32_e32 v86, v0
	v_mov_b32_e32 v87, v0
	v_mov_b32_e32 v108, v0
	v_mov_b32_e32 v109, v0
	v_mov_b32_e32 v110, v0
	v_mov_b32_e32 v111, v0
	v_mov_b32_e32 v116, v0
	v_mov_b32_e32 v117, v0
	v_mov_b32_e32 v118, v0
	v_mov_b32_e32 v119, v0
	v_mov_b32_e32 v140, v0
	v_mov_b32_e32 v141, v0
	v_mov_b32_e32 v142, v0
	v_mov_b32_e32 v143, v0
	v_mov_b32_e32 v148, v0
	v_mov_b32_e32 v149, v0
	v_mov_b32_e32 v150, v0
	v_mov_b32_e32 v151, v0
	v_mov_b32_e32 v72, v0
	v_mov_b32_e32 v73, v0
	v_mov_b32_e32 v74, v0
	v_mov_b32_e32 v75, v0
	v_mov_b32_e32 v80, v0
	v_mov_b32_e32 v81, v0
	v_mov_b32_e32 v82, v0
	v_mov_b32_e32 v83, v0
	v_mov_b32_e32 v104, v0
	v_mov_b32_e32 v105, v0
	v_mov_b32_e32 v106, v0
	v_mov_b32_e32 v107, v0
	v_mov_b32_e32 v112, v0
	v_mov_b32_e32 v113, v0
	v_mov_b32_e32 v114, v0
	v_mov_b32_e32 v115, v0
	v_mov_b32_e32 v136, v0
	v_mov_b32_e32 v137, v0
	v_mov_b32_e32 v138, v0
	v_mov_b32_e32 v139, v0
	v_mov_b32_e32 v144, v0
	v_mov_b32_e32 v145, v0
	v_mov_b32_e32 v146, v0
	v_mov_b32_e32 v147, v0
	v_mov_b32_e32 v152, v0
	v_mov_b32_e32 v153, v0
	v_mov_b32_e32 v154, v0
	v_mov_b32_e32 v155, v0
	v_mov_b32_e32 v156, v0
	v_mov_b32_e32 v157, v0
	v_mov_b32_e32 v158, v0
	v_mov_b32_e32 v159, v0
	v_lshl_or_b32 v246, s50, 8, v184
	v_lshl_add_u32 v199, s30, 8, v182
	v_lshl_add_u32 v246, v199, 11, v246
	v_lshlrev_b32_e32 v246, 1, v246
	global_load_dwordx4 v[226:229], v246, s[14:15] nt
	global_load_dwordx4 v[230:233], v246, s[14:15] offset:256 nt
	v_add_u32_e32 v199, 0x10000, v246
	global_load_dwordx4 v[234:237], v199, s[14:15] nt
	global_load_dwordx4 v[238:241], v199, s[14:15] offset:256 nt
	v_add_u32_e32 v199, 0x20000, v246
	global_load_dwordx4 v[242:245], v199, s[14:15] nt

; __device__ __forceinline__ float bf_lo(unsigned w) { return __uint_as_float(w << 16); }
; __device__ __forceinline__ float bf_hi(unsigned w) { return __uint_as_float(w & 0xffff0000u); }
; __device__ __forceinline__ u32x4 pack8(f32x4 v0, f32x4 v1) { u32x4 w; w.x = cvt_pk_bf16(v0[0], v0[1]); w.y = cvt_pk_bf16(v0[2], v0[3]); w.z = cvt_pk_bf16(v1[0], v1[1]); w.w = cvt_pk_bf16(v1[2], v1[3]); return w; }
;     __device__ __forceinline__ void operator()(const f32x4 (&acc)[2][2][4][2], const Unit& u, int wr, int wc, int fr, int fq) const {
;     ...
;             for (int n = 0; n < 2; ++n) { bv[bj][n] = *(const f32x4*)(bias + col0 + bj * HALF + 4 * n); sv[bj][n] = *(const f32x4*)(scale + col0 + bj * HALF + 4 * n); }
; #pragma unroll
;         for (int ai = 0; ai < 2; ++ai)
; #pragma unroll
;             for (int m = 0; m < 4; ++m) { const size_t off = (size_t)(row0 + ai * HALF + m * 16) * DM + col0;
; #pragma unroll
;                 for (int bj = 0; bj < 2; ++bj) { const u32x4 gw = *(const u32x4*)(SG + off + bj * HALF);
;                     f32x4 v0 = (acc[ai][bj][m][0] + bv[bj][0]) * sv[bj][0], v1 = (acc[ai][bj][m][1] + bv[bj][1]) * sv[bj][1];
;                     v0 = v0 * (f32x4){bf_lo(gw.x), bf_hi(gw.x), bf_lo(gw.y), bf_hi(gw.y)}; v1 = v1 * (f32x4){bf_lo(gw.z), bf_hi(gw.z), bf_lo(gw.w), bf_hi(gw.w)};
;                     *(u32x4*)(Z + off + bj * HALF) = pack8(v0, v1); } }
.LBB0_577:
	v_lshl_or_b32 v178, s50, 8, v184
	v_readlane_b32 s68, v247, 0
	v_ashrrev_i32_e32 v179, 31, v178
	v_readlane_b32 s69, v247, 1
	v_readlane_b32 s70, v247, 2
	v_readlane_b32 s71, v247, 3
	v_readlane_b32 s72, v247, 4
	v_readlane_b32 s73, v247, 5
	v_lshlrev_b64 v[88:89], 2, v[178:179]
	v_readlane_b32 s74, v247, 6
	v_readlane_b32 s75, v247, 7
	s_mov_b64 s[68:69], s[72:73]
	v_lshl_add_u32 v180, s30, 8, v182
	s_mov_b64 s[70:71], s[74:75]
	v_lshl_add_u64 v[90:91], s[68:69], 0, v[88:89]
	v_ashrrev_i32_e32 v181, 31, v180
	v_lshl_add_u64 v[96:97], s[70:71], 0, v[88:89]
	global_load_dwordx4 v[124:127], v[90:91], off offset:16
	global_load_dwordx4 v[132:135], v[90:91], off
	global_load_dwordx4 v[120:123], v[96:97], off offset:16
	global_load_dwordx4 v[128:131], v[96:97], off
	v_lshlrev_b64 v[88:89], 11, v[180:181]
	v_lshl_add_u64 v[88:89], v[88:89], 0, v[178:179]
	v_lshlrev_b64 v[176:177], 1, v[88:89]
	v_lshl_add_u64 v[192:193], s[14:15], 0, v[176:177]
	global_load_dwordx4 v[92:95], v[90:91], off offset:528
	global_load_dwordx4 v[100:103], v[90:91], off offset:512
	s_nop 0
	global_load_dwordx4 v[88:91], v[96:97], off offset:528
	s_nop 0
	global_load_dwordx4 v[96:99], v[96:97], off offset:512
	v_add_u32_e32 v199, 0x20000, v176
	global_load_dwordx4 v[200:203], v199, s[14:15] offset:256 nt
	v_add_u32_e32 v199, 0x30000, v176
	global_load_dwordx4 v[204:207], v199, s[14:15] nt
	v_add_u32_e32 v199, 0x30000, v176
	global_load_dwordx4 v[208:211], v199, s[14:15] offset:256 nt
	v_add_u32_e32 v199, 0x80000, v176
	global_load_dwordx4 v[212:215], v199, s[14:15] nt
	v_add_u32_e32 v199, 0x80000, v176
	global_load_dwordx4 v[216:219], v199, s[14:15] offset:256 nt
	s_mov_b64 s[4:5], 0x80000
	v_readlane_b32 s76, v247, 8
	v_readlane_b32 s77, v247, 9
	v_readlane_b32 s78, v247, 10
	v_readlane_b32 s79, v247, 11
	v_readlane_b32 s80, v247, 12
	v_readlane_b32 s81, v247, 13
	v_readlane_b32 s82, v247, 14
	v_readlane_b32 s83, v247, 15
	v_readlane_b32 s68, v247, 34
	s_and_b64 vcc, exec, s[0:1]
	s_mov_b64 s[0:1], -1
	v_readlane_b32 s69, v247, 35
	v_readlane_b32 s70, v247, 36
	v_readlane_b32 s71, v247, 37
	v_readlane_b32 s72, v247, 38
	v_readlane_b32 s73, v247, 39
	v_readlane_b32 s74, v247, 40
	v_readlane_b32 s75, v247, 41
	v_readlane_b32 s76, v247, 42
	v_readlane_b32 s77, v247, 43
	v_readlane_b32 s78, v247, 44
	v_readlane_b32 s79, v247, 45
	v_readlane_b32 s80, v247, 46
	v_readlane_b32 s81, v247, 47
	v_readlane_b32 s82, v247, 48
	v_readlane_b32 s83, v247, 49
	s_waitcnt vmcnt(5)
	v_pk_add_f32 v[154:155], v[154:155], v[126:127]
	v_pk_add_f32 v[158:159], v[158:159], v[134:135]
	v_pk_add_f32 v[156:157], v[156:157], v[132:133]
	v_pk_add_f32 v[152:153], v[152:153], v[124:125]
	v_pk_mul_f32 v[158:159], v[130:131], v[158:159]
	v_pk_mul_f32 v[156:157], v[128:129], v[156:157]
	v_pk_mul_f32 v[154:155], v[122:123], v[154:155]
	v_pk_mul_f32 v[152:153], v[120:121], v[152:153]
	v_lshlrev_b32_e32 v194, 16, v226
	v_and_b32_e32 v195, 0xffff0000, v226
	v_lshlrev_b32_e32 v188, 16, v227
	v_and_b32_e32 v189, 0xffff0000, v227
	v_lshlrev_b32_e32 v196, 16, v228
	v_and_b32_e32 v197, 0xffff0000, v228
	v_lshlrev_b32_e32 v190, 16, v229
	v_and_b32_e32 v191, 0xffff0000, v229
	v_pk_mul_f32 v[158:159], v[158:159], v[188:189]
	v_pk_mul_f32 v[156:157], v[156:157], v[194:195]
	v_pk_mul_f32 v[188:189], v[154:155], v[190:191]
	v_pk_mul_f32 v[154:155], v[152:153], v[196:197]
	v_cvt_pk_bf16_f32 v152, v156, v157
	v_cvt_pk_bf16_f32 v153, v158, v159
	v_lshl_add_u64 v[190:191], s[18:19], 0, v[176:177]
	v_cvt_pk_bf16_f32 v154, v154, v155
	v_cvt_pk_bf16_f32 v155, v188, v189
	v_add_u32_e32 v199, 0x90000, v176
	global_load_dwordx4 v[226:229], v199, s[14:15] nt
	v_or_b32_e32 v188, 16, v180
	v_ashrrev_i32_e32 v189, 31, v188
	v_lshlrev_b64 v[188:189], 11, v[188:189]
	v_pk_add_f32 v[148:149], v[148:149], v[100:101]
	v_pk_add_f32 v[142:143], v[142:143], v[94:95]
	v_pk_add_f32 v[140:141], v[140:141], v[92:93]
	v_lshl_add_u64 v[188:189], v[188:189], 0, v[178:179]
	v_pk_add_f32 v[150:151], v[150:151], v[102:103]
	v_pk_mul_f32 v[148:149], v[96:97], v[148:149]
	v_pk_mul_f32 v[142:143], v[90:91], v[142:143]
	v_pk_mul_f32 v[140:141], v[88:89], v[140:141]
	global_store_dwordx4 v[190:191], v[152:155], off
	v_lshlrev_b64 v[188:189], 1, v[188:189]
	v_pk_mul_f32 v[150:151], v[98:99], v[150:151]
	v_lshl_add_u64 v[192:193], s[14:15], 0, v[188:189]
	v_pk_add_f32 v[146:147], v[146:147], v[134:135]
	v_pk_add_f32 v[138:139], v[138:139], v[126:127]
	v_pk_add_f32 v[136:137], v[136:137], v[124:125]
	v_pk_add_f32 v[144:145], v[144:145], v[132:133]
	v_pk_mul_f32 v[146:147], v[130:131], v[146:147]
	v_pk_mul_f32 v[138:139], v[122:123], v[138:139]
	v_pk_mul_f32 v[136:137], v[120:121], v[136:137]
	v_pk_mul_f32 v[144:145], v[128:129], v[144:145]
	v_pk_add_f32 v[116:117], v[116:117], v[100:101]
	v_pk_add_f32 v[110:111], v[110:111], v[94:95]
	v_pk_add_f32 v[108:109], v[108:109], v[92:93]
	v_pk_add_f32 v[118:119], v[118:119], v[102:103]
	v_pk_mul_f32 v[116:117], v[96:97], v[116:117]
	v_pk_mul_f32 v[110:111], v[90:91], v[110:111]
	v_pk_mul_f32 v[108:109], v[88:89], v[108:109]
	v_pk_mul_f32 v[118:119], v[98:99], v[118:119]
	v_pk_add_f32 v[114:115], v[114:115], v[134:135]
	v_pk_add_f32 v[106:107], v[106:107], v[126:127]
	v_pk_add_f32 v[104:105], v[104:105], v[124:125]
	v_pk_add_f32 v[112:113], v[112:113], v[132:133]
	v_pk_mul_f32 v[114:115], v[130:131], v[114:115]
	v_pk_mul_f32 v[106:107], v[122:123], v[106:107]
	v_pk_mul_f32 v[104:105], v[120:121], v[104:105]
	v_pk_mul_f32 v[112:113], v[128:129], v[112:113]
	v_pk_add_f32 v[84:85], v[84:85], v[100:101]
	v_pk_add_f32 v[78:79], v[78:79], v[94:95]
	v_pk_add_f32 v[76:77], v[76:77], v[92:93]
; __device__ __forceinline__ float bf_lo(unsigned w) { return __uint_as_float(w << 16); }
; __device__ __forceinline__ float bf_hi(unsigned w) { return __uint_as_float(w & 0xffff0000u); }
; __device__ __forceinline__ u32x4 pack8(f32x4 v0, f32x4 v1) { u32x4 w; w.x = cvt_pk_bf16(v0[0], v0[1]); w.y = cvt_pk_bf16(v0[2], v0[3]); w.z = cvt_pk_bf16(v1[0], v1[1]); w.w = cvt_pk_bf16(v1[2], v1[3]); return w; }
;     __device__ __forceinline__ void operator()(const f32x4 (&acc)[2][2][4][2], const Unit& u, int wr, int wc, int fr, int fq) const {
;     ...
;             for (int m = 0; m < 4; ++m) { const size_t off = (size_t)(row0 + ai * HALF + m * 16) * DM + col0;
; #pragma unroll
;                 for (int bj = 0; bj < 2; ++bj) { const u32x4 gw = *(const u32x4*)(SG + off + bj * HALF);
;                     f32x4 v0 = (acc[ai][bj][m][0] + bv[bj][0]) * sv[bj][0], v1 = (acc[ai][bj][m][1] + bv[bj][1]) * sv[bj][1];
;                     v0 = v0 * (f32x4){bf_lo(gw.x), bf_hi(gw.x), bf_lo(gw.y), bf_hi(gw.y)}; v1 = v1 * (f32x4){bf_lo(gw.z), bf_hi(gw.z), bf_lo(gw.w), bf_hi(gw.w)};
;                     *(u32x4*)(Z + off + bj * HALF) = pack8(v0, v1); } }
	v_pk_add_f32 v[86:87], v[86:87], v[102:103]
	v_pk_mul_f32 v[84:85], v[96:97], v[84:85]
	v_pk_mul_f32 v[78:79], v[90:91], v[78:79]
	v_pk_mul_f32 v[76:77], v[88:89], v[76:77]
	v_pk_mul_f32 v[86:87], v[98:99], v[86:87]
	v_pk_add_f32 v[82:83], v[82:83], v[134:135]
	v_pk_add_f32 v[74:75], v[74:75], v[126:127]
	v_pk_add_f32 v[72:73], v[72:73], v[124:125]
	v_pk_add_f32 v[80:81], v[80:81], v[132:133]
	v_pk_mul_f32 v[82:83], v[130:131], v[82:83]
	v_pk_mul_f32 v[74:75], v[122:123], v[74:75]
	v_pk_mul_f32 v[72:73], v[120:121], v[72:73]
	v_pk_mul_f32 v[80:81], v[128:129], v[80:81]
	v_pk_add_f32 v[68:69], v[68:69], v[100:101]
	v_pk_add_f32 v[66:67], v[66:67], v[94:95]
	v_pk_add_f32 v[64:65], v[64:65], v[92:93]
	v_pk_add_f32 v[70:71], v[70:71], v[102:103]
	v_pk_mul_f32 v[68:69], v[96:97], v[68:69]
	v_pk_mul_f32 v[66:67], v[90:91], v[66:67]
	v_pk_mul_f32 v[64:65], v[88:89], v[64:65]
	v_pk_mul_f32 v[70:71], v[98:99], v[70:71]
	v_pk_add_f32 v[62:63], v[62:63], v[134:135]
	v_pk_add_f32 v[60:61], v[60:61], v[132:133]
	v_pk_add_f32 v[58:59], v[58:59], v[126:127]
	v_pk_add_f32 v[56:57], v[56:57], v[124:125]
	v_pk_mul_f32 v[62:63], v[130:131], v[62:63]
	v_pk_mul_f32 v[60:61], v[128:129], v[60:61]
	v_pk_mul_f32 v[58:59], v[122:123], v[58:59]
	v_pk_mul_f32 v[56:57], v[120:121], v[56:57]
	v_pk_add_f32 v[52:53], v[52:53], v[100:101]
	v_pk_add_f32 v[46:47], v[46:47], v[94:95]
	v_pk_add_f32 v[44:45], v[44:45], v[92:93]
	v_pk_add_f32 v[54:55], v[54:55], v[102:103]
	v_pk_mul_f32 v[52:53], v[96:97], v[52:53]
	v_pk_mul_f32 v[46:47], v[90:91], v[46:47]
	v_pk_mul_f32 v[44:45], v[88:89], v[44:45]
	v_pk_mul_f32 v[54:55], v[98:99], v[54:55]
	v_lshlrev_b32_e32 v152, 16, v230
	v_and_b32_e32 v153, 0xffff0000, v230
	v_lshlrev_b32_e32 v154, 16, v231
	v_and_b32_e32 v155, 0xffff0000, v231
	v_lshlrev_b32_e32 v156, 16, v232
	v_and_b32_e32 v157, 0xffff0000, v232
	v_lshlrev_b32_e32 v158, 16, v233
	v_and_b32_e32 v159, 0xffff0000, v233
	v_pk_mul_f32 v[148:149], v[148:149], v[152:153]
	v_pk_mul_f32 v[152:153], v[142:143], v[158:159]
	v_pk_mul_f32 v[142:143], v[140:141], v[156:157]
	v_pk_mul_f32 v[150:151], v[150:151], v[154:155]
	v_cvt_pk_bf16_f32 v140, v148, v149
	v_pk_add_f32 v[50:51], v[50:51], v[134:135]
	v_cvt_pk_bf16_f32 v141, v150, v151
	v_cvt_pk_bf16_f32 v142, v142, v143
	v_cvt_pk_bf16_f32 v143, v152, v153
	global_store_dwordx4 v[190:191], v[140:143], off offset:256
	v_add_u32_e32 v199, 0x90000, v176
	global_load_dwordx4 v[230:233], v199, s[14:15] offset:256 nt
	v_pk_add_f32 v[42:43], v[42:43], v[126:127]
	v_pk_add_f32 v[40:41], v[40:41], v[124:125]
	v_pk_add_f32 v[48:49], v[48:49], v[132:133]
	v_pk_mul_f32 v[50:51], v[130:131], v[50:51]
	v_pk_mul_f32 v[42:43], v[122:123], v[42:43]
	v_pk_mul_f32 v[40:41], v[120:121], v[40:41]
	v_pk_mul_f32 v[48:49], v[128:129], v[48:49]
	v_pk_add_f32 v[36:37], v[36:37], v[100:101]
	v_pk_add_f32 v[30:31], v[30:31], v[94:95]
	v_pk_add_f32 v[28:29], v[28:29], v[92:93]
	v_pk_add_f32 v[38:39], v[38:39], v[102:103]
	v_pk_mul_f32 v[36:37], v[96:97], v[36:37]
	v_pk_mul_f32 v[30:31], v[90:91], v[30:31]
	v_pk_mul_f32 v[28:29], v[88:89], v[28:29]
	v_pk_mul_f32 v[38:39], v[98:99], v[38:39]
	v_pk_add_f32 v[34:35], v[34:35], v[134:135]
	v_pk_add_f32 v[26:27], v[26:27], v[126:127]
	v_pk_add_f32 v[24:25], v[24:25], v[124:125]
	v_pk_add_f32 v[32:33], v[32:33], v[132:133]
	v_pk_mul_f32 v[34:35], v[130:131], v[34:35]
	v_pk_mul_f32 v[26:27], v[122:123], v[26:27]
	v_pk_mul_f32 v[24:25], v[120:121], v[24:25]
	v_pk_mul_f32 v[32:33], v[128:129], v[32:33]
	v_pk_add_f32 v[20:21], v[20:21], v[100:101]
	v_pk_add_f32 v[14:15], v[14:15], v[94:95]
	v_pk_add_f32 v[12:13], v[12:13], v[92:93]
	v_pk_add_f32 v[22:23], v[22:23], v[102:103]
	v_pk_mul_f32 v[20:21], v[96:97], v[20:21]
	v_pk_mul_f32 v[14:15], v[90:91], v[14:15]
	v_pk_mul_f32 v[12:13], v[88:89], v[12:13]
	v_pk_mul_f32 v[22:23], v[98:99], v[22:23]
	v_pk_add_f32 v[18:19], v[18:19], v[134:135]
	v_pk_add_f32 v[10:11], v[10:11], v[126:127]
	v_pk_add_f32 v[8:9], v[8:9], v[124:125]
	v_pk_add_f32 v[16:17], v[16:17], v[132:133]
	v_pk_mul_f32 v[18:19], v[130:131], v[18:19]
	v_pk_mul_f32 v[10:11], v[122:123], v[10:11]
	v_pk_mul_f32 v[8:9], v[120:121], v[8:9]
	v_pk_mul_f32 v[16:17], v[128:129], v[16:17]
	v_pk_add_f32 v[4:5], v[4:5], v[100:101]
	v_pk_add_f32 v[2:3], v[2:3], v[94:95]
	v_pk_add_f32 v[0:1], v[0:1], v[92:93]
	v_pk_add_f32 v[6:7], v[6:7], v[102:103]
	v_pk_mul_f32 v[4:5], v[96:97], v[4:5]
	v_pk_mul_f32 v[2:3], v[90:91], v[2:3]
	v_pk_mul_f32 v[0:1], v[88:89], v[0:1]
	v_pk_mul_f32 v[6:7], v[98:99], v[6:7]
	v_lshlrev_b32_e32 v148, 16, v234
	v_and_b32_e32 v149, 0xffff0000, v234
	v_lshlrev_b32_e32 v140, 16, v235
	v_and_b32_e32 v141, 0xffff0000, v235
	v_lshlrev_b32_e32 v150, 16, v236
	v_and_b32_e32 v151, 0xffff0000, v236
	v_lshlrev_b32_e32 v142, 16, v237
	v_and_b32_e32 v143, 0xffff0000, v237
	v_pk_mul_f32 v[140:141], v[146:147], v[140:141]
	v_pk_mul_f32 v[142:143], v[138:139], v[142:143]
	v_pk_mul_f32 v[138:139], v[136:137], v[150:151]
	v_pk_mul_f32 v[144:145], v[144:145], v[148:149]
	v_lshl_add_u64 v[146:147], s[18:19], 0, v[188:189]
	v_cvt_pk_bf16_f32 v136, v144, v145
	v_cvt_pk_bf16_f32 v137, v140, v141
	v_cvt_pk_bf16_f32 v138, v138, v139
	v_cvt_pk_bf16_f32 v139, v142, v143
	v_add_u32_e32 v199, 0xa0000, v176
	global_load_dwordx4 v[234:237], v199, s[14:15] nt
	v_or_b32_e32 v144, 32, v180
	v_ashrrev_i32_e32 v145, 31, v144
	v_lshlrev_b64 v[144:145], 11, v[144:145]
	v_lshl_add_u64 v[144:145], v[144:145], 0, v[178:179]
	global_store_dwordx4 v[146:147], v[136:139], off
	v_lshlrev_b64 v[144:145], 1, v[144:145]
	v_lshl_add_u64 v[148:149], s[14:15], 0, v[144:145]
	v_lshlrev_b32_e32 v136, 16, v238
	v_and_b32_e32 v137, 0xffff0000, v238
; __device__ __forceinline__ float bf_lo(unsigned w) { return __uint_as_float(w << 16); }
; __device__ __forceinline__ float bf_hi(unsigned w) { return __uint_as_float(w & 0xffff0000u); }
; __device__ __forceinline__ u32x4 pack8(f32x4 v0, f32x4 v1) { u32x4 w; w.x = cvt_pk_bf16(v0[0], v0[1]); w.y = cvt_pk_bf16(v0[2], v0[3]); w.z = cvt_pk_bf16(v1[0], v1[1]); w.w = cvt_pk_bf16(v1[2], v1[3]); return w; }
;     __device__ __forceinline__ void operator()(const f32x4 (&acc)[2][2][4][2], const Unit& u, int wr, int wc, int fr, int fq) const {
;     ...
;             for (int m = 0; m < 4; ++m) { const size_t off = (size_t)(row0 + ai * HALF + m * 16) * DM + col0;
; #pragma unroll
;                 for (int bj = 0; bj < 2; ++bj) { const u32x4 gw = *(const u32x4*)(SG + off + bj * HALF);
;                     f32x4 v0 = (acc[ai][bj][m][0] + bv[bj][0]) * sv[bj][0], v1 = (acc[ai][bj][m][1] + bv[bj][1]) * sv[bj][1];
;                     v0 = v0 * (f32x4){bf_lo(gw.x), bf_hi(gw.x), bf_lo(gw.y), bf_hi(gw.y)}; v1 = v1 * (f32x4){bf_lo(gw.z), bf_hi(gw.z), bf_lo(gw.w), bf_hi(gw.w)};
;                     *(u32x4*)(Z + off + bj * HALF) = pack8(v0, v1); } }
	v_lshlrev_b32_e32 v138, 16, v239
	v_and_b32_e32 v139, 0xffff0000, v239
	v_lshlrev_b32_e32 v140, 16, v240
	v_and_b32_e32 v141, 0xffff0000, v240
	v_lshlrev_b32_e32 v142, 16, v241
	v_and_b32_e32 v143, 0xffff0000, v241
	v_pk_mul_f32 v[116:117], v[116:117], v[136:137]
	v_pk_mul_f32 v[136:137], v[110:111], v[142:143]
	v_pk_mul_f32 v[110:111], v[108:109], v[140:141]
	v_pk_mul_f32 v[118:119], v[118:119], v[138:139]
	v_cvt_pk_bf16_f32 v108, v116, v117
	s_nop 0
	v_cvt_pk_bf16_f32 v109, v118, v119
	v_cvt_pk_bf16_f32 v110, v110, v111
	v_cvt_pk_bf16_f32 v111, v136, v137
	global_store_dwordx4 v[146:147], v[108:111], off offset:256
	v_add_u32_e32 v199, 0xa0000, v176
	global_load_dwordx4 v[238:241], v199, s[14:15] offset:256 nt
	v_lshlrev_b32_e32 v116, 16, v242
	v_and_b32_e32 v117, 0xffff0000, v242
	v_lshlrev_b32_e32 v108, 16, v243
	v_and_b32_e32 v109, 0xffff0000, v243
	v_lshlrev_b32_e32 v118, 16, v244
	v_and_b32_e32 v119, 0xffff0000, v244
	v_lshlrev_b32_e32 v110, 16, v245
	v_and_b32_e32 v111, 0xffff0000, v245
	v_pk_mul_f32 v[108:109], v[114:115], v[108:109]
	v_pk_mul_f32 v[110:111], v[106:107], v[110:111]
	v_pk_mul_f32 v[106:107], v[104:105], v[118:119]
	v_pk_mul_f32 v[112:113], v[112:113], v[116:117]
	v_lshl_add_u64 v[114:115], s[18:19], 0, v[144:145]
	v_cvt_pk_bf16_f32 v104, v112, v113
	v_cvt_pk_bf16_f32 v105, v108, v109
	v_cvt_pk_bf16_f32 v106, v106, v107
	v_cvt_pk_bf16_f32 v107, v110, v111
	v_add_u32_e32 v199, 0xb0000, v176
	global_load_dwordx4 v[242:245], v199, s[14:15] nt
	v_or_b32_e32 v112, 48, v180
	v_ashrrev_i32_e32 v113, 31, v112
	v_lshlrev_b64 v[112:113], 11, v[112:113]
	v_lshl_add_u64 v[112:113], v[112:113], 0, v[178:179]
	global_store_dwordx4 v[114:115], v[104:107], off
	v_lshlrev_b64 v[112:113], 1, v[112:113]
	v_lshl_add_u64 v[116:117], s[14:15], 0, v[112:113]
	s_waitcnt vmcnt(14)
	v_lshlrev_b32_e32 v104, 16, v200
	v_and_b32_e32 v105, 0xffff0000, v200
	v_lshlrev_b32_e32 v106, 16, v201
	v_and_b32_e32 v107, 0xffff0000, v201
	v_lshlrev_b32_e32 v108, 16, v202
	v_and_b32_e32 v109, 0xffff0000, v202
	v_lshlrev_b32_e32 v110, 16, v203
	v_and_b32_e32 v111, 0xffff0000, v203
	v_pk_mul_f32 v[84:85], v[84:85], v[104:105]
	v_pk_mul_f32 v[104:105], v[78:79], v[110:111]
	v_pk_mul_f32 v[78:79], v[76:77], v[108:109]
	v_pk_mul_f32 v[86:87], v[86:87], v[106:107]
	v_cvt_pk_bf16_f32 v76, v84, v85
	s_nop 0
	v_cvt_pk_bf16_f32 v77, v86, v87
	v_cvt_pk_bf16_f32 v78, v78, v79
	v_cvt_pk_bf16_f32 v79, v104, v105
	global_store_dwordx4 v[114:115], v[76:79], off offset:256
	v_add_u32_e32 v199, 0xb0000, v176
	global_load_dwordx4 v[200:203], v199, s[14:15] offset:256 nt
	s_waitcnt vmcnt(15)
	v_lshlrev_b32_e32 v84, 16, v204
	v_and_b32_e32 v85, 0xffff0000, v204
	v_lshlrev_b32_e32 v76, 16, v205
	v_and_b32_e32 v77, 0xffff0000, v205
	v_lshlrev_b32_e32 v86, 16, v206
	v_and_b32_e32 v87, 0xffff0000, v206
	v_lshlrev_b32_e32 v78, 16, v207
	v_and_b32_e32 v79, 0xffff0000, v207
	v_pk_mul_f32 v[76:77], v[82:83], v[76:77]
	v_pk_mul_f32 v[78:79], v[74:75], v[78:79]
	v_pk_mul_f32 v[74:75], v[72:73], v[86:87]
	v_pk_mul_f32 v[80:81], v[80:81], v[84:85]
	v_lshl_add_u64 v[82:83], s[18:19], 0, v[112:113]
	v_cvt_pk_bf16_f32 v72, v80, v81
	v_cvt_pk_bf16_f32 v73, v76, v77
	v_cvt_pk_bf16_f32 v74, v74, v75
	v_cvt_pk_bf16_f32 v75, v78, v79
	v_lshl_add_u64 v[80:81], v[176:177], 0, s[4:5]
	global_store_dwordx4 v[82:83], v[72:75], off
	v_lshl_add_u64 v[84:85], s[14:15], 0, v[80:81]
	s_mov_b64 s[4:5], 0x90000
	s_waitcnt vmcnt(15)
	v_lshlrev_b32_e32 v72, 16, v208
	v_and_b32_e32 v73, 0xffff0000, v208
	v_lshlrev_b32_e32 v74, 16, v209
	v_and_b32_e32 v75, 0xffff0000, v209
	v_lshlrev_b32_e32 v76, 16, v210
	v_and_b32_e32 v77, 0xffff0000, v210
	v_lshlrev_b32_e32 v78, 16, v211
	v_and_b32_e32 v79, 0xffff0000, v211
	v_pk_mul_f32 v[68:69], v[68:69], v[72:73]
	v_pk_mul_f32 v[72:73], v[66:67], v[78:79]
	v_pk_mul_f32 v[66:67], v[64:65], v[76:77]
	v_pk_mul_f32 v[70:71], v[70:71], v[74:75]
	v_cvt_pk_bf16_f32 v64, v68, v69
	s_nop 0
	v_cvt_pk_bf16_f32 v65, v70, v71
	v_cvt_pk_bf16_f32 v66, v66, v67
	v_cvt_pk_bf16_f32 v67, v72, v73
	global_store_dwordx4 v[82:83], v[64:67], off offset:256
	s_waitcnt vmcnt(15)
	v_lshlrev_b32_e32 v68, 16, v212
	v_and_b32_e32 v69, 0xffff0000, v212
	v_lshlrev_b32_e32 v64, 16, v213
	v_and_b32_e32 v65, 0xffff0000, v213
	v_lshlrev_b32_e32 v70, 16, v214
	v_and_b32_e32 v71, 0xffff0000, v214
	v_lshlrev_b32_e32 v66, 16, v215
	v_and_b32_e32 v67, 0xffff0000, v215
	v_pk_mul_f32 v[62:63], v[62:63], v[64:65]
	v_pk_mul_f32 v[60:61], v[60:61], v[68:69]
	v_pk_mul_f32 v[64:65], v[58:59], v[66:67]
	v_pk_mul_f32 v[58:59], v[56:57], v[70:71]
	v_cvt_pk_bf16_f32 v56, v60, v61
	v_cvt_pk_bf16_f32 v57, v62, v63
	v_lshl_add_u64 v[66:67], s[18:19], 0, v[80:81]
	v_cvt_pk_bf16_f32 v58, v58, v59
	v_cvt_pk_bf16_f32 v59, v64, v65
	v_lshl_add_u64 v[64:65], v[176:177], 0, s[4:5]
	global_store_dwordx4 v[66:67], v[56:59], off
	v_lshl_add_u64 v[68:69], s[14:15], 0, v[64:65]
	s_mov_b64 s[4:5], 0xa0000
	s_waitcnt vmcnt(15)
; __device__ __forceinline__ float bf_lo(unsigned w) { return __uint_as_float(w << 16); }
; __device__ __forceinline__ float bf_hi(unsigned w) { return __uint_as_float(w & 0xffff0000u); }
; __device__ __forceinline__ u32x4 pack8(f32x4 v0, f32x4 v1) { u32x4 w; w.x = cvt_pk_bf16(v0[0], v0[1]); w.y = cvt_pk_bf16(v0[2], v0[3]); w.z = cvt_pk_bf16(v1[0], v1[1]); w.w = cvt_pk_bf16(v1[2], v1[3]); return w; }
;     __device__ __forceinline__ void operator()(const f32x4 (&acc)[2][2][4][2], const Unit& u, int wr, int wc, int fr, int fq) const {
;     ...
;             for (int m = 0; m < 4; ++m) { const size_t off = (size_t)(row0 + ai * HALF + m * 16) * DM + col0;
; #pragma unroll
;                 for (int bj = 0; bj < 2; ++bj) { const u32x4 gw = *(const u32x4*)(SG + off + bj * HALF);
;                     f32x4 v0 = (acc[ai][bj][m][0] + bv[bj][0]) * sv[bj][0], v1 = (acc[ai][bj][m][1] + bv[bj][1]) * sv[bj][1];
;                     v0 = v0 * (f32x4){bf_lo(gw.x), bf_hi(gw.x), bf_lo(gw.y), bf_hi(gw.y)}; v1 = v1 * (f32x4){bf_lo(gw.z), bf_hi(gw.z), bf_lo(gw.w), bf_hi(gw.w)};
;                     *(u32x4*)(Z + off + bj * HALF) = pack8(v0, v1); } }
	v_lshlrev_b32_e32 v56, 16, v216
	v_and_b32_e32 v57, 0xffff0000, v216
	v_lshlrev_b32_e32 v58, 16, v217
	v_and_b32_e32 v59, 0xffff0000, v217
	v_lshlrev_b32_e32 v60, 16, v218
	v_and_b32_e32 v61, 0xffff0000, v218
	v_lshlrev_b32_e32 v62, 16, v219
	v_and_b32_e32 v63, 0xffff0000, v219
	v_pk_mul_f32 v[52:53], v[52:53], v[56:57]
	v_pk_mul_f32 v[56:57], v[46:47], v[62:63]
	v_pk_mul_f32 v[46:47], v[44:45], v[60:61]
	v_pk_mul_f32 v[54:55], v[54:55], v[58:59]
	v_cvt_pk_bf16_f32 v44, v52, v53
	s_nop 0
	v_cvt_pk_bf16_f32 v45, v54, v55
	v_cvt_pk_bf16_f32 v46, v46, v47
	v_cvt_pk_bf16_f32 v47, v56, v57
	global_store_dwordx4 v[66:67], v[44:47], off offset:256
	s_waitcnt vmcnt(15)
	v_lshlrev_b32_e32 v52, 16, v226
	v_and_b32_e32 v53, 0xffff0000, v226
	v_lshlrev_b32_e32 v44, 16, v227
	v_and_b32_e32 v45, 0xffff0000, v227
	v_lshlrev_b32_e32 v54, 16, v228
	v_and_b32_e32 v55, 0xffff0000, v228
	v_lshlrev_b32_e32 v46, 16, v229
	v_and_b32_e32 v47, 0xffff0000, v229
	v_pk_mul_f32 v[44:45], v[50:51], v[44:45]
	v_pk_mul_f32 v[46:47], v[42:43], v[46:47]
	v_pk_mul_f32 v[42:43], v[40:41], v[54:55]
	v_pk_mul_f32 v[48:49], v[48:49], v[52:53]
	v_lshl_add_u64 v[50:51], s[18:19], 0, v[64:65]
	v_cvt_pk_bf16_f32 v40, v48, v49
	v_cvt_pk_bf16_f32 v41, v44, v45
	v_cvt_pk_bf16_f32 v42, v42, v43
	v_cvt_pk_bf16_f32 v43, v46, v47
	v_lshl_add_u64 v[48:49], v[176:177], 0, s[4:5]
	global_store_dwordx4 v[50:51], v[40:43], off
	v_lshl_add_u64 v[52:53], s[14:15], 0, v[48:49]
	s_mov_b64 s[4:5], 0xb0000
	s_waitcnt vmcnt(13)
	v_lshlrev_b32_e32 v40, 16, v230
	v_and_b32_e32 v41, 0xffff0000, v230
	v_lshlrev_b32_e32 v42, 16, v231
	v_and_b32_e32 v43, 0xffff0000, v231
	v_lshlrev_b32_e32 v44, 16, v232
	v_and_b32_e32 v45, 0xffff0000, v232
	v_lshlrev_b32_e32 v46, 16, v233
	v_and_b32_e32 v47, 0xffff0000, v233
	v_pk_mul_f32 v[36:37], v[36:37], v[40:41]
	v_pk_mul_f32 v[40:41], v[30:31], v[46:47]
	v_pk_mul_f32 v[30:31], v[28:29], v[44:45]
	v_pk_mul_f32 v[38:39], v[38:39], v[42:43]
	v_cvt_pk_bf16_f32 v28, v36, v37
	s_nop 0
	v_cvt_pk_bf16_f32 v29, v38, v39
	v_cvt_pk_bf16_f32 v30, v30, v31
	v_cvt_pk_bf16_f32 v31, v40, v41
	global_store_dwordx4 v[50:51], v[28:31], off offset:256
	s_waitcnt vmcnt(13)
	v_lshlrev_b32_e32 v36, 16, v234
	v_and_b32_e32 v37, 0xffff0000, v234
	v_lshlrev_b32_e32 v28, 16, v235
	v_and_b32_e32 v29, 0xffff0000, v235
	v_lshlrev_b32_e32 v38, 16, v236
	v_and_b32_e32 v39, 0xffff0000, v236
	v_lshlrev_b32_e32 v30, 16, v237
	v_and_b32_e32 v31, 0xffff0000, v237
	v_pk_mul_f32 v[28:29], v[34:35], v[28:29]
	v_pk_mul_f32 v[30:31], v[26:27], v[30:31]
	v_pk_mul_f32 v[26:27], v[24:25], v[38:39]
	v_pk_mul_f32 v[32:33], v[32:33], v[36:37]
	v_lshl_add_u64 v[34:35], s[18:19], 0, v[48:49]
	v_cvt_pk_bf16_f32 v24, v32, v33
	v_cvt_pk_bf16_f32 v25, v28, v29
	v_cvt_pk_bf16_f32 v26, v26, v27
	v_cvt_pk_bf16_f32 v27, v30, v31
	v_lshl_add_u64 v[32:33], v[176:177], 0, s[4:5]
	global_store_dwordx4 v[34:35], v[24:27], off
	v_lshl_add_u64 v[36:37], s[14:15], 0, v[32:33]
	s_waitcnt vmcnt(11)
	v_lshlrev_b32_e32 v24, 16, v238
	v_and_b32_e32 v25, 0xffff0000, v238
	v_lshlrev_b32_e32 v26, 16, v239
	v_and_b32_e32 v27, 0xffff0000, v239
	v_lshlrev_b32_e32 v28, 16, v240
	v_and_b32_e32 v29, 0xffff0000, v240
	v_lshlrev_b32_e32 v30, 16, v241
	v_and_b32_e32 v31, 0xffff0000, v241
	v_pk_mul_f32 v[20:21], v[20:21], v[24:25]
	v_pk_mul_f32 v[24:25], v[14:15], v[30:31]
	v_pk_mul_f32 v[14:15], v[12:13], v[28:29]
	v_pk_mul_f32 v[22:23], v[22:23], v[26:27]
	v_cvt_pk_bf16_f32 v12, v20, v21
	s_nop 0
	v_cvt_pk_bf16_f32 v13, v22, v23
	v_cvt_pk_bf16_f32 v14, v14, v15
	v_cvt_pk_bf16_f32 v15, v24, v25
	global_store_dwordx4 v[34:35], v[12:15], off offset:256
	s_waitcnt vmcnt(11)
	v_lshlrev_b32_e32 v20, 16, v242
	v_and_b32_e32 v21, 0xffff0000, v242
	v_lshlrev_b32_e32 v12, 16, v243
	v_and_b32_e32 v13, 0xffff0000, v243
	v_lshlrev_b32_e32 v22, 16, v244
	v_and_b32_e32 v23, 0xffff0000, v244
	v_lshlrev_b32_e32 v14, 16, v245
	v_and_b32_e32 v15, 0xffff0000, v245
	v_pk_mul_f32 v[12:13], v[18:19], v[12:13]
	v_pk_mul_f32 v[14:15], v[10:11], v[14:15]
	v_pk_mul_f32 v[10:11], v[8:9], v[22:23]
	v_pk_mul_f32 v[16:17], v[16:17], v[20:21]
	s_nop 0
	v_cvt_pk_bf16_f32 v8, v16, v17
	v_cvt_pk_bf16_f32 v9, v12, v13
	v_cvt_pk_bf16_f32 v10, v10, v11
	v_cvt_pk_bf16_f32 v11, v14, v15
	v_lshl_add_u64 v[16:17], s[18:19], 0, v[32:33]
	global_store_dwordx4 v[16:17], v[8:11], off
	s_waitcnt vmcnt(9)
	s_nop 0
	v_lshlrev_b32_e32 v8, 16, v200
	v_and_b32_e32 v9, 0xffff0000, v200
	v_lshlrev_b32_e32 v10, 16, v201
	v_and_b32_e32 v11, 0xffff0000, v201
	v_lshlrev_b32_e32 v12, 16, v202
	v_and_b32_e32 v13, 0xffff0000, v202
	v_lshlrev_b32_e32 v14, 16, v203
	v_and_b32_e32 v15, 0xffff0000, v203
	v_pk_mul_f32 v[4:5], v[4:5], v[8:9]
	v_pk_mul_f32 v[8:9], v[2:3], v[14:15]
	v_pk_mul_f32 v[2:3], v[0:1], v[12:13]
	v_pk_mul_f32 v[6:7], v[6:7], v[10:11]
	v_cvt_pk_bf16_f32 v0, v4, v5
	s_nop 0
	v_cvt_pk_bf16_f32 v1, v6, v7
	v_cvt_pk_bf16_f32 v2, v2, v3
	v_cvt_pk_bf16_f32 v3, v8, v9
	global_store_dwordx4 v[16:17], v[0:3], off offset:256
	s_cbranch_vccnz .LBB0_568
	s_andn2_b64 vcc, exec, s[10:11]
	s_cbranch_vccnz .LBB0_567
	s_barrier
	s_branch .LBB0_567

; #define LAS __attribute__((address_space(3)))
; __device__ __forceinline__ void tr_load(const TrDesc& d, int lane, f32x4 (&wv)[8]) {
;     const int nblk = d.N / 32, kb = d.item / nblk, nb = d.item % nblk, k0 = 64 * kb, n0 = 32 * nb;
; #pragma unroll
;     for (int i = 0; i < 8; ++i) wv[i] = *(const f32x4*)(d.W + (size_t)(k0 + 8 * i + (lane >> 3)) * d.N + n0 + (lane & 7) * 4);
; }
; __device__ __forceinline__ void tr_run(const Args& a, int list, int first, int stride, int lane, LAS float* scr, int n_end = -1) {
;     const int n = n_end >= 0 ? n_end : (list == 0 ? I_LIST0 : (list == 1 ? I_LIST1 : I_LIST2));
;     int it = first; if (it >= n) return;
;     TrDesc d = tr_desc(a, list, it); f32x4 wv[8]; tr_load(d, lane, wv);
; __global__ void __launch_bounds__(NWAVES * 64, 2) mk_fwd(Args args) {
;     ...
;         if (F.G == 256 && (int)blockIdx.x >= 64) {
;             const int lb = (int)blockIdx.x - 64;
;             if (F.wave < 4) gemv_item(c, c_ctx, ada_w, ada_b, mod, 768 + lb * 4 + F.wave, threadIdx.x & 63);
;             else tr_run(args, 2, lb * 4 + (F.wave - 4), 192 * 4, threadIdx.x & 63, (LAS float*)(F.lds + F.wave * 16384));
.LBB0_648:
	s_cmpk_lg_i32 s63, 0x100
	s_cselect_b64 s[0:1], -1, 0
	s_cmp_lt_i32 s2, 64
	s_cselect_b64 s[6:7], -1, 0
	s_or_b64 s[0:1], s[6:7], s[0:1]
	s_and_b64 vcc, exec, s[0:1]
	s_cbranch_vccnz .LBB0_666
	s_lshl_b32 s6, s2, 2
	s_cmpk_gt_u32 s57, 0xff
	s_mov_b64 s[0:1], -1
	s_cbranch_scc0 .LBB0_658
	s_add_i32 s0, s6, s3
	s_add_i32 s10, s0, 0xfffffefc
	s_cmpk_gt_i32 s10, 0x7ff
	s_cbranch_scc1 .LBB0_657
	s_ashr_i32 s0, s10, 31
	s_lshr_b32 s0, s0, 26
	s_add_i32 s0, s10, s0
	s_and_b32 s1, s0, 0xffffffc0
	v_bfe_u32 v68, v198, 3, 3
	s_sub_i32 s0, s10, s1
	v_or_b32_e32 v0, s1, v68
	s_lshl_b32 s0, s0, 5
	v_ashrrev_i32_e32 v1, 31, v0
	v_or_b32_e32 v6, 8, v0
	s_ashr_i32 s1, s0, 31
	v_lshlrev_b64 v[4:5], 13, v[0:1]
	v_ashrrev_i32_e32 v7, 31, v6
	v_and_b32_e32 v2, 28, v146
	v_lshl_add_u64 v[4:5], s[92:93], 0, v[4:5]
	s_lshl_b64 s[0:1], s[0:1], 2
	v_lshlrev_b64 v[6:7], 13, v[6:7]
	v_mov_b32_e32 v65, 0
	v_lshl_add_u64 v[4:5], v[4:5], 0, s[0:1]
	v_lshlrev_b32_e32 v64, 2, v2
	v_lshl_add_u64 v[6:7], s[92:93], 0, v[6:7]
	v_lshl_add_u64 v[4:5], v[4:5], 0, v[64:65]
	v_lshl_add_u64 v[6:7], v[6:7], 0, s[0:1]
	v_lshl_add_u64 v[6:7], v[6:7], 0, v[64:65]
	global_load_dwordx4 v[56:59], v[4:5], off nt
	global_load_dwordx4 v[44:47], v[6:7], off nt
	v_or_b32_e32 v4, 16, v0
	v_ashrrev_i32_e32 v5, 31, v4
	v_or_b32_e32 v6, 24, v0
	v_lshlrev_b64 v[4:5], 13, v[4:5]
	v_ashrrev_i32_e32 v7, 31, v6
	v_lshl_add_u64 v[4:5], s[92:93], 0, v[4:5]
	v_lshlrev_b64 v[6:7], 13, v[6:7]
	v_lshl_add_u64 v[4:5], v[4:5], 0, s[0:1]
	v_lshl_add_u64 v[6:7], s[92:93], 0, v[6:7]
	v_lshl_add_u64 v[4:5], v[4:5], 0, v[64:65]
	v_lshl_add_u64 v[6:7], v[6:7], 0, s[0:1]
	v_lshl_add_u64 v[6:7], v[6:7], 0, v[64:65]
	global_load_dwordx4 v[52:55], v[4:5], off nt
	global_load_dwordx4 v[36:39], v[6:7], off nt
	v_or_b32_e32 v4, 32, v0
	v_ashrrev_i32_e32 v5, 31, v4
	v_or_b32_e32 v6, 40, v0
	v_lshlrev_b64 v[4:5], 13, v[4:5]
	v_ashrrev_i32_e32 v7, 31, v6
	v_lshl_add_u64 v[4:5], s[92:93], 0, v[4:5]
	v_lshlrev_b64 v[6:7], 13, v[6:7]
	v_lshl_add_u64 v[4:5], v[4:5], 0, s[0:1]
	v_lshl_add_u64 v[6:7], s[92:93], 0, v[6:7]
	v_lshl_add_u64 v[4:5], v[4:5], 0, v[64:65]
	v_lshl_add_u64 v[6:7], v[6:7], 0, s[0:1]
	v_lshl_add_u64 v[6:7], v[6:7], 0, v[64:65]
	global_load_dwordx4 v[48:51], v[4:5], off nt
	global_load_dwordx4 v[32:35], v[6:7], off nt
	v_or_b32_e32 v4, 48, v0
	v_ashrrev_i32_e32 v5, 31, v4
	v_or_b32_e32 v0, 56, v0
	v_lshlrev_b64 v[4:5], 13, v[4:5]
	v_ashrrev_i32_e32 v1, 31, v0
	v_lshl_add_u64 v[4:5], s[92:93], 0, v[4:5]
	v_lshlrev_b64 v[0:1], 13, v[0:1]
	v_lshl_add_u64 v[4:5], v[4:5], 0, s[0:1]
	v_lshl_add_u64 v[0:1], s[92:93], 0, v[0:1]
	v_lshl_add_u64 v[4:5], v[4:5], 0, v[64:65]
	v_lshl_add_u64 v[0:1], v[0:1], 0, s[0:1]
	v_lshl_add_u64 v[0:1], v[0:1], 0, v[64:65]
	global_load_dwordx4 v[40:43], v[4:5], off nt
	global_load_dwordx4 v[60:63], v[0:1], off nt
	v_lshlrev_b32_e32 v0, 3, v198
	s_lshl_b32 s0, s3, 14
	v_and_b32_e32 v0, 56, v0
	s_add_i32 s0, s0, 0
	v_mul_u32_u24_e32 v4, 0x84, v0
	v_lshlrev_b32_e32 v5, 2, v68
	v_add_u32_e32 v1, s0, v64
	v_mul_u32_u24_e32 v3, 0x84, v68
	v_add3_u32 v72, s0, v4, v5
	s_lshl_b32 s0, s10, 5
	v_or_b32_e32 v69, 8, v68
	v_or_b32_e32 v70, 16, v68
	v_or_b32_e32 v71, 24, v68
	s_add_i32 s7, s0, 0x6000
	v_lshlrev_b32_e32 v66, 2, v2
	v_add_u32_e32 v73, v1, v3
	v_lshlrev_b32_e32 v64, 1, v0
	s_mov_b32 s8, s10
	s_mov_b32 s9, s10
	s_branch .LBB0_653

; __device__ __forceinline__ void tr_load(const TrDesc& d, int lane, f32x4 (&wv)[8]) {
;     const int nblk = d.N / 32, kb = d.item / nblk, nb = d.item % nblk, k0 = 64 * kb, n0 = 32 * nb;
; #pragma unroll
;     for (int i = 0; i < 8; ++i) wv[i] = *(const f32x4*)(d.W + (size_t)(k0 + 8 * i + (lane >> 3)) * d.N + n0 + (lane & 7) * 4);
; }
; __device__ __forceinline__ void tr_run(const Args& a, int list, int first, int stride, int lane, LAS float* scr, int n_end = -1) {
;     ...
;         const int nit = it + stride; const bool more = nit < n;
;         TrDesc dn = d; f32x4 wn[8];
;         if (more) { dn = tr_desc(a, list, nit); tr_load(dn, lane, wn); }
.LBB0_653:
	s_mov_b32 s11, s8
	s_addk_i32 s8, 0x300
	s_cmpk_lt_i32 s11, 0x500
	s_cselect_b64 s[0:1], -1, 0
	s_cmpk_gt_i32 s11, 0x4ff
	s_cbranch_scc1 .LBB0_655
	s_ashr_i32 s9, s8, 31
	s_lshr_b32 s9, s9, 26
	s_add_i32 s9, s8, s9
	s_and_b32 s11, s9, 0xffffffc0
	v_or_b32_e32 v24, s11, v68
	s_lshl_b32 s9, s9, 5
	v_ashrrev_i32_e32 v25, 31, v24
	s_and_b32 s9, s9, 0xfffff800
	v_lshlrev_b64 v[0:1], 13, v[24:25]
	v_or_b32_e32 v2, 8, v24
	v_or_b32_e32 v8, 16, v24
	v_or_b32_e32 v10, 24, v24
	v_or_b32_e32 v16, 32, v24
	v_or_b32_e32 v18, 40, v24
	v_or_b32_e32 v26, 48, v24
	v_or_b32_e32 v24, 56, v24
	s_sub_i32 s22, s7, s9
	v_ashrrev_i32_e32 v3, 31, v2
	v_ashrrev_i32_e32 v9, 31, v8
	v_ashrrev_i32_e32 v11, 31, v10
	v_ashrrev_i32_e32 v17, 31, v16
	v_ashrrev_i32_e32 v19, 31, v18
	v_ashrrev_i32_e32 v27, 31, v26
	v_ashrrev_i32_e32 v25, 31, v24
	s_ashr_i32 s23, s22, 31
	v_lshlrev_b64 v[2:3], 13, v[2:3]
	v_lshlrev_b64 v[8:9], 13, v[8:9]
	v_lshlrev_b64 v[10:11], 13, v[10:11]
	v_lshlrev_b64 v[16:17], 13, v[16:17]
	v_lshlrev_b64 v[18:19], 13, v[18:19]
	v_lshlrev_b64 v[26:27], 13, v[26:27]
	v_lshlrev_b64 v[24:25], 13, v[24:25]
	v_lshl_add_u64 v[0:1], s[92:93], 0, v[0:1]
	s_lshl_b64 s[22:23], s[22:23], 2
	v_lshl_add_u64 v[2:3], s[92:93], 0, v[2:3]
	v_lshl_add_u64 v[8:9], s[92:93], 0, v[8:9]
	v_lshl_add_u64 v[10:11], s[92:93], 0, v[10:11]
	v_lshl_add_u64 v[16:17], s[92:93], 0, v[16:17]
	v_lshl_add_u64 v[18:19], s[92:93], 0, v[18:19]
	v_lshl_add_u64 v[26:27], s[92:93], 0, v[26:27]
	v_lshl_add_u64 v[24:25], s[92:93], 0, v[24:25]
	v_lshl_add_u64 v[0:1], v[0:1], 0, s[22:23]
	v_mov_b32_e32 v67, v65
	v_lshl_add_u64 v[2:3], v[2:3], 0, s[22:23]
	v_lshl_add_u64 v[8:9], v[8:9], 0, s[22:23]
	v_lshl_add_u64 v[10:11], v[10:11], 0, s[22:23]
	v_lshl_add_u64 v[16:17], v[16:17], 0, s[22:23]
	v_lshl_add_u64 v[18:19], v[18:19], 0, s[22:23]
	v_lshl_add_u64 v[26:27], v[26:27], 0, s[22:23]
	v_lshl_add_u64 v[24:25], v[24:25], 0, s[22:23]
	v_lshl_add_u64 v[0:1], v[0:1], 0, v[66:67]
	v_lshl_add_u64 v[2:3], v[2:3], 0, v[66:67]
	v_lshl_add_u64 v[8:9], v[8:9], 0, v[66:67]
	v_lshl_add_u64 v[10:11], v[10:11], 0, v[66:67]
	v_lshl_add_u64 v[16:17], v[16:17], 0, v[66:67]
	v_lshl_add_u64 v[18:19], v[18:19], 0, v[66:67]
	v_lshl_add_u64 v[26:27], v[26:27], 0, v[66:67]
	v_lshl_add_u64 v[24:25], v[24:25], 0, v[66:67]
	global_load_dwordx4 v[4:7], v[0:1], off nt
	s_nop 0
	global_load_dwordx4 v[0:3], v[2:3], off nt
	s_nop 0
	global_load_dwordx4 v[12:15], v[8:9], off nt
	s_nop 0
	global_load_dwordx4 v[8:11], v[10:11], off nt
	s_nop 0
	global_load_dwordx4 v[20:23], v[16:17], off nt
	s_nop 0
	global_load_dwordx4 v[16:19], v[18:19], off nt
	s_nop 0
	global_load_dwordx4 v[28:31], v[26:27], off nt
	s_nop 0
	global_load_dwordx4 v[24:27], v[24:25], off nt
	s_mov_b32 s9, s8

; __device__ __forceinline__ void gemv_item(const float* c, const float* c_ctx, const float* ada_w, const float* ada_b, float* mod, int it, int lane) {
;     ...
;     for (int kk = 0; kk < 64; ++kk) { const f32x4 w = *(const f32x4*)(W + (size_t)kk * 6144);
; #pragma unroll
;         for (int r = 0; r < 9; ++r) { const float sk = __uint_as_float(__builtin_amdgcn_readlane(__float_as_uint(s[r]), kk)); acc[r] += w * sk; } }
.LBB0_660:
	v_add_co_u32_e32 v48, vcc, s11, v0
	v_readlane_b32 s36, v3, s9
	s_nop 0
	v_addc_co_u32_e32 v49, vcc, -1, v1, vcc
	global_load_dwordx4 v[48:51], v[48:49], off nt
	s_waitcnt vmcnt(0)
	v_pk_fma_f32 v[36:37], v[50:51], s[36:37], v[36:37] op_sel_hi:[1,0,1]
	v_pk_fma_f32 v[38:39], v[48:49], s[36:37], v[38:39] op_sel_hi:[1,0,1]
	v_readlane_b32 s36, v40, s9
	s_nop 1
	v_pk_fma_f32 v[32:33], v[50:51], s[36:37], v[32:33] op_sel_hi:[1,0,1]
	v_pk_fma_f32 v[34:35], v[48:49], s[36:37], v[34:35] op_sel_hi:[1,0,1]
	v_readlane_b32 s36, v41, s9
	s_nop 1
	v_pk_fma_f32 v[28:29], v[50:51], s[36:37], v[28:29] op_sel_hi:[1,0,1]
	v_pk_fma_f32 v[30:31], v[48:49], s[36:37], v[30:31] op_sel_hi:[1,0,1]
	v_readlane_b32 s36, v42, s9
	s_nop 1
	v_pk_fma_f32 v[24:25], v[50:51], s[36:37], v[24:25] op_sel_hi:[1,0,1]
	v_pk_fma_f32 v[26:27], v[48:49], s[36:37], v[26:27] op_sel_hi:[1,0,1]
	v_readlane_b32 s36, v43, s9
	s_nop 1
	v_pk_fma_f32 v[20:21], v[50:51], s[36:37], v[20:21] op_sel_hi:[1,0,1]
	v_pk_fma_f32 v[22:23], v[48:49], s[36:37], v[22:23] op_sel_hi:[1,0,1]
	v_readlane_b32 s36, v44, s9
	s_nop 1
	v_pk_fma_f32 v[16:17], v[50:51], s[36:37], v[16:17] op_sel_hi:[1,0,1]
	v_pk_fma_f32 v[18:19], v[48:49], s[36:37], v[18:19] op_sel_hi:[1,0,1]
	v_readlane_b32 s36, v45, s9
	s_nop 1
	v_pk_fma_f32 v[12:13], v[50:51], s[36:37], v[12:13] op_sel_hi:[1,0,1]
	v_pk_fma_f32 v[14:15], v[48:49], s[36:37], v[14:15] op_sel_hi:[1,0,1]
	v_readlane_b32 s36, v46, s9
	s_nop 1
	v_pk_fma_f32 v[8:9], v[50:51], s[36:37], v[8:9] op_sel_hi:[1,0,1]
	v_pk_fma_f32 v[10:11], v[48:49], s[36:37], v[10:11] op_sel_hi:[1,0,1]
	v_readlane_b32 s36, v47, s9
	s_nop 1
	v_pk_fma_f32 v[48:49], v[48:49], s[36:37], v[4:5] op_sel_hi:[1,0,1]
	v_add_co_u32_e32 v4, vcc, s22, v0
	v_pk_fma_f32 v[50:51], v[50:51], s[36:37], v[6:7] op_sel_hi:[1,0,1]
	s_nop 0
	v_addc_co_u32_e32 v5, vcc, -1, v1, vcc
	global_load_dwordx4 v[4:7], v[4:5], off nt
	s_add_i32 s37, s9, 1
	v_readlane_b32 s36, v3, s37
	s_waitcnt vmcnt(0)
	s_nop 0
	v_pk_fma_f32 v[36:37], v[6:7], s[36:37], v[36:37] op_sel_hi:[1,0,1]
	v_pk_fma_f32 v[38:39], v[4:5], s[36:37], v[38:39] op_sel_hi:[1,0,1]
	v_readlane_b32 s36, v40, s37
	s_nop 1
	v_pk_fma_f32 v[32:33], v[6:7], s[36:37], v[32:33] op_sel_hi:[1,0,1]
	v_pk_fma_f32 v[34:35], v[4:5], s[36:37], v[34:35] op_sel_hi:[1,0,1]
	v_readlane_b32 s36, v41, s37
	s_nop 1
	v_pk_fma_f32 v[28:29], v[6:7], s[36:37], v[28:29] op_sel_hi:[1,0,1]
	v_pk_fma_f32 v[30:31], v[4:5], s[36:37], v[30:31] op_sel_hi:[1,0,1]
	v_readlane_b32 s36, v42, s37
	s_nop 1
	v_pk_fma_f32 v[24:25], v[6:7], s[36:37], v[24:25] op_sel_hi:[1,0,1]
	v_pk_fma_f32 v[26:27], v[4:5], s[36:37], v[26:27] op_sel_hi:[1,0,1]
	v_readlane_b32 s36, v43, s37
	s_nop 1
	v_pk_fma_f32 v[20:21], v[6:7], s[36:37], v[20:21] op_sel_hi:[1,0,1]
	v_pk_fma_f32 v[22:23], v[4:5], s[36:37], v[22:23] op_sel_hi:[1,0,1]
	v_readlane_b32 s36, v44, s37
	s_nop 1
	v_pk_fma_f32 v[16:17], v[6:7], s[36:37], v[16:17] op_sel_hi:[1,0,1]
	v_pk_fma_f32 v[18:19], v[4:5], s[36:37], v[18:19] op_sel_hi:[1,0,1]
	v_readlane_b32 s36, v45, s37
	s_nop 1
	v_pk_fma_f32 v[12:13], v[6:7], s[36:37], v[12:13] op_sel_hi:[1,0,1]
	v_pk_fma_f32 v[14:15], v[4:5], s[36:37], v[14:15] op_sel_hi:[1,0,1]
	v_readlane_b32 s36, v46, s37
	s_nop 1
	v_pk_fma_f32 v[8:9], v[6:7], s[36:37], v[8:9] op_sel_hi:[1,0,1]
	v_pk_fma_f32 v[10:11], v[4:5], s[36:37], v[10:11] op_sel_hi:[1,0,1]
	v_readlane_b32 s36, v47, s37
	s_nop 1
	v_pk_fma_f32 v[48:49], v[4:5], s[36:37], v[48:49] op_sel_hi:[1,0,1]
	v_add_co_u32_e32 v4, vcc, s23, v0
	v_pk_fma_f32 v[50:51], v[6:7], s[36:37], v[50:51] op_sel_hi:[1,0,1]
	s_nop 0
	v_addc_co_u32_e32 v5, vcc, -1, v1, vcc
	global_load_dwordx4 v[4:7], v[4:5], off nt
	s_add_i32 s37, s9, 2
	v_readlane_b32 s36, v3, s37
	s_waitcnt vmcnt(0)
	s_nop 0
	v_pk_fma_f32 v[36:37], v[6:7], s[36:37], v[36:37] op_sel_hi:[1,0,1]
	v_pk_fma_f32 v[38:39], v[4:5], s[36:37], v[38:39] op_sel_hi:[1,0,1]
	v_readlane_b32 s36, v40, s37
	s_nop 1
	v_pk_fma_f32 v[32:33], v[6:7], s[36:37], v[32:33] op_sel_hi:[1,0,1]
	v_pk_fma_f32 v[34:35], v[4:5], s[36:37], v[34:35] op_sel_hi:[1,0,1]
	v_readlane_b32 s36, v41, s37
	s_nop 1
	v_pk_fma_f32 v[28:29], v[6:7], s[36:37], v[28:29] op_sel_hi:[1,0,1]
	v_pk_fma_f32 v[30:31], v[4:5], s[36:37], v[30:31] op_sel_hi:[1,0,1]
	v_readlane_b32 s36, v42, s37
	s_nop 1
	v_pk_fma_f32 v[24:25], v[6:7], s[36:37], v[24:25] op_sel_hi:[1,0,1]
	v_pk_fma_f32 v[26:27], v[4:5], s[36:37], v[26:27] op_sel_hi:[1,0,1]
	v_readlane_b32 s36, v43, s37
	s_nop 1
	v_pk_fma_f32 v[20:21], v[6:7], s[36:37], v[20:21] op_sel_hi:[1,0,1]
	v_pk_fma_f32 v[22:23], v[4:5], s[36:37], v[22:23] op_sel_hi:[1,0,1]
	v_readlane_b32 s36, v44, s37
	s_nop 1
	v_pk_fma_f32 v[16:17], v[6:7], s[36:37], v[16:17] op_sel_hi:[1,0,1]
	v_pk_fma_f32 v[18:19], v[4:5], s[36:37], v[18:19] op_sel_hi:[1,0,1]
	v_readlane_b32 s36, v45, s37
	s_nop 1
	v_pk_fma_f32 v[12:13], v[6:7], s[36:37], v[12:13] op_sel_hi:[1,0,1]
	v_pk_fma_f32 v[14:15], v[4:5], s[36:37], v[14:15] op_sel_hi:[1,0,1]
	v_readlane_b32 s36, v46, s37
	s_nop 1
	v_pk_fma_f32 v[8:9], v[6:7], s[36:37], v[8:9] op_sel_hi:[1,0,1]
	v_pk_fma_f32 v[10:11], v[4:5], s[36:37], v[10:11] op_sel_hi:[1,0,1]
	v_readlane_b32 s36, v47, s37
	s_nop 1
	v_pk_fma_f32 v[48:49], v[4:5], s[36:37], v[48:49] op_sel_hi:[1,0,1]
	v_add_co_u32_e32 v4, vcc, s24, v0
	v_pk_fma_f32 v[50:51], v[6:7], s[36:37], v[50:51] op_sel_hi:[1,0,1]
	s_nop 0
	v_addc_co_u32_e32 v5, vcc, -1, v1, vcc
	global_load_dwordx4 v[4:7], v[4:5], off nt
	s_add_i32 s37, s9, 3
	v_readlane_b32 s36, v3, s37
	s_waitcnt vmcnt(0)
; __device__ __forceinline__ void gemv_item(const float* c, const float* c_ctx, const float* ada_w, const float* ada_b, float* mod, int it, int lane) {
;     ...
;     for (int kk = 0; kk < 64; ++kk) { const f32x4 w = *(const f32x4*)(W + (size_t)kk * 6144);
; #pragma unroll
;         for (int r = 0; r < 9; ++r) { const float sk = __uint_as_float(__builtin_amdgcn_readlane(__float_as_uint(s[r]), kk)); acc[r] += w * sk; } }
	s_nop 0
	v_pk_fma_f32 v[36:37], v[6:7], s[36:37], v[36:37] op_sel_hi:[1,0,1]
	v_pk_fma_f32 v[38:39], v[4:5], s[36:37], v[38:39] op_sel_hi:[1,0,1]
	v_readlane_b32 s36, v40, s37
	s_nop 1
	v_pk_fma_f32 v[32:33], v[6:7], s[36:37], v[32:33] op_sel_hi:[1,0,1]
	v_pk_fma_f32 v[34:35], v[4:5], s[36:37], v[34:35] op_sel_hi:[1,0,1]
	v_readlane_b32 s36, v41, s37
	s_nop 1
	v_pk_fma_f32 v[28:29], v[6:7], s[36:37], v[28:29] op_sel_hi:[1,0,1]
	v_pk_fma_f32 v[30:31], v[4:5], s[36:37], v[30:31] op_sel_hi:[1,0,1]
	v_readlane_b32 s36, v42, s37
	s_nop 1
	v_pk_fma_f32 v[24:25], v[6:7], s[36:37], v[24:25] op_sel_hi:[1,0,1]
	v_pk_fma_f32 v[26:27], v[4:5], s[36:37], v[26:27] op_sel_hi:[1,0,1]
	v_readlane_b32 s36, v43, s37
	s_nop 1
	v_pk_fma_f32 v[20:21], v[6:7], s[36:37], v[20:21] op_sel_hi:[1,0,1]
	v_pk_fma_f32 v[22:23], v[4:5], s[36:37], v[22:23] op_sel_hi:[1,0,1]
	v_readlane_b32 s36, v44, s37
	s_nop 1
	v_pk_fma_f32 v[16:17], v[6:7], s[36:37], v[16:17] op_sel_hi:[1,0,1]
	v_pk_fma_f32 v[18:19], v[4:5], s[36:37], v[18:19] op_sel_hi:[1,0,1]
	v_readlane_b32 s36, v45, s37
	s_nop 1
	v_pk_fma_f32 v[12:13], v[6:7], s[36:37], v[12:13] op_sel_hi:[1,0,1]
	v_pk_fma_f32 v[14:15], v[4:5], s[36:37], v[14:15] op_sel_hi:[1,0,1]
	v_readlane_b32 s36, v46, s37
	s_nop 1
	v_pk_fma_f32 v[8:9], v[6:7], s[36:37], v[8:9] op_sel_hi:[1,0,1]
	v_pk_fma_f32 v[10:11], v[4:5], s[36:37], v[10:11] op_sel_hi:[1,0,1]
	v_readlane_b32 s36, v47, s37
	s_nop 1
	v_pk_fma_f32 v[48:49], v[4:5], s[36:37], v[48:49] op_sel_hi:[1,0,1]
	v_add_co_u32_e32 v4, vcc, s25, v0
	v_pk_fma_f32 v[50:51], v[6:7], s[36:37], v[50:51] op_sel_hi:[1,0,1]
	s_nop 0
	v_addc_co_u32_e32 v5, vcc, -1, v1, vcc
	global_load_dwordx4 v[4:7], v[4:5], off nt
	s_add_i32 s37, s9, 4
	v_readlane_b32 s36, v3, s37
	s_waitcnt vmcnt(0)
	s_nop 0
	v_pk_fma_f32 v[36:37], v[6:7], s[36:37], v[36:37] op_sel_hi:[1,0,1]
	v_pk_fma_f32 v[38:39], v[4:5], s[36:37], v[38:39] op_sel_hi:[1,0,1]
	v_readlane_b32 s36, v40, s37
	s_nop 1
	v_pk_fma_f32 v[32:33], v[6:7], s[36:37], v[32:33] op_sel_hi:[1,0,1]
	v_pk_fma_f32 v[34:35], v[4:5], s[36:37], v[34:35] op_sel_hi:[1,0,1]
	v_readlane_b32 s36, v41, s37
	s_nop 1
	v_pk_fma_f32 v[28:29], v[6:7], s[36:37], v[28:29] op_sel_hi:[1,0,1]
	v_pk_fma_f32 v[30:31], v[4:5], s[36:37], v[30:31] op_sel_hi:[1,0,1]
	v_readlane_b32 s36, v42, s37
	s_nop 1
	v_pk_fma_f32 v[24:25], v[6:7], s[36:37], v[24:25] op_sel_hi:[1,0,1]
	v_pk_fma_f32 v[26:27], v[4:5], s[36:37], v[26:27] op_sel_hi:[1,0,1]
	v_readlane_b32 s36, v43, s37
	s_nop 1
	v_pk_fma_f32 v[20:21], v[6:7], s[36:37], v[20:21] op_sel_hi:[1,0,1]
	v_pk_fma_f32 v[22:23], v[4:5], s[36:37], v[22:23] op_sel_hi:[1,0,1]
	v_readlane_b32 s36, v44, s37
	s_nop 1
	v_pk_fma_f32 v[16:17], v[6:7], s[36:37], v[16:17] op_sel_hi:[1,0,1]
	v_pk_fma_f32 v[18:19], v[4:5], s[36:37], v[18:19] op_sel_hi:[1,0,1]
	v_readlane_b32 s36, v45, s37
	s_nop 1
	v_pk_fma_f32 v[12:13], v[6:7], s[36:37], v[12:13] op_sel_hi:[1,0,1]
	v_pk_fma_f32 v[14:15], v[4:5], s[36:37], v[14:15] op_sel_hi:[1,0,1]
	v_readlane_b32 s36, v46, s37
	s_nop 1
	v_pk_fma_f32 v[8:9], v[6:7], s[36:37], v[8:9] op_sel_hi:[1,0,1]
	v_pk_fma_f32 v[10:11], v[4:5], s[36:37], v[10:11] op_sel_hi:[1,0,1]
	v_readlane_b32 s36, v47, s37
	s_nop 1
	v_pk_fma_f32 v[48:49], v[4:5], s[36:37], v[48:49] op_sel_hi:[1,0,1]
	v_add_co_u32_e32 v4, vcc, s26, v0
	v_pk_fma_f32 v[50:51], v[6:7], s[36:37], v[50:51] op_sel_hi:[1,0,1]
	s_nop 0
	v_addc_co_u32_e32 v5, vcc, -1, v1, vcc
	global_load_dwordx4 v[4:7], v[4:5], off nt
	s_add_i32 s37, s9, 5
	v_readlane_b32 s36, v3, s37
	s_waitcnt vmcnt(0)
	s_nop 0
	v_pk_fma_f32 v[36:37], v[6:7], s[36:37], v[36:37] op_sel_hi:[1,0,1]
	v_pk_fma_f32 v[38:39], v[4:5], s[36:37], v[38:39] op_sel_hi:[1,0,1]
	v_readlane_b32 s36, v40, s37
	s_nop 1
	v_pk_fma_f32 v[32:33], v[6:7], s[36:37], v[32:33] op_sel_hi:[1,0,1]
	v_pk_fma_f32 v[34:35], v[4:5], s[36:37], v[34:35] op_sel_hi:[1,0,1]
	v_readlane_b32 s36, v41, s37
	s_nop 1
	v_pk_fma_f32 v[28:29], v[6:7], s[36:37], v[28:29] op_sel_hi:[1,0,1]
	v_pk_fma_f32 v[30:31], v[4:5], s[36:37], v[30:31] op_sel_hi:[1,0,1]
	v_readlane_b32 s36, v42, s37
	s_nop 1
	v_pk_fma_f32 v[24:25], v[6:7], s[36:37], v[24:25] op_sel_hi:[1,0,1]
	v_pk_fma_f32 v[26:27], v[4:5], s[36:37], v[26:27] op_sel_hi:[1,0,1]
	v_readlane_b32 s36, v43, s37
	s_nop 1
	v_pk_fma_f32 v[20:21], v[6:7], s[36:37], v[20:21] op_sel_hi:[1,0,1]
	v_pk_fma_f32 v[22:23], v[4:5], s[36:37], v[22:23] op_sel_hi:[1,0,1]
	v_readlane_b32 s36, v44, s37
	s_nop 1
	v_pk_fma_f32 v[16:17], v[6:7], s[36:37], v[16:17] op_sel_hi:[1,0,1]
	v_pk_fma_f32 v[18:19], v[4:5], s[36:37], v[18:19] op_sel_hi:[1,0,1]
	v_readlane_b32 s36, v45, s37
	s_nop 1
	v_pk_fma_f32 v[12:13], v[6:7], s[36:37], v[12:13] op_sel_hi:[1,0,1]
	v_pk_fma_f32 v[14:15], v[4:5], s[36:37], v[14:15] op_sel_hi:[1,0,1]
	v_readlane_b32 s36, v46, s37
	s_nop 1
	v_pk_fma_f32 v[8:9], v[6:7], s[36:37], v[8:9] op_sel_hi:[1,0,1]
	v_pk_fma_f32 v[10:11], v[4:5], s[36:37], v[10:11] op_sel_hi:[1,0,1]
	v_readlane_b32 s36, v47, s37
	s_nop 1
	v_pk_fma_f32 v[48:49], v[4:5], s[36:37], v[48:49] op_sel_hi:[1,0,1]
	v_add_co_u32_e32 v4, vcc, s27, v0
	v_pk_fma_f32 v[50:51], v[6:7], s[36:37], v[50:51] op_sel_hi:[1,0,1]
	s_nop 0
	v_addc_co_u32_e32 v5, vcc, -1, v1, vcc
	global_load_dwordx4 v[4:7], v[4:5], off nt
	s_add_i32 s37, s9, 6
	v_readlane_b32 s36, v3, s37
	s_waitcnt vmcnt(0)
; __device__ __forceinline__ void gemv_item(const float* c, const float* c_ctx, const float* ada_w, const float* ada_b, float* mod, int it, int lane) {
;     ...
; #pragma unroll 16
;     for (int kk = 0; kk < 64; ++kk) { const f32x4 w = *(const f32x4*)(W + (size_t)kk * 6144);
; #pragma unroll
;         for (int r = 0; r < 9; ++r) { const float sk = __uint_as_float(__builtin_amdgcn_readlane(__float_as_uint(s[r]), kk)); acc[r] += w * sk; } }
	s_nop 0
	v_pk_fma_f32 v[36:37], v[6:7], s[36:37], v[36:37] op_sel_hi:[1,0,1]
	v_pk_fma_f32 v[38:39], v[4:5], s[36:37], v[38:39] op_sel_hi:[1,0,1]
	v_readlane_b32 s36, v40, s37
	s_nop 1
	v_pk_fma_f32 v[32:33], v[6:7], s[36:37], v[32:33] op_sel_hi:[1,0,1]
	v_pk_fma_f32 v[34:35], v[4:5], s[36:37], v[34:35] op_sel_hi:[1,0,1]
	v_readlane_b32 s36, v41, s37
	s_nop 1
	v_pk_fma_f32 v[28:29], v[6:7], s[36:37], v[28:29] op_sel_hi:[1,0,1]
	v_pk_fma_f32 v[30:31], v[4:5], s[36:37], v[30:31] op_sel_hi:[1,0,1]
	v_readlane_b32 s36, v42, s37
	s_nop 1
	v_pk_fma_f32 v[24:25], v[6:7], s[36:37], v[24:25] op_sel_hi:[1,0,1]
	v_pk_fma_f32 v[26:27], v[4:5], s[36:37], v[26:27] op_sel_hi:[1,0,1]
	v_readlane_b32 s36, v43, s37
	s_nop 1
	v_pk_fma_f32 v[20:21], v[6:7], s[36:37], v[20:21] op_sel_hi:[1,0,1]
	v_pk_fma_f32 v[22:23], v[4:5], s[36:37], v[22:23] op_sel_hi:[1,0,1]
	v_readlane_b32 s36, v44, s37
	s_nop 1
	v_pk_fma_f32 v[16:17], v[6:7], s[36:37], v[16:17] op_sel_hi:[1,0,1]
	v_pk_fma_f32 v[18:19], v[4:5], s[36:37], v[18:19] op_sel_hi:[1,0,1]
	v_readlane_b32 s36, v45, s37
	s_nop 1
	v_pk_fma_f32 v[12:13], v[6:7], s[36:37], v[12:13] op_sel_hi:[1,0,1]
	v_pk_fma_f32 v[14:15], v[4:5], s[36:37], v[14:15] op_sel_hi:[1,0,1]
	v_readlane_b32 s36, v46, s37
	s_nop 1
	v_pk_fma_f32 v[8:9], v[6:7], s[36:37], v[8:9] op_sel_hi:[1,0,1]
	v_pk_fma_f32 v[10:11], v[4:5], s[36:37], v[10:11] op_sel_hi:[1,0,1]
	v_readlane_b32 s36, v47, s37
	s_nop 1
	v_pk_fma_f32 v[48:49], v[4:5], s[36:37], v[48:49] op_sel_hi:[1,0,1]
	v_add_co_u32_e32 v4, vcc, s28, v0
	v_pk_fma_f32 v[50:51], v[6:7], s[36:37], v[50:51] op_sel_hi:[1,0,1]
	s_nop 0
	v_addc_co_u32_e32 v5, vcc, -1, v1, vcc
	global_load_dwordx4 v[4:7], v[4:5], off nt
	s_add_i32 s37, s9, 7
	v_readlane_b32 s36, v3, s37
	s_waitcnt vmcnt(0)
	s_nop 0
	v_pk_fma_f32 v[36:37], v[6:7], s[36:37], v[36:37] op_sel_hi:[1,0,1]
	v_pk_fma_f32 v[38:39], v[4:5], s[36:37], v[38:39] op_sel_hi:[1,0,1]
	v_readlane_b32 s36, v40, s37
	s_nop 1
	v_pk_fma_f32 v[32:33], v[6:7], s[36:37], v[32:33] op_sel_hi:[1,0,1]
	v_pk_fma_f32 v[34:35], v[4:5], s[36:37], v[34:35] op_sel_hi:[1,0,1]
	v_readlane_b32 s36, v41, s37
	s_nop 1
	v_pk_fma_f32 v[28:29], v[6:7], s[36:37], v[28:29] op_sel_hi:[1,0,1]
	v_pk_fma_f32 v[30:31], v[4:5], s[36:37], v[30:31] op_sel_hi:[1,0,1]
	v_readlane_b32 s36, v42, s37
	s_nop 1
	v_pk_fma_f32 v[24:25], v[6:7], s[36:37], v[24:25] op_sel_hi:[1,0,1]
	v_pk_fma_f32 v[26:27], v[4:5], s[36:37], v[26:27] op_sel_hi:[1,0,1]
	v_readlane_b32 s36, v43, s37
	s_nop 1
	v_pk_fma_f32 v[20:21], v[6:7], s[36:37], v[20:21] op_sel_hi:[1,0,1]
	v_pk_fma_f32 v[22:23], v[4:5], s[36:37], v[22:23] op_sel_hi:[1,0,1]
	v_readlane_b32 s36, v44, s37
	s_nop 1
	v_pk_fma_f32 v[16:17], v[6:7], s[36:37], v[16:17] op_sel_hi:[1,0,1]
	v_pk_fma_f32 v[18:19], v[4:5], s[36:37], v[18:19] op_sel_hi:[1,0,1]
	v_readlane_b32 s36, v45, s37
	s_nop 1
	v_pk_fma_f32 v[12:13], v[6:7], s[36:37], v[12:13] op_sel_hi:[1,0,1]
	v_pk_fma_f32 v[14:15], v[4:5], s[36:37], v[14:15] op_sel_hi:[1,0,1]
	v_readlane_b32 s36, v46, s37
	s_nop 1
	v_pk_fma_f32 v[8:9], v[6:7], s[36:37], v[8:9] op_sel_hi:[1,0,1]
	v_pk_fma_f32 v[10:11], v[4:5], s[36:37], v[10:11] op_sel_hi:[1,0,1]
	v_readlane_b32 s36, v47, s37
	s_nop 1
	v_pk_fma_f32 v[50:51], v[6:7], s[36:37], v[50:51] op_sel_hi:[1,0,1]
	v_pk_fma_f32 v[48:49], v[4:5], s[36:37], v[48:49] op_sel_hi:[1,0,1]
	global_load_dwordx4 v[4:7], v[0:1], off nt
	s_add_i32 s37, s9, 8
	v_readlane_b32 s36, v3, s37
	s_waitcnt vmcnt(0)
	s_nop 0
	v_pk_fma_f32 v[36:37], v[6:7], s[36:37], v[36:37] op_sel_hi:[1,0,1]
	v_pk_fma_f32 v[38:39], v[4:5], s[36:37], v[38:39] op_sel_hi:[1,0,1]
	v_readlane_b32 s36, v40, s37
	s_nop 1
	v_pk_fma_f32 v[32:33], v[6:7], s[36:37], v[32:33] op_sel_hi:[1,0,1]
	v_pk_fma_f32 v[34:35], v[4:5], s[36:37], v[34:35] op_sel_hi:[1,0,1]
	v_readlane_b32 s36, v41, s37
	s_nop 1
	v_pk_fma_f32 v[28:29], v[6:7], s[36:37], v[28:29] op_sel_hi:[1,0,1]
	v_pk_fma_f32 v[30:31], v[4:5], s[36:37], v[30:31] op_sel_hi:[1,0,1]
	v_readlane_b32 s36, v42, s37
	s_nop 1
	v_pk_fma_f32 v[24:25], v[6:7], s[36:37], v[24:25] op_sel_hi:[1,0,1]
	v_pk_fma_f32 v[26:27], v[4:5], s[36:37], v[26:27] op_sel_hi:[1,0,1]
	v_readlane_b32 s36, v43, s37
	s_nop 1
	v_pk_fma_f32 v[20:21], v[6:7], s[36:37], v[20:21] op_sel_hi:[1,0,1]
	v_pk_fma_f32 v[22:23], v[4:5], s[36:37], v[22:23] op_sel_hi:[1,0,1]
	v_readlane_b32 s36, v44, s37
	s_nop 1
	v_pk_fma_f32 v[16:17], v[6:7], s[36:37], v[16:17] op_sel_hi:[1,0,1]
	v_pk_fma_f32 v[18:19], v[4:5], s[36:37], v[18:19] op_sel_hi:[1,0,1]
	v_readlane_b32 s36, v45, s37
	s_nop 1
	v_pk_fma_f32 v[12:13], v[6:7], s[36:37], v[12:13] op_sel_hi:[1,0,1]
	v_pk_fma_f32 v[14:15], v[4:5], s[36:37], v[14:15] op_sel_hi:[1,0,1]
	v_readlane_b32 s36, v46, s37
	s_nop 1
	v_pk_fma_f32 v[8:9], v[6:7], s[36:37], v[8:9] op_sel_hi:[1,0,1]
	v_pk_fma_f32 v[10:11], v[4:5], s[36:37], v[10:11] op_sel_hi:[1,0,1]
	v_readlane_b32 s36, v47, s37
	s_nop 1
	v_pk_fma_f32 v[48:49], v[4:5], s[36:37], v[48:49] op_sel_hi:[1,0,1]
	v_add_co_u32_e32 v4, vcc, s6, v0
	v_pk_fma_f32 v[50:51], v[6:7], s[36:37], v[50:51] op_sel_hi:[1,0,1]
	s_nop 0
	v_addc_co_u32_e32 v5, vcc, 0, v1, vcc
	global_load_dwordx4 v[4:7], v[4:5], off nt
	s_add_i32 s37, s9, 9
	v_readlane_b32 s36, v3, s37
	s_waitcnt vmcnt(0)
; __device__ __forceinline__ void gemv_item(const float* c, const float* c_ctx, const float* ada_w, const float* ada_b, float* mod, int it, int lane) {
;     ...
; #pragma unroll 16
;     for (int kk = 0; kk < 64; ++kk) { const f32x4 w = *(const f32x4*)(W + (size_t)kk * 6144);
; #pragma unroll
;         for (int r = 0; r < 9; ++r) { const float sk = __uint_as_float(__builtin_amdgcn_readlane(__float_as_uint(s[r]), kk)); acc[r] += w * sk; } }
	s_nop 0
	v_pk_fma_f32 v[36:37], v[6:7], s[36:37], v[36:37] op_sel_hi:[1,0,1]
	v_pk_fma_f32 v[38:39], v[4:5], s[36:37], v[38:39] op_sel_hi:[1,0,1]
	v_readlane_b32 s36, v40, s37
	s_nop 1
	v_pk_fma_f32 v[32:33], v[6:7], s[36:37], v[32:33] op_sel_hi:[1,0,1]
	v_pk_fma_f32 v[34:35], v[4:5], s[36:37], v[34:35] op_sel_hi:[1,0,1]
	v_readlane_b32 s36, v41, s37
	s_nop 1
	v_pk_fma_f32 v[28:29], v[6:7], s[36:37], v[28:29] op_sel_hi:[1,0,1]
	v_pk_fma_f32 v[30:31], v[4:5], s[36:37], v[30:31] op_sel_hi:[1,0,1]
	v_readlane_b32 s36, v42, s37
	s_nop 1
	v_pk_fma_f32 v[24:25], v[6:7], s[36:37], v[24:25] op_sel_hi:[1,0,1]
	v_pk_fma_f32 v[26:27], v[4:5], s[36:37], v[26:27] op_sel_hi:[1,0,1]
	v_readlane_b32 s36, v43, s37
	s_nop 1
	v_pk_fma_f32 v[20:21], v[6:7], s[36:37], v[20:21] op_sel_hi:[1,0,1]
	v_pk_fma_f32 v[22:23], v[4:5], s[36:37], v[22:23] op_sel_hi:[1,0,1]
	v_readlane_b32 s36, v44, s37
	s_nop 1
	v_pk_fma_f32 v[16:17], v[6:7], s[36:37], v[16:17] op_sel_hi:[1,0,1]
	v_pk_fma_f32 v[18:19], v[4:5], s[36:37], v[18:19] op_sel_hi:[1,0,1]
	v_readlane_b32 s36, v45, s37
	s_nop 1
	v_pk_fma_f32 v[12:13], v[6:7], s[36:37], v[12:13] op_sel_hi:[1,0,1]
	v_pk_fma_f32 v[14:15], v[4:5], s[36:37], v[14:15] op_sel_hi:[1,0,1]
	v_readlane_b32 s36, v46, s37
	s_nop 1
	v_pk_fma_f32 v[8:9], v[6:7], s[36:37], v[8:9] op_sel_hi:[1,0,1]
	v_pk_fma_f32 v[10:11], v[4:5], s[36:37], v[10:11] op_sel_hi:[1,0,1]
	v_readlane_b32 s36, v47, s37
	s_nop 1
	v_pk_fma_f32 v[48:49], v[4:5], s[36:37], v[48:49] op_sel_hi:[1,0,1]
	v_add_co_u32_e32 v4, vcc, s7, v0
	v_pk_fma_f32 v[50:51], v[6:7], s[36:37], v[50:51] op_sel_hi:[1,0,1]
	s_nop 0
	v_addc_co_u32_e32 v5, vcc, 0, v1, vcc
	global_load_dwordx4 v[4:7], v[4:5], off nt
	s_add_i32 s37, s9, 10
	v_readlane_b32 s36, v3, s37
	s_waitcnt vmcnt(0)
	s_nop 0
	v_pk_fma_f32 v[36:37], v[6:7], s[36:37], v[36:37] op_sel_hi:[1,0,1]
	v_pk_fma_f32 v[38:39], v[4:5], s[36:37], v[38:39] op_sel_hi:[1,0,1]
	v_readlane_b32 s36, v40, s37
	s_nop 1
	v_pk_fma_f32 v[32:33], v[6:7], s[36:37], v[32:33] op_sel_hi:[1,0,1]
	v_pk_fma_f32 v[34:35], v[4:5], s[36:37], v[34:35] op_sel_hi:[1,0,1]
	v_readlane_b32 s36, v41, s37
	s_nop 1
	v_pk_fma_f32 v[28:29], v[6:7], s[36:37], v[28:29] op_sel_hi:[1,0,1]
	v_pk_fma_f32 v[30:31], v[4:5], s[36:37], v[30:31] op_sel_hi:[1,0,1]
	v_readlane_b32 s36, v42, s37
	s_nop 1
	v_pk_fma_f32 v[24:25], v[6:7], s[36:37], v[24:25] op_sel_hi:[1,0,1]
	v_pk_fma_f32 v[26:27], v[4:5], s[36:37], v[26:27] op_sel_hi:[1,0,1]
	v_readlane_b32 s36, v43, s37
	s_nop 1
	v_pk_fma_f32 v[20:21], v[6:7], s[36:37], v[20:21] op_sel_hi:[1,0,1]
	v_pk_fma_f32 v[22:23], v[4:5], s[36:37], v[22:23] op_sel_hi:[1,0,1]
	v_readlane_b32 s36, v44, s37
	s_nop 1
	v_pk_fma_f32 v[16:17], v[6:7], s[36:37], v[16:17] op_sel_hi:[1,0,1]
	v_pk_fma_f32 v[18:19], v[4:5], s[36:37], v[18:19] op_sel_hi:[1,0,1]
	v_readlane_b32 s36, v45, s37
	s_nop 1
	v_pk_fma_f32 v[12:13], v[6:7], s[36:37], v[12:13] op_sel_hi:[1,0,1]
	v_pk_fma_f32 v[14:15], v[4:5], s[36:37], v[14:15] op_sel_hi:[1,0,1]
	v_readlane_b32 s36, v46, s37
	s_nop 1
	v_pk_fma_f32 v[8:9], v[6:7], s[36:37], v[8:9] op_sel_hi:[1,0,1]
	v_pk_fma_f32 v[10:11], v[4:5], s[36:37], v[10:11] op_sel_hi:[1,0,1]
	v_readlane_b32 s36, v47, s37
	s_nop 1
	v_pk_fma_f32 v[48:49], v[4:5], s[36:37], v[48:49] op_sel_hi:[1,0,1]
	v_add_co_u32_e32 v4, vcc, s29, v0
	v_pk_fma_f32 v[50:51], v[6:7], s[36:37], v[50:51] op_sel_hi:[1,0,1]
	s_nop 0
	v_addc_co_u32_e32 v5, vcc, 0, v1, vcc
	global_load_dwordx4 v[4:7], v[4:5], off nt
	s_add_i32 s37, s9, 11
	v_readlane_b32 s36, v3, s37
	s_waitcnt vmcnt(0)
	s_nop 0
	v_pk_fma_f32 v[36:37], v[6:7], s[36:37], v[36:37] op_sel_hi:[1,0,1]
	v_pk_fma_f32 v[38:39], v[4:5], s[36:37], v[38:39] op_sel_hi:[1,0,1]
	v_readlane_b32 s36, v40, s37
	s_nop 1
	v_pk_fma_f32 v[32:33], v[6:7], s[36:37], v[32:33] op_sel_hi:[1,0,1]
	v_pk_fma_f32 v[34:35], v[4:5], s[36:37], v[34:35] op_sel_hi:[1,0,1]
	v_readlane_b32 s36, v41, s37
	s_nop 1
	v_pk_fma_f32 v[28:29], v[6:7], s[36:37], v[28:29] op_sel_hi:[1,0,1]
	v_pk_fma_f32 v[30:31], v[4:5], s[36:37], v[30:31] op_sel_hi:[1,0,1]
	v_readlane_b32 s36, v42, s37
	s_nop 1
	v_pk_fma_f32 v[24:25], v[6:7], s[36:37], v[24:25] op_sel_hi:[1,0,1]
	v_pk_fma_f32 v[26:27], v[4:5], s[36:37], v[26:27] op_sel_hi:[1,0,1]
	v_readlane_b32 s36, v43, s37
	s_nop 1
	v_pk_fma_f32 v[20:21], v[6:7], s[36:37], v[20:21] op_sel_hi:[1,0,1]
	v_pk_fma_f32 v[22:23], v[4:5], s[36:37], v[22:23] op_sel_hi:[1,0,1]
	v_readlane_b32 s36, v44, s37
	s_nop 1
	v_pk_fma_f32 v[16:17], v[6:7], s[36:37], v[16:17] op_sel_hi:[1,0,1]
	v_pk_fma_f32 v[18:19], v[4:5], s[36:37], v[18:19] op_sel_hi:[1,0,1]
	v_readlane_b32 s36, v45, s37
	s_nop 1
	v_pk_fma_f32 v[12:13], v[6:7], s[36:37], v[12:13] op_sel_hi:[1,0,1]
	v_pk_fma_f32 v[14:15], v[4:5], s[36:37], v[14:15] op_sel_hi:[1,0,1]
	v_readlane_b32 s36, v46, s37
	s_nop 1
	v_pk_fma_f32 v[8:9], v[6:7], s[36:37], v[8:9] op_sel_hi:[1,0,1]
	v_pk_fma_f32 v[10:11], v[4:5], s[36:37], v[10:11] op_sel_hi:[1,0,1]
	v_readlane_b32 s36, v47, s37
	s_nop 1
	v_pk_fma_f32 v[48:49], v[4:5], s[36:37], v[48:49] op_sel_hi:[1,0,1]
	v_add_co_u32_e32 v4, vcc, s30, v0
	v_pk_fma_f32 v[50:51], v[6:7], s[36:37], v[50:51] op_sel_hi:[1,0,1]
	s_nop 0
	v_addc_co_u32_e32 v5, vcc, 0, v1, vcc
	global_load_dwordx4 v[4:7], v[4:5], off nt
	s_add_i32 s37, s9, 12
	v_readlane_b32 s36, v3, s37
	s_waitcnt vmcnt(0)
; __device__ __forceinline__ void gemv_item(const float* c, const float* c_ctx, const float* ada_w, const float* ada_b, float* mod, int it, int lane) {
;     ...
; #pragma unroll 16
;     for (int kk = 0; kk < 64; ++kk) { const f32x4 w = *(const f32x4*)(W + (size_t)kk * 6144);
; #pragma unroll
;         for (int r = 0; r < 9; ++r) { const float sk = __uint_as_float(__builtin_amdgcn_readlane(__float_as_uint(s[r]), kk)); acc[r] += w * sk; } }
	s_nop 0
	v_pk_fma_f32 v[36:37], v[6:7], s[36:37], v[36:37] op_sel_hi:[1,0,1]
	v_pk_fma_f32 v[38:39], v[4:5], s[36:37], v[38:39] op_sel_hi:[1,0,1]
	v_readlane_b32 s36, v40, s37
	s_nop 1
	v_pk_fma_f32 v[32:33], v[6:7], s[36:37], v[32:33] op_sel_hi:[1,0,1]
	v_pk_fma_f32 v[34:35], v[4:5], s[36:37], v[34:35] op_sel_hi:[1,0,1]
	v_readlane_b32 s36, v41, s37
	s_nop 1
	v_pk_fma_f32 v[28:29], v[6:7], s[36:37], v[28:29] op_sel_hi:[1,0,1]
	v_pk_fma_f32 v[30:31], v[4:5], s[36:37], v[30:31] op_sel_hi:[1,0,1]
	v_readlane_b32 s36, v42, s37
	s_nop 1
	v_pk_fma_f32 v[24:25], v[6:7], s[36:37], v[24:25] op_sel_hi:[1,0,1]
	v_pk_fma_f32 v[26:27], v[4:5], s[36:37], v[26:27] op_sel_hi:[1,0,1]
	v_readlane_b32 s36, v43, s37
	s_nop 1
	v_pk_fma_f32 v[20:21], v[6:7], s[36:37], v[20:21] op_sel_hi:[1,0,1]
	v_pk_fma_f32 v[22:23], v[4:5], s[36:37], v[22:23] op_sel_hi:[1,0,1]
	v_readlane_b32 s36, v44, s37
	s_nop 1
	v_pk_fma_f32 v[16:17], v[6:7], s[36:37], v[16:17] op_sel_hi:[1,0,1]
	v_pk_fma_f32 v[18:19], v[4:5], s[36:37], v[18:19] op_sel_hi:[1,0,1]
	v_readlane_b32 s36, v45, s37
	s_nop 1
	v_pk_fma_f32 v[12:13], v[6:7], s[36:37], v[12:13] op_sel_hi:[1,0,1]
	v_pk_fma_f32 v[14:15], v[4:5], s[36:37], v[14:15] op_sel_hi:[1,0,1]
	v_readlane_b32 s36, v46, s37
	s_nop 1
	v_pk_fma_f32 v[8:9], v[6:7], s[36:37], v[8:9] op_sel_hi:[1,0,1]
	v_pk_fma_f32 v[10:11], v[4:5], s[36:37], v[10:11] op_sel_hi:[1,0,1]
	v_readlane_b32 s36, v47, s37
	s_nop 1
	v_pk_fma_f32 v[48:49], v[4:5], s[36:37], v[48:49] op_sel_hi:[1,0,1]
	v_add_co_u32_e32 v4, vcc, s31, v0
	v_pk_fma_f32 v[50:51], v[6:7], s[36:37], v[50:51] op_sel_hi:[1,0,1]
	s_nop 0
	v_addc_co_u32_e32 v5, vcc, 0, v1, vcc
	global_load_dwordx4 v[4:7], v[4:5], off nt
	s_add_i32 s37, s9, 13
	v_readlane_b32 s36, v3, s37
	s_waitcnt vmcnt(0)
	s_nop 0
	v_pk_fma_f32 v[36:37], v[6:7], s[36:37], v[36:37] op_sel_hi:[1,0,1]
	v_pk_fma_f32 v[38:39], v[4:5], s[36:37], v[38:39] op_sel_hi:[1,0,1]
	v_readlane_b32 s36, v40, s37
	s_nop 1
	v_pk_fma_f32 v[32:33], v[6:7], s[36:37], v[32:33] op_sel_hi:[1,0,1]
	v_pk_fma_f32 v[34:35], v[4:5], s[36:37], v[34:35] op_sel_hi:[1,0,1]
	v_readlane_b32 s36, v41, s37
	s_nop 1
	v_pk_fma_f32 v[28:29], v[6:7], s[36:37], v[28:29] op_sel_hi:[1,0,1]
	v_pk_fma_f32 v[30:31], v[4:5], s[36:37], v[30:31] op_sel_hi:[1,0,1]
	v_readlane_b32 s36, v42, s37
	s_nop 1
	v_pk_fma_f32 v[24:25], v[6:7], s[36:37], v[24:25] op_sel_hi:[1,0,1]
	v_pk_fma_f32 v[26:27], v[4:5], s[36:37], v[26:27] op_sel_hi:[1,0,1]
	v_readlane_b32 s36, v43, s37
	s_nop 1
	v_pk_fma_f32 v[20:21], v[6:7], s[36:37], v[20:21] op_sel_hi:[1,0,1]
	v_pk_fma_f32 v[22:23], v[4:5], s[36:37], v[22:23] op_sel_hi:[1,0,1]
	v_readlane_b32 s36, v44, s37
	s_nop 1
	v_pk_fma_f32 v[16:17], v[6:7], s[36:37], v[16:17] op_sel_hi:[1,0,1]
	v_pk_fma_f32 v[18:19], v[4:5], s[36:37], v[18:19] op_sel_hi:[1,0,1]
	v_readlane_b32 s36, v45, s37
	s_nop 1
	v_pk_fma_f32 v[12:13], v[6:7], s[36:37], v[12:13] op_sel_hi:[1,0,1]
	v_pk_fma_f32 v[14:15], v[4:5], s[36:37], v[14:15] op_sel_hi:[1,0,1]
	v_readlane_b32 s36, v46, s37
	s_nop 1
	v_pk_fma_f32 v[8:9], v[6:7], s[36:37], v[8:9] op_sel_hi:[1,0,1]
	v_pk_fma_f32 v[10:11], v[4:5], s[36:37], v[10:11] op_sel_hi:[1,0,1]
	v_readlane_b32 s36, v47, s37
	s_nop 1
	v_pk_fma_f32 v[48:49], v[4:5], s[36:37], v[48:49] op_sel_hi:[1,0,1]
	v_add_co_u32_e32 v4, vcc, s34, v0
	v_pk_fma_f32 v[50:51], v[6:7], s[36:37], v[50:51] op_sel_hi:[1,0,1]
	s_nop 0
	v_addc_co_u32_e32 v5, vcc, 0, v1, vcc
	global_load_dwordx4 v[4:7], v[4:5], off nt
	s_add_i32 s37, s9, 14
	v_readlane_b32 s36, v3, s37
	s_waitcnt vmcnt(0)
	s_nop 0
	v_pk_fma_f32 v[36:37], v[6:7], s[36:37], v[36:37] op_sel_hi:[1,0,1]
	v_pk_fma_f32 v[38:39], v[4:5], s[36:37], v[38:39] op_sel_hi:[1,0,1]
	v_readlane_b32 s36, v40, s37
	s_nop 1
	v_pk_fma_f32 v[32:33], v[6:7], s[36:37], v[32:33] op_sel_hi:[1,0,1]
	v_pk_fma_f32 v[34:35], v[4:5], s[36:37], v[34:35] op_sel_hi:[1,0,1]
	v_readlane_b32 s36, v41, s37
	s_nop 1
	v_pk_fma_f32 v[28:29], v[6:7], s[36:37], v[28:29] op_sel_hi:[1,0,1]
	v_pk_fma_f32 v[30:31], v[4:5], s[36:37], v[30:31] op_sel_hi:[1,0,1]
	v_readlane_b32 s36, v42, s37
	s_nop 1
	v_pk_fma_f32 v[24:25], v[6:7], s[36:37], v[24:25] op_sel_hi:[1,0,1]
	v_pk_fma_f32 v[26:27], v[4:5], s[36:37], v[26:27] op_sel_hi:[1,0,1]
	v_readlane_b32 s36, v43, s37
	s_nop 1
	v_pk_fma_f32 v[20:21], v[6:7], s[36:37], v[20:21] op_sel_hi:[1,0,1]
	v_pk_fma_f32 v[22:23], v[4:5], s[36:37], v[22:23] op_sel_hi:[1,0,1]
	v_readlane_b32 s36, v44, s37
	s_nop 1
	v_pk_fma_f32 v[16:17], v[6:7], s[36:37], v[16:17] op_sel_hi:[1,0,1]
	v_pk_fma_f32 v[18:19], v[4:5], s[36:37], v[18:19] op_sel_hi:[1,0,1]
	v_readlane_b32 s36, v45, s37
	s_nop 1
	v_pk_fma_f32 v[12:13], v[6:7], s[36:37], v[12:13] op_sel_hi:[1,0,1]
	v_pk_fma_f32 v[14:15], v[4:5], s[36:37], v[14:15] op_sel_hi:[1,0,1]
	v_readlane_b32 s36, v46, s37
	s_nop 1
	v_pk_fma_f32 v[8:9], v[6:7], s[36:37], v[8:9] op_sel_hi:[1,0,1]
	v_pk_fma_f32 v[10:11], v[4:5], s[36:37], v[10:11] op_sel_hi:[1,0,1]
	v_readlane_b32 s36, v47, s37
	s_nop 1
	v_pk_fma_f32 v[48:49], v[4:5], s[36:37], v[48:49] op_sel_hi:[1,0,1]
	v_add_co_u32_e32 v4, vcc, s35, v0
	v_pk_fma_f32 v[50:51], v[6:7], s[36:37], v[50:51] op_sel_hi:[1,0,1]
	s_nop 0
	v_addc_co_u32_e32 v5, vcc, 0, v1, vcc
	global_load_dwordx4 v[4:7], v[4:5], off nt
	s_add_i32 s37, s9, 15
	v_readlane_b32 s36, v3, s37
	s_add_i32 s9, s9, 16
	v_lshl_add_u64 v[0:1], v[0:1], 0, s[0:1]
	s_cmp_eq_u32 s9, 64
	s_waitcnt vmcnt(0)
	v_pk_fma_f32 v[36:37], v[6:7], s[36:37], v[36:37] op_sel_hi:[1,0,1]
	v_pk_fma_f32 v[38:39], v[4:5], s[36:37], v[38:39] op_sel_hi:[1,0,1]
	v_readlane_b32 s36, v40, s37
	s_nop 1
	v_pk_fma_f32 v[32:33], v[6:7], s[36:37], v[32:33] op_sel_hi:[1,0,1]
	v_pk_fma_f32 v[34:35], v[4:5], s[36:37], v[34:35] op_sel_hi:[1,0,1]
	v_readlane_b32 s36, v41, s37
	s_nop 1
	v_pk_fma_f32 v[28:29], v[6:7], s[36:37], v[28:29] op_sel_hi:[1,0,1]
	v_pk_fma_f32 v[30:31], v[4:5], s[36:37], v[30:31] op_sel_hi:[1,0,1]
	v_readlane_b32 s36, v42, s37
	s_nop 1
	v_pk_fma_f32 v[24:25], v[6:7], s[36:37], v[24:25] op_sel_hi:[1,0,1]
	v_pk_fma_f32 v[26:27], v[4:5], s[36:37], v[26:27] op_sel_hi:[1,0,1]
	v_readlane_b32 s36, v43, s37
	s_nop 1
	v_pk_fma_f32 v[20:21], v[6:7], s[36:37], v[20:21] op_sel_hi:[1,0,1]
	v_pk_fma_f32 v[22:23], v[4:5], s[36:37], v[22:23] op_sel_hi:[1,0,1]
	v_readlane_b32 s36, v44, s37
	s_nop 1
	v_pk_fma_f32 v[16:17], v[6:7], s[36:37], v[16:17] op_sel_hi:[1,0,1]
	v_pk_fma_f32 v[18:19], v[4:5], s[36:37], v[18:19] op_sel_hi:[1,0,1]
	v_readlane_b32 s36, v45, s37
	s_nop 1
	v_pk_fma_f32 v[12:13], v[6:7], s[36:37], v[12:13] op_sel_hi:[1,0,1]
	v_pk_fma_f32 v[14:15], v[4:5], s[36:37], v[14:15] op_sel_hi:[1,0,1]
	v_readlane_b32 s36, v46, s37
	s_nop 1
	v_pk_fma_f32 v[8:9], v[6:7], s[36:37], v[8:9] op_sel_hi:[1,0,1]
	v_pk_fma_f32 v[10:11], v[4:5], s[36:37], v[10:11] op_sel_hi:[1,0,1]
	v_readlane_b32 s36, v47, s37
	s_nop 1
	v_pk_fma_f32 v[6:7], v[6:7], s[36:37], v[50:51] op_sel_hi:[1,0,1]
	v_pk_fma_f32 v[4:5], v[4:5], s[36:37], v[48:49] op_sel_hi:[1,0,1]
	s_cbranch_scc0 .LBB0_660
; __device__ __forceinline__ void gemv_item(const float* c, const float* c_ctx, const float* ada_w, const float* ada_b, float* mod, int it, int lane) {
;     ...
;     const int col = cgp * 256 + lane * 4;
;     f32x4 bv = (f32x4){0.f, 0.f, 0.f, 0.f};
;     if (kc == 0) bv = *(const f32x4*)(ada_b + l * 6144 + col);
	s_and_b32 s0, 0xffff, s10
	v_lshl_or_b32 v40, v2, 2, s0
	s_cmp_lt_u32 s3, 24
	v_mov_b32_e32 v0, 0
	s_mov_b64 s[0:1], -1
	s_cbranch_scc1 .LBB0_663
	s_mov_b64 s[0:1], 0
.LBB0_663:
	s_andn2_b64 vcc, exec, s[0:1]
	v_mov_b32_e32 v1, 0
	v_mov_b32_e32 v2, 0
	v_mov_b32_e32 v3, 0
	s_cbranch_vccnz .LBB0_665
	s_mul_i32 s0, s8, 0x1800
	s_mov_b32 s1, 0
	s_lshl_b64 s[0:1], s[0:1], 2
	s_add_u32 s0, s78, s0
	s_addc_u32 s1, s79, s1
	v_lshlrev_b32_e32 v0, 2, v40
	global_load_dwordx4 v[0:3], v0, s[0:1] nt

; #define ABAR() do { asm volatile("s_waitcnt lgkmcnt(0)" ::: "memory"); __builtin_amdgcn_s_barrier(); asm volatile("" ::: "memory"); } while (0)
; #define VWAIT() asm volatile("s_waitcnt vmcnt(0)" ::: "memory")
; #define DMA_TK(t_) do { const int ui_ = (t_) / NT, j_ = (t_) - ui_ * NT, un_ = vcu + ui_ * G; DMA_K(j_, (un_ >> 7), ((un_ >> 3) & 15), ((t_) % 3)); } while (0)
; #define DMA_TV(t_) do { const int ui_ = (t_) / NT, j_ = (t_) - ui_ * NT, un_ = vcu + ui_ * G; DMA_V(j_, (un_ >> 7), ((un_ >> 3) & 15), ((t_) % 3)); } while (0)
; __device__ __forceinline__ void attn_phase(const bf16_t* __restrict__ Q, const bf16_t* __restrict__ KN, const bf16_t* __restrict__ KR, const bf16_t* __restrict__ V, ...
;     ...
;     if (half == 1) { DMA_TK(0); DMA_TK(1); } else { DMA_TV(0); DMA_TV(1); }
;     LOADQ(vcu);
;     VWAIT(); __syncthreads();
;     if (half == 1) ABAR();
.LBB0_1087:
	s_lshl_b32 s4, s46, 4
	s_and_b32 s6, s4, 0xfffff800
	s_lshl_b32 s4, s46, 8
	s_and_b32 s7, s4, 0x700
	v_and_b32_e32 v6, 31, v198
	s_or_b32 s6, s7, s6
	s_lshl_b32 s4, s42, 5
	v_or_b32_e32 v0, s6, v6
	s_bfe_u32 s5, s46, 0x40003
	v_add_u32_e32 v7, s4, v0
	s_movk_i32 s49, 0x1800
	v_mov_b64_e32 v[0:1], s[16:17]
	v_lshrrev_b32_e32 v5, 5, v4
	v_mad_i64_i32 v[0:1], s[6:7], v7, s49, v[0:1]
	s_mul_i32 s40, s5, 0x180
	s_mov_b32 s41, 0
	v_mov_b32_e32 v32, 0
	v_lshl_add_u64 v[8:9], v[0:1], 0, s[40:41]
	v_lshlrev_b32_e32 v0, 4, v5
	v_mov_b32_e32 v1, v32
	v_lshl_add_u64 v[8:9], v[8:9], 0, v[0:1]
	global_load_dwordx4 v[112:115], v[8:9], off nt
	global_load_dwordx4 v[116:119], v[8:9], off offset:32 nt
	global_load_dwordx4 v[120:123], v[8:9], off offset:64 nt
	global_load_dwordx4 v[124:127], v[8:9], off offset:96 nt
	global_load_dwordx4 v[128:131], v[8:9], off offset:128 nt
	global_load_dwordx4 v[132:135], v[8:9], off offset:160 nt
	global_load_dwordx4 v[136:139], v[8:9], off offset:192 nt
	global_load_dwordx4 v[140:143], v[8:9], off offset:224 nt
	global_load_dwordx4 v[144:147], v[8:9], off offset:256 nt
	global_load_dwordx4 v[148:151], v[8:9], off offset:288 nt
	global_load_dwordx4 v[152:155], v[8:9], off offset:320 nt
	global_load_dwordx4 v[156:159], v[8:9], off offset:352 nt
	s_waitcnt vmcnt(0)
	v_cndmask_b32_e64 v7, 0, 1, s[0:1]
	v_lshlrev_b32_e32 v1, 3, v5
	v_cmp_ne_u32_e64 s[8:9], 1, v7
	s_andn2_b64 vcc, exec, s[0:1]
	s_waitcnt vmcnt(0) lgkmcnt(0)
	s_barrier
	s_cbranch_vccnz .LBB0_1089
	s_waitcnt lgkmcnt(0)
	s_barrier

; #define SBAR() __builtin_amdgcn_sched_barrier(0)
; __device__ __forceinline__ void pv_d0(f32x16* o, int vb, bf16x8 pa0, bf16x8 pa1, bf16x8 pa2, bf16x8 pa3) {
;   VFrag fa, fb;
;   v_read8<0>(fa, vb); v_read8<1>(fb, vb);
;   asm volatile("s_waitcnt lgkmcnt(8)" ::: "memory"); SBAR(); pv_mma(o[0], fa, pa0, pa1, pa2, pa3); SBAR();
;   v_read8<2>(fa, vb);
;   asm volatile("s_waitcnt lgkmcnt(8)" ::: "memory"); SBAR(); pv_mma(o[1], fb, pa0, pa1, pa2, pa3); SBAR();
;   v_read8<3>(fb, vb);
;   asm volatile("s_waitcnt lgkmcnt(8)" ::: "memory"); SBAR(); pv_mma(o[2], fa, pa0, pa1, pa2, pa3); SBAR();
;   asm volatile("s_waitcnt lgkmcnt(0)" ::: "memory"); SBAR(); pv_mma(o[3], fb, pa0, pa1, pa2, pa3); SBAR();
; }
.LBB0_1090:
	s_cmp_eq_u32 s70, 0
	s_cbranch_scc1 .LBB0_1094
	s_add_i32 s4, s70, -1
	s_mul_i32 s4, s4, s63
	s_add_i32 s4, s4, s46
	s_lshl_b32 s5, s4, 4
	s_lshl_b32 s4, s4, 8
	s_and_b32 s6, s5, 0xfffff800
	s_and_b32 s4, s4, 0x700
	s_or_b32 s4, s6, s4
	v_add_u32_e32 v34, s4, v210
	v_ashrrev_i32_e32 v35, 31, v34
	v_lshlrev_b64 v[46:47], 11, v[34:35]
	s_and_b32 s4, s5, 0x780
	v_or_b32_e32 v33, s4, v46
	v_or_b32_e32 v46, v33, v184
	v_lshl_add_u64 v[34:35], v[46:47], 1, s[14:15]
	v_add_co_u32_e32 v36, vcc, s62, v34
	v_lshl_add_u32 v33, s72, 14, v209
	s_nop 0
	v_addc_co_u32_e32 v37, vcc, 0, v35, vcc
	v_add_co_u32_e32 v38, vcc, s64, v34
	s_nop 1
	v_addc_co_u32_e32 v39, vcc, 0, v35, vcc
	v_add_co_u32_e32 v214, vcc, s66, v34
	s_nop 1
	v_addc_co_u32_e32 v215, vcc, 0, v35, vcc
	global_load_dwordx4 v[160:163], v[34:35], off nt
	global_load_dwordx4 v[80:83], v[34:35], off offset:128 nt
	global_load_dwordx4 v[108:111], v[36:37], off nt
	global_load_dwordx4 v[42:45], v[36:37], off offset:128 nt
	global_load_dwordx4 v[104:107], v[38:39], off nt
	s_nop 0
	global_load_dwordx4 v[38:41], v[38:39], off offset:128 nt
	s_nop 0
	global_load_dwordx4 v[100:103], v[214:215], off nt
	global_load_dwordx4 v[34:37], v[214:215], off offset:128 nt
	ds_read_b64_tr_b16 v[214:215], v33 offset:0
	ds_read_b64_tr_b16 v[216:217], v33 offset:0x800
	ds_read_b64_tr_b16 v[218:219], v33 offset:0x1000
	ds_read_b64_tr_b16 v[220:221], v33 offset:0x1800
	ds_read_b64_tr_b16 v[222:223], v33 offset:0x2000
	ds_read_b64_tr_b16 v[224:225], v33 offset:0x2800
	ds_read_b64_tr_b16 v[226:227], v33 offset:0x3000
	ds_read_b64_tr_b16 v[228:229], v33 offset:0x3800
	ds_read_b64_tr_b16 v[230:231], v33 offset:0x200
	ds_read_b64_tr_b16 v[232:233], v33 offset:0xa00
	ds_read_b64_tr_b16 v[234:235], v33 offset:0x1200
	ds_read_b64_tr_b16 v[236:237], v33 offset:0x1a00
	ds_read_b64_tr_b16 v[238:239], v33 offset:0x2200
	ds_read_b64_tr_b16 v[240:241], v33 offset:0x2a00
	ds_read_b64_tr_b16 v[242:243], v33 offset:0x3200
	ds_read_b64_tr_b16 v[244:245], v33 offset:0x3a00
	s_waitcnt lgkmcnt(8)
	s_nop 0
	v_mfma_f32_32x32x16_bf16 v[64:79], v[96:99], v[214:217], v[64:79]
	v_mfma_f32_32x32x16_bf16 v[64:79], v[92:95], v[218:221], v[64:79]
	v_mfma_f32_32x32x16_bf16 v[64:79], v[88:91], v[222:225], v[64:79]
	v_mfma_f32_32x32x16_bf16 v[64:79], v[84:87], v[226:229], v[64:79]
	ds_read_b64_tr_b16 v[214:215], v33 offset:0x400
	ds_read_b64_tr_b16 v[216:217], v33 offset:0xc00
	ds_read_b64_tr_b16 v[218:219], v33 offset:0x1400
	ds_read_b64_tr_b16 v[220:221], v33 offset:0x1c00
	ds_read_b64_tr_b16 v[222:223], v33 offset:0x2400
	ds_read_b64_tr_b16 v[224:225], v33 offset:0x2c00
	ds_read_b64_tr_b16 v[226:227], v33 offset:0x3400
	ds_read_b64_tr_b16 v[228:229], v33 offset:0x3c00
	s_waitcnt lgkmcnt(8)
	v_mfma_f32_32x32x16_bf16 v[48:63], v[96:99], v[230:233], v[48:63]
	v_mfma_f32_32x32x16_bf16 v[48:63], v[92:95], v[234:237], v[48:63]
	v_mfma_f32_32x32x16_bf16 v[48:63], v[88:91], v[238:241], v[48:63]
	v_mfma_f32_32x32x16_bf16 v[48:63], v[84:87], v[242:245], v[48:63]
	ds_read_b64_tr_b16 v[230:231], v33 offset:0x600
	ds_read_b64_tr_b16 v[232:233], v33 offset:0xe00
	ds_read_b64_tr_b16 v[234:235], v33 offset:0x1600
	ds_read_b64_tr_b16 v[236:237], v33 offset:0x1e00
	ds_read_b64_tr_b16 v[238:239], v33 offset:0x2600
	ds_read_b64_tr_b16 v[240:241], v33 offset:0x2e00
	ds_read_b64_tr_b16 v[242:243], v33 offset:0x3600
	ds_read_b64_tr_b16 v[244:245], v33 offset:0x3e00
	s_waitcnt lgkmcnt(8)
	v_mfma_f32_32x32x16_bf16 v[16:31], v[96:99], v[214:217], v[16:31]
	v_mfma_f32_32x32x16_bf16 v[16:31], v[92:95], v[218:221], v[16:31]
	v_mfma_f32_32x32x16_bf16 v[16:31], v[88:91], v[222:225], v[16:31]
	v_mfma_f32_32x32x16_bf16 v[16:31], v[84:87], v[226:229], v[16:31]
	s_waitcnt lgkmcnt(0)
	v_mfma_f32_32x32x16_bf16 v[0:15], v[96:99], v[230:233], v[0:15]
	v_mfma_f32_32x32x16_bf16 v[0:15], v[92:95], v[234:237], v[0:15]
	v_mfma_f32_32x32x16_bf16 v[0:15], v[88:91], v[238:241], v[0:15]
	v_mfma_f32_32x32x16_bf16 v[0:15], v[84:87], v[242:245], v[0:15]
	s_and_saveexec_b64 s[4:5], s[0:1]
	ds_write_b32 v208, v187
	s_or_b64 exec, exec, s[4:5]
	s_waitcnt lgkmcnt(0)
	ds_read_b32 v230, v185
	ds_read_b32 v231, v185 offset:4
	ds_read_b32 v232, v185 offset:8
	ds_read_b32 v233, v185 offset:12
	ds_read_b32 v234, v185 offset:32
	ds_read_b32 v235, v185 offset:36
	ds_read_b32 v236, v185 offset:40
	ds_read_b32 v237, v185 offset:44
	ds_read_b32 v238, v185 offset:64
	ds_read_b32 v239, v185 offset:68
	ds_read_b32 v240, v185 offset:72
	ds_read_b32 v241, v185 offset:76
	ds_read_b32 v242, v185 offset:96
	ds_read_b32 v243, v185 offset:100
	ds_read_b32 v244, v185 offset:104
	ds_read_b32 v245, v185 offset:108
	s_waitcnt lgkmcnt(0)
	v_rcp_f32_e32 v230, v230
	v_rcp_f32_e32 v231, v231
	v_rcp_f32_e32 v232, v232
	v_rcp_f32_e32 v233, v233
	v_rcp_f32_e32 v234, v234
	v_rcp_f32_e32 v235, v235
	v_rcp_f32_e32 v236, v236
	v_rcp_f32_e32 v237, v237
	v_rcp_f32_e32 v238, v238
	v_rcp_f32_e32 v239, v239
	v_rcp_f32_e32 v240, v240
	v_rcp_f32_e32 v241, v241
	v_rcp_f32_e32 v242, v242
	v_rcp_f32_e32 v243, v243
	v_rcp_f32_e32 v244, v244
	v_rcp_f32_e32 v245, v245
	s_nop 0
	v_add_u32_e32 v84, v190, v207
	v_lshl_add_u64 v[46:47], v[46:47], 1, s[18:19]
	v_mov_b32_e32 v187, 0
	s_nop 0
	v_mul_f32_e32 v64, v64, v230
	v_mul_f32_e32 v33, v48, v230
	v_cvt_pk_bf16_f32 v48, v64, v32
	ds_write_b16 v84, v48
	v_cvt_pk_bf16_f32 v33, v33, v32
	ds_write_b16 v84, v33 offset:64
	v_add_u32_e32 v64, v190, v206
	s_nop 0
	v_mul_f32_e32 v33, v65, v231
	v_mul_f32_e32 v48, v49, v231
	v_cvt_pk_bf16_f32 v33, v33, v32
	ds_write_b16 v64, v33
	v_cvt_pk_bf16_f32 v33, v48, v32
	ds_write_b16 v64, v33 offset:64
	v_add_u32_e32 v65, v190, v205
	s_nop 0
	v_mul_f32_e32 v33, v66, v232
	v_mul_f32_e32 v48, v50, v232
	v_cvt_pk_bf16_f32 v33, v33, v32
	ds_write_b16 v65, v33
	v_cvt_pk_bf16_f32 v33, v48, v32
	ds_write_b16 v65, v33 offset:64
	v_add_u32_e32 v66, v190, v204
	s_nop 0
	v_mul_f32_e32 v33, v67, v233
	v_mul_f32_e32 v48, v51, v233
	v_cvt_pk_bf16_f32 v33, v33, v32
	ds_write_b16 v66, v33
	v_cvt_pk_bf16_f32 v33, v48, v32
	ds_write_b16 v66, v33 offset:64
	v_add_u32_e32 v67, v190, v203
	s_nop 0
	v_mul_f32_e32 v33, v68, v234
	v_mul_f32_e32 v48, v52, v234
	v_cvt_pk_bf16_f32 v33, v33, v32
	ds_write_b16 v67, v33
	v_cvt_pk_bf16_f32 v33, v48, v32
	ds_write_b16 v67, v33 offset:64
	v_add_u32_e32 v68, v190, v202
	s_waitcnt vmcnt(0)
	v_lshlrev_b32_e32 v52, 16, v160
	s_nop 0
	v_mul_f32_e32 v33, v69, v235
	v_mul_f32_e32 v48, v53, v235
	v_cvt_pk_bf16_f32 v33, v33, v32
	ds_write_b16 v68, v33
	v_cvt_pk_bf16_f32 v33, v48, v32
	ds_write_b16 v68, v33 offset:64
	v_add_u32_e32 v69, v190, v201
	v_and_b32_e32 v53, 0xffff0000, v160
	v_mov_b32_e32 v160, 0xf149f2ca
	s_nop 0
	v_mul_f32_e32 v33, v70, v236
	v_mul_f32_e32 v48, v54, v236
	v_cvt_pk_bf16_f32 v33, v33, v32
	ds_write_b16 v69, v33
	v_cvt_pk_bf16_f32 v33, v48, v32
	ds_write_b16 v69, v33 offset:64
	v_add_u32_e32 v70, v190, v200
	v_lshlrev_b32_e32 v54, 16, v161
	s_nop 0
	v_mul_f32_e32 v33, v71, v237
	v_mul_f32_e32 v48, v55, v237
	v_cvt_pk_bf16_f32 v33, v33, v32
	ds_write_b16 v70, v33
	v_cvt_pk_bf16_f32 v33, v48, v32
	ds_write_b16 v70, v33 offset:64
	v_add_u32_e32 v71, v190, v199
	v_and_b32_e32 v55, 0xffff0000, v161
	s_nop 0
	v_mul_f32_e32 v33, v72, v238
	v_mul_f32_e32 v48, v56, v238
	v_cvt_pk_bf16_f32 v33, v33, v32
	ds_write_b16 v71, v33
	v_cvt_pk_bf16_f32 v33, v48, v32
	ds_write_b16 v71, v33 offset:64
	v_add_u32_e32 v72, v190, v197
	v_lshlrev_b32_e32 v56, 16, v162
	s_nop 0
	v_mul_f32_e32 v33, v73, v239
	v_mul_f32_e32 v48, v57, v239
	v_cvt_pk_bf16_f32 v33, v33, v32
	ds_write_b16 v72, v33
	v_cvt_pk_bf16_f32 v33, v48, v32
	ds_write_b16 v72, v33 offset:64
	v_add_u32_e32 v73, v190, v196
	v_and_b32_e32 v57, 0xffff0000, v162
	s_nop 0
	v_mul_f32_e32 v33, v74, v240
	v_mul_f32_e32 v48, v58, v240
	v_cvt_pk_bf16_f32 v33, v33, v32
	ds_write_b16 v73, v33
	v_cvt_pk_bf16_f32 v33, v48, v32
	ds_write_b16 v73, v33 offset:64
	v_add_u32_e32 v74, v190, v195
	v_and_b32_e32 v58, 0xffff0000, v163
	s_nop 0
	v_mul_f32_e32 v33, v75, v241
	v_mul_f32_e32 v48, v59, v241
	v_cvt_pk_bf16_f32 v33, v33, v32
	ds_write_b16 v74, v33
	v_cvt_pk_bf16_f32 v33, v48, v32
	ds_write_b16 v74, v33 offset:64
	v_add_u32_e32 v75, v190, v194
	s_waitcnt vmcnt(5)
	v_lshlrev_b32_e32 v59, 16, v108
	s_nop 0
	v_mul_f32_e32 v33, v76, v242
	v_mul_f32_e32 v48, v60, v242
	v_cvt_pk_bf16_f32 v33, v33, v32
	ds_write_b16 v75, v33
	v_cvt_pk_bf16_f32 v33, v48, v32
	ds_write_b16 v75, v33 offset:64
	v_add_u32_e32 v60, v190, v193
	v_add_u32_e32 v76, v190, v191
	s_nop 0
	v_mul_f32_e32 v33, v77, v243
	v_mul_f32_e32 v48, v61, v243
	v_cvt_pk_bf16_f32 v33, v33, v32
	ds_write_b16 v60, v33
	v_cvt_pk_bf16_f32 v33, v48, v32
	ds_write_b16 v60, v33 offset:64
	v_add_u32_e32 v61, v190, v192
	v_add_u32_e32 v77, v188, v189
	s_nop 0
	v_mul_f32_e32 v33, v78, v244
	v_mul_f32_e32 v48, v62, v244
	v_cvt_pk_bf16_f32 v33, v33, v32
	ds_write_b16 v61, v33
	v_cvt_pk_bf16_f32 v33, v48, v32
	ds_write_b16 v61, v33 offset:64
	v_and_b32_e32 v62, 0xffff0000, v108
	s_nop 0
	v_mul_f32_e32 v33, v79, v245
	v_cvt_pk_bf16_f32 v33, v33, v32
	v_mul_f32_e32 v48, v63, v245
	ds_write_b16 v76, v33
	v_cvt_pk_bf16_f32 v33, v48, v32
	ds_write_b16 v76, v33 offset:64
	s_waitcnt lgkmcnt(0)
	ds_read_b128 v[214:217], v77
	ds_read_b128 v[218:221], v77 offset:1024
	ds_read_b128 v[222:225], v77 offset:2048
	ds_read_b128 v[226:229], v77 offset:3072
	v_lshlrev_b32_e32 v33, 16, v163
	s_waitcnt lgkmcnt(0)
	v_lshlrev_b32_e32 v63, 16, v214
	v_and_b32_e32 v48, 0xffff0000, v214
	v_lshlrev_b32_e32 v78, 16, v215
	v_and_b32_e32 v49, 0xffff0000, v215
	v_lshlrev_b32_e32 v79, 16, v216
	v_and_b32_e32 v50, 0xffff0000, v216
	v_lshlrev_b32_e32 v85, 16, v217
	v_and_b32_e32 v51, 0xffff0000, v217
	v_mul_f32_e32 v52, v63, v52
	v_mul_f32_e32 v48, v48, v53
	v_mul_f32_e32 v53, v78, v54
	v_mul_f32_e32 v49, v49, v55
	v_mul_f32_e32 v54, v79, v56
	v_mul_f32_e32 v50, v50, v57
	v_mul_f32_e32 v51, v51, v58
	v_mul_f32_e32 v33, v85, v33
	v_cvt_pk_bf16_f32 v48, v52, v48
	v_cvt_pk_bf16_f32 v49, v53, v49
	v_cvt_pk_bf16_f32 v50, v54, v50
	v_cvt_pk_bf16_f32 v51, v33, v51
	global_store_dwordx4 v[46:47], v[48:51], off
	v_lshlrev_b32_e32 v33, 16, v109
	v_and_b32_e32 v56, 0xffff0000, v109
	v_lshlrev_b32_e32 v57, 16, v110
	s_waitcnt lgkmcnt(0)
	v_lshlrev_b32_e32 v48, 16, v218
	v_and_b32_e32 v49, 0xffff0000, v218
	v_lshlrev_b32_e32 v50, 16, v219
	v_and_b32_e32 v51, 0xffff0000, v219
	v_mul_f32_e32 v48, v48, v59
	v_mul_f32_e32 v49, v49, v62
	v_lshlrev_b32_e32 v52, 16, v220
	v_mul_f32_e32 v33, v50, v33
	v_mul_f32_e32 v51, v51, v56
	v_cvt_pk_bf16_f32 v50, v48, v49
	v_and_b32_e32 v48, 0xffff0000, v220
	v_and_b32_e32 v49, 0xffff0000, v110
	v_cvt_pk_bf16_f32 v51, v33, v51
	v_mul_f32_e32 v33, v52, v57
	v_mul_f32_e32 v48, v48, v49
	v_cvt_pk_bf16_f32 v52, v33, v48
	v_lshlrev_b32_e32 v33, 16, v111
	v_lshlrev_b32_e32 v48, 16, v221
	v_mul_f32_e32 v33, v48, v33
	v_and_b32_e32 v48, 0xffff0000, v221
	v_and_b32_e32 v49, 0xffff0000, v111
	v_mul_f32_e32 v48, v48, v49
	v_cvt_pk_bf16_f32 v53, v33, v48
	v_add_co_u32_e32 v48, vcc, s62, v46
	s_waitcnt vmcnt(4)
	v_lshlrev_b32_e32 v33, 16, v104
	v_addc_co_u32_e32 v49, vcc, 0, v47, vcc
	global_store_dwordx4 v[48:49], v[50:53], off
	s_waitcnt lgkmcnt(0)
	s_nop 0
	v_lshlrev_b32_e32 v50, 16, v222
	v_mul_f32_e32 v33, v50, v33
	v_and_b32_e32 v50, 0xffff0000, v222
	v_and_b32_e32 v51, 0xffff0000, v104
	v_mul_f32_e32 v50, v50, v51
	v_cvt_pk_bf16_f32 v52, v33, v50
	v_lshlrev_b32_e32 v33, 16, v105
	v_lshlrev_b32_e32 v50, 16, v223
	v_mul_f32_e32 v33, v50, v33
	v_and_b32_e32 v50, 0xffff0000, v223
	v_and_b32_e32 v51, 0xffff0000, v105
	v_mul_f32_e32 v50, v50, v51
	v_cvt_pk_bf16_f32 v53, v33, v50
	v_lshlrev_b32_e32 v33, 16, v106
	v_lshlrev_b32_e32 v50, 16, v224
	v_mul_f32_e32 v33, v50, v33
	v_and_b32_e32 v50, 0xffff0000, v224
	v_and_b32_e32 v51, 0xffff0000, v106
	v_mul_f32_e32 v50, v50, v51
	v_cvt_pk_bf16_f32 v54, v33, v50
	v_lshlrev_b32_e32 v33, 16, v107
	v_lshlrev_b32_e32 v50, 16, v225
	v_mul_f32_e32 v33, v50, v33
	v_and_b32_e32 v50, 0xffff0000, v225
	v_and_b32_e32 v51, 0xffff0000, v107
	v_mul_f32_e32 v50, v50, v51
	v_cvt_pk_bf16_f32 v55, v33, v50
	v_add_co_u32_e32 v50, vcc, s64, v46
	s_waitcnt vmcnt(3)
	v_lshlrev_b32_e32 v33, 16, v100
	v_addc_co_u32_e32 v51, vcc, 0, v47, vcc
	global_store_dwordx4 v[50:51], v[52:55], off
	s_waitcnt lgkmcnt(0)
	s_nop 0
	v_lshlrev_b32_e32 v52, 16, v226
	v_mul_f32_e32 v33, v52, v33
	v_and_b32_e32 v52, 0xffff0000, v226
	v_and_b32_e32 v53, 0xffff0000, v100
	v_mul_f32_e32 v52, v52, v53
	v_cvt_pk_bf16_f32 v54, v33, v52
	v_lshlrev_b32_e32 v33, 16, v101
	v_lshlrev_b32_e32 v52, 16, v227
	v_mul_f32_e32 v33, v52, v33
	v_and_b32_e32 v52, 0xffff0000, v227
	v_and_b32_e32 v53, 0xffff0000, v101
	v_mul_f32_e32 v52, v52, v53
	v_cvt_pk_bf16_f32 v55, v33, v52
	v_lshlrev_b32_e32 v33, 16, v102
	v_lshlrev_b32_e32 v52, 16, v228
	v_mul_f32_e32 v33, v52, v33
	v_and_b32_e32 v52, 0xffff0000, v228
	v_and_b32_e32 v53, 0xffff0000, v102
	v_mul_f32_e32 v52, v52, v53
	v_cvt_pk_bf16_f32 v56, v33, v52
	v_lshlrev_b32_e32 v33, 16, v103
	v_lshlrev_b32_e32 v52, 16, v229
	v_mul_f32_e32 v33, v52, v33
	v_and_b32_e32 v52, 0xffff0000, v229
	v_and_b32_e32 v53, 0xffff0000, v103
	v_mul_f32_e32 v52, v52, v53
	v_cvt_pk_bf16_f32 v57, v33, v52
	v_add_co_u32_e32 v52, vcc, s66, v46
	s_nop 1
	v_addc_co_u32_e32 v53, vcc, 0, v47, vcc
	global_store_dwordx4 v[52:53], v[54:57], off
	s_waitcnt lgkmcnt(0)
	s_nop 0
	v_mul_f32_e32 v16, v16, v230
	v_cvt_pk_bf16_f32 v16, v16, v32
	v_mul_f32_e32 v0, v0, v230
	ds_write_b16 v84, v16
	v_cvt_pk_bf16_f32 v0, v0, v32
	ds_write_b16 v84, v0 offset:64
	v_mov_b32_e32 v33, v32
	s_nop 0
	v_mul_f32_e32 v0, v17, v231
	v_cvt_pk_bf16_f32 v0, v0, v32
	ds_write_b16 v64, v0
	v_mul_f32_e32 v0, v1, v231
	v_cvt_pk_bf16_f32 v0, v0, v32
	ds_write_b16 v64, v0 offset:64
	s_nop 0
	v_mul_f32_e32 v0, v18, v232
	v_cvt_pk_bf16_f32 v0, v0, v32
	ds_write_b16 v65, v0
	v_mul_f32_e32 v0, v2, v232
	v_cvt_pk_bf16_f32 v0, v0, v32
	ds_write_b16 v65, v0 offset:64
	s_nop 0
	v_mul_f32_e32 v0, v19, v233
	v_cvt_pk_bf16_f32 v0, v0, v32
	ds_write_b16 v66, v0
	v_mul_f32_e32 v0, v3, v233
	v_cvt_pk_bf16_f32 v0, v0, v32
	ds_write_b16 v66, v0 offset:64
	s_nop 0
	v_mul_f32_e32 v0, v20, v234
	v_cvt_pk_bf16_f32 v0, v0, v32
	ds_write_b16 v67, v0
	v_mul_f32_e32 v0, v4, v234
	v_cvt_pk_bf16_f32 v0, v0, v32
	ds_write_b16 v67, v0 offset:64
	v_lshlrev_b32_e32 v4, 16, v80
	s_nop 0
	v_mul_f32_e32 v0, v21, v235
	v_cvt_pk_bf16_f32 v0, v0, v32
	ds_write_b16 v68, v0
	v_mul_f32_e32 v0, v5, v235
	v_cvt_pk_bf16_f32 v0, v0, v32
	ds_write_b16 v68, v0 offset:64
	s_nop 0
	v_mul_f32_e32 v0, v22, v236
	v_cvt_pk_bf16_f32 v0, v0, v32
	ds_write_b16 v69, v0
	v_mul_f32_e32 v0, v6, v236
	v_cvt_pk_bf16_f32 v0, v0, v32
	ds_write_b16 v69, v0 offset:64
	s_nop 0
	v_mul_f32_e32 v0, v23, v237
	v_cvt_pk_bf16_f32 v0, v0, v32
	ds_write_b16 v70, v0
	v_mul_f32_e32 v0, v7, v237
	v_cvt_pk_bf16_f32 v0, v0, v32
	ds_write_b16 v70, v0 offset:64
	s_nop 0
	v_mul_f32_e32 v0, v24, v238
	v_cvt_pk_bf16_f32 v0, v0, v32
	ds_write_b16 v71, v0
	v_mul_f32_e32 v0, v8, v238
	v_cvt_pk_bf16_f32 v0, v0, v32
	ds_write_b16 v71, v0 offset:64
	s_nop 0
	v_mul_f32_e32 v0, v25, v239
	v_cvt_pk_bf16_f32 v0, v0, v32
	ds_write_b16 v72, v0
	v_mul_f32_e32 v0, v9, v239
	v_cvt_pk_bf16_f32 v0, v0, v32
	ds_write_b16 v72, v0 offset:64
	s_nop 0
	v_mul_f32_e32 v0, v26, v240
	v_cvt_pk_bf16_f32 v0, v0, v32
	ds_write_b16 v73, v0
	v_mul_f32_e32 v0, v10, v240
	v_cvt_pk_bf16_f32 v0, v0, v32
	ds_write_b16 v73, v0 offset:64
	s_nop 0
	v_mul_f32_e32 v0, v27, v241
	v_cvt_pk_bf16_f32 v0, v0, v32
	ds_write_b16 v74, v0
	v_mul_f32_e32 v0, v11, v241
	v_cvt_pk_bf16_f32 v0, v0, v32
	ds_write_b16 v74, v0 offset:64
	s_nop 0
	v_mul_f32_e32 v0, v28, v242
	v_cvt_pk_bf16_f32 v0, v0, v32
	ds_write_b16 v75, v0
	v_mul_f32_e32 v0, v12, v242
	v_cvt_pk_bf16_f32 v0, v0, v32
	ds_write_b16 v75, v0 offset:64
	s_nop 0
	v_mul_f32_e32 v0, v29, v243
	v_cvt_pk_bf16_f32 v0, v0, v32
	ds_write_b16 v60, v0
	v_mul_f32_e32 v0, v13, v243
	v_cvt_pk_bf16_f32 v0, v0, v32
	ds_write_b16 v60, v0 offset:64
	s_nop 0
	v_mul_f32_e32 v0, v30, v244
	v_cvt_pk_bf16_f32 v0, v0, v32
	ds_write_b16 v61, v0
	v_mul_f32_e32 v0, v14, v244
	v_cvt_pk_bf16_f32 v0, v0, v32
	ds_write_b16 v61, v0 offset:64
	s_nop 0
	v_mul_f32_e32 v0, v31, v245
	v_cvt_pk_bf16_f32 v0, v0, v32
	ds_write_b16 v76, v0
	v_mul_f32_e32 v0, v15, v245
	v_cvt_pk_bf16_f32 v0, v0, v32
	ds_write_b16 v76, v0 offset:64
	s_waitcnt lgkmcnt(0)
	ds_read_b128 v[214:217], v77
	ds_read_b128 v[218:221], v77 offset:1024
	ds_read_b128 v[222:225], v77 offset:2048
	ds_read_b128 v[226:229], v77 offset:3072
	s_waitcnt lgkmcnt(0)
; __device__ __forceinline__ void attn_phase(const bf16_t* __restrict__ Q, const bf16_t* __restrict__ KN, const bf16_t* __restrict__ KR, const bf16_t* __restrict__ V, ...
;     ...
;         m_reg = -1e30f; l_reg = 0;
; #pragma unroll
;         for (int d = 0; d < 4; ++d) o[d] = f32x16{};
	v_lshlrev_b32_e32 v5, 16, v214
	v_mul_f32_e32 v4, v5, v4
	v_and_b32_e32 v0, 0xffff0000, v214
	v_and_b32_e32 v5, 0xffff0000, v80
	v_mul_f32_e32 v0, v0, v5
	v_cvt_pk_bf16_f32 v0, v4, v0
	v_lshlrev_b32_e32 v4, 16, v81
	v_lshlrev_b32_e32 v5, 16, v215
	v_mul_f32_e32 v4, v5, v4
	v_and_b32_e32 v1, 0xffff0000, v215
	v_and_b32_e32 v5, 0xffff0000, v81
	v_mul_f32_e32 v1, v1, v5
	v_cvt_pk_bf16_f32 v1, v4, v1
	v_lshlrev_b32_e32 v4, 16, v82
	v_lshlrev_b32_e32 v5, 16, v216
	v_mul_f32_e32 v4, v5, v4
	v_and_b32_e32 v2, 0xffff0000, v216
	v_and_b32_e32 v5, 0xffff0000, v82
	v_mul_f32_e32 v2, v2, v5
	v_cvt_pk_bf16_f32 v2, v4, v2
	v_lshlrev_b32_e32 v4, 16, v83
	v_lshlrev_b32_e32 v5, 16, v217
	v_mul_f32_e32 v4, v5, v4
	v_and_b32_e32 v3, 0xffff0000, v217
	v_and_b32_e32 v5, 0xffff0000, v83
	v_mul_f32_e32 v3, v3, v5
	v_cvt_pk_bf16_f32 v3, v4, v3
	global_store_dwordx4 v[46:47], v[0:3], off offset:128
	v_mov_b32_e32 v46, v32
	v_mov_b32_e32 v47, v32
	v_lshlrev_b32_e32 v0, 16, v42
	s_waitcnt lgkmcnt(0)
	v_lshlrev_b32_e32 v1, 16, v218
	v_mul_f32_e32 v0, v1, v0
	v_and_b32_e32 v1, 0xffff0000, v218
	v_and_b32_e32 v2, 0xffff0000, v42
	v_mul_f32_e32 v1, v1, v2
	v_cvt_pk_bf16_f32 v0, v0, v1
	v_lshlrev_b32_e32 v1, 16, v43
	v_lshlrev_b32_e32 v2, 16, v219
	v_mul_f32_e32 v1, v2, v1
	v_and_b32_e32 v2, 0xffff0000, v219
	v_and_b32_e32 v3, 0xffff0000, v43
	v_mul_f32_e32 v2, v2, v3
	v_cvt_pk_bf16_f32 v1, v1, v2
	v_lshlrev_b32_e32 v2, 16, v44
	v_lshlrev_b32_e32 v3, 16, v220
	v_mul_f32_e32 v2, v3, v2
	v_and_b32_e32 v3, 0xffff0000, v220
	v_and_b32_e32 v4, 0xffff0000, v44
	v_mul_f32_e32 v3, v3, v4
	v_cvt_pk_bf16_f32 v2, v2, v3
	v_lshlrev_b32_e32 v3, 16, v45
	v_lshlrev_b32_e32 v4, 16, v221
	v_mul_f32_e32 v3, v4, v3
	v_and_b32_e32 v4, 0xffff0000, v221
	v_and_b32_e32 v5, 0xffff0000, v45
	v_mul_f32_e32 v4, v4, v5
	v_cvt_pk_bf16_f32 v3, v3, v4
	global_store_dwordx4 v[48:49], v[0:3], off offset:128
	v_mov_b32_e32 v42, v32
	v_mov_b32_e32 v43, v32
	v_lshlrev_b32_e32 v0, 16, v38
	s_waitcnt lgkmcnt(0)
	v_lshlrev_b32_e32 v1, 16, v222
	v_mul_f32_e32 v0, v1, v0
	v_and_b32_e32 v1, 0xffff0000, v222
	v_and_b32_e32 v2, 0xffff0000, v38
	v_mul_f32_e32 v1, v1, v2
	v_cvt_pk_bf16_f32 v0, v0, v1
	v_lshlrev_b32_e32 v1, 16, v39
	v_lshlrev_b32_e32 v2, 16, v223
	v_mul_f32_e32 v1, v2, v1
	v_and_b32_e32 v2, 0xffff0000, v223
	v_and_b32_e32 v3, 0xffff0000, v39
	v_mul_f32_e32 v2, v2, v3
	v_cvt_pk_bf16_f32 v1, v1, v2
	v_lshlrev_b32_e32 v2, 16, v40
	v_lshlrev_b32_e32 v3, 16, v224
	v_mul_f32_e32 v2, v3, v2
	v_and_b32_e32 v3, 0xffff0000, v224
	v_and_b32_e32 v4, 0xffff0000, v40
	v_mul_f32_e32 v3, v3, v4
	v_cvt_pk_bf16_f32 v2, v2, v3
	v_lshlrev_b32_e32 v3, 16, v41
	v_lshlrev_b32_e32 v4, 16, v225
	v_mul_f32_e32 v3, v4, v3
	v_and_b32_e32 v4, 0xffff0000, v225
	v_and_b32_e32 v5, 0xffff0000, v41
	v_mul_f32_e32 v4, v4, v5
	v_cvt_pk_bf16_f32 v3, v3, v4
	global_store_dwordx4 v[50:51], v[0:3], off offset:128
	v_mov_b32_e32 v38, v32
	v_mov_b32_e32 v39, v32
	s_waitcnt vmcnt(7)
	v_lshlrev_b32_e32 v0, 16, v34
	s_waitcnt lgkmcnt(0)
	v_lshlrev_b32_e32 v1, 16, v226
	v_mul_f32_e32 v0, v1, v0
	v_and_b32_e32 v1, 0xffff0000, v226
	v_and_b32_e32 v2, 0xffff0000, v34
	v_mul_f32_e32 v1, v1, v2
	v_cvt_pk_bf16_f32 v0, v0, v1
	v_lshlrev_b32_e32 v1, 16, v35
	v_lshlrev_b32_e32 v2, 16, v227
	v_mul_f32_e32 v1, v2, v1
	v_and_b32_e32 v2, 0xffff0000, v227
	v_and_b32_e32 v3, 0xffff0000, v35
	v_mul_f32_e32 v2, v2, v3
	v_cvt_pk_bf16_f32 v1, v1, v2
	v_lshlrev_b32_e32 v2, 16, v36
	v_lshlrev_b32_e32 v3, 16, v228
	v_mul_f32_e32 v2, v3, v2
	v_and_b32_e32 v3, 0xffff0000, v228
	v_and_b32_e32 v4, 0xffff0000, v36
	v_mul_f32_e32 v3, v3, v4
	v_cvt_pk_bf16_f32 v2, v2, v3
	v_lshlrev_b32_e32 v3, 16, v37
	v_lshlrev_b32_e32 v4, 16, v229
	v_mul_f32_e32 v3, v4, v3
	v_and_b32_e32 v4, 0xffff0000, v229
	v_and_b32_e32 v5, 0xffff0000, v37
	v_mul_f32_e32 v4, v4, v5
	v_cvt_pk_bf16_f32 v3, v3, v4
	global_store_dwordx4 v[52:53], v[0:3], off offset:128
	s_waitcnt lgkmcnt(0)
	v_mov_b32_e32 v34, v32
	v_mov_b32_e32 v35, v32
	v_mov_b32_e32 v36, v32
	v_mov_b32_e32 v37, v32
	v_mov_b32_e32 v40, v32
	v_mov_b32_e32 v41, v32
	v_mov_b32_e32 v44, v32
	v_mov_b32_e32 v45, v32
	v_mov_b64_e32 v[78:79], v[46:47]
	v_mov_b64_e32 v[62:63], v[46:47]
	v_mov_b64_e32 v[16:17], v[32:33]
	v_mov_b64_e32 v[0:1], v[32:33]
	v_mov_b64_e32 v[76:77], v[44:45]
	v_mov_b64_e32 v[74:75], v[42:43]
	v_mov_b64_e32 v[72:73], v[40:41]
	v_mov_b64_e32 v[70:71], v[38:39]
	v_mov_b64_e32 v[68:69], v[36:37]
	v_mov_b64_e32 v[66:67], v[34:35]
	v_mov_b64_e32 v[64:65], v[32:33]
	v_mov_b64_e32 v[60:61], v[44:45]
	v_mov_b64_e32 v[58:59], v[42:43]
	v_mov_b64_e32 v[56:57], v[40:41]
	v_mov_b64_e32 v[54:55], v[38:39]
	v_mov_b64_e32 v[52:53], v[36:37]
	v_mov_b64_e32 v[50:51], v[34:35]
	v_mov_b64_e32 v[48:49], v[32:33]
	v_mov_b64_e32 v[18:19], v[34:35]
	v_mov_b64_e32 v[20:21], v[36:37]
	v_mov_b64_e32 v[22:23], v[38:39]
	v_mov_b64_e32 v[24:25], v[40:41]
	v_mov_b64_e32 v[26:27], v[42:43]
	v_mov_b64_e32 v[28:29], v[44:45]
	v_mov_b64_e32 v[30:31], v[46:47]
	v_mov_b64_e32 v[2:3], v[34:35]
	v_mov_b64_e32 v[4:5], v[36:37]
	v_mov_b64_e32 v[6:7], v[38:39]
	v_mov_b64_e32 v[8:9], v[40:41]
	v_mov_b64_e32 v[10:11], v[42:43]
	v_mov_b64_e32 v[12:13], v[44:45]
	v_mov_b64_e32 v[14:15], v[46:47]

; #define SBAR() __builtin_amdgcn_sched_barrier(0)
; #define KLD(d) do { k0[(d) % 4] = *reinterpret_cast<const bf16x8*>(kb + (d) * 512); k1[(d) % 4] = *reinterpret_cast<const bf16x8*>(kb + 12288 + (d) * 512); } while (0)
; #define KLD(d) do { k0[(d) % 4] = *reinterpret_cast<const bf16x8*>(kb + (d) * 512); k1[(d) % 4] = *reinterpret_cast<const bf16x8*>(kb + 12288 + (d) * 512); } while (0)
; __device__ __forceinline__ void qkt_pv(f32x16& p0, f32x16& p1, const char* Ks, const bf16x8* qr, const char* Qr, int kbase, f32x16* o, int vb, bf16x8 pa0, bf16x8 pa1, bf16x8 pa2, bf16x8 pa3) {
;   p0 = f32x16{}; p1 = f32x16{};
;   const char* kb = Ks + kbase;
;   bf16x8 k0[4], k1[4]; VFrag fa, fb;
;     ...
;   KLD(0); KLD(1); KLD(2);
;   __builtin_amdgcn_s_setprio(1);
; #pragma unroll
;   for (int d0 = 0; d0 < 12; ++d0) {
;     if (d0 + 3 < 12) KLD(d0 + 3);
;     if (d0 == 10) v_read8<0>(fa, vb);
;     const bf16x8 qf = d0 < NQREG ? qr[d0 < NQREG ? d0 : 0] : *reinterpret_cast<const bf16x8*>(Qr + (d0 - NQREG) * 8192);
;     p0 = __builtin_amdgcn_mfma_f32_32x32x16_bf16(k0[d0 % 4], qf, p0, 0, 0, 0);
;     p1 = __builtin_amdgcn_mfma_f32_32x32x16_bf16(k1[d0 % 4], qf, p1, 0, 0, 0);
;     SBAR(); }
;     ...
;   v_read8<1>(fb, vb);
;   asm volatile("s_waitcnt lgkmcnt(8)" ::: "memory"); SBAR(); pv_mma(o[0], fa, pa0, pa1, pa2, pa3); SBAR();
;   v_read8<2>(fa, vb);
;   asm volatile("s_waitcnt lgkmcnt(8)" ::: "memory"); SBAR(); pv_mma(o[1], fb, pa0, pa1, pa2, pa3); SBAR();
;   v_read8<3>(fb, vb);
;   asm volatile("s_waitcnt lgkmcnt(8)" ::: "memory"); SBAR(); pv_mma(o[2], fa, pa0, pa1, pa2, pa3); SBAR();
;   asm volatile("s_waitcnt lgkmcnt(0)" ::: "memory"); SBAR(); pv_mma(o[3], fb, pa0, pa1, pa2, pa3); SBAR();
;   __builtin_amdgcn_s_setprio(0);
; }
; __device__ __forceinline__ void attn_phase(const bf16_t* __restrict__ Q, const bf16_t* __restrict__ KN, const bf16_t* __restrict__ KR, const bf16_t* __restrict__ V, ...
;     ...
;         const bool qpre_ = (j == NT - 1 && ui + 1 < nun_wg);
;         if (qpre_) LOADQ(vcu + (ui + 1) * G);
.LBB0_1133:
	s_add_i32 s70, s70, 1
	s_cmp_ge_i32 s70, s47
	s_cselect_b64 s[6:7], -1, 0
	s_mul_i32 s30, s72, 0x6000
	v_add_u32_e32 v47, s30, v211
	ds_read_b128 v[80:83], v47
	ds_read_b128 v[214:217], v47 offset:512
	ds_read_b128 v[84:87], v47 offset:12288
	ds_read_b128 v[218:221], v47 offset:1024
	ds_read_b128 v[222:225], v47 offset:12800
	ds_read_b128 v[226:229], v47 offset:13312
	v_lshl_add_u32 v187, s40, 14, v209
	s_waitcnt lgkmcnt(0)
	v_mfma_f32_32x32x16_bf16 v[96:111], v[80:83], v[112:115], 0
	ds_read_b128 v[230:233], v47 offset:1536
	ds_read_b128 v[234:237], v47 offset:13824
	v_mfma_f32_32x32x16_bf16 v[80:95], v[84:87], v[112:115], 0
	v_mfma_f32_32x32x16_bf16 v[96:111], v[214:217], v[116:119], v[96:111]
	ds_read_b128 v[214:217], v47 offset:2048
	ds_read_b128 v[238:241], v47 offset:14336
	v_mfma_f32_32x32x16_bf16 v[80:95], v[222:225], v[116:119], v[80:95]
	v_mfma_f32_32x32x16_bf16 v[96:111], v[218:221], v[120:123], v[96:111]
	ds_read_b128 v[218:221], v47 offset:2560
	ds_read_b128 v[222:225], v47 offset:14848
	v_mfma_f32_32x32x16_bf16 v[80:95], v[226:229], v[120:123], v[80:95]
	s_waitcnt lgkmcnt(0)
	v_mfma_f32_32x32x16_bf16 v[96:111], v[230:233], v[124:127], v[96:111]
	ds_read_b128 v[226:229], v47 offset:3072
	ds_read_b128 v[230:233], v47 offset:15360
	v_mfma_f32_32x32x16_bf16 v[80:95], v[234:237], v[124:127], v[80:95]
	v_mfma_f32_32x32x16_bf16 v[96:111], v[214:217], v[128:131], v[96:111]
	ds_read_b128 v[214:217], v47 offset:3584
	ds_read_b128 v[234:237], v47 offset:15872
	v_mfma_f32_32x32x16_bf16 v[80:95], v[238:241], v[128:131], v[80:95]
	v_mfma_f32_32x32x16_bf16 v[96:111], v[218:221], v[132:135], v[96:111]
	ds_read_b128 v[218:221], v47 offset:4096
	ds_read_b128 v[238:241], v47 offset:16384
	v_mfma_f32_32x32x16_bf16 v[80:95], v[222:225], v[132:135], v[80:95]
	s_waitcnt lgkmcnt(0)
	v_mfma_f32_32x32x16_bf16 v[96:111], v[226:229], v[136:139], v[96:111]
	ds_read_b128 v[222:225], v47 offset:4608
	ds_read_b128 v[226:229], v47 offset:16896
	v_mfma_f32_32x32x16_bf16 v[80:95], v[230:233], v[136:139], v[80:95]
	v_mfma_f32_32x32x16_bf16 v[96:111], v[214:217], v[140:143], v[96:111]
	ds_read_b128 v[214:217], v47 offset:5120
	ds_read_b128 v[230:233], v47 offset:17408
	v_mfma_f32_32x32x16_bf16 v[80:95], v[234:237], v[140:143], v[80:95]
	v_mfma_f32_32x32x16_bf16 v[96:111], v[218:221], v[144:147], v[96:111]
	ds_read_b128 v[218:221], v47 offset:5632
	ds_read_b128 v[234:237], v47 offset:17920
	v_mfma_f32_32x32x16_bf16 v[80:95], v[238:241], v[144:147], v[80:95]
	s_waitcnt lgkmcnt(0)
	v_mfma_f32_32x32x16_bf16 v[96:111], v[222:225], v[148:151], v[96:111]
	v_mfma_f32_32x32x16_bf16 v[80:95], v[226:229], v[148:151], v[80:95]
	ds_read_b64_tr_b16 v[222:223], v187 offset:0
	ds_read_b64_tr_b16 v[224:225], v187 offset:0x800
	v_mfma_f32_32x32x16_bf16 v[96:111], v[214:217], v[152:155], v[96:111]
	ds_read_b64_tr_b16 v[214:215], v187 offset:0x1000
	ds_read_b64_tr_b16 v[216:217], v187 offset:0x1800
	ds_read_b64_tr_b16 v[226:227], v187 offset:0x2000
	ds_read_b64_tr_b16 v[228:229], v187 offset:0x2800
	ds_read_b64_tr_b16 v[238:239], v187 offset:0x3000
	ds_read_b64_tr_b16 v[240:241], v187 offset:0x3800
	v_mfma_f32_32x32x16_bf16 v[80:95], v[230:233], v[152:155], v[80:95]
	v_mfma_f32_32x32x16_bf16 v[96:111], v[218:221], v[156:159], v[96:111]
	v_mfma_f32_32x32x16_bf16 v[80:95], v[234:237], v[156:159], v[80:95]
	ds_read_b64_tr_b16 v[218:219], v187 offset:0x200
	ds_read_b64_tr_b16 v[220:221], v187 offset:0xa00
	ds_read_b64_tr_b16 v[230:231], v187 offset:0x1200
	ds_read_b64_tr_b16 v[232:233], v187 offset:0x1a00
	ds_read_b64_tr_b16 v[234:235], v187 offset:0x2200
	ds_read_b64_tr_b16 v[236:237], v187 offset:0x2a00
	ds_read_b64_tr_b16 v[242:243], v187 offset:0x3200
	ds_read_b64_tr_b16 v[244:245], v187 offset:0x3a00
	s_waitcnt lgkmcnt(8)
	v_mfma_f32_32x32x16_bf16 v[64:79], v[34:37], v[222:225], v[64:79]
	v_mfma_f32_32x32x16_bf16 v[64:79], v[38:41], v[214:217], v[64:79]
	v_mfma_f32_32x32x16_bf16 v[64:79], v[42:45], v[226:229], v[64:79]
	v_mfma_f32_32x32x16_bf16 v[64:79], v[160:163], v[238:241], v[64:79]
	ds_read_b64_tr_b16 v[214:215], v187 offset:0x400
	ds_read_b64_tr_b16 v[216:217], v187 offset:0xc00
	ds_read_b64_tr_b16 v[222:223], v187 offset:0x1400
	ds_read_b64_tr_b16 v[224:225], v187 offset:0x1c00
	ds_read_b64_tr_b16 v[226:227], v187 offset:0x2400
	ds_read_b64_tr_b16 v[228:229], v187 offset:0x2c00
	ds_read_b64_tr_b16 v[238:239], v187 offset:0x3400
	ds_read_b64_tr_b16 v[240:241], v187 offset:0x3c00
	s_waitcnt lgkmcnt(8)
	v_mfma_f32_32x32x16_bf16 v[48:63], v[34:37], v[218:221], v[48:63]
	v_mfma_f32_32x32x16_bf16 v[48:63], v[38:41], v[230:233], v[48:63]
	v_mfma_f32_32x32x16_bf16 v[48:63], v[42:45], v[234:237], v[48:63]
	v_mfma_f32_32x32x16_bf16 v[48:63], v[160:163], v[242:245], v[48:63]
	ds_read_b64_tr_b16 v[218:219], v187 offset:0x600
	ds_read_b64_tr_b16 v[220:221], v187 offset:0xe00
	ds_read_b64_tr_b16 v[230:231], v187 offset:0x1600
	ds_read_b64_tr_b16 v[232:233], v187 offset:0x1e00
	ds_read_b64_tr_b16 v[234:235], v187 offset:0x2600
	ds_read_b64_tr_b16 v[236:237], v187 offset:0x2e00
	ds_read_b64_tr_b16 v[242:243], v187 offset:0x3600
	ds_read_b64_tr_b16 v[244:245], v187 offset:0x3e00
	s_waitcnt lgkmcnt(8)
	v_mfma_f32_32x32x16_bf16 v[16:31], v[34:37], v[214:217], v[16:31]
	v_mfma_f32_32x32x16_bf16 v[16:31], v[38:41], v[222:225], v[16:31]
	v_mfma_f32_32x32x16_bf16 v[16:31], v[42:45], v[226:229], v[16:31]
	v_mfma_f32_32x32x16_bf16 v[16:31], v[160:163], v[238:241], v[16:31]
	s_waitcnt lgkmcnt(0)
	v_mfma_f32_32x32x16_bf16 v[0:15], v[34:37], v[218:221], v[0:15]
	v_mfma_f32_32x32x16_bf16 v[0:15], v[38:41], v[230:233], v[0:15]
	v_mfma_f32_32x32x16_bf16 v[0:15], v[42:45], v[234:237], v[0:15]
	v_mfma_f32_32x32x16_bf16 v[0:15], v[160:163], v[242:245], v[0:15]
	s_and_b64 vcc, exec, s[6:7]
	s_cbranch_vccnz .LBB0_1135
	s_mul_i32 s30, s70, s63
	s_add_i32 s30, s30, s46
	s_bfe_u32 s34, s30, 0x40003
	s_lshl_b32 s31, s30, 4
	s_lshl_b32 s30, s30, 8
	s_and_b32 s31, s31, 0xfffff800
	s_and_b32 s30, s30, 0x700
	s_or_b32 s30, s31, s30
	v_add_u32_e32 v36, s30, v212
	v_mov_b64_e32 v[34:35], s[16:17]
	v_mad_i64_i32 v[34:35], s[30:31], v36, s49, v[34:35]
	s_mul_i32 s40, s34, 0x180
	v_lshl_add_u64 v[34:35], v[34:35], 0, s[40:41]
	v_mov_b32_e32 v187, v32
	v_lshl_add_u64 v[34:35], v[34:35], 0, v[186:187]
	global_load_dwordx4 v[112:115], v[34:35], off nt
	global_load_dwordx4 v[116:119], v[34:35], off offset:32 nt
	global_load_dwordx4 v[120:123], v[34:35], off offset:64 nt
	global_load_dwordx4 v[124:127], v[34:35], off offset:96 nt
	global_load_dwordx4 v[128:131], v[34:35], off offset:128 nt
	global_load_dwordx4 v[132:135], v[34:35], off offset:160 nt
	global_load_dwordx4 v[136:139], v[34:35], off offset:192 nt
	global_load_dwordx4 v[140:143], v[34:35], off offset:224 nt
	global_load_dwordx4 v[144:147], v[34:35], off offset:256 nt
	global_load_dwordx4 v[148:151], v[34:35], off offset:288 nt
	global_load_dwordx4 v[152:155], v[34:35], off offset:320 nt
	global_load_dwordx4 v[156:159], v[34:35], off offset:352 nt

; #define SBAR() __builtin_amdgcn_sched_barrier(0)
; __device__ __forceinline__ void pv_d0(f32x16* o, int vb, bf16x8 pa0, bf16x8 pa1, bf16x8 pa2, bf16x8 pa3) {
;   VFrag fa, fb;
;   v_read8<0>(fa, vb); v_read8<1>(fb, vb);
;   asm volatile("s_waitcnt lgkmcnt(8)" ::: "memory"); SBAR(); pv_mma(o[0], fa, pa0, pa1, pa2, pa3); SBAR();
;   v_read8<2>(fa, vb);
;   asm volatile("s_waitcnt lgkmcnt(8)" ::: "memory"); SBAR(); pv_mma(o[1], fb, pa0, pa1, pa2, pa3); SBAR();
;   v_read8<3>(fb, vb);
;   asm volatile("s_waitcnt lgkmcnt(8)" ::: "memory"); SBAR(); pv_mma(o[2], fa, pa0, pa1, pa2, pa3); SBAR();
;   asm volatile("s_waitcnt lgkmcnt(0)" ::: "memory"); SBAR(); pv_mma(o[3], fb, pa0, pa1, pa2, pa3); SBAR();
; }
.LBB0_1158:
	s_add_i32 s3, s47, -1
	s_mul_i32 s3, s3, s63
	s_add_i32 s3, s3, s46
	s_lshl_b32 s6, s3, 4
	s_lshl_b32 s3, s3, 8
	s_and_b32 s7, s6, 0xfffff800
	s_and_b32 s3, s3, 0x700
	s_or_b32 s3, s7, s3
	v_add_u32_e32 v32, s3, v210
	v_ashrrev_i32_e32 v33, 31, v32
	s_waitcnt vmcnt(0)
	v_lshlrev_b64 v[112:113], 11, v[32:33]
	s_and_b32 s3, s6, 0x780
	v_or_b32_e32 v32, s3, v112
	v_or_b32_e32 v112, v32, v184
	v_lshl_add_u64 v[32:33], v[112:113], 1, s[14:15]
	s_mov_b32 s9, 0x8000
	v_add_co_u32_e32 v34, vcc, s9, v32
	s_mov_b32 s8, 0x10000
	s_nop 0
	v_addc_co_u32_e32 v35, vcc, 0, v33, vcc
	v_add_co_u32_e32 v36, vcc, s8, v32
	s_mov_b32 s3, 0x18000
	s_nop 0
	v_addc_co_u32_e32 v37, vcc, 0, v33, vcc
	v_add_co_u32_e32 v114, vcc, s3, v32
	v_lshl_add_u32 v146, s72, 14, v209
	s_nop 0
	v_addc_co_u32_e32 v115, vcc, 0, v33, vcc
	global_load_dwordx4 v[108:111], v[32:33], off nt
	global_load_dwordx4 v[44:47], v[32:33], off offset:128 nt
	global_load_dwordx4 v[104:107], v[34:35], off nt
	global_load_dwordx4 v[40:43], v[34:35], off offset:128 nt
	global_load_dwordx4 v[100:103], v[36:37], off nt
	s_nop 0
	global_load_dwordx4 v[36:39], v[36:37], off offset:128 nt
	s_nop 0
	global_load_dwordx4 v[80:83], v[114:115], off nt
	global_load_dwordx4 v[32:35], v[114:115], off offset:128 nt
	ds_read_b64_tr_b16 v[114:115], v146 offset:0
	ds_read_b64_tr_b16 v[116:117], v146 offset:0x800
	ds_read_b64_tr_b16 v[118:119], v146 offset:0x1000
	ds_read_b64_tr_b16 v[120:121], v146 offset:0x1800
	ds_read_b64_tr_b16 v[122:123], v146 offset:0x2000
	ds_read_b64_tr_b16 v[124:125], v146 offset:0x2800
	ds_read_b64_tr_b16 v[126:127], v146 offset:0x3000
	ds_read_b64_tr_b16 v[128:129], v146 offset:0x3800
	ds_read_b64_tr_b16 v[130:131], v146 offset:0x200
	ds_read_b64_tr_b16 v[132:133], v146 offset:0xa00
	ds_read_b64_tr_b16 v[134:135], v146 offset:0x1200
	ds_read_b64_tr_b16 v[136:137], v146 offset:0x1a00
	ds_read_b64_tr_b16 v[138:139], v146 offset:0x2200
	ds_read_b64_tr_b16 v[140:141], v146 offset:0x2a00
	ds_read_b64_tr_b16 v[142:143], v146 offset:0x3200
	ds_read_b64_tr_b16 v[144:145], v146 offset:0x3a00
	s_waitcnt lgkmcnt(8)
	s_nop 0
	v_mfma_f32_32x32x16_bf16 v[64:79], v[96:99], v[114:117], v[64:79]
	v_mfma_f32_32x32x16_bf16 v[64:79], v[92:95], v[118:121], v[64:79]
	v_mfma_f32_32x32x16_bf16 v[64:79], v[88:91], v[122:125], v[64:79]
	v_mfma_f32_32x32x16_bf16 v[64:79], v[84:87], v[126:129], v[64:79]
	ds_read_b64_tr_b16 v[114:115], v146 offset:0x400
	ds_read_b64_tr_b16 v[116:117], v146 offset:0xc00
	ds_read_b64_tr_b16 v[118:119], v146 offset:0x1400
	ds_read_b64_tr_b16 v[120:121], v146 offset:0x1c00
	ds_read_b64_tr_b16 v[122:123], v146 offset:0x2400
	ds_read_b64_tr_b16 v[124:125], v146 offset:0x2c00
	ds_read_b64_tr_b16 v[126:127], v146 offset:0x3400
	ds_read_b64_tr_b16 v[128:129], v146 offset:0x3c00
	s_waitcnt lgkmcnt(8)
	v_mfma_f32_32x32x16_bf16 v[48:63], v[96:99], v[130:133], v[48:63]
	v_mfma_f32_32x32x16_bf16 v[48:63], v[92:95], v[134:137], v[48:63]
	v_mfma_f32_32x32x16_bf16 v[48:63], v[88:91], v[138:141], v[48:63]
	v_mfma_f32_32x32x16_bf16 v[48:63], v[84:87], v[142:145], v[48:63]
	ds_read_b64_tr_b16 v[130:131], v146 offset:0x600
	ds_read_b64_tr_b16 v[132:133], v146 offset:0xe00
	ds_read_b64_tr_b16 v[134:135], v146 offset:0x1600
	ds_read_b64_tr_b16 v[136:137], v146 offset:0x1e00
	ds_read_b64_tr_b16 v[138:139], v146 offset:0x2600
	ds_read_b64_tr_b16 v[140:141], v146 offset:0x2e00
	ds_read_b64_tr_b16 v[142:143], v146 offset:0x3600
	ds_read_b64_tr_b16 v[144:145], v146 offset:0x3e00
	s_waitcnt lgkmcnt(8)
	v_mfma_f32_32x32x16_bf16 v[16:31], v[96:99], v[114:117], v[16:31]
	v_mfma_f32_32x32x16_bf16 v[16:31], v[92:95], v[118:121], v[16:31]
	v_mfma_f32_32x32x16_bf16 v[16:31], v[88:91], v[122:125], v[16:31]
	v_mfma_f32_32x32x16_bf16 v[16:31], v[84:87], v[126:129], v[16:31]
	s_waitcnt lgkmcnt(0)
	v_mfma_f32_32x32x16_bf16 v[0:15], v[96:99], v[130:133], v[0:15]
	v_mfma_f32_32x32x16_bf16 v[0:15], v[92:95], v[134:137], v[0:15]
	v_mfma_f32_32x32x16_bf16 v[0:15], v[88:91], v[138:141], v[0:15]
	v_mfma_f32_32x32x16_bf16 v[0:15], v[84:87], v[142:145], v[0:15]
	s_and_saveexec_b64 s[6:7], s[0:1]
	ds_write_b32 v208, v187
	s_or_b64 exec, exec, s[6:7]
	s_waitcnt lgkmcnt(0)
	ds_read_b32 v230, v185
	ds_read_b32 v231, v185 offset:4
	ds_read_b32 v232, v185 offset:8
	ds_read_b32 v233, v185 offset:12
	ds_read_b32 v234, v185 offset:32
	ds_read_b32 v235, v185 offset:36
	ds_read_b32 v236, v185 offset:40
	ds_read_b32 v237, v185 offset:44
	ds_read_b32 v238, v185 offset:64
	ds_read_b32 v239, v185 offset:68
	ds_read_b32 v240, v185 offset:72
	ds_read_b32 v241, v185 offset:76
	ds_read_b32 v242, v185 offset:96
	ds_read_b32 v243, v185 offset:100
	ds_read_b32 v244, v185 offset:104
	ds_read_b32 v245, v185 offset:108
	s_waitcnt lgkmcnt(0)
	v_rcp_f32_e32 v230, v230
	v_rcp_f32_e32 v231, v231
	v_rcp_f32_e32 v232, v232
	v_rcp_f32_e32 v233, v233
	v_rcp_f32_e32 v234, v234
	v_rcp_f32_e32 v235, v235
	v_rcp_f32_e32 v236, v236
	v_rcp_f32_e32 v237, v237
	v_rcp_f32_e32 v238, v238
	v_rcp_f32_e32 v239, v239
	v_rcp_f32_e32 v240, v240
	v_rcp_f32_e32 v241, v241
	v_rcp_f32_e32 v242, v242
	v_rcp_f32_e32 v243, v243
	v_rcp_f32_e32 v244, v244
	v_rcp_f32_e32 v245, v245
	s_nop 0
	v_add_u32_e32 v86, v190, v207
	v_add_u32_e32 v87, v188, v189
	v_readlane_b32 s68, v247, 34
	v_readlane_b32 s82, v247, 48
	v_mov_b32_e32 v84, 0
	v_readlane_b32 s83, v247, 49
	v_readlane_b32 s69, v247, 35
	v_mul_f32_e32 v64, v64, v230
	v_mul_f32_e32 v48, v48, v230
	v_cvt_pk_bf16_f32 v64, v64, v84
	ds_write_b16 v86, v64
	v_cvt_pk_bf16_f32 v48, v48, v84
	ds_write_b16 v86, v48 offset:64
	v_add_u32_e32 v85, v190, v206
	v_readlane_b32 s70, v247, 36
	v_readlane_b32 s71, v247, 37
	v_readlane_b32 s72, v247, 38
	v_readlane_b32 s73, v247, 39
	v_readlane_b32 s74, v247, 40
	v_mul_f32_e32 v48, v65, v231
	v_mul_f32_e32 v49, v49, v231
	v_cvt_pk_bf16_f32 v48, v48, v84
	ds_write_b16 v85, v48
	v_cvt_pk_bf16_f32 v48, v49, v84
	ds_write_b16 v85, v48 offset:64
	v_add_u32_e32 v64, v190, v205
	v_add_u32_e32 v65, v190, v204
	v_readlane_b32 s75, v247, 41
	v_readlane_b32 s76, v247, 42
	v_readlane_b32 s77, v247, 43
	v_readlane_b32 s78, v247, 44
	v_mul_f32_e32 v48, v66, v232
	v_mul_f32_e32 v49, v50, v232
	v_cvt_pk_bf16_f32 v48, v48, v84
	ds_write_b16 v64, v48
	v_cvt_pk_bf16_f32 v48, v49, v84
	ds_write_b16 v64, v48 offset:64
	v_add_u32_e32 v66, v190, v203
	v_readlane_b32 s79, v247, 45
	v_readlane_b32 s80, v247, 46
	v_readlane_b32 s81, v247, 47
	v_mul_f32_e32 v48, v67, v233
	v_mul_f32_e32 v49, v51, v233
	v_cvt_pk_bf16_f32 v48, v48, v84
	ds_write_b16 v65, v48
	v_cvt_pk_bf16_f32 v48, v49, v84
	ds_write_b16 v65, v48 offset:64
	v_add_u32_e32 v67, v190, v202
	s_nop 0
	v_mul_f32_e32 v48, v68, v234
	v_mul_f32_e32 v49, v52, v234
	v_cvt_pk_bf16_f32 v48, v48, v84
	ds_write_b16 v66, v48
	v_cvt_pk_bf16_f32 v48, v49, v84
	ds_write_b16 v66, v48 offset:64
	v_add_u32_e32 v68, v190, v201
	s_nop 0
	v_mul_f32_e32 v48, v69, v235
	v_mul_f32_e32 v49, v53, v235
	v_cvt_pk_bf16_f32 v48, v48, v84
	ds_write_b16 v67, v48
	v_cvt_pk_bf16_f32 v48, v49, v84
	ds_write_b16 v67, v48 offset:64
	v_add_u32_e32 v69, v190, v200
	s_nop 0
	v_mul_f32_e32 v48, v70, v236
	v_mul_f32_e32 v49, v54, v236
	v_cvt_pk_bf16_f32 v48, v48, v84
	ds_write_b16 v68, v48
	v_cvt_pk_bf16_f32 v48, v49, v84
	ds_write_b16 v68, v48 offset:64
	v_add_u32_e32 v70, v190, v199
	s_waitcnt vmcnt(7)
	v_lshlrev_b32_e32 v54, 16, v108
	s_nop 0
	v_mul_f32_e32 v48, v71, v237
	v_mul_f32_e32 v49, v55, v237
	v_cvt_pk_bf16_f32 v48, v48, v84
	ds_write_b16 v69, v48
	v_cvt_pk_bf16_f32 v48, v49, v84
	ds_write_b16 v69, v48 offset:64
	v_add_u32_e32 v71, v190, v197
	v_and_b32_e32 v55, 0xffff0000, v108
	s_nop 0
	v_mul_f32_e32 v48, v72, v238
	v_mul_f32_e32 v49, v56, v238
	v_cvt_pk_bf16_f32 v48, v48, v84
	ds_write_b16 v70, v48
	v_cvt_pk_bf16_f32 v48, v49, v84
	ds_write_b16 v70, v48 offset:64
	v_add_u32_e32 v72, v190, v196
	v_lshlrev_b32_e32 v56, 16, v109
	s_nop 0
	v_mul_f32_e32 v48, v73, v239
	v_mul_f32_e32 v49, v57, v239
	v_cvt_pk_bf16_f32 v48, v48, v84
	ds_write_b16 v71, v48
	v_cvt_pk_bf16_f32 v48, v49, v84
	ds_write_b16 v71, v48 offset:64
	v_add_u32_e32 v73, v190, v195
	v_and_b32_e32 v57, 0xffff0000, v109
	s_nop 0
	v_mul_f32_e32 v48, v74, v240
	v_mul_f32_e32 v49, v58, v240
	v_cvt_pk_bf16_f32 v48, v48, v84
	ds_write_b16 v72, v48
	v_cvt_pk_bf16_f32 v48, v49, v84
	ds_write_b16 v72, v48 offset:64
	v_add_u32_e32 v74, v190, v194
	v_lshlrev_b32_e32 v58, 16, v110
	s_nop 0
	v_mul_f32_e32 v48, v75, v241
	v_mul_f32_e32 v49, v59, v241
	v_cvt_pk_bf16_f32 v48, v48, v84
	ds_write_b16 v73, v48
	v_cvt_pk_bf16_f32 v48, v49, v84
	ds_write_b16 v73, v48 offset:64
	v_add_u32_e32 v75, v190, v193
	v_and_b32_e32 v59, 0xffff0000, v110
	s_nop 0
	v_mul_f32_e32 v48, v76, v242
	v_mul_f32_e32 v49, v60, v242
	v_cvt_pk_bf16_f32 v48, v48, v84
	ds_write_b16 v74, v48
	v_cvt_pk_bf16_f32 v48, v49, v84
	ds_write_b16 v74, v48 offset:64
	v_add_u32_e32 v76, v190, v192
	v_lshlrev_b32_e32 v60, 16, v111
	s_nop 0
	v_mul_f32_e32 v48, v77, v243
	v_mul_f32_e32 v49, v61, v243
	v_cvt_pk_bf16_f32 v48, v48, v84
	ds_write_b16 v75, v48
	v_cvt_pk_bf16_f32 v50, v49, v84
	ds_write_b16 v75, v50 offset:64
	v_add_u32_e32 v77, v190, v191
	v_and_b32_e32 v61, 0xffff0000, v111
	v_lshl_add_u64 v[48:49], v[112:113], 1, s[18:19]
	s_nop 0
	v_mul_f32_e32 v50, v78, v244
	v_mul_f32_e32 v51, v62, v244
	v_cvt_pk_bf16_f32 v50, v50, v84
	ds_write_b16 v76, v50
	v_cvt_pk_bf16_f32 v50, v51, v84
	ds_write_b16 v76, v50 offset:64
	s_waitcnt vmcnt(5)
	v_lshlrev_b32_e32 v62, 16, v104
	s_nop 0
	v_mul_f32_e32 v50, v79, v245
	v_cvt_pk_bf16_f32 v50, v50, v84
	v_mul_f32_e32 v51, v63, v245
	ds_write_b16 v77, v50
	v_cvt_pk_bf16_f32 v50, v51, v84
	ds_write_b16 v77, v50 offset:64
	s_waitcnt lgkmcnt(0)
	ds_read_b128 v[214:217], v87
	ds_read_b128 v[218:221], v87 offset:1024
	ds_read_b128 v[222:225], v87 offset:2048
	ds_read_b128 v[226:229], v87 offset:3072
	v_and_b32_e32 v63, 0xffff0000, v104
	s_waitcnt lgkmcnt(0)
	v_lshlrev_b32_e32 v78, 16, v214
	v_and_b32_e32 v50, 0xffff0000, v214
	v_lshlrev_b32_e32 v79, 16, v215
	v_and_b32_e32 v51, 0xffff0000, v215
	v_lshlrev_b32_e32 v88, 16, v216
	v_and_b32_e32 v52, 0xffff0000, v216
	v_lshlrev_b32_e32 v89, 16, v217
	v_and_b32_e32 v53, 0xffff0000, v217
	v_mul_f32_e32 v54, v78, v54
	v_mul_f32_e32 v50, v50, v55
	v_mul_f32_e32 v55, v79, v56
	v_mul_f32_e32 v51, v51, v57
	v_mul_f32_e32 v56, v88, v58
	v_mul_f32_e32 v52, v52, v59
	v_mul_f32_e32 v57, v89, v60
	v_mul_f32_e32 v53, v53, v61
	v_cvt_pk_bf16_f32 v50, v54, v50
	v_cvt_pk_bf16_f32 v51, v55, v51
	v_cvt_pk_bf16_f32 v52, v56, v52
	v_cvt_pk_bf16_f32 v53, v57, v53
	v_lshlrev_b32_e32 v58, 16, v105
	v_and_b32_e32 v59, 0xffff0000, v105
	global_store_dwordx4 v[48:49], v[50:53], off
	v_lshlrev_b32_e32 v60, 16, v106
	s_waitcnt lgkmcnt(0)
	v_lshlrev_b32_e32 v50, 16, v218
	v_and_b32_e32 v51, 0xffff0000, v218
	v_lshlrev_b32_e32 v52, 16, v219
	v_and_b32_e32 v53, 0xffff0000, v219
	v_mul_f32_e32 v50, v50, v62
	v_mul_f32_e32 v51, v51, v63
	v_mul_f32_e32 v54, v52, v58
	v_mul_f32_e32 v53, v53, v59
	v_cvt_pk_bf16_f32 v52, v50, v51
	v_cvt_pk_bf16_f32 v53, v54, v53
	v_lshlrev_b32_e32 v50, 16, v220
	v_and_b32_e32 v51, 0xffff0000, v220
	v_and_b32_e32 v54, 0xffff0000, v106
	v_mul_f32_e32 v50, v50, v60
	v_mul_f32_e32 v51, v51, v54
	v_cvt_pk_bf16_f32 v54, v50, v51
	v_lshlrev_b32_e32 v50, 16, v107
	v_lshlrev_b32_e32 v51, 16, v221
	v_mul_f32_e32 v50, v51, v50
	v_and_b32_e32 v51, 0xffff0000, v221
	v_and_b32_e32 v55, 0xffff0000, v107
	v_mul_f32_e32 v51, v51, v55
	v_cvt_pk_bf16_f32 v55, v50, v51
	v_add_co_u32_e32 v50, vcc, s9, v48
	s_nop 1
	v_addc_co_u32_e32 v51, vcc, 0, v49, vcc
	global_store_dwordx4 v[50:51], v[52:55], off
	s_waitcnt vmcnt(5)
	s_nop 0
	v_lshlrev_b32_e32 v52, 16, v100
	s_waitcnt lgkmcnt(0)
	v_lshlrev_b32_e32 v53, 16, v222
	v_mul_f32_e32 v52, v53, v52
	v_and_b32_e32 v53, 0xffff0000, v222
	v_and_b32_e32 v54, 0xffff0000, v100
	v_mul_f32_e32 v53, v53, v54
	v_cvt_pk_bf16_f32 v54, v52, v53
	v_lshlrev_b32_e32 v52, 16, v101
	v_lshlrev_b32_e32 v53, 16, v223
	v_mul_f32_e32 v52, v53, v52
	v_and_b32_e32 v53, 0xffff0000, v223
	v_and_b32_e32 v55, 0xffff0000, v101
	v_mul_f32_e32 v53, v53, v55
	v_cvt_pk_bf16_f32 v55, v52, v53
	v_lshlrev_b32_e32 v52, 16, v102
	v_lshlrev_b32_e32 v53, 16, v224
	v_mul_f32_e32 v52, v53, v52
	v_and_b32_e32 v53, 0xffff0000, v224
	v_and_b32_e32 v56, 0xffff0000, v102
	v_mul_f32_e32 v53, v53, v56
	v_cvt_pk_bf16_f32 v56, v52, v53
	v_lshlrev_b32_e32 v52, 16, v103
	v_lshlrev_b32_e32 v53, 16, v225
	v_mul_f32_e32 v52, v53, v52
	v_and_b32_e32 v53, 0xffff0000, v225
	v_and_b32_e32 v57, 0xffff0000, v103
	v_mul_f32_e32 v53, v53, v57
	v_cvt_pk_bf16_f32 v57, v52, v53
	v_add_co_u32_e32 v52, vcc, s8, v48
	s_nop 1
	v_addc_co_u32_e32 v53, vcc, 0, v49, vcc
	global_store_dwordx4 v[52:53], v[54:57], off
	s_waitcnt vmcnt(4)
	s_nop 0
	v_lshlrev_b32_e32 v54, 16, v80
	s_waitcnt lgkmcnt(0)
	v_lshlrev_b32_e32 v55, 16, v226
	v_mul_f32_e32 v54, v55, v54
	v_and_b32_e32 v55, 0xffff0000, v226
	v_and_b32_e32 v56, 0xffff0000, v80
	v_mul_f32_e32 v55, v55, v56
	v_cvt_pk_bf16_f32 v56, v54, v55
	v_lshlrev_b32_e32 v54, 16, v81
	v_lshlrev_b32_e32 v55, 16, v227
	v_mul_f32_e32 v54, v55, v54
	v_and_b32_e32 v55, 0xffff0000, v227
	v_and_b32_e32 v57, 0xffff0000, v81
	v_mul_f32_e32 v55, v55, v57
	v_cvt_pk_bf16_f32 v57, v54, v55
	v_lshlrev_b32_e32 v54, 16, v82
	v_lshlrev_b32_e32 v55, 16, v228
	v_mul_f32_e32 v54, v55, v54
	v_and_b32_e32 v55, 0xffff0000, v228
	v_and_b32_e32 v58, 0xffff0000, v82
	v_mul_f32_e32 v55, v55, v58
	v_cvt_pk_bf16_f32 v58, v54, v55
	v_lshlrev_b32_e32 v54, 16, v83
	v_lshlrev_b32_e32 v55, 16, v229
	v_mul_f32_e32 v54, v55, v54
	v_and_b32_e32 v55, 0xffff0000, v229
	v_and_b32_e32 v59, 0xffff0000, v83
	v_mul_f32_e32 v55, v55, v59
	v_cvt_pk_bf16_f32 v59, v54, v55
	v_add_co_u32_e32 v54, vcc, s3, v48
	s_nop 1
	v_addc_co_u32_e32 v55, vcc, 0, v49, vcc
	global_store_dwordx4 v[54:55], v[56:59], off
	s_waitcnt lgkmcnt(0)
	s_and_b64 vcc, exec, s[4:5]
	s_nop 0
	v_mul_f32_e32 v16, v16, v230
	v_cvt_pk_bf16_f32 v16, v16, v84
	v_mul_f32_e32 v0, v0, v230
	ds_write_b16 v86, v16
	v_cvt_pk_bf16_f32 v0, v0, v84
	ds_write_b16 v86, v0 offset:64
	s_nop 0
	v_mul_f32_e32 v0, v17, v231
	v_cvt_pk_bf16_f32 v0, v0, v84
	ds_write_b16 v85, v0
	v_mul_f32_e32 v0, v1, v231
	v_cvt_pk_bf16_f32 v0, v0, v84
	ds_write_b16 v85, v0 offset:64
	s_nop 0
	v_mul_f32_e32 v0, v18, v232
	v_cvt_pk_bf16_f32 v0, v0, v84
	ds_write_b16 v64, v0
	v_mul_f32_e32 v0, v2, v232
	v_cvt_pk_bf16_f32 v0, v0, v84
	ds_write_b16 v64, v0 offset:64
	s_nop 0
	v_mul_f32_e32 v0, v19, v233
	v_cvt_pk_bf16_f32 v0, v0, v84
	ds_write_b16 v65, v0
	v_mul_f32_e32 v0, v3, v233
	v_cvt_pk_bf16_f32 v0, v0, v84
	ds_write_b16 v65, v0 offset:64
	s_nop 0
	v_mul_f32_e32 v0, v20, v234
	v_cvt_pk_bf16_f32 v0, v0, v84
	ds_write_b16 v66, v0
	v_mul_f32_e32 v0, v4, v234
	v_cvt_pk_bf16_f32 v0, v0, v84
	ds_write_b16 v66, v0 offset:64
	v_lshlrev_b32_e32 v4, 16, v44
	s_nop 0
	v_mul_f32_e32 v0, v21, v235
	v_cvt_pk_bf16_f32 v0, v0, v84
	ds_write_b16 v67, v0
	v_mul_f32_e32 v0, v5, v235
	v_cvt_pk_bf16_f32 v0, v0, v84
	ds_write_b16 v67, v0 offset:64
	s_nop 0
	v_mul_f32_e32 v0, v22, v236
	v_cvt_pk_bf16_f32 v0, v0, v84
	ds_write_b16 v68, v0
	v_mul_f32_e32 v0, v6, v236
	v_cvt_pk_bf16_f32 v0, v0, v84
	ds_write_b16 v68, v0 offset:64
	s_nop 0
	v_mul_f32_e32 v0, v23, v237
	v_cvt_pk_bf16_f32 v0, v0, v84
	ds_write_b16 v69, v0
	v_mul_f32_e32 v0, v7, v237
	v_cvt_pk_bf16_f32 v0, v0, v84
	ds_write_b16 v69, v0 offset:64
	s_nop 0
	v_mul_f32_e32 v0, v24, v238
	v_cvt_pk_bf16_f32 v0, v0, v84
	ds_write_b16 v70, v0
	v_mul_f32_e32 v0, v8, v238
	v_cvt_pk_bf16_f32 v0, v0, v84
	ds_write_b16 v70, v0 offset:64
	s_nop 0
	v_mul_f32_e32 v0, v25, v239
	v_cvt_pk_bf16_f32 v0, v0, v84
	ds_write_b16 v71, v0
	v_mul_f32_e32 v0, v9, v239
	v_cvt_pk_bf16_f32 v0, v0, v84
	ds_write_b16 v71, v0 offset:64
	s_nop 0
	v_mul_f32_e32 v0, v26, v240
	v_cvt_pk_bf16_f32 v0, v0, v84
	ds_write_b16 v72, v0
	v_mul_f32_e32 v0, v10, v240
	v_cvt_pk_bf16_f32 v0, v0, v84
	ds_write_b16 v72, v0 offset:64
	s_nop 0
	v_mul_f32_e32 v0, v27, v241
	v_cvt_pk_bf16_f32 v0, v0, v84
	ds_write_b16 v73, v0
	v_mul_f32_e32 v0, v11, v241
	v_cvt_pk_bf16_f32 v0, v0, v84
	ds_write_b16 v73, v0 offset:64
	s_nop 0
	v_mul_f32_e32 v0, v28, v242
	v_cvt_pk_bf16_f32 v0, v0, v84
	ds_write_b16 v74, v0
	v_mul_f32_e32 v0, v12, v242
	v_cvt_pk_bf16_f32 v0, v0, v84
	ds_write_b16 v74, v0 offset:64
	s_nop 0
	v_mul_f32_e32 v0, v29, v243
	v_cvt_pk_bf16_f32 v0, v0, v84
	ds_write_b16 v75, v0
	v_mul_f32_e32 v0, v13, v243
	v_cvt_pk_bf16_f32 v0, v0, v84
	ds_write_b16 v75, v0 offset:64
	s_nop 0
	v_mul_f32_e32 v0, v30, v244
	v_cvt_pk_bf16_f32 v0, v0, v84
	ds_write_b16 v76, v0
	v_mul_f32_e32 v0, v14, v244
	v_cvt_pk_bf16_f32 v0, v0, v84
	ds_write_b16 v76, v0 offset:64
	s_nop 0
	v_mul_f32_e32 v0, v31, v245
	v_cvt_pk_bf16_f32 v0, v0, v84
	ds_write_b16 v77, v0
	v_mul_f32_e32 v0, v15, v245
	v_cvt_pk_bf16_f32 v0, v0, v84
	ds_write_b16 v77, v0 offset:64
	s_waitcnt lgkmcnt(0)
	ds_read_b128 v[214:217], v87
	ds_read_b128 v[218:221], v87 offset:1024
	ds_read_b128 v[222:225], v87 offset:2048
	ds_read_b128 v[226:229], v87 offset:3072
	s_waitcnt lgkmcnt(0)
	v_lshlrev_b32_e32 v5, 16, v214
	v_mul_f32_e32 v4, v5, v4
	v_and_b32_e32 v0, 0xffff0000, v214
	v_and_b32_e32 v5, 0xffff0000, v44
	v_mul_f32_e32 v0, v0, v5
	v_cvt_pk_bf16_f32 v0, v4, v0
	v_lshlrev_b32_e32 v4, 16, v45
	v_lshlrev_b32_e32 v5, 16, v215
	v_mul_f32_e32 v4, v5, v4
	v_and_b32_e32 v1, 0xffff0000, v215
	v_and_b32_e32 v5, 0xffff0000, v45
	v_mul_f32_e32 v1, v1, v5
	v_cvt_pk_bf16_f32 v1, v4, v1
	v_lshlrev_b32_e32 v4, 16, v46
	v_lshlrev_b32_e32 v5, 16, v216
	v_mul_f32_e32 v4, v5, v4
	v_and_b32_e32 v2, 0xffff0000, v216
	v_and_b32_e32 v5, 0xffff0000, v46
	v_mul_f32_e32 v2, v2, v5
	v_cvt_pk_bf16_f32 v2, v4, v2
	v_lshlrev_b32_e32 v4, 16, v47
	v_lshlrev_b32_e32 v5, 16, v217
	v_mul_f32_e32 v4, v5, v4
	v_and_b32_e32 v3, 0xffff0000, v217
	v_and_b32_e32 v5, 0xffff0000, v47
	v_mul_f32_e32 v3, v3, v5
	v_cvt_pk_bf16_f32 v3, v4, v3
	global_store_dwordx4 v[48:49], v[0:3], off offset:128
	s_nop 1
	v_lshlrev_b32_e32 v0, 16, v40
	s_waitcnt lgkmcnt(0)
	v_lshlrev_b32_e32 v1, 16, v218
	v_mul_f32_e32 v0, v1, v0
	v_and_b32_e32 v1, 0xffff0000, v218
	v_and_b32_e32 v2, 0xffff0000, v40
	v_mul_f32_e32 v1, v1, v2
	v_cvt_pk_bf16_f32 v0, v0, v1
	v_lshlrev_b32_e32 v1, 16, v41
	v_lshlrev_b32_e32 v2, 16, v219
	v_mul_f32_e32 v1, v2, v1
	v_and_b32_e32 v2, 0xffff0000, v219
	v_and_b32_e32 v3, 0xffff0000, v41
	v_mul_f32_e32 v2, v2, v3
	v_cvt_pk_bf16_f32 v1, v1, v2
	v_lshlrev_b32_e32 v2, 16, v42
	v_lshlrev_b32_e32 v3, 16, v220
	v_mul_f32_e32 v2, v3, v2
	v_and_b32_e32 v3, 0xffff0000, v220
	v_and_b32_e32 v4, 0xffff0000, v42
	v_mul_f32_e32 v3, v3, v4
	v_cvt_pk_bf16_f32 v2, v2, v3
	v_lshlrev_b32_e32 v3, 16, v43
	v_lshlrev_b32_e32 v4, 16, v221
	v_mul_f32_e32 v3, v4, v3
	v_and_b32_e32 v4, 0xffff0000, v221
	v_and_b32_e32 v5, 0xffff0000, v43
	v_mul_f32_e32 v4, v4, v5
	v_cvt_pk_bf16_f32 v3, v3, v4
	global_store_dwordx4 v[50:51], v[0:3], off offset:128
	s_nop 1
	v_lshlrev_b32_e32 v0, 16, v36
	s_waitcnt lgkmcnt(0)
	v_lshlrev_b32_e32 v1, 16, v222
	v_mul_f32_e32 v0, v1, v0
	v_and_b32_e32 v1, 0xffff0000, v222
	v_and_b32_e32 v2, 0xffff0000, v36
	v_mul_f32_e32 v1, v1, v2
	v_cvt_pk_bf16_f32 v0, v0, v1
	v_lshlrev_b32_e32 v1, 16, v37
	v_lshlrev_b32_e32 v2, 16, v223
	v_mul_f32_e32 v1, v2, v1
	v_and_b32_e32 v2, 0xffff0000, v223
	v_and_b32_e32 v3, 0xffff0000, v37
	v_mul_f32_e32 v2, v2, v3
	v_cvt_pk_bf16_f32 v1, v1, v2
	v_lshlrev_b32_e32 v2, 16, v38
	v_lshlrev_b32_e32 v3, 16, v224
	v_mul_f32_e32 v2, v3, v2
	v_and_b32_e32 v3, 0xffff0000, v224
	v_and_b32_e32 v4, 0xffff0000, v38
	v_mul_f32_e32 v3, v3, v4
	v_cvt_pk_bf16_f32 v2, v2, v3
	v_lshlrev_b32_e32 v3, 16, v39
	v_lshlrev_b32_e32 v4, 16, v225
	v_mul_f32_e32 v3, v4, v3
	v_and_b32_e32 v4, 0xffff0000, v225
	v_and_b32_e32 v5, 0xffff0000, v39
	v_mul_f32_e32 v4, v4, v5
	v_cvt_pk_bf16_f32 v3, v3, v4
	global_store_dwordx4 v[52:53], v[0:3], off offset:128
	s_waitcnt vmcnt(7)
	s_nop 0
	v_lshlrev_b32_e32 v0, 16, v32
	s_waitcnt lgkmcnt(0)
	v_lshlrev_b32_e32 v1, 16, v226
	v_mul_f32_e32 v0, v1, v0
	v_and_b32_e32 v1, 0xffff0000, v226
	v_and_b32_e32 v2, 0xffff0000, v32
	v_mul_f32_e32 v1, v1, v2
	v_cvt_pk_bf16_f32 v0, v0, v1
	v_lshlrev_b32_e32 v1, 16, v33
	v_lshlrev_b32_e32 v2, 16, v227
	v_mul_f32_e32 v1, v2, v1
	v_and_b32_e32 v2, 0xffff0000, v227
	v_and_b32_e32 v3, 0xffff0000, v33
	v_mul_f32_e32 v2, v2, v3
	v_cvt_pk_bf16_f32 v1, v1, v2
	v_lshlrev_b32_e32 v2, 16, v34
	v_lshlrev_b32_e32 v3, 16, v228
	v_mul_f32_e32 v2, v3, v2
	v_and_b32_e32 v3, 0xffff0000, v228
	v_and_b32_e32 v4, 0xffff0000, v34
	v_mul_f32_e32 v3, v3, v4
	v_cvt_pk_bf16_f32 v2, v2, v3
	v_lshlrev_b32_e32 v3, 16, v35
	v_lshlrev_b32_e32 v4, 16, v229
	v_mul_f32_e32 v3, v4, v3
	v_and_b32_e32 v4, 0xffff0000, v229
	v_and_b32_e32 v5, 0xffff0000, v35
	v_mul_f32_e32 v4, v4, v5
	v_cvt_pk_bf16_f32 v3, v3, v4
	global_store_dwordx4 v[54:55], v[0:3], off offset:128
	s_waitcnt lgkmcnt(0)
	s_cbranch_vccnz .LBB0_1162
	s_waitcnt lgkmcnt(0)
	s_barrier
